# also the barrier between the branch GEMM and outproj: MERGED tiles released per panel (write-through, LDS-transposed rows), outproj tile acquires its panel counter
# speedup vs baseline: 1.0352x; 1.0124x over previous
.Lop_tile:
	s_and_b32 s0, s78, 3
	s_or_b32 s0, s0, s77
	v_readlane_b32 s12, v253, 5
	v_readlane_b32 s13, v253, 6
	s_lshl_b32 s2, s0, 2
	s_add_u32 s2, s2, 0x100
	v_mov_b32_e32 v170, s2
	s_add_i32 s3, s82, 1
	s_lshl_b32 s3, s3, 3
	s_movk_i32 s14, 0x1000
	s_cmp_lg_u32 s76, 0
	s_cbranch_scc1 .Lop_acqw
	s_nop 2
.Lop_acqp:
	global_load_dword v171, v170, s[12:13] sc1
	s_waitcnt vmcnt(0)
	v_readfirstlane_b32 s15, v171
	s_cmp_ge_u32 s15, s3
	s_cbranch_scc1 .Lop_acqok
	s_sleep 1
	s_add_i32 s14, s14, -1
	s_cmp_lg_u32 s14, 0
	s_cbranch_scc1 .Lop_acqp

.Lop_acqw:
	s_barrier
	s_lshr_b32 s1, s78, 2
	s_lshl_b32 s1, s1, 7
	s_lshl_b32 s2, s0, 8
	s_mul_i32 s3, s2, 0x800
	s_add_u32 s68, s18, s3
	s_addc_u32 s69, s19, 0
	s_mul_i32 s3, s1, 0x800
	s_add_u32 s70, s80, s3
	s_addc_u32 s71, s81, 0
	s_lshl_b32 s3, s2, 11
	s_lshl_b32 s12, s1, 1
	s_add_u32 s3, s3, s12
	s_add_u32 s74, s24, s3
	s_addc_u32 s75, s25, 0
	s_add_i32 s12, s0, -12
	s_lshr_b32 s12, s12, 2
	s_cmp_lt_u32 s0, 16
	s_cselect_b32 s12, 0, s12
	s_cselect_b32 s14, s52, s54
	s_cselect_b32 s15, s53, s55
	s_mul_i32 s13, s82, 5
	s_add_i32 s12, s12, s13
	s_mul_i32 s12, s12, 0x6000
	s_add_u32 s12, s12, 0x2000
	s_lshl_b32 s13, s1, 2
	s_add_u32 s12, s12, s13
	s_add_u32 s72, s30, s12
	s_addc_u32 s73, s31, 0
	s_and_b32 s12, s0, 15
	s_lshl_b32 s12, s12, 20
	s_add_u32 s12, s12, s13
	s_add_u32 s14, s14, s12
	s_addc_u32 s15, s15, 0
	s_cmp_eq_u32 s82, 0
	s_cselect_b32 s14, s14, s74
	s_cselect_b32 s15, s15, s75
	s_cselect_b32 s38, 64, 32
	s_cselect_b64 vcc, -1, 0
	s_lshl_b32 s39, s38, 1
	s_add_u32 s40, s39, s38
	v_cndmask_b32_e32 v191, v206, v210, vcc
	v_cndmask_b32_e32 v192, v207, v211, vcc
	v_cndmask_b32_e32 v193, v208, v168, vcc
	v_cndmask_b32_e32 v244, v209, v169, vcc
	s_add_u32 m0, s76, 0x0
	s_nop 0
	global_load_lds_dwordx4 v196, s[68:69]
	s_add_u32 m0, s76, 0x2000
	s_nop 0
	global_load_lds_dwordx4 v197, s[68:69]
	s_add_u32 m0, s76, 0x4000
	s_nop 0
	global_load_lds_dwordx4 v198, s[68:69]
	s_add_u32 m0, s76, 0x6000
	s_nop 0
	global_load_lds_dwordx4 v199, s[68:69]
	s_add_u32 m0, s76, 0x8000
	s_nop 0
	global_load_lds_dwordx4 v196, s[70:71]
	s_add_u32 m0, s76, 0xa000
	s_nop 0
	global_load_lds_dwordx4 v197, s[70:71]
	s_add_u32 s68, s68, 0x80
	s_addc_u32 s69, s69, 0
	s_add_u32 s70, s70, 0x80
	s_addc_u32 s71, s71, 0
	s_add_u32 m0, s76, 0xc000
	s_nop 0
	global_load_lds_dwordx4 v196, s[68:69]
	s_add_u32 m0, s76, 0xe000
	s_nop 0
	global_load_lds_dwordx4 v197, s[68:69]
	s_add_u32 m0, s76, 0x10000
	s_nop 0
	global_load_lds_dwordx4 v198, s[68:69]
	s_add_u32 m0, s76, 0x12000
	s_nop 0
	global_load_lds_dwordx4 v199, s[68:69]
	s_add_u32 m0, s76, 0x14000
	s_nop 0
	global_load_lds_dwordx4 v196, s[70:71]
	s_add_u32 m0, s76, 0x16000
	s_nop 0
	global_load_lds_dwordx4 v197, s[70:71]
	s_add_u32 s68, s68, 0x80
	s_addc_u32 s69, s69, 0
	s_add_u32 s70, s70, 0x80
	s_addc_u32 s71, s71, 0
	s_waitcnt vmcnt(6)
	s_barrier
	s_cmp_ge_u32 s76, 0x1000
	s_cbranch_scc1 .Lop_streamB
	v_add_u32_e32 v204, 0x0, v200
	v_add_u32_e32 v205, 0x0, v202
	ds_read_b128 v[130:133], v204 offset:0
	ds_read_b128 v[134:137], v204 offset:2048
	ds_read_b128 v[138:141], v204 offset:4096
	ds_read_b128 v[142:145], v204 offset:6144
	ds_read_b128 v[146:149], v205 offset:0
	ds_read_b128 v[150:153], v205 offset:2048
	ds_read_b128 v[154:157], v205 offset:4096
	ds_read_b128 v[158:161], v205 offset:6144
	v_add_u32_e32 v204, 0x0, v201
	v_add_u32_e32 v205, 0x0, v203
	ds_read_b128 v[212:215], v204 offset:0
	ds_read_b128 v[216:219], v204 offset:2048
	ds_read_b128 v[220:223], v204 offset:4096
	ds_read_b128 v[224:227], v204 offset:6144
	ds_read_b128 v[228:231], v205 offset:0
	ds_read_b128 v[232:235], v205 offset:2048
	ds_read_b128 v[236:239], v205 offset:4096
	ds_read_b128 v[240:243], v205 offset:6144
	s_add_u32 m0, s76, 0x18000
	s_nop 0
	global_load_lds_dwordx4 v196, s[68:69]
	s_add_u32 m0, s76, 0x1a000
	s_nop 0
	global_load_lds_dwordx4 v197, s[68:69]
	s_add_u32 m0, s76, 0x1c000
	s_nop 0
	global_load_lds_dwordx4 v198, s[68:69]
	s_add_u32 m0, s76, 0x1e000
	s_nop 0
	global_load_lds_dwordx4 v199, s[68:69]
	s_add_u32 m0, s76, 0x20000
	s_nop 0
	global_load_lds_dwordx4 v196, s[70:71]
	s_add_u32 m0, s76, 0x22000
	s_nop 0
	global_load_lds_dwordx4 v197, s[70:71]
	s_add_u32 s68, s68, 0x80
	s_addc_u32 s69, s69, 0
	s_add_u32 s70, s70, 0x80
	s_addc_u32 s71, s71, 0
	global_load_dwordx4 v[174:177], v190, s[72:73] offset:0
	global_load_dwordx4 v[178:181], v190, s[72:73] offset:64
	s_waitcnt lgkmcnt(0)
	s_barrier
	v_mfma_f32_16x16x32_bf16 v[2:5], v[146:149], v[130:133], 0
	v_mfma_f32_16x16x32_bf16 v[6:9], v[150:153], v[130:133], 0
	v_mfma_f32_16x16x32_bf16 v[10:13], v[154:157], v[130:133], 0
	v_mfma_f32_16x16x32_bf16 v[14:17], v[158:161], v[130:133], 0
	v_mfma_f32_16x16x32_bf16 v[18:21], v[146:149], v[134:137], 0
	v_mfma_f32_16x16x32_bf16 v[22:25], v[150:153], v[134:137], 0
	v_mfma_f32_16x16x32_bf16 v[26:29], v[154:157], v[134:137], 0
	v_mfma_f32_16x16x32_bf16 v[30:33], v[158:161], v[134:137], 0
	v_mfma_f32_16x16x32_bf16 v[34:37], v[146:149], v[138:141], 0
	v_mfma_f32_16x16x32_bf16 v[38:41], v[150:153], v[138:141], 0
	v_mfma_f32_16x16x32_bf16 v[42:45], v[154:157], v[138:141], 0
	v_mfma_f32_16x16x32_bf16 v[46:49], v[158:161], v[138:141], 0
	v_mfma_f32_16x16x32_bf16 v[50:53], v[146:149], v[142:145], 0
	v_mfma_f32_16x16x32_bf16 v[54:57], v[150:153], v[142:145], 0
	v_mfma_f32_16x16x32_bf16 v[58:61], v[154:157], v[142:145], 0
	v_mfma_f32_16x16x32_bf16 v[62:65], v[158:161], v[142:145], 0
	v_mfma_f32_16x16x32_bf16 v[2:5], v[228:231], v[212:215], v[2:5]
	v_mfma_f32_16x16x32_bf16 v[6:9], v[232:235], v[212:215], v[6:9]
	v_mfma_f32_16x16x32_bf16 v[10:13], v[236:239], v[212:215], v[10:13]
	v_mfma_f32_16x16x32_bf16 v[14:17], v[240:243], v[212:215], v[14:17]
	v_mfma_f32_16x16x32_bf16 v[18:21], v[228:231], v[216:219], v[18:21]
	v_mfma_f32_16x16x32_bf16 v[22:25], v[232:235], v[216:219], v[22:25]
	v_mfma_f32_16x16x32_bf16 v[26:29], v[236:239], v[216:219], v[26:29]
	v_mfma_f32_16x16x32_bf16 v[30:33], v[240:243], v[216:219], v[30:33]
	v_mfma_f32_16x16x32_bf16 v[34:37], v[228:231], v[220:223], v[34:37]
	v_mfma_f32_16x16x32_bf16 v[38:41], v[232:235], v[220:223], v[38:41]
	v_mfma_f32_16x16x32_bf16 v[42:45], v[236:239], v[220:223], v[42:45]
	v_mfma_f32_16x16x32_bf16 v[46:49], v[240:243], v[220:223], v[46:49]
	v_mfma_f32_16x16x32_bf16 v[50:53], v[228:231], v[224:227], v[50:53]
	v_mfma_f32_16x16x32_bf16 v[54:57], v[232:235], v[224:227], v[54:57]
	v_mfma_f32_16x16x32_bf16 v[58:61], v[236:239], v[224:227], v[58:61]
	v_mfma_f32_16x16x32_bf16 v[62:65], v[240:243], v[224:227], v[62:65]
	s_waitcnt vmcnt(8)
	s_barrier
	v_add_u32_e32 v204, 0xc000, v200
	v_add_u32_e32 v205, 0xc000, v202
	ds_read_b128 v[130:133], v204 offset:0
	ds_read_b128 v[134:137], v204 offset:2048
	ds_read_b128 v[138:141], v204 offset:4096
	ds_read_b128 v[142:145], v204 offset:6144
	ds_read_b128 v[146:149], v205 offset:0
	ds_read_b128 v[150:153], v205 offset:2048
	ds_read_b128 v[154:157], v205 offset:4096
	ds_read_b128 v[158:161], v205 offset:6144
	v_add_u32_e32 v204, 0xc000, v201
	v_add_u32_e32 v205, 0xc000, v203
	ds_read_b128 v[212:215], v204 offset:0
	ds_read_b128 v[216:219], v204 offset:2048
	ds_read_b128 v[220:223], v204 offset:4096
	ds_read_b128 v[224:227], v204 offset:6144
	ds_read_b128 v[228:231], v205 offset:0
	ds_read_b128 v[232:235], v205 offset:2048
	ds_read_b128 v[236:239], v205 offset:4096
	ds_read_b128 v[240:243], v205 offset:6144
	s_add_u32 m0, s76, 0x0
	s_nop 0
	global_load_lds_dwordx4 v196, s[68:69]
	s_add_u32 m0, s76, 0x2000
	s_nop 0
	global_load_lds_dwordx4 v197, s[68:69]
	s_add_u32 m0, s76, 0x4000
	s_nop 0
	global_load_lds_dwordx4 v198, s[68:69]
	s_add_u32 m0, s76, 0x6000
	s_nop 0
	global_load_lds_dwordx4 v199, s[68:69]
	s_add_u32 m0, s76, 0x8000
	s_nop 0
	global_load_lds_dwordx4 v196, s[70:71]
	s_add_u32 m0, s76, 0xa000
	s_nop 0
	global_load_lds_dwordx4 v197, s[70:71]
	s_add_u32 s68, s68, 0x80
	s_addc_u32 s69, s69, 0
	s_add_u32 s70, s70, 0x80
	s_addc_u32 s71, s71, 0
	global_load_dwordx4 v[182:185], v190, s[72:73] offset:128
	global_load_dwordx4 v[186:189], v190, s[72:73] offset:192
	s_waitcnt lgkmcnt(0)
	s_barrier
	v_mfma_f32_16x16x32_bf16 v[2:5], v[146:149], v[130:133], v[2:5]
	v_mfma_f32_16x16x32_bf16 v[6:9], v[150:153], v[130:133], v[6:9]
	v_mfma_f32_16x16x32_bf16 v[10:13], v[154:157], v[130:133], v[10:13]
	v_mfma_f32_16x16x32_bf16 v[14:17], v[158:161], v[130:133], v[14:17]
	v_mfma_f32_16x16x32_bf16 v[18:21], v[146:149], v[134:137], v[18:21]
	v_mfma_f32_16x16x32_bf16 v[22:25], v[150:153], v[134:137], v[22:25]
	v_mfma_f32_16x16x32_bf16 v[26:29], v[154:157], v[134:137], v[26:29]
	v_mfma_f32_16x16x32_bf16 v[30:33], v[158:161], v[134:137], v[30:33]
	v_mfma_f32_16x16x32_bf16 v[34:37], v[146:149], v[138:141], v[34:37]
	v_mfma_f32_16x16x32_bf16 v[38:41], v[150:153], v[138:141], v[38:41]
	v_mfma_f32_16x16x32_bf16 v[42:45], v[154:157], v[138:141], v[42:45]
	v_mfma_f32_16x16x32_bf16 v[46:49], v[158:161], v[138:141], v[46:49]
	v_mfma_f32_16x16x32_bf16 v[50:53], v[146:149], v[142:145], v[50:53]
	v_mfma_f32_16x16x32_bf16 v[54:57], v[150:153], v[142:145], v[54:57]
	v_mfma_f32_16x16x32_bf16 v[58:61], v[154:157], v[142:145], v[58:61]
	v_mfma_f32_16x16x32_bf16 v[62:65], v[158:161], v[142:145], v[62:65]
	v_mfma_f32_16x16x32_bf16 v[2:5], v[228:231], v[212:215], v[2:5]
	v_mfma_f32_16x16x32_bf16 v[6:9], v[232:235], v[212:215], v[6:9]
	v_mfma_f32_16x16x32_bf16 v[10:13], v[236:239], v[212:215], v[10:13]
	v_mfma_f32_16x16x32_bf16 v[14:17], v[240:243], v[212:215], v[14:17]
	v_mfma_f32_16x16x32_bf16 v[18:21], v[228:231], v[216:219], v[18:21]
	v_mfma_f32_16x16x32_bf16 v[22:25], v[232:235], v[216:219], v[22:25]
	v_mfma_f32_16x16x32_bf16 v[26:29], v[236:239], v[216:219], v[26:29]
	v_mfma_f32_16x16x32_bf16 v[30:33], v[240:243], v[216:219], v[30:33]
	v_mfma_f32_16x16x32_bf16 v[34:37], v[228:231], v[220:223], v[34:37]
	v_mfma_f32_16x16x32_bf16 v[38:41], v[232:235], v[220:223], v[38:41]
	v_mfma_f32_16x16x32_bf16 v[42:45], v[236:239], v[220:223], v[42:45]
	v_mfma_f32_16x16x32_bf16 v[46:49], v[240:243], v[220:223], v[46:49]
	v_mfma_f32_16x16x32_bf16 v[50:53], v[228:231], v[224:227], v[50:53]
	v_mfma_f32_16x16x32_bf16 v[54:57], v[232:235], v[224:227], v[54:57]
	v_mfma_f32_16x16x32_bf16 v[58:61], v[236:239], v[224:227], v[58:61]
	v_mfma_f32_16x16x32_bf16 v[62:65], v[240:243], v[224:227], v[62:65]
	s_waitcnt vmcnt(10)
	s_barrier
	v_add_u32_e32 v204, 0x18000, v200
	v_add_u32_e32 v205, 0x18000, v202
	ds_read_b128 v[130:133], v204 offset:0
	ds_read_b128 v[134:137], v204 offset:2048
	ds_read_b128 v[138:141], v204 offset:4096
	ds_read_b128 v[142:145], v204 offset:6144
	ds_read_b128 v[146:149], v205 offset:0
	ds_read_b128 v[150:153], v205 offset:2048
	ds_read_b128 v[154:157], v205 offset:4096
	ds_read_b128 v[158:161], v205 offset:6144
	v_add_u32_e32 v204, 0x18000, v201
	v_add_u32_e32 v205, 0x18000, v203
	ds_read_b128 v[212:215], v204 offset:0
	ds_read_b128 v[216:219], v204 offset:2048
	ds_read_b128 v[220:223], v204 offset:4096
	ds_read_b128 v[224:227], v204 offset:6144
	ds_read_b128 v[228:231], v205 offset:0
	ds_read_b128 v[232:235], v205 offset:2048
	ds_read_b128 v[236:239], v205 offset:4096
	ds_read_b128 v[240:243], v205 offset:6144
	s_add_u32 m0, s76, 0xc000
	s_nop 0
	global_load_lds_dwordx4 v196, s[68:69]
	s_add_u32 m0, s76, 0xe000
	s_nop 0
	global_load_lds_dwordx4 v197, s[68:69]
	s_add_u32 m0, s76, 0x10000
	s_nop 0
	global_load_lds_dwordx4 v198, s[68:69]
	s_add_u32 m0, s76, 0x12000
	s_nop 0
	global_load_lds_dwordx4 v199, s[68:69]
	s_add_u32 m0, s76, 0x14000
	s_nop 0
	global_load_lds_dwordx4 v196, s[70:71]
	s_add_u32 m0, s76, 0x16000
	s_nop 0
	global_load_lds_dwordx4 v197, s[70:71]
	s_add_u32 s68, s68, 0x80
	s_addc_u32 s69, s69, 0
	s_add_u32 s70, s70, 0x80
	s_addc_u32 s71, s71, 0
	global_load_dwordx4 v[66:69], v191, s[14:15]
	v_add_u32_e32 v170, s38, v191
	global_load_dwordx4 v[70:73], v170, s[14:15]
	s_waitcnt lgkmcnt(0)
	s_barrier
	v_mfma_f32_16x16x32_bf16 v[2:5], v[146:149], v[130:133], v[2:5]
	v_mfma_f32_16x16x32_bf16 v[6:9], v[150:153], v[130:133], v[6:9]
	v_mfma_f32_16x16x32_bf16 v[10:13], v[154:157], v[130:133], v[10:13]
	v_mfma_f32_16x16x32_bf16 v[14:17], v[158:161], v[130:133], v[14:17]
	v_mfma_f32_16x16x32_bf16 v[18:21], v[146:149], v[134:137], v[18:21]
	v_mfma_f32_16x16x32_bf16 v[22:25], v[150:153], v[134:137], v[22:25]
	v_mfma_f32_16x16x32_bf16 v[26:29], v[154:157], v[134:137], v[26:29]
	v_mfma_f32_16x16x32_bf16 v[30:33], v[158:161], v[134:137], v[30:33]
	v_mfma_f32_16x16x32_bf16 v[34:37], v[146:149], v[138:141], v[34:37]
	v_mfma_f32_16x16x32_bf16 v[38:41], v[150:153], v[138:141], v[38:41]
	v_mfma_f32_16x16x32_bf16 v[42:45], v[154:157], v[138:141], v[42:45]
	v_mfma_f32_16x16x32_bf16 v[46:49], v[158:161], v[138:141], v[46:49]
	v_mfma_f32_16x16x32_bf16 v[50:53], v[146:149], v[142:145], v[50:53]
	v_mfma_f32_16x16x32_bf16 v[54:57], v[150:153], v[142:145], v[54:57]
	v_mfma_f32_16x16x32_bf16 v[58:61], v[154:157], v[142:145], v[58:61]
	v_mfma_f32_16x16x32_bf16 v[62:65], v[158:161], v[142:145], v[62:65]
	v_mfma_f32_16x16x32_bf16 v[2:5], v[228:231], v[212:215], v[2:5]
	v_mfma_f32_16x16x32_bf16 v[6:9], v[232:235], v[212:215], v[6:9]
	v_mfma_f32_16x16x32_bf16 v[10:13], v[236:239], v[212:215], v[10:13]
	v_mfma_f32_16x16x32_bf16 v[14:17], v[240:243], v[212:215], v[14:17]
	v_mfma_f32_16x16x32_bf16 v[18:21], v[228:231], v[216:219], v[18:21]
	v_mfma_f32_16x16x32_bf16 v[22:25], v[232:235], v[216:219], v[22:25]
	v_mfma_f32_16x16x32_bf16 v[26:29], v[236:239], v[216:219], v[26:29]
	v_mfma_f32_16x16x32_bf16 v[30:33], v[240:243], v[216:219], v[30:33]
	v_mfma_f32_16x16x32_bf16 v[34:37], v[228:231], v[220:223], v[34:37]
	v_mfma_f32_16x16x32_bf16 v[38:41], v[232:235], v[220:223], v[38:41]
	v_mfma_f32_16x16x32_bf16 v[42:45], v[236:239], v[220:223], v[42:45]
	v_mfma_f32_16x16x32_bf16 v[46:49], v[240:243], v[220:223], v[46:49]
	v_mfma_f32_16x16x32_bf16 v[50:53], v[228:231], v[224:227], v[50:53]
	v_mfma_f32_16x16x32_bf16 v[54:57], v[232:235], v[224:227], v[54:57]
	v_mfma_f32_16x16x32_bf16 v[58:61], v[236:239], v[224:227], v[58:61]
	v_mfma_f32_16x16x32_bf16 v[62:65], v[240:243], v[224:227], v[62:65]
	s_waitcnt vmcnt(10)
	s_barrier
	v_add_u32_e32 v204, 0x0, v200
	v_add_u32_e32 v205, 0x0, v202
	ds_read_b128 v[130:133], v204 offset:0
	ds_read_b128 v[134:137], v204 offset:2048
	ds_read_b128 v[138:141], v204 offset:4096
	ds_read_b128 v[142:145], v204 offset:6144
	ds_read_b128 v[146:149], v205 offset:0
	ds_read_b128 v[150:153], v205 offset:2048
	ds_read_b128 v[154:157], v205 offset:4096
	ds_read_b128 v[158:161], v205 offset:6144
	v_add_u32_e32 v204, 0x0, v201
	v_add_u32_e32 v205, 0x0, v203
	ds_read_b128 v[212:215], v204 offset:0
	ds_read_b128 v[216:219], v204 offset:2048
	ds_read_b128 v[220:223], v204 offset:4096
	ds_read_b128 v[224:227], v204 offset:6144
	ds_read_b128 v[228:231], v205 offset:0
	ds_read_b128 v[232:235], v205 offset:2048
	ds_read_b128 v[236:239], v205 offset:4096
	ds_read_b128 v[240:243], v205 offset:6144
	s_add_u32 m0, s76, 0x18000
	s_nop 0
	global_load_lds_dwordx4 v196, s[68:69]
	s_add_u32 m0, s76, 0x1a000
	s_nop 0
	global_load_lds_dwordx4 v197, s[68:69]
	s_add_u32 m0, s76, 0x1c000
	s_nop 0
	global_load_lds_dwordx4 v198, s[68:69]
	s_add_u32 m0, s76, 0x1e000
	s_nop 0
	global_load_lds_dwordx4 v199, s[68:69]
	s_add_u32 m0, s76, 0x20000
	s_nop 0
	global_load_lds_dwordx4 v196, s[70:71]
	s_add_u32 m0, s76, 0x22000
	s_nop 0
	global_load_lds_dwordx4 v197, s[70:71]
	s_add_u32 s68, s68, 0x80
	s_addc_u32 s69, s69, 0
	s_add_u32 s70, s70, 0x80
	s_addc_u32 s71, s71, 0
	v_add_u32_e32 v170, s39, v191
	global_load_dwordx4 v[74:77], v170, s[14:15]
	v_add_u32_e32 v170, s40, v191
	global_load_dwordx4 v[78:81], v170, s[14:15]
	s_waitcnt lgkmcnt(0)
	s_barrier
	v_mfma_f32_16x16x32_bf16 v[2:5], v[146:149], v[130:133], v[2:5]
	v_mfma_f32_16x16x32_bf16 v[6:9], v[150:153], v[130:133], v[6:9]
	v_mfma_f32_16x16x32_bf16 v[10:13], v[154:157], v[130:133], v[10:13]
	v_mfma_f32_16x16x32_bf16 v[14:17], v[158:161], v[130:133], v[14:17]
	v_mfma_f32_16x16x32_bf16 v[18:21], v[146:149], v[134:137], v[18:21]
	v_mfma_f32_16x16x32_bf16 v[22:25], v[150:153], v[134:137], v[22:25]
	v_mfma_f32_16x16x32_bf16 v[26:29], v[154:157], v[134:137], v[26:29]
	v_mfma_f32_16x16x32_bf16 v[30:33], v[158:161], v[134:137], v[30:33]
	v_mfma_f32_16x16x32_bf16 v[34:37], v[146:149], v[138:141], v[34:37]
	v_mfma_f32_16x16x32_bf16 v[38:41], v[150:153], v[138:141], v[38:41]
	v_mfma_f32_16x16x32_bf16 v[42:45], v[154:157], v[138:141], v[42:45]
	v_mfma_f32_16x16x32_bf16 v[46:49], v[158:161], v[138:141], v[46:49]
	v_mfma_f32_16x16x32_bf16 v[50:53], v[146:149], v[142:145], v[50:53]
	v_mfma_f32_16x16x32_bf16 v[54:57], v[150:153], v[142:145], v[54:57]
	v_mfma_f32_16x16x32_bf16 v[58:61], v[154:157], v[142:145], v[58:61]
	v_mfma_f32_16x16x32_bf16 v[62:65], v[158:161], v[142:145], v[62:65]
	v_mfma_f32_16x16x32_bf16 v[2:5], v[228:231], v[212:215], v[2:5]
	v_mfma_f32_16x16x32_bf16 v[6:9], v[232:235], v[212:215], v[6:9]
	v_mfma_f32_16x16x32_bf16 v[10:13], v[236:239], v[212:215], v[10:13]
	v_mfma_f32_16x16x32_bf16 v[14:17], v[240:243], v[212:215], v[14:17]
	v_mfma_f32_16x16x32_bf16 v[18:21], v[228:231], v[216:219], v[18:21]
	v_mfma_f32_16x16x32_bf16 v[22:25], v[232:235], v[216:219], v[22:25]
	v_mfma_f32_16x16x32_bf16 v[26:29], v[236:239], v[216:219], v[26:29]
	v_mfma_f32_16x16x32_bf16 v[30:33], v[240:243], v[216:219], v[30:33]
	v_mfma_f32_16x16x32_bf16 v[34:37], v[228:231], v[220:223], v[34:37]
	v_mfma_f32_16x16x32_bf16 v[38:41], v[232:235], v[220:223], v[38:41]
	v_mfma_f32_16x16x32_bf16 v[42:45], v[236:239], v[220:223], v[42:45]
	v_mfma_f32_16x16x32_bf16 v[46:49], v[240:243], v[220:223], v[46:49]
	v_mfma_f32_16x16x32_bf16 v[50:53], v[228:231], v[224:227], v[50:53]
	v_mfma_f32_16x16x32_bf16 v[54:57], v[232:235], v[224:227], v[54:57]
	v_mfma_f32_16x16x32_bf16 v[58:61], v[236:239], v[224:227], v[58:61]
	v_mfma_f32_16x16x32_bf16 v[62:65], v[240:243], v[224:227], v[62:65]
	s_waitcnt vmcnt(10)
	s_barrier
	v_add_u32_e32 v204, 0xc000, v200
	v_add_u32_e32 v205, 0xc000, v202
	ds_read_b128 v[130:133], v204 offset:0
	ds_read_b128 v[134:137], v204 offset:2048
	ds_read_b128 v[138:141], v204 offset:4096
	ds_read_b128 v[142:145], v204 offset:6144
	ds_read_b128 v[146:149], v205 offset:0
	ds_read_b128 v[150:153], v205 offset:2048
	ds_read_b128 v[154:157], v205 offset:4096
	ds_read_b128 v[158:161], v205 offset:6144
	v_add_u32_e32 v204, 0xc000, v201
	v_add_u32_e32 v205, 0xc000, v203
	ds_read_b128 v[212:215], v204 offset:0
	ds_read_b128 v[216:219], v204 offset:2048
	ds_read_b128 v[220:223], v204 offset:4096
	ds_read_b128 v[224:227], v204 offset:6144
	ds_read_b128 v[228:231], v205 offset:0
	ds_read_b128 v[232:235], v205 offset:2048
	ds_read_b128 v[236:239], v205 offset:4096
	ds_read_b128 v[240:243], v205 offset:6144
	s_add_u32 m0, s76, 0x0
	s_nop 0
	global_load_lds_dwordx4 v196, s[68:69]
	s_add_u32 m0, s76, 0x2000
	s_nop 0
	global_load_lds_dwordx4 v197, s[68:69]
	s_add_u32 m0, s76, 0x4000
	s_nop 0
	global_load_lds_dwordx4 v198, s[68:69]
	s_add_u32 m0, s76, 0x6000
	s_nop 0
	global_load_lds_dwordx4 v199, s[68:69]
	s_add_u32 m0, s76, 0x8000
	s_nop 0
	global_load_lds_dwordx4 v196, s[70:71]
	s_add_u32 m0, s76, 0xa000
	s_nop 0
	global_load_lds_dwordx4 v197, s[70:71]
	s_add_u32 s68, s68, 0x80
	s_addc_u32 s69, s69, 0
	s_add_u32 s70, s70, 0x80
	s_addc_u32 s71, s71, 0
	global_load_dwordx4 v[82:85], v192, s[14:15]
	v_add_u32_e32 v170, s38, v192
	global_load_dwordx4 v[86:89], v170, s[14:15]
	s_waitcnt lgkmcnt(0)
	s_barrier
	v_mfma_f32_16x16x32_bf16 v[2:5], v[146:149], v[130:133], v[2:5]
	v_mfma_f32_16x16x32_bf16 v[6:9], v[150:153], v[130:133], v[6:9]
	v_mfma_f32_16x16x32_bf16 v[10:13], v[154:157], v[130:133], v[10:13]
	v_mfma_f32_16x16x32_bf16 v[14:17], v[158:161], v[130:133], v[14:17]
	v_mfma_f32_16x16x32_bf16 v[18:21], v[146:149], v[134:137], v[18:21]
	v_mfma_f32_16x16x32_bf16 v[22:25], v[150:153], v[134:137], v[22:25]
	v_mfma_f32_16x16x32_bf16 v[26:29], v[154:157], v[134:137], v[26:29]
	v_mfma_f32_16x16x32_bf16 v[30:33], v[158:161], v[134:137], v[30:33]
	v_mfma_f32_16x16x32_bf16 v[34:37], v[146:149], v[138:141], v[34:37]
	v_mfma_f32_16x16x32_bf16 v[38:41], v[150:153], v[138:141], v[38:41]
	v_mfma_f32_16x16x32_bf16 v[42:45], v[154:157], v[138:141], v[42:45]
	v_mfma_f32_16x16x32_bf16 v[46:49], v[158:161], v[138:141], v[46:49]
	v_mfma_f32_16x16x32_bf16 v[50:53], v[146:149], v[142:145], v[50:53]
	v_mfma_f32_16x16x32_bf16 v[54:57], v[150:153], v[142:145], v[54:57]
	v_mfma_f32_16x16x32_bf16 v[58:61], v[154:157], v[142:145], v[58:61]
	v_mfma_f32_16x16x32_bf16 v[62:65], v[158:161], v[142:145], v[62:65]
	v_mfma_f32_16x16x32_bf16 v[2:5], v[228:231], v[212:215], v[2:5]
	v_mfma_f32_16x16x32_bf16 v[6:9], v[232:235], v[212:215], v[6:9]
	v_mfma_f32_16x16x32_bf16 v[10:13], v[236:239], v[212:215], v[10:13]
	v_mfma_f32_16x16x32_bf16 v[14:17], v[240:243], v[212:215], v[14:17]
	v_mfma_f32_16x16x32_bf16 v[18:21], v[228:231], v[216:219], v[18:21]
	v_mfma_f32_16x16x32_bf16 v[22:25], v[232:235], v[216:219], v[22:25]
	v_mfma_f32_16x16x32_bf16 v[26:29], v[236:239], v[216:219], v[26:29]
	v_mfma_f32_16x16x32_bf16 v[30:33], v[240:243], v[216:219], v[30:33]
	v_mfma_f32_16x16x32_bf16 v[34:37], v[228:231], v[220:223], v[34:37]
	v_mfma_f32_16x16x32_bf16 v[38:41], v[232:235], v[220:223], v[38:41]
	v_mfma_f32_16x16x32_bf16 v[42:45], v[236:239], v[220:223], v[42:45]
	v_mfma_f32_16x16x32_bf16 v[46:49], v[240:243], v[220:223], v[46:49]
	v_mfma_f32_16x16x32_bf16 v[50:53], v[228:231], v[224:227], v[50:53]
	v_mfma_f32_16x16x32_bf16 v[54:57], v[232:235], v[224:227], v[54:57]
	v_mfma_f32_16x16x32_bf16 v[58:61], v[236:239], v[224:227], v[58:61]
	v_mfma_f32_16x16x32_bf16 v[62:65], v[240:243], v[224:227], v[62:65]
	s_waitcnt vmcnt(10)
	s_barrier
	v_add_u32_e32 v204, 0x18000, v200
	v_add_u32_e32 v205, 0x18000, v202
	ds_read_b128 v[130:133], v204 offset:0
	ds_read_b128 v[134:137], v204 offset:2048
	ds_read_b128 v[138:141], v204 offset:4096
	ds_read_b128 v[142:145], v204 offset:6144
	ds_read_b128 v[146:149], v205 offset:0
	ds_read_b128 v[150:153], v205 offset:2048
	ds_read_b128 v[154:157], v205 offset:4096
	ds_read_b128 v[158:161], v205 offset:6144
	v_add_u32_e32 v204, 0x18000, v201
	v_add_u32_e32 v205, 0x18000, v203
	ds_read_b128 v[212:215], v204 offset:0
	ds_read_b128 v[216:219], v204 offset:2048
	ds_read_b128 v[220:223], v204 offset:4096
	ds_read_b128 v[224:227], v204 offset:6144
	ds_read_b128 v[228:231], v205 offset:0
	ds_read_b128 v[232:235], v205 offset:2048
	ds_read_b128 v[236:239], v205 offset:4096
	ds_read_b128 v[240:243], v205 offset:6144
	s_add_u32 m0, s76, 0xc000
	s_nop 0
	global_load_lds_dwordx4 v196, s[68:69]
	s_add_u32 m0, s76, 0xe000
	s_nop 0
	global_load_lds_dwordx4 v197, s[68:69]
	s_add_u32 m0, s76, 0x10000
	s_nop 0
	global_load_lds_dwordx4 v198, s[68:69]
	s_add_u32 m0, s76, 0x12000
	s_nop 0
	global_load_lds_dwordx4 v199, s[68:69]
	s_add_u32 m0, s76, 0x14000
	s_nop 0
	global_load_lds_dwordx4 v196, s[70:71]
	s_add_u32 m0, s76, 0x16000
	s_nop 0
	global_load_lds_dwordx4 v197, s[70:71]
	s_add_u32 s68, s68, 0x80
	s_addc_u32 s69, s69, 0
	s_add_u32 s70, s70, 0x80
	s_addc_u32 s71, s71, 0
	v_add_u32_e32 v170, s39, v192
	global_load_dwordx4 v[90:93], v170, s[14:15]
	v_add_u32_e32 v170, s40, v192
	global_load_dwordx4 v[94:97], v170, s[14:15]
	s_waitcnt lgkmcnt(0)
	s_barrier
	v_mfma_f32_16x16x32_bf16 v[2:5], v[146:149], v[130:133], v[2:5]
	v_mfma_f32_16x16x32_bf16 v[6:9], v[150:153], v[130:133], v[6:9]
	v_mfma_f32_16x16x32_bf16 v[10:13], v[154:157], v[130:133], v[10:13]
	v_mfma_f32_16x16x32_bf16 v[14:17], v[158:161], v[130:133], v[14:17]
	v_mfma_f32_16x16x32_bf16 v[18:21], v[146:149], v[134:137], v[18:21]
	v_mfma_f32_16x16x32_bf16 v[22:25], v[150:153], v[134:137], v[22:25]
	v_mfma_f32_16x16x32_bf16 v[26:29], v[154:157], v[134:137], v[26:29]
	v_mfma_f32_16x16x32_bf16 v[30:33], v[158:161], v[134:137], v[30:33]
	v_mfma_f32_16x16x32_bf16 v[34:37], v[146:149], v[138:141], v[34:37]
	v_mfma_f32_16x16x32_bf16 v[38:41], v[150:153], v[138:141], v[38:41]
	v_mfma_f32_16x16x32_bf16 v[42:45], v[154:157], v[138:141], v[42:45]
	v_mfma_f32_16x16x32_bf16 v[46:49], v[158:161], v[138:141], v[46:49]
	v_mfma_f32_16x16x32_bf16 v[50:53], v[146:149], v[142:145], v[50:53]
	v_mfma_f32_16x16x32_bf16 v[54:57], v[150:153], v[142:145], v[54:57]
	v_mfma_f32_16x16x32_bf16 v[58:61], v[154:157], v[142:145], v[58:61]
	v_mfma_f32_16x16x32_bf16 v[62:65], v[158:161], v[142:145], v[62:65]
	v_mfma_f32_16x16x32_bf16 v[2:5], v[228:231], v[212:215], v[2:5]
	v_mfma_f32_16x16x32_bf16 v[6:9], v[232:235], v[212:215], v[6:9]
	v_mfma_f32_16x16x32_bf16 v[10:13], v[236:239], v[212:215], v[10:13]
	v_mfma_f32_16x16x32_bf16 v[14:17], v[240:243], v[212:215], v[14:17]
	v_mfma_f32_16x16x32_bf16 v[18:21], v[228:231], v[216:219], v[18:21]
	v_mfma_f32_16x16x32_bf16 v[22:25], v[232:235], v[216:219], v[22:25]
	v_mfma_f32_16x16x32_bf16 v[26:29], v[236:239], v[216:219], v[26:29]
	v_mfma_f32_16x16x32_bf16 v[30:33], v[240:243], v[216:219], v[30:33]
	v_mfma_f32_16x16x32_bf16 v[34:37], v[228:231], v[220:223], v[34:37]
	v_mfma_f32_16x16x32_bf16 v[38:41], v[232:235], v[220:223], v[38:41]
	v_mfma_f32_16x16x32_bf16 v[42:45], v[236:239], v[220:223], v[42:45]
	v_mfma_f32_16x16x32_bf16 v[46:49], v[240:243], v[220:223], v[46:49]
	v_mfma_f32_16x16x32_bf16 v[50:53], v[228:231], v[224:227], v[50:53]
	v_mfma_f32_16x16x32_bf16 v[54:57], v[232:235], v[224:227], v[54:57]
	v_mfma_f32_16x16x32_bf16 v[58:61], v[236:239], v[224:227], v[58:61]
	v_mfma_f32_16x16x32_bf16 v[62:65], v[240:243], v[224:227], v[62:65]
	s_waitcnt vmcnt(10)
	s_barrier
	v_add_u32_e32 v204, 0x0, v200
	v_add_u32_e32 v205, 0x0, v202
	ds_read_b128 v[130:133], v204 offset:0
	ds_read_b128 v[134:137], v204 offset:2048
	ds_read_b128 v[138:141], v204 offset:4096
	ds_read_b128 v[142:145], v204 offset:6144
	ds_read_b128 v[146:149], v205 offset:0
	ds_read_b128 v[150:153], v205 offset:2048
	ds_read_b128 v[154:157], v205 offset:4096
	ds_read_b128 v[158:161], v205 offset:6144
	v_add_u32_e32 v204, 0x0, v201
	v_add_u32_e32 v205, 0x0, v203
	ds_read_b128 v[212:215], v204 offset:0
	ds_read_b128 v[216:219], v204 offset:2048
	ds_read_b128 v[220:223], v204 offset:4096
	ds_read_b128 v[224:227], v204 offset:6144
	ds_read_b128 v[228:231], v205 offset:0
	ds_read_b128 v[232:235], v205 offset:2048
	ds_read_b128 v[236:239], v205 offset:4096
	ds_read_b128 v[240:243], v205 offset:6144
	s_add_u32 m0, s76, 0x18000
	s_nop 0
	global_load_lds_dwordx4 v196, s[68:69]
	s_add_u32 m0, s76, 0x1a000
	s_nop 0
	global_load_lds_dwordx4 v197, s[68:69]
	s_add_u32 m0, s76, 0x1c000
	s_nop 0
	global_load_lds_dwordx4 v198, s[68:69]
	s_add_u32 m0, s76, 0x1e000
	s_nop 0
	global_load_lds_dwordx4 v199, s[68:69]
	s_add_u32 m0, s76, 0x20000
	s_nop 0
	global_load_lds_dwordx4 v196, s[70:71]
	s_add_u32 m0, s76, 0x22000
	s_nop 0
	global_load_lds_dwordx4 v197, s[70:71]
	s_add_u32 s68, s68, 0x80
	s_addc_u32 s69, s69, 0
	s_add_u32 s70, s70, 0x80
	s_addc_u32 s71, s71, 0
	global_load_dwordx4 v[98:101], v193, s[14:15]
	v_add_u32_e32 v170, s38, v193
	global_load_dwordx4 v[102:105], v170, s[14:15]
	s_waitcnt lgkmcnt(0)
	s_barrier
	v_mfma_f32_16x16x32_bf16 v[2:5], v[146:149], v[130:133], v[2:5]
	v_mfma_f32_16x16x32_bf16 v[6:9], v[150:153], v[130:133], v[6:9]
	v_mfma_f32_16x16x32_bf16 v[10:13], v[154:157], v[130:133], v[10:13]
	v_mfma_f32_16x16x32_bf16 v[14:17], v[158:161], v[130:133], v[14:17]
	v_mfma_f32_16x16x32_bf16 v[18:21], v[146:149], v[134:137], v[18:21]
	v_mfma_f32_16x16x32_bf16 v[22:25], v[150:153], v[134:137], v[22:25]
	v_mfma_f32_16x16x32_bf16 v[26:29], v[154:157], v[134:137], v[26:29]
	v_mfma_f32_16x16x32_bf16 v[30:33], v[158:161], v[134:137], v[30:33]
	v_mfma_f32_16x16x32_bf16 v[34:37], v[146:149], v[138:141], v[34:37]
	v_mfma_f32_16x16x32_bf16 v[38:41], v[150:153], v[138:141], v[38:41]
	v_mfma_f32_16x16x32_bf16 v[42:45], v[154:157], v[138:141], v[42:45]
	v_mfma_f32_16x16x32_bf16 v[46:49], v[158:161], v[138:141], v[46:49]
	v_mfma_f32_16x16x32_bf16 v[50:53], v[146:149], v[142:145], v[50:53]
	v_mfma_f32_16x16x32_bf16 v[54:57], v[150:153], v[142:145], v[54:57]
	v_mfma_f32_16x16x32_bf16 v[58:61], v[154:157], v[142:145], v[58:61]
	v_mfma_f32_16x16x32_bf16 v[62:65], v[158:161], v[142:145], v[62:65]
	v_mfma_f32_16x16x32_bf16 v[2:5], v[228:231], v[212:215], v[2:5]
	v_mfma_f32_16x16x32_bf16 v[6:9], v[232:235], v[212:215], v[6:9]
	v_mfma_f32_16x16x32_bf16 v[10:13], v[236:239], v[212:215], v[10:13]
	v_mfma_f32_16x16x32_bf16 v[14:17], v[240:243], v[212:215], v[14:17]
	v_mfma_f32_16x16x32_bf16 v[18:21], v[228:231], v[216:219], v[18:21]
	v_mfma_f32_16x16x32_bf16 v[22:25], v[232:235], v[216:219], v[22:25]
	v_mfma_f32_16x16x32_bf16 v[26:29], v[236:239], v[216:219], v[26:29]
	v_mfma_f32_16x16x32_bf16 v[30:33], v[240:243], v[216:219], v[30:33]
	v_mfma_f32_16x16x32_bf16 v[34:37], v[228:231], v[220:223], v[34:37]
	v_mfma_f32_16x16x32_bf16 v[38:41], v[232:235], v[220:223], v[38:41]
	v_mfma_f32_16x16x32_bf16 v[42:45], v[236:239], v[220:223], v[42:45]
	v_mfma_f32_16x16x32_bf16 v[46:49], v[240:243], v[220:223], v[46:49]
	v_mfma_f32_16x16x32_bf16 v[50:53], v[228:231], v[224:227], v[50:53]
	v_mfma_f32_16x16x32_bf16 v[54:57], v[232:235], v[224:227], v[54:57]
	v_mfma_f32_16x16x32_bf16 v[58:61], v[236:239], v[224:227], v[58:61]
	v_mfma_f32_16x16x32_bf16 v[62:65], v[240:243], v[224:227], v[62:65]
	s_waitcnt vmcnt(10)
	s_barrier
	v_add_u32_e32 v204, 0xc000, v200
	v_add_u32_e32 v205, 0xc000, v202
	ds_read_b128 v[130:133], v204 offset:0
	ds_read_b128 v[134:137], v204 offset:2048
	ds_read_b128 v[138:141], v204 offset:4096
	ds_read_b128 v[142:145], v204 offset:6144
	ds_read_b128 v[146:149], v205 offset:0
	ds_read_b128 v[150:153], v205 offset:2048
	ds_read_b128 v[154:157], v205 offset:4096
	ds_read_b128 v[158:161], v205 offset:6144
	v_add_u32_e32 v204, 0xc000, v201
	v_add_u32_e32 v205, 0xc000, v203
	ds_read_b128 v[212:215], v204 offset:0
	ds_read_b128 v[216:219], v204 offset:2048
	ds_read_b128 v[220:223], v204 offset:4096
	ds_read_b128 v[224:227], v204 offset:6144
	ds_read_b128 v[228:231], v205 offset:0
	ds_read_b128 v[232:235], v205 offset:2048
	ds_read_b128 v[236:239], v205 offset:4096
	ds_read_b128 v[240:243], v205 offset:6144
	s_add_u32 m0, s76, 0x0
	s_nop 0
	global_load_lds_dwordx4 v196, s[68:69]
	s_add_u32 m0, s76, 0x2000
	s_nop 0
	global_load_lds_dwordx4 v197, s[68:69]
	s_add_u32 m0, s76, 0x4000
	s_nop 0
	global_load_lds_dwordx4 v198, s[68:69]
	s_add_u32 m0, s76, 0x6000
	s_nop 0
	global_load_lds_dwordx4 v199, s[68:69]
	s_add_u32 m0, s76, 0x8000
	s_nop 0
	global_load_lds_dwordx4 v196, s[70:71]
	s_add_u32 m0, s76, 0xa000
	s_nop 0
	global_load_lds_dwordx4 v197, s[70:71]
	s_add_u32 s68, s68, 0x80
	s_addc_u32 s69, s69, 0
	s_add_u32 s70, s70, 0x80
	s_addc_u32 s71, s71, 0
	v_add_u32_e32 v170, s39, v193
	global_load_dwordx4 v[106:109], v170, s[14:15]
	v_add_u32_e32 v170, s40, v193
	global_load_dwordx4 v[110:113], v170, s[14:15]
	s_waitcnt lgkmcnt(0)
	s_barrier
	v_mfma_f32_16x16x32_bf16 v[2:5], v[146:149], v[130:133], v[2:5]
	v_mfma_f32_16x16x32_bf16 v[6:9], v[150:153], v[130:133], v[6:9]
	v_mfma_f32_16x16x32_bf16 v[10:13], v[154:157], v[130:133], v[10:13]
	v_mfma_f32_16x16x32_bf16 v[14:17], v[158:161], v[130:133], v[14:17]
	v_mfma_f32_16x16x32_bf16 v[18:21], v[146:149], v[134:137], v[18:21]
	v_mfma_f32_16x16x32_bf16 v[22:25], v[150:153], v[134:137], v[22:25]
	v_mfma_f32_16x16x32_bf16 v[26:29], v[154:157], v[134:137], v[26:29]
	v_mfma_f32_16x16x32_bf16 v[30:33], v[158:161], v[134:137], v[30:33]
	v_mfma_f32_16x16x32_bf16 v[34:37], v[146:149], v[138:141], v[34:37]
	v_mfma_f32_16x16x32_bf16 v[38:41], v[150:153], v[138:141], v[38:41]
	v_mfma_f32_16x16x32_bf16 v[42:45], v[154:157], v[138:141], v[42:45]
	v_mfma_f32_16x16x32_bf16 v[46:49], v[158:161], v[138:141], v[46:49]
	v_mfma_f32_16x16x32_bf16 v[50:53], v[146:149], v[142:145], v[50:53]
	v_mfma_f32_16x16x32_bf16 v[54:57], v[150:153], v[142:145], v[54:57]
	v_mfma_f32_16x16x32_bf16 v[58:61], v[154:157], v[142:145], v[58:61]
	v_mfma_f32_16x16x32_bf16 v[62:65], v[158:161], v[142:145], v[62:65]
	v_mfma_f32_16x16x32_bf16 v[2:5], v[228:231], v[212:215], v[2:5]
	v_mfma_f32_16x16x32_bf16 v[6:9], v[232:235], v[212:215], v[6:9]
	v_mfma_f32_16x16x32_bf16 v[10:13], v[236:239], v[212:215], v[10:13]
	v_mfma_f32_16x16x32_bf16 v[14:17], v[240:243], v[212:215], v[14:17]
	v_mfma_f32_16x16x32_bf16 v[18:21], v[228:231], v[216:219], v[18:21]
	v_mfma_f32_16x16x32_bf16 v[22:25], v[232:235], v[216:219], v[22:25]
	v_mfma_f32_16x16x32_bf16 v[26:29], v[236:239], v[216:219], v[26:29]
	v_mfma_f32_16x16x32_bf16 v[30:33], v[240:243], v[216:219], v[30:33]
	v_mfma_f32_16x16x32_bf16 v[34:37], v[228:231], v[220:223], v[34:37]
	v_mfma_f32_16x16x32_bf16 v[38:41], v[232:235], v[220:223], v[38:41]
	v_mfma_f32_16x16x32_bf16 v[42:45], v[236:239], v[220:223], v[42:45]
	v_mfma_f32_16x16x32_bf16 v[46:49], v[240:243], v[220:223], v[46:49]
	v_mfma_f32_16x16x32_bf16 v[50:53], v[228:231], v[224:227], v[50:53]
	v_mfma_f32_16x16x32_bf16 v[54:57], v[232:235], v[224:227], v[54:57]
	v_mfma_f32_16x16x32_bf16 v[58:61], v[236:239], v[224:227], v[58:61]
	v_mfma_f32_16x16x32_bf16 v[62:65], v[240:243], v[224:227], v[62:65]
	s_waitcnt vmcnt(10)
	s_barrier
	v_add_u32_e32 v204, 0x18000, v200
	v_add_u32_e32 v205, 0x18000, v202
	ds_read_b128 v[130:133], v204 offset:0
	ds_read_b128 v[134:137], v204 offset:2048
	ds_read_b128 v[138:141], v204 offset:4096
	ds_read_b128 v[142:145], v204 offset:6144
	ds_read_b128 v[146:149], v205 offset:0
	ds_read_b128 v[150:153], v205 offset:2048
	ds_read_b128 v[154:157], v205 offset:4096
	ds_read_b128 v[158:161], v205 offset:6144
	v_add_u32_e32 v204, 0x18000, v201
	v_add_u32_e32 v205, 0x18000, v203
	ds_read_b128 v[212:215], v204 offset:0
	ds_read_b128 v[216:219], v204 offset:2048
	ds_read_b128 v[220:223], v204 offset:4096
	ds_read_b128 v[224:227], v204 offset:6144
	ds_read_b128 v[228:231], v205 offset:0
	ds_read_b128 v[232:235], v205 offset:2048
	ds_read_b128 v[236:239], v205 offset:4096
	ds_read_b128 v[240:243], v205 offset:6144
	s_add_u32 m0, s76, 0xc000
	s_nop 0
	global_load_lds_dwordx4 v196, s[68:69]
	s_add_u32 m0, s76, 0xe000
	s_nop 0
	global_load_lds_dwordx4 v197, s[68:69]
	s_add_u32 m0, s76, 0x10000
	s_nop 0
	global_load_lds_dwordx4 v198, s[68:69]
	s_add_u32 m0, s76, 0x12000
	s_nop 0
	global_load_lds_dwordx4 v199, s[68:69]
	s_add_u32 m0, s76, 0x14000
	s_nop 0
	global_load_lds_dwordx4 v196, s[70:71]
	s_add_u32 m0, s76, 0x16000
	s_nop 0
	global_load_lds_dwordx4 v197, s[70:71]
	s_add_u32 s68, s68, 0x80
	s_addc_u32 s69, s69, 0
	s_add_u32 s70, s70, 0x80
	s_addc_u32 s71, s71, 0
	global_load_dwordx4 v[114:117], v244, s[14:15]
	v_add_u32_e32 v170, s38, v244
	global_load_dwordx4 v[118:121], v170, s[14:15]
	s_waitcnt lgkmcnt(0)
	s_barrier
	v_mfma_f32_16x16x32_bf16 v[2:5], v[146:149], v[130:133], v[2:5]
	v_mfma_f32_16x16x32_bf16 v[6:9], v[150:153], v[130:133], v[6:9]
	v_mfma_f32_16x16x32_bf16 v[10:13], v[154:157], v[130:133], v[10:13]
	v_mfma_f32_16x16x32_bf16 v[14:17], v[158:161], v[130:133], v[14:17]
	v_mfma_f32_16x16x32_bf16 v[18:21], v[146:149], v[134:137], v[18:21]
	v_mfma_f32_16x16x32_bf16 v[22:25], v[150:153], v[134:137], v[22:25]
	v_mfma_f32_16x16x32_bf16 v[26:29], v[154:157], v[134:137], v[26:29]
	v_mfma_f32_16x16x32_bf16 v[30:33], v[158:161], v[134:137], v[30:33]
	v_mfma_f32_16x16x32_bf16 v[34:37], v[146:149], v[138:141], v[34:37]
	v_mfma_f32_16x16x32_bf16 v[38:41], v[150:153], v[138:141], v[38:41]
	v_mfma_f32_16x16x32_bf16 v[42:45], v[154:157], v[138:141], v[42:45]
	v_mfma_f32_16x16x32_bf16 v[46:49], v[158:161], v[138:141], v[46:49]
	v_mfma_f32_16x16x32_bf16 v[50:53], v[146:149], v[142:145], v[50:53]
	v_mfma_f32_16x16x32_bf16 v[54:57], v[150:153], v[142:145], v[54:57]
	v_mfma_f32_16x16x32_bf16 v[58:61], v[154:157], v[142:145], v[58:61]
	v_mfma_f32_16x16x32_bf16 v[62:65], v[158:161], v[142:145], v[62:65]
	v_mfma_f32_16x16x32_bf16 v[2:5], v[228:231], v[212:215], v[2:5]
	v_mfma_f32_16x16x32_bf16 v[6:9], v[232:235], v[212:215], v[6:9]
	v_mfma_f32_16x16x32_bf16 v[10:13], v[236:239], v[212:215], v[10:13]
	v_mfma_f32_16x16x32_bf16 v[14:17], v[240:243], v[212:215], v[14:17]
	v_mfma_f32_16x16x32_bf16 v[18:21], v[228:231], v[216:219], v[18:21]
	v_mfma_f32_16x16x32_bf16 v[22:25], v[232:235], v[216:219], v[22:25]
	v_mfma_f32_16x16x32_bf16 v[26:29], v[236:239], v[216:219], v[26:29]
	v_mfma_f32_16x16x32_bf16 v[30:33], v[240:243], v[216:219], v[30:33]
	v_mfma_f32_16x16x32_bf16 v[34:37], v[228:231], v[220:223], v[34:37]
	v_mfma_f32_16x16x32_bf16 v[38:41], v[232:235], v[220:223], v[38:41]
	v_mfma_f32_16x16x32_bf16 v[42:45], v[236:239], v[220:223], v[42:45]
	v_mfma_f32_16x16x32_bf16 v[46:49], v[240:243], v[220:223], v[46:49]
	v_mfma_f32_16x16x32_bf16 v[50:53], v[228:231], v[224:227], v[50:53]
	v_mfma_f32_16x16x32_bf16 v[54:57], v[232:235], v[224:227], v[54:57]
	v_mfma_f32_16x16x32_bf16 v[58:61], v[236:239], v[224:227], v[58:61]
	v_mfma_f32_16x16x32_bf16 v[62:65], v[240:243], v[224:227], v[62:65]
	s_waitcnt vmcnt(10)
	s_barrier
	v_add_u32_e32 v204, 0x0, v200
	v_add_u32_e32 v205, 0x0, v202
	ds_read_b128 v[130:133], v204 offset:0
	ds_read_b128 v[134:137], v204 offset:2048
	ds_read_b128 v[138:141], v204 offset:4096
	ds_read_b128 v[142:145], v204 offset:6144
	ds_read_b128 v[146:149], v205 offset:0
	ds_read_b128 v[150:153], v205 offset:2048
	ds_read_b128 v[154:157], v205 offset:4096
	ds_read_b128 v[158:161], v205 offset:6144
	v_add_u32_e32 v204, 0x0, v201
	v_add_u32_e32 v205, 0x0, v203
	ds_read_b128 v[212:215], v204 offset:0
	ds_read_b128 v[216:219], v204 offset:2048
	ds_read_b128 v[220:223], v204 offset:4096
	ds_read_b128 v[224:227], v204 offset:6144
	ds_read_b128 v[228:231], v205 offset:0
	ds_read_b128 v[232:235], v205 offset:2048
	ds_read_b128 v[236:239], v205 offset:4096
	ds_read_b128 v[240:243], v205 offset:6144
	s_add_u32 m0, s76, 0x18000
	s_nop 0
	global_load_lds_dwordx4 v196, s[68:69]
	s_add_u32 m0, s76, 0x1a000
	s_nop 0
	global_load_lds_dwordx4 v197, s[68:69]
	s_add_u32 m0, s76, 0x1c000
	s_nop 0
	global_load_lds_dwordx4 v198, s[68:69]
	s_add_u32 m0, s76, 0x1e000
	s_nop 0
	global_load_lds_dwordx4 v199, s[68:69]
	s_add_u32 m0, s76, 0x20000
	s_nop 0
	global_load_lds_dwordx4 v196, s[70:71]
	s_add_u32 m0, s76, 0x22000
	s_nop 0
	global_load_lds_dwordx4 v197, s[70:71]
	s_add_u32 s68, s68, 0x80
	s_addc_u32 s69, s69, 0
	s_add_u32 s70, s70, 0x80
	s_addc_u32 s71, s71, 0
	v_add_u32_e32 v170, s39, v244
	global_load_dwordx4 v[122:125], v170, s[14:15]
	v_add_u32_e32 v170, s40, v244
	global_load_dwordx4 v[126:129], v170, s[14:15]
	s_waitcnt lgkmcnt(0)
	s_barrier
	v_mfma_f32_16x16x32_bf16 v[2:5], v[146:149], v[130:133], v[2:5]
	v_mfma_f32_16x16x32_bf16 v[6:9], v[150:153], v[130:133], v[6:9]
	v_mfma_f32_16x16x32_bf16 v[10:13], v[154:157], v[130:133], v[10:13]
	v_mfma_f32_16x16x32_bf16 v[14:17], v[158:161], v[130:133], v[14:17]
	v_mfma_f32_16x16x32_bf16 v[18:21], v[146:149], v[134:137], v[18:21]
	v_mfma_f32_16x16x32_bf16 v[22:25], v[150:153], v[134:137], v[22:25]
	v_mfma_f32_16x16x32_bf16 v[26:29], v[154:157], v[134:137], v[26:29]
	v_mfma_f32_16x16x32_bf16 v[30:33], v[158:161], v[134:137], v[30:33]
	v_mfma_f32_16x16x32_bf16 v[34:37], v[146:149], v[138:141], v[34:37]
	v_mfma_f32_16x16x32_bf16 v[38:41], v[150:153], v[138:141], v[38:41]
	v_mfma_f32_16x16x32_bf16 v[42:45], v[154:157], v[138:141], v[42:45]
	v_mfma_f32_16x16x32_bf16 v[46:49], v[158:161], v[138:141], v[46:49]
	v_mfma_f32_16x16x32_bf16 v[50:53], v[146:149], v[142:145], v[50:53]
	v_mfma_f32_16x16x32_bf16 v[54:57], v[150:153], v[142:145], v[54:57]
	v_mfma_f32_16x16x32_bf16 v[58:61], v[154:157], v[142:145], v[58:61]
	v_mfma_f32_16x16x32_bf16 v[62:65], v[158:161], v[142:145], v[62:65]
	v_mfma_f32_16x16x32_bf16 v[2:5], v[228:231], v[212:215], v[2:5]
	v_mfma_f32_16x16x32_bf16 v[6:9], v[232:235], v[212:215], v[6:9]
	v_mfma_f32_16x16x32_bf16 v[10:13], v[236:239], v[212:215], v[10:13]
	v_mfma_f32_16x16x32_bf16 v[14:17], v[240:243], v[212:215], v[14:17]
	v_mfma_f32_16x16x32_bf16 v[18:21], v[228:231], v[216:219], v[18:21]
	v_mfma_f32_16x16x32_bf16 v[22:25], v[232:235], v[216:219], v[22:25]
	v_mfma_f32_16x16x32_bf16 v[26:29], v[236:239], v[216:219], v[26:29]
	v_mfma_f32_16x16x32_bf16 v[30:33], v[240:243], v[216:219], v[30:33]
	v_mfma_f32_16x16x32_bf16 v[34:37], v[228:231], v[220:223], v[34:37]
	v_mfma_f32_16x16x32_bf16 v[38:41], v[232:235], v[220:223], v[38:41]
	v_mfma_f32_16x16x32_bf16 v[42:45], v[236:239], v[220:223], v[42:45]
	v_mfma_f32_16x16x32_bf16 v[46:49], v[240:243], v[220:223], v[46:49]
	v_mfma_f32_16x16x32_bf16 v[50:53], v[228:231], v[224:227], v[50:53]
	v_mfma_f32_16x16x32_bf16 v[54:57], v[232:235], v[224:227], v[54:57]
	v_mfma_f32_16x16x32_bf16 v[58:61], v[236:239], v[224:227], v[58:61]
	v_mfma_f32_16x16x32_bf16 v[62:65], v[240:243], v[224:227], v[62:65]
	s_waitcnt vmcnt(10)
	s_barrier
	v_add_u32_e32 v204, 0xc000, v200
	v_add_u32_e32 v205, 0xc000, v202
	ds_read_b128 v[130:133], v204 offset:0
	ds_read_b128 v[134:137], v204 offset:2048
	ds_read_b128 v[138:141], v204 offset:4096
	ds_read_b128 v[142:145], v204 offset:6144
	ds_read_b128 v[146:149], v205 offset:0
	ds_read_b128 v[150:153], v205 offset:2048
	ds_read_b128 v[154:157], v205 offset:4096
	ds_read_b128 v[158:161], v205 offset:6144
	v_add_u32_e32 v204, 0xc000, v201
	v_add_u32_e32 v205, 0xc000, v203
	ds_read_b128 v[212:215], v204 offset:0
	ds_read_b128 v[216:219], v204 offset:2048
	ds_read_b128 v[220:223], v204 offset:4096
	ds_read_b128 v[224:227], v204 offset:6144
	ds_read_b128 v[228:231], v205 offset:0
	ds_read_b128 v[232:235], v205 offset:2048
	ds_read_b128 v[236:239], v205 offset:4096
	ds_read_b128 v[240:243], v205 offset:6144
	s_add_u32 m0, s76, 0x0
	s_nop 0
	global_load_lds_dwordx4 v196, s[68:69]
	s_add_u32 m0, s76, 0x2000
	s_nop 0
	global_load_lds_dwordx4 v197, s[68:69]
	s_add_u32 m0, s76, 0x4000
	s_nop 0
	global_load_lds_dwordx4 v198, s[68:69]
	s_add_u32 m0, s76, 0x6000
	s_nop 0
	global_load_lds_dwordx4 v199, s[68:69]
	s_add_u32 m0, s76, 0x8000
	s_nop 0
	global_load_lds_dwordx4 v196, s[70:71]
	s_add_u32 m0, s76, 0xa000
	s_nop 0
	global_load_lds_dwordx4 v197, s[70:71]
	s_add_u32 s68, s68, 0x80
	s_addc_u32 s69, s69, 0
	s_add_u32 s70, s70, 0x80
	s_addc_u32 s71, s71, 0
	s_waitcnt lgkmcnt(0)
	s_barrier
	v_mfma_f32_16x16x32_bf16 v[2:5], v[146:149], v[130:133], v[2:5]
	v_mfma_f32_16x16x32_bf16 v[6:9], v[150:153], v[130:133], v[6:9]
	v_mfma_f32_16x16x32_bf16 v[10:13], v[154:157], v[130:133], v[10:13]
	v_mfma_f32_16x16x32_bf16 v[14:17], v[158:161], v[130:133], v[14:17]
	v_mfma_f32_16x16x32_bf16 v[18:21], v[146:149], v[134:137], v[18:21]
	v_mfma_f32_16x16x32_bf16 v[22:25], v[150:153], v[134:137], v[22:25]
	v_mfma_f32_16x16x32_bf16 v[26:29], v[154:157], v[134:137], v[26:29]
	v_mfma_f32_16x16x32_bf16 v[30:33], v[158:161], v[134:137], v[30:33]
	v_mfma_f32_16x16x32_bf16 v[34:37], v[146:149], v[138:141], v[34:37]
	v_mfma_f32_16x16x32_bf16 v[38:41], v[150:153], v[138:141], v[38:41]
	v_mfma_f32_16x16x32_bf16 v[42:45], v[154:157], v[138:141], v[42:45]
	v_mfma_f32_16x16x32_bf16 v[46:49], v[158:161], v[138:141], v[46:49]
	v_mfma_f32_16x16x32_bf16 v[50:53], v[146:149], v[142:145], v[50:53]
	v_mfma_f32_16x16x32_bf16 v[54:57], v[150:153], v[142:145], v[54:57]
	v_mfma_f32_16x16x32_bf16 v[58:61], v[154:157], v[142:145], v[58:61]
	v_mfma_f32_16x16x32_bf16 v[62:65], v[158:161], v[142:145], v[62:65]
	v_mfma_f32_16x16x32_bf16 v[2:5], v[228:231], v[212:215], v[2:5]
	v_mfma_f32_16x16x32_bf16 v[6:9], v[232:235], v[212:215], v[6:9]
	v_mfma_f32_16x16x32_bf16 v[10:13], v[236:239], v[212:215], v[10:13]
	v_mfma_f32_16x16x32_bf16 v[14:17], v[240:243], v[212:215], v[14:17]
	v_mfma_f32_16x16x32_bf16 v[18:21], v[228:231], v[216:219], v[18:21]
	v_mfma_f32_16x16x32_bf16 v[22:25], v[232:235], v[216:219], v[22:25]
	v_mfma_f32_16x16x32_bf16 v[26:29], v[236:239], v[216:219], v[26:29]
	v_mfma_f32_16x16x32_bf16 v[30:33], v[240:243], v[216:219], v[30:33]
	v_mfma_f32_16x16x32_bf16 v[34:37], v[228:231], v[220:223], v[34:37]
	v_mfma_f32_16x16x32_bf16 v[38:41], v[232:235], v[220:223], v[38:41]
	v_mfma_f32_16x16x32_bf16 v[42:45], v[236:239], v[220:223], v[42:45]
	v_mfma_f32_16x16x32_bf16 v[46:49], v[240:243], v[220:223], v[46:49]
	v_mfma_f32_16x16x32_bf16 v[50:53], v[228:231], v[224:227], v[50:53]
	v_mfma_f32_16x16x32_bf16 v[54:57], v[232:235], v[224:227], v[54:57]
	v_mfma_f32_16x16x32_bf16 v[58:61], v[236:239], v[224:227], v[58:61]
	v_mfma_f32_16x16x32_bf16 v[62:65], v[240:243], v[224:227], v[62:65]
	s_waitcnt vmcnt(8)
	s_barrier
	v_add_u32_e32 v204, 0x18000, v200
	v_add_u32_e32 v205, 0x18000, v202
	ds_read_b128 v[130:133], v204 offset:0
	ds_read_b128 v[134:137], v204 offset:2048
	ds_read_b128 v[138:141], v204 offset:4096
	ds_read_b128 v[142:145], v204 offset:6144
	ds_read_b128 v[146:149], v205 offset:0
	ds_read_b128 v[150:153], v205 offset:2048
	ds_read_b128 v[154:157], v205 offset:4096
	ds_read_b128 v[158:161], v205 offset:6144
	v_add_u32_e32 v204, 0x18000, v201
	v_add_u32_e32 v205, 0x18000, v203
	ds_read_b128 v[212:215], v204 offset:0
	ds_read_b128 v[216:219], v204 offset:2048
	ds_read_b128 v[220:223], v204 offset:4096
	ds_read_b128 v[224:227], v204 offset:6144
	ds_read_b128 v[228:231], v205 offset:0
	ds_read_b128 v[232:235], v205 offset:2048
	ds_read_b128 v[236:239], v205 offset:4096
	ds_read_b128 v[240:243], v205 offset:6144
	s_add_u32 m0, s76, 0xc000
	s_nop 0
	global_load_lds_dwordx4 v196, s[68:69]
	s_add_u32 m0, s76, 0xe000
	s_nop 0
	global_load_lds_dwordx4 v197, s[68:69]
	s_add_u32 m0, s76, 0x10000
	s_nop 0
	global_load_lds_dwordx4 v198, s[68:69]
	s_add_u32 m0, s76, 0x12000
	s_nop 0
	global_load_lds_dwordx4 v199, s[68:69]
	s_add_u32 m0, s76, 0x14000
	s_nop 0
	global_load_lds_dwordx4 v196, s[70:71]
	s_add_u32 m0, s76, 0x16000
	s_nop 0
	global_load_lds_dwordx4 v197, s[70:71]
	s_add_u32 s68, s68, 0x80
	s_addc_u32 s69, s69, 0
	s_add_u32 s70, s70, 0x80
	s_addc_u32 s71, s71, 0
	s_waitcnt lgkmcnt(0)
	s_barrier
	v_mfma_f32_16x16x32_bf16 v[2:5], v[146:149], v[130:133], v[2:5]
	v_mfma_f32_16x16x32_bf16 v[6:9], v[150:153], v[130:133], v[6:9]
	v_mfma_f32_16x16x32_bf16 v[10:13], v[154:157], v[130:133], v[10:13]
	v_mfma_f32_16x16x32_bf16 v[14:17], v[158:161], v[130:133], v[14:17]
	v_mfma_f32_16x16x32_bf16 v[18:21], v[146:149], v[134:137], v[18:21]
	v_mfma_f32_16x16x32_bf16 v[22:25], v[150:153], v[134:137], v[22:25]
	v_mfma_f32_16x16x32_bf16 v[26:29], v[154:157], v[134:137], v[26:29]
	v_mfma_f32_16x16x32_bf16 v[30:33], v[158:161], v[134:137], v[30:33]
	v_mfma_f32_16x16x32_bf16 v[34:37], v[146:149], v[138:141], v[34:37]
	v_mfma_f32_16x16x32_bf16 v[38:41], v[150:153], v[138:141], v[38:41]
	v_mfma_f32_16x16x32_bf16 v[42:45], v[154:157], v[138:141], v[42:45]
	v_mfma_f32_16x16x32_bf16 v[46:49], v[158:161], v[138:141], v[46:49]
	v_mfma_f32_16x16x32_bf16 v[50:53], v[146:149], v[142:145], v[50:53]
	v_mfma_f32_16x16x32_bf16 v[54:57], v[150:153], v[142:145], v[54:57]
	v_mfma_f32_16x16x32_bf16 v[58:61], v[154:157], v[142:145], v[58:61]
	v_mfma_f32_16x16x32_bf16 v[62:65], v[158:161], v[142:145], v[62:65]
	v_mfma_f32_16x16x32_bf16 v[2:5], v[228:231], v[212:215], v[2:5]
	v_mfma_f32_16x16x32_bf16 v[6:9], v[232:235], v[212:215], v[6:9]
	v_mfma_f32_16x16x32_bf16 v[10:13], v[236:239], v[212:215], v[10:13]
	v_mfma_f32_16x16x32_bf16 v[14:17], v[240:243], v[212:215], v[14:17]
	v_mfma_f32_16x16x32_bf16 v[18:21], v[228:231], v[216:219], v[18:21]
	v_mfma_f32_16x16x32_bf16 v[22:25], v[232:235], v[216:219], v[22:25]
	v_mfma_f32_16x16x32_bf16 v[26:29], v[236:239], v[216:219], v[26:29]
	v_mfma_f32_16x16x32_bf16 v[30:33], v[240:243], v[216:219], v[30:33]
	v_mfma_f32_16x16x32_bf16 v[34:37], v[228:231], v[220:223], v[34:37]
	v_mfma_f32_16x16x32_bf16 v[38:41], v[232:235], v[220:223], v[38:41]
	v_mfma_f32_16x16x32_bf16 v[42:45], v[236:239], v[220:223], v[42:45]
	v_mfma_f32_16x16x32_bf16 v[46:49], v[240:243], v[220:223], v[46:49]
	v_mfma_f32_16x16x32_bf16 v[50:53], v[228:231], v[224:227], v[50:53]
	v_mfma_f32_16x16x32_bf16 v[54:57], v[232:235], v[224:227], v[54:57]
	v_mfma_f32_16x16x32_bf16 v[58:61], v[236:239], v[224:227], v[58:61]
	v_mfma_f32_16x16x32_bf16 v[62:65], v[240:243], v[224:227], v[62:65]
	s_waitcnt vmcnt(6)
	s_barrier
	v_add_u32_e32 v204, 0x0, v200
	v_add_u32_e32 v205, 0x0, v202
	ds_read_b128 v[130:133], v204 offset:0
	ds_read_b128 v[134:137], v204 offset:2048
	ds_read_b128 v[138:141], v204 offset:4096
	ds_read_b128 v[142:145], v204 offset:6144
	ds_read_b128 v[146:149], v205 offset:0
	ds_read_b128 v[150:153], v205 offset:2048
	ds_read_b128 v[154:157], v205 offset:4096
	ds_read_b128 v[158:161], v205 offset:6144
	v_add_u32_e32 v204, 0x0, v201
	v_add_u32_e32 v205, 0x0, v203
	ds_read_b128 v[212:215], v204 offset:0
	ds_read_b128 v[216:219], v204 offset:2048
	ds_read_b128 v[220:223], v204 offset:4096
	ds_read_b128 v[224:227], v204 offset:6144
	ds_read_b128 v[228:231], v205 offset:0
	ds_read_b128 v[232:235], v205 offset:2048
	ds_read_b128 v[236:239], v205 offset:4096
	ds_read_b128 v[240:243], v205 offset:6144
	s_add_u32 m0, s76, 0x18000
	s_nop 0
	global_load_lds_dwordx4 v196, s[68:69]
	s_add_u32 m0, s76, 0x1a000
	s_nop 0
	global_load_lds_dwordx4 v197, s[68:69]
	s_add_u32 m0, s76, 0x1c000
	s_nop 0
	global_load_lds_dwordx4 v198, s[68:69]
	s_add_u32 m0, s76, 0x1e000
	s_nop 0
	global_load_lds_dwordx4 v199, s[68:69]
	s_add_u32 m0, s76, 0x20000
	s_nop 0
	global_load_lds_dwordx4 v196, s[70:71]
	s_add_u32 m0, s76, 0x22000
	s_nop 0
	global_load_lds_dwordx4 v197, s[70:71]
	s_add_u32 s68, s68, 0x80
	s_addc_u32 s69, s69, 0
	s_add_u32 s70, s70, 0x80
	s_addc_u32 s71, s71, 0
	s_waitcnt lgkmcnt(0)
	s_barrier
	v_mfma_f32_16x16x32_bf16 v[2:5], v[146:149], v[130:133], v[2:5]
	v_mfma_f32_16x16x32_bf16 v[6:9], v[150:153], v[130:133], v[6:9]
	v_mfma_f32_16x16x32_bf16 v[10:13], v[154:157], v[130:133], v[10:13]
	v_mfma_f32_16x16x32_bf16 v[14:17], v[158:161], v[130:133], v[14:17]
	v_mfma_f32_16x16x32_bf16 v[18:21], v[146:149], v[134:137], v[18:21]
	v_mfma_f32_16x16x32_bf16 v[22:25], v[150:153], v[134:137], v[22:25]
	v_mfma_f32_16x16x32_bf16 v[26:29], v[154:157], v[134:137], v[26:29]
	v_mfma_f32_16x16x32_bf16 v[30:33], v[158:161], v[134:137], v[30:33]
	v_mfma_f32_16x16x32_bf16 v[34:37], v[146:149], v[138:141], v[34:37]
	v_mfma_f32_16x16x32_bf16 v[38:41], v[150:153], v[138:141], v[38:41]
	v_mfma_f32_16x16x32_bf16 v[42:45], v[154:157], v[138:141], v[42:45]
	v_mfma_f32_16x16x32_bf16 v[46:49], v[158:161], v[138:141], v[46:49]
	v_mfma_f32_16x16x32_bf16 v[50:53], v[146:149], v[142:145], v[50:53]
	v_mfma_f32_16x16x32_bf16 v[54:57], v[150:153], v[142:145], v[54:57]
	v_mfma_f32_16x16x32_bf16 v[58:61], v[154:157], v[142:145], v[58:61]
	v_mfma_f32_16x16x32_bf16 v[62:65], v[158:161], v[142:145], v[62:65]
	v_mfma_f32_16x16x32_bf16 v[2:5], v[228:231], v[212:215], v[2:5]
	v_mfma_f32_16x16x32_bf16 v[6:9], v[232:235], v[212:215], v[6:9]
	v_mfma_f32_16x16x32_bf16 v[10:13], v[236:239], v[212:215], v[10:13]
	v_mfma_f32_16x16x32_bf16 v[14:17], v[240:243], v[212:215], v[14:17]
	v_mfma_f32_16x16x32_bf16 v[18:21], v[228:231], v[216:219], v[18:21]
	v_mfma_f32_16x16x32_bf16 v[22:25], v[232:235], v[216:219], v[22:25]
	v_mfma_f32_16x16x32_bf16 v[26:29], v[236:239], v[216:219], v[26:29]
	v_mfma_f32_16x16x32_bf16 v[30:33], v[240:243], v[216:219], v[30:33]
	v_mfma_f32_16x16x32_bf16 v[34:37], v[228:231], v[220:223], v[34:37]
	v_mfma_f32_16x16x32_bf16 v[38:41], v[232:235], v[220:223], v[38:41]
	v_mfma_f32_16x16x32_bf16 v[42:45], v[236:239], v[220:223], v[42:45]
	v_mfma_f32_16x16x32_bf16 v[46:49], v[240:243], v[220:223], v[46:49]
	v_mfma_f32_16x16x32_bf16 v[50:53], v[228:231], v[224:227], v[50:53]
	v_mfma_f32_16x16x32_bf16 v[54:57], v[232:235], v[224:227], v[54:57]
	v_mfma_f32_16x16x32_bf16 v[58:61], v[236:239], v[224:227], v[58:61]
	v_mfma_f32_16x16x32_bf16 v[62:65], v[240:243], v[224:227], v[62:65]
	s_waitcnt vmcnt(6)
	s_barrier
	v_add_u32_e32 v204, 0xc000, v200
	v_add_u32_e32 v205, 0xc000, v202
	ds_read_b128 v[130:133], v204 offset:0
	ds_read_b128 v[134:137], v204 offset:2048
	ds_read_b128 v[138:141], v204 offset:4096
	ds_read_b128 v[142:145], v204 offset:6144
	ds_read_b128 v[146:149], v205 offset:0
	ds_read_b128 v[150:153], v205 offset:2048
	ds_read_b128 v[154:157], v205 offset:4096
	ds_read_b128 v[158:161], v205 offset:6144
	v_add_u32_e32 v204, 0xc000, v201
	v_add_u32_e32 v205, 0xc000, v203
	ds_read_b128 v[212:215], v204 offset:0
	ds_read_b128 v[216:219], v204 offset:2048
	ds_read_b128 v[220:223], v204 offset:4096
	ds_read_b128 v[224:227], v204 offset:6144
	ds_read_b128 v[228:231], v205 offset:0
	ds_read_b128 v[232:235], v205 offset:2048
	ds_read_b128 v[236:239], v205 offset:4096
	ds_read_b128 v[240:243], v205 offset:6144
	s_add_u32 m0, s76, 0x0
	s_nop 0
	global_load_lds_dwordx4 v196, s[68:69]
	s_add_u32 m0, s76, 0x2000
	s_nop 0
	global_load_lds_dwordx4 v197, s[68:69]
	s_add_u32 m0, s76, 0x4000
	s_nop 0
	global_load_lds_dwordx4 v198, s[68:69]
	s_add_u32 m0, s76, 0x6000
	s_nop 0
	global_load_lds_dwordx4 v199, s[68:69]
	s_add_u32 m0, s76, 0x8000
	s_nop 0
	global_load_lds_dwordx4 v196, s[70:71]
	s_add_u32 m0, s76, 0xa000
	s_nop 0
	global_load_lds_dwordx4 v197, s[70:71]
	s_add_u32 s68, s68, 0x80
	s_addc_u32 s69, s69, 0
	s_add_u32 s70, s70, 0x80
	s_addc_u32 s71, s71, 0
	s_waitcnt lgkmcnt(0)
	s_barrier
	v_mfma_f32_16x16x32_bf16 v[2:5], v[146:149], v[130:133], v[2:5]
	v_mfma_f32_16x16x32_bf16 v[6:9], v[150:153], v[130:133], v[6:9]
	v_mfma_f32_16x16x32_bf16 v[10:13], v[154:157], v[130:133], v[10:13]
	v_mfma_f32_16x16x32_bf16 v[14:17], v[158:161], v[130:133], v[14:17]
	v_mfma_f32_16x16x32_bf16 v[18:21], v[146:149], v[134:137], v[18:21]
	v_mfma_f32_16x16x32_bf16 v[22:25], v[150:153], v[134:137], v[22:25]
	v_mfma_f32_16x16x32_bf16 v[26:29], v[154:157], v[134:137], v[26:29]
	v_mfma_f32_16x16x32_bf16 v[30:33], v[158:161], v[134:137], v[30:33]
	v_mfma_f32_16x16x32_bf16 v[34:37], v[146:149], v[138:141], v[34:37]
	v_mfma_f32_16x16x32_bf16 v[38:41], v[150:153], v[138:141], v[38:41]
	v_mfma_f32_16x16x32_bf16 v[42:45], v[154:157], v[138:141], v[42:45]
	v_mfma_f32_16x16x32_bf16 v[46:49], v[158:161], v[138:141], v[46:49]
	v_mfma_f32_16x16x32_bf16 v[50:53], v[146:149], v[142:145], v[50:53]
	v_mfma_f32_16x16x32_bf16 v[54:57], v[150:153], v[142:145], v[54:57]
	v_mfma_f32_16x16x32_bf16 v[58:61], v[154:157], v[142:145], v[58:61]
	v_mfma_f32_16x16x32_bf16 v[62:65], v[158:161], v[142:145], v[62:65]
	v_mfma_f32_16x16x32_bf16 v[2:5], v[228:231], v[212:215], v[2:5]
	v_mfma_f32_16x16x32_bf16 v[6:9], v[232:235], v[212:215], v[6:9]
	v_mfma_f32_16x16x32_bf16 v[10:13], v[236:239], v[212:215], v[10:13]
	v_mfma_f32_16x16x32_bf16 v[14:17], v[240:243], v[212:215], v[14:17]
	v_mfma_f32_16x16x32_bf16 v[18:21], v[228:231], v[216:219], v[18:21]
	v_mfma_f32_16x16x32_bf16 v[22:25], v[232:235], v[216:219], v[22:25]
	v_mfma_f32_16x16x32_bf16 v[26:29], v[236:239], v[216:219], v[26:29]
	v_mfma_f32_16x16x32_bf16 v[30:33], v[240:243], v[216:219], v[30:33]
	v_mfma_f32_16x16x32_bf16 v[34:37], v[228:231], v[220:223], v[34:37]
	v_mfma_f32_16x16x32_bf16 v[38:41], v[232:235], v[220:223], v[38:41]
	v_mfma_f32_16x16x32_bf16 v[42:45], v[236:239], v[220:223], v[42:45]
	v_mfma_f32_16x16x32_bf16 v[46:49], v[240:243], v[220:223], v[46:49]
	v_mfma_f32_16x16x32_bf16 v[50:53], v[228:231], v[224:227], v[50:53]
	v_mfma_f32_16x16x32_bf16 v[54:57], v[232:235], v[224:227], v[54:57]
	v_mfma_f32_16x16x32_bf16 v[58:61], v[236:239], v[224:227], v[58:61]
	v_mfma_f32_16x16x32_bf16 v[62:65], v[240:243], v[224:227], v[62:65]
	s_waitcnt vmcnt(6)
	s_barrier
	v_add_u32_e32 v204, 0x18000, v200
	v_add_u32_e32 v205, 0x18000, v202
	ds_read_b128 v[130:133], v204 offset:0
	ds_read_b128 v[134:137], v204 offset:2048
	ds_read_b128 v[138:141], v204 offset:4096
	ds_read_b128 v[142:145], v204 offset:6144
	ds_read_b128 v[146:149], v205 offset:0
	ds_read_b128 v[150:153], v205 offset:2048
	ds_read_b128 v[154:157], v205 offset:4096
	ds_read_b128 v[158:161], v205 offset:6144
	v_add_u32_e32 v204, 0x18000, v201
	v_add_u32_e32 v205, 0x18000, v203
	ds_read_b128 v[212:215], v204 offset:0
	ds_read_b128 v[216:219], v204 offset:2048
	ds_read_b128 v[220:223], v204 offset:4096
	ds_read_b128 v[224:227], v204 offset:6144
	ds_read_b128 v[228:231], v205 offset:0
	ds_read_b128 v[232:235], v205 offset:2048
	ds_read_b128 v[236:239], v205 offset:4096
	ds_read_b128 v[240:243], v205 offset:6144
	s_waitcnt lgkmcnt(0)
	s_barrier
	v_mfma_f32_16x16x32_bf16 v[2:5], v[146:149], v[130:133], v[2:5]
	v_mfma_f32_16x16x32_bf16 v[6:9], v[150:153], v[130:133], v[6:9]
	v_mfma_f32_16x16x32_bf16 v[10:13], v[154:157], v[130:133], v[10:13]
	v_mfma_f32_16x16x32_bf16 v[14:17], v[158:161], v[130:133], v[14:17]
	v_mfma_f32_16x16x32_bf16 v[18:21], v[146:149], v[134:137], v[18:21]
	v_mfma_f32_16x16x32_bf16 v[22:25], v[150:153], v[134:137], v[22:25]
	v_mfma_f32_16x16x32_bf16 v[26:29], v[154:157], v[134:137], v[26:29]
	v_mfma_f32_16x16x32_bf16 v[30:33], v[158:161], v[134:137], v[30:33]
	v_mfma_f32_16x16x32_bf16 v[34:37], v[146:149], v[138:141], v[34:37]
	v_mfma_f32_16x16x32_bf16 v[38:41], v[150:153], v[138:141], v[38:41]
	v_mfma_f32_16x16x32_bf16 v[42:45], v[154:157], v[138:141], v[42:45]
	v_mfma_f32_16x16x32_bf16 v[46:49], v[158:161], v[138:141], v[46:49]
	v_mfma_f32_16x16x32_bf16 v[50:53], v[146:149], v[142:145], v[50:53]
	v_mfma_f32_16x16x32_bf16 v[54:57], v[150:153], v[142:145], v[54:57]
	v_mfma_f32_16x16x32_bf16 v[58:61], v[154:157], v[142:145], v[58:61]
	v_mfma_f32_16x16x32_bf16 v[62:65], v[158:161], v[142:145], v[62:65]
	v_mfma_f32_16x16x32_bf16 v[2:5], v[228:231], v[212:215], v[2:5]
	v_mfma_f32_16x16x32_bf16 v[6:9], v[232:235], v[212:215], v[6:9]
	v_mfma_f32_16x16x32_bf16 v[10:13], v[236:239], v[212:215], v[10:13]
	v_mfma_f32_16x16x32_bf16 v[14:17], v[240:243], v[212:215], v[14:17]
	v_mfma_f32_16x16x32_bf16 v[18:21], v[228:231], v[216:219], v[18:21]
	v_mfma_f32_16x16x32_bf16 v[22:25], v[232:235], v[216:219], v[22:25]
	v_mfma_f32_16x16x32_bf16 v[26:29], v[236:239], v[216:219], v[26:29]
	v_mfma_f32_16x16x32_bf16 v[30:33], v[240:243], v[216:219], v[30:33]
	v_mfma_f32_16x16x32_bf16 v[34:37], v[228:231], v[220:223], v[34:37]
	v_mfma_f32_16x16x32_bf16 v[38:41], v[232:235], v[220:223], v[38:41]
	v_mfma_f32_16x16x32_bf16 v[42:45], v[236:239], v[220:223], v[42:45]
	v_mfma_f32_16x16x32_bf16 v[46:49], v[240:243], v[220:223], v[46:49]
	v_mfma_f32_16x16x32_bf16 v[50:53], v[228:231], v[224:227], v[50:53]
	v_mfma_f32_16x16x32_bf16 v[54:57], v[232:235], v[224:227], v[54:57]
	v_mfma_f32_16x16x32_bf16 v[58:61], v[236:239], v[224:227], v[58:61]
	v_mfma_f32_16x16x32_bf16 v[62:65], v[240:243], v[224:227], v[62:65]
	s_waitcnt vmcnt(0)
	s_barrier
	v_add_u32_e32 v204, 0x0, v200
	v_add_u32_e32 v205, 0x0, v202
	ds_read_b128 v[130:133], v204 offset:0
	ds_read_b128 v[134:137], v204 offset:2048
	ds_read_b128 v[138:141], v204 offset:4096
	ds_read_b128 v[142:145], v204 offset:6144
	ds_read_b128 v[146:149], v205 offset:0
	ds_read_b128 v[150:153], v205 offset:2048
	ds_read_b128 v[154:157], v205 offset:4096
	ds_read_b128 v[158:161], v205 offset:6144
	v_add_u32_e32 v204, 0x0, v201
	v_add_u32_e32 v205, 0x0, v203
	ds_read_b128 v[212:215], v204 offset:0
	ds_read_b128 v[216:219], v204 offset:2048
	ds_read_b128 v[220:223], v204 offset:4096
	ds_read_b128 v[224:227], v204 offset:6144
	ds_read_b128 v[228:231], v205 offset:0
	ds_read_b128 v[232:235], v205 offset:2048
	ds_read_b128 v[236:239], v205 offset:4096
	ds_read_b128 v[240:243], v205 offset:6144
	s_waitcnt lgkmcnt(0)
	s_barrier
	v_mfma_f32_16x16x32_bf16 v[2:5], v[146:149], v[130:133], v[2:5]
	v_mfma_f32_16x16x32_bf16 v[6:9], v[150:153], v[130:133], v[6:9]
	v_mfma_f32_16x16x32_bf16 v[10:13], v[154:157], v[130:133], v[10:13]
	v_mfma_f32_16x16x32_bf16 v[14:17], v[158:161], v[130:133], v[14:17]
	v_mfma_f32_16x16x32_bf16 v[18:21], v[146:149], v[134:137], v[18:21]
	v_mfma_f32_16x16x32_bf16 v[22:25], v[150:153], v[134:137], v[22:25]
	v_mfma_f32_16x16x32_bf16 v[26:29], v[154:157], v[134:137], v[26:29]
	v_mfma_f32_16x16x32_bf16 v[30:33], v[158:161], v[134:137], v[30:33]
	v_mfma_f32_16x16x32_bf16 v[34:37], v[146:149], v[138:141], v[34:37]
	v_mfma_f32_16x16x32_bf16 v[38:41], v[150:153], v[138:141], v[38:41]
	v_mfma_f32_16x16x32_bf16 v[42:45], v[154:157], v[138:141], v[42:45]
	v_mfma_f32_16x16x32_bf16 v[46:49], v[158:161], v[138:141], v[46:49]
	v_mfma_f32_16x16x32_bf16 v[50:53], v[146:149], v[142:145], v[50:53]
	v_mfma_f32_16x16x32_bf16 v[54:57], v[150:153], v[142:145], v[54:57]
	v_mfma_f32_16x16x32_bf16 v[58:61], v[154:157], v[142:145], v[58:61]
	v_mfma_f32_16x16x32_bf16 v[62:65], v[158:161], v[142:145], v[62:65]
	v_mfma_f32_16x16x32_bf16 v[2:5], v[228:231], v[212:215], v[2:5]
	v_mfma_f32_16x16x32_bf16 v[6:9], v[232:235], v[212:215], v[6:9]
	v_mfma_f32_16x16x32_bf16 v[10:13], v[236:239], v[212:215], v[10:13]
	v_mfma_f32_16x16x32_bf16 v[14:17], v[240:243], v[212:215], v[14:17]
	v_mfma_f32_16x16x32_bf16 v[18:21], v[228:231], v[216:219], v[18:21]
	v_mfma_f32_16x16x32_bf16 v[22:25], v[232:235], v[216:219], v[22:25]
	v_mfma_f32_16x16x32_bf16 v[26:29], v[236:239], v[216:219], v[26:29]
	v_mfma_f32_16x16x32_bf16 v[30:33], v[240:243], v[216:219], v[30:33]
	v_mfma_f32_16x16x32_bf16 v[34:37], v[228:231], v[220:223], v[34:37]
	v_mfma_f32_16x16x32_bf16 v[38:41], v[232:235], v[220:223], v[38:41]
	v_mfma_f32_16x16x32_bf16 v[42:45], v[236:239], v[220:223], v[42:45]
	v_mfma_f32_16x16x32_bf16 v[46:49], v[240:243], v[220:223], v[46:49]
	v_mfma_f32_16x16x32_bf16 v[50:53], v[228:231], v[224:227], v[50:53]
	v_mfma_f32_16x16x32_bf16 v[54:57], v[232:235], v[224:227], v[54:57]
	v_mfma_f32_16x16x32_bf16 v[58:61], v[236:239], v[224:227], v[58:61]
	v_mfma_f32_16x16x32_bf16 v[62:65], v[240:243], v[224:227], v[62:65]
	s_barrier
	s_branch .Lop_join

.Lbr_tile:
	s_and_b32 s0, s78, 3
	s_or_b32 s0, s0, s77
	s_lshl_b32 s0, s0, 8
	s_lshr_b32 s1, s78, 2
	s_lshl_b32 s1, s1, 7
	s_mul_i32 s2, s0, 0xc00
	s_add_u32 s68, s8, s2
	s_addc_u32 s69, s9, 0
	s_mul_i32 s2, s1, 0xc00
	s_add_u32 s70, s80, s2
	s_addc_u32 s71, s81, 0
	s_mul_i32 s2, s0, 0x3400
	s_lshl_b32 s3, s1, 1
	s_add_u32 s2, s2, s3
	s_add_u32 s2, s2, 0x1c00
	s_add_u32 s72, s4, s2
	s_addc_u32 s73, s5, 0
	s_lshl_b32 s2, s0, 11
	s_add_u32 s2, s2, s3
	s_add_u32 s74, s10, s2
	s_addc_u32 s75, s11, 0
	s_add_u32 m0, s76, 0x0
	s_nop 0
	global_load_lds_dwordx4 v196, s[68:69]
	s_add_u32 m0, s76, 0x2000
	s_nop 0
	global_load_lds_dwordx4 v197, s[68:69]
	s_add_u32 m0, s76, 0x4000
	s_nop 0
	global_load_lds_dwordx4 v198, s[68:69]
	s_add_u32 m0, s76, 0x6000
	s_nop 0
	global_load_lds_dwordx4 v199, s[68:69]
	s_add_u32 m0, s76, 0x8000
	s_nop 0
	global_load_lds_dwordx4 v196, s[70:71]
	s_add_u32 m0, s76, 0xa000
	s_nop 0
	global_load_lds_dwordx4 v197, s[70:71]
	s_add_u32 s68, s68, 0x80
	s_addc_u32 s69, s69, 0
	s_add_u32 s70, s70, 0x80
	s_addc_u32 s71, s71, 0
	s_add_u32 m0, s76, 0xc000
	s_nop 0
	global_load_lds_dwordx4 v196, s[68:69]
	s_add_u32 m0, s76, 0xe000
	s_nop 0
	global_load_lds_dwordx4 v197, s[68:69]
	s_add_u32 m0, s76, 0x10000
	s_nop 0
	global_load_lds_dwordx4 v198, s[68:69]
	s_add_u32 m0, s76, 0x12000
	s_nop 0
	global_load_lds_dwordx4 v199, s[68:69]
	s_add_u32 m0, s76, 0x14000
	s_nop 0
	global_load_lds_dwordx4 v196, s[70:71]
	s_add_u32 m0, s76, 0x16000
	s_nop 0
	global_load_lds_dwordx4 v197, s[70:71]
	s_add_u32 s68, s68, 0x80
	s_addc_u32 s69, s69, 0
	s_add_u32 s70, s70, 0x80
	s_addc_u32 s71, s71, 0
	v_mov_b32_e32 v66, 0
	v_mov_b32_e32 v67, 0
	v_mov_b32_e32 v68, 0
	v_mov_b32_e32 v69, 0
	v_mov_b32_e32 v70, 0
	v_mov_b32_e32 v71, 0
	v_mov_b32_e32 v72, 0
	v_mov_b32_e32 v73, 0
	v_mov_b32_e32 v74, 0
	v_mov_b32_e32 v75, 0
	v_mov_b32_e32 v76, 0
	v_mov_b32_e32 v77, 0
	v_mov_b32_e32 v78, 0
	v_mov_b32_e32 v79, 0
	v_mov_b32_e32 v80, 0
	v_mov_b32_e32 v81, 0
	v_mov_b32_e32 v82, 0
	v_mov_b32_e32 v83, 0
	v_mov_b32_e32 v84, 0
	v_mov_b32_e32 v85, 0
	v_mov_b32_e32 v86, 0
	v_mov_b32_e32 v87, 0
	v_mov_b32_e32 v88, 0
	v_mov_b32_e32 v89, 0
	v_mov_b32_e32 v90, 0
	v_mov_b32_e32 v91, 0
	v_mov_b32_e32 v92, 0
	v_mov_b32_e32 v93, 0
	v_mov_b32_e32 v94, 0
	v_mov_b32_e32 v95, 0
	v_mov_b32_e32 v96, 0
	v_mov_b32_e32 v97, 0
	v_mov_b32_e32 v98, 0
	v_mov_b32_e32 v99, 0
	v_mov_b32_e32 v100, 0
	v_mov_b32_e32 v101, 0
	v_mov_b32_e32 v102, 0
	v_mov_b32_e32 v103, 0
	v_mov_b32_e32 v104, 0
	v_mov_b32_e32 v105, 0
	v_mov_b32_e32 v106, 0
	v_mov_b32_e32 v107, 0
	v_mov_b32_e32 v108, 0
	v_mov_b32_e32 v109, 0
	v_mov_b32_e32 v110, 0
	v_mov_b32_e32 v111, 0
	v_mov_b32_e32 v112, 0
	v_mov_b32_e32 v113, 0
	v_mov_b32_e32 v114, 0
	v_mov_b32_e32 v115, 0
	v_mov_b32_e32 v116, 0
	v_mov_b32_e32 v117, 0
	v_mov_b32_e32 v118, 0
	v_mov_b32_e32 v119, 0
	v_mov_b32_e32 v120, 0
	v_mov_b32_e32 v121, 0
	v_mov_b32_e32 v122, 0
	v_mov_b32_e32 v123, 0
	v_mov_b32_e32 v124, 0
	v_mov_b32_e32 v125, 0
	v_mov_b32_e32 v126, 0
	v_mov_b32_e32 v127, 0
	v_mov_b32_e32 v128, 0
	v_mov_b32_e32 v129, 0
	s_waitcnt vmcnt(6)
	s_barrier
	s_cmp_ge_u32 s76, 0x1000
	s_cbranch_scc1 .Lbr_streamB
	v_add_u32_e32 v204, 0x0, v200
	v_add_u32_e32 v205, 0x0, v202
	ds_read_b128 v[130:133], v204 offset:0
	ds_read_b128 v[134:137], v204 offset:2048
	ds_read_b128 v[138:141], v204 offset:4096
	ds_read_b128 v[142:145], v204 offset:6144
	ds_read_b128 v[146:149], v205 offset:0
	ds_read_b128 v[150:153], v205 offset:2048
	ds_read_b128 v[154:157], v205 offset:4096
	ds_read_b128 v[158:161], v205 offset:6144
	v_add_u32_e32 v204, 0x0, v201
	v_add_u32_e32 v205, 0x0, v203
	ds_read_b128 v[212:215], v204 offset:0
	ds_read_b128 v[216:219], v204 offset:2048
	ds_read_b128 v[220:223], v204 offset:4096
	ds_read_b128 v[224:227], v204 offset:6144
	ds_read_b128 v[228:231], v205 offset:0
	ds_read_b128 v[232:235], v205 offset:2048
	ds_read_b128 v[236:239], v205 offset:4096
	ds_read_b128 v[240:243], v205 offset:6144
	s_add_u32 m0, s76, 0x18000
	s_nop 0
	global_load_lds_dwordx4 v196, s[68:69]
	s_add_u32 m0, s76, 0x1a000
	s_nop 0
	global_load_lds_dwordx4 v197, s[68:69]
	s_add_u32 m0, s76, 0x1c000
	s_nop 0
	global_load_lds_dwordx4 v198, s[68:69]
	s_add_u32 m0, s76, 0x1e000
	s_nop 0
	global_load_lds_dwordx4 v199, s[68:69]
	s_add_u32 m0, s76, 0x20000
	s_nop 0
	global_load_lds_dwordx4 v196, s[70:71]
	s_add_u32 m0, s76, 0x22000
	s_nop 0
	global_load_lds_dwordx4 v197, s[70:71]
	s_add_u32 s68, s68, 0x80
	s_addc_u32 s69, s69, 0
	s_add_u32 s70, s70, 0x80
	s_addc_u32 s71, s71, 0
	global_load_dwordx2 v[174:175], v206, s[72:73] offset:0
	global_load_dwordx2 v[176:177], v206, s[72:73] offset:32
	global_load_dwordx2 v[178:179], v206, s[72:73] offset:64
	global_load_dwordx2 v[180:181], v206, s[72:73] offset:96
	global_load_dwordx2 v[182:183], v207, s[72:73] offset:0
	global_load_dwordx2 v[184:185], v207, s[72:73] offset:32
	s_waitcnt lgkmcnt(0)
	s_barrier
	v_mfma_f32_16x16x32_bf16 v[2:5], v[146:149], v[130:133], 0
	v_mfma_f32_16x16x32_bf16 v[6:9], v[150:153], v[130:133], 0
	v_mfma_f32_16x16x32_bf16 v[10:13], v[154:157], v[130:133], 0
	v_mfma_f32_16x16x32_bf16 v[14:17], v[158:161], v[130:133], 0
	v_mfma_f32_16x16x32_bf16 v[18:21], v[146:149], v[134:137], 0
	v_mfma_f32_16x16x32_bf16 v[22:25], v[150:153], v[134:137], 0
	v_mfma_f32_16x16x32_bf16 v[26:29], v[154:157], v[134:137], 0
	v_mfma_f32_16x16x32_bf16 v[30:33], v[158:161], v[134:137], 0
	v_mfma_f32_16x16x32_bf16 v[34:37], v[146:149], v[138:141], 0
	v_mfma_f32_16x16x32_bf16 v[38:41], v[150:153], v[138:141], 0
	v_mfma_f32_16x16x32_bf16 v[42:45], v[154:157], v[138:141], 0
	v_mfma_f32_16x16x32_bf16 v[46:49], v[158:161], v[138:141], 0
	v_mfma_f32_16x16x32_bf16 v[50:53], v[146:149], v[142:145], 0
	v_mfma_f32_16x16x32_bf16 v[54:57], v[150:153], v[142:145], 0
	v_mfma_f32_16x16x32_bf16 v[58:61], v[154:157], v[142:145], 0
	v_mfma_f32_16x16x32_bf16 v[62:65], v[158:161], v[142:145], 0
	v_mfma_f32_16x16x32_bf16 v[2:5], v[228:231], v[212:215], v[2:5]
	v_mfma_f32_16x16x32_bf16 v[6:9], v[232:235], v[212:215], v[6:9]
	v_mfma_f32_16x16x32_bf16 v[10:13], v[236:239], v[212:215], v[10:13]
	v_mfma_f32_16x16x32_bf16 v[14:17], v[240:243], v[212:215], v[14:17]
	v_mfma_f32_16x16x32_bf16 v[18:21], v[228:231], v[216:219], v[18:21]
	v_mfma_f32_16x16x32_bf16 v[22:25], v[232:235], v[216:219], v[22:25]
	v_mfma_f32_16x16x32_bf16 v[26:29], v[236:239], v[216:219], v[26:29]
	v_mfma_f32_16x16x32_bf16 v[30:33], v[240:243], v[216:219], v[30:33]
	v_mfma_f32_16x16x32_bf16 v[34:37], v[228:231], v[220:223], v[34:37]
	v_mfma_f32_16x16x32_bf16 v[38:41], v[232:235], v[220:223], v[38:41]
	v_mfma_f32_16x16x32_bf16 v[42:45], v[236:239], v[220:223], v[42:45]
	v_mfma_f32_16x16x32_bf16 v[46:49], v[240:243], v[220:223], v[46:49]
	v_mfma_f32_16x16x32_bf16 v[50:53], v[228:231], v[224:227], v[50:53]
	v_mfma_f32_16x16x32_bf16 v[54:57], v[232:235], v[224:227], v[54:57]
	v_mfma_f32_16x16x32_bf16 v[58:61], v[236:239], v[224:227], v[58:61]
	v_mfma_f32_16x16x32_bf16 v[62:65], v[240:243], v[224:227], v[62:65]
	s_waitcnt vmcnt(12)
	s_barrier
	v_add_u32_e32 v204, 0xc000, v200
	v_add_u32_e32 v205, 0xc000, v202
	ds_read_b128 v[130:133], v204 offset:0
	ds_read_b128 v[134:137], v204 offset:2048
	ds_read_b128 v[138:141], v204 offset:4096
	ds_read_b128 v[142:145], v204 offset:6144
	ds_read_b128 v[146:149], v205 offset:0
	ds_read_b128 v[150:153], v205 offset:2048
	ds_read_b128 v[154:157], v205 offset:4096
	ds_read_b128 v[158:161], v205 offset:6144
	v_add_u32_e32 v204, 0xc000, v201
	v_add_u32_e32 v205, 0xc000, v203
	ds_read_b128 v[212:215], v204 offset:0
	ds_read_b128 v[216:219], v204 offset:2048
	ds_read_b128 v[220:223], v204 offset:4096
	ds_read_b128 v[224:227], v204 offset:6144
	ds_read_b128 v[228:231], v205 offset:0
	ds_read_b128 v[232:235], v205 offset:2048
	ds_read_b128 v[236:239], v205 offset:4096
	ds_read_b128 v[240:243], v205 offset:6144
	s_add_u32 m0, s76, 0x0
	s_nop 0
	global_load_lds_dwordx4 v196, s[68:69]
	s_add_u32 m0, s76, 0x2000
	s_nop 0
	global_load_lds_dwordx4 v197, s[68:69]
	s_add_u32 m0, s76, 0x4000
	s_nop 0
	global_load_lds_dwordx4 v198, s[68:69]
	s_add_u32 m0, s76, 0x6000
	s_nop 0
	global_load_lds_dwordx4 v199, s[68:69]
	s_add_u32 m0, s76, 0x8000
	s_nop 0
	global_load_lds_dwordx4 v196, s[70:71]
	s_add_u32 m0, s76, 0xa000
	s_nop 0
	global_load_lds_dwordx4 v197, s[70:71]
	s_add_u32 s68, s68, 0x80
	s_addc_u32 s69, s69, 0
	s_add_u32 s70, s70, 0x80
	s_addc_u32 s71, s71, 0
	global_load_dwordx2 v[186:187], v207, s[72:73] offset:64
	global_load_dwordx2 v[188:189], v207, s[72:73] offset:96
	global_load_dwordx2 v[190:191], v208, s[72:73] offset:0
	global_load_dwordx2 v[192:193], v208, s[72:73] offset:32
	global_load_dwordx2 v[244:245], v208, s[72:73] offset:64
	global_load_dwordx2 v[246:247], v208, s[72:73] offset:96
	s_waitcnt lgkmcnt(0)
	s_barrier
	v_mfma_f32_16x16x32_bf16 v[2:5], v[146:149], v[130:133], v[2:5]
	v_mfma_f32_16x16x32_bf16 v[6:9], v[150:153], v[130:133], v[6:9]
	v_mfma_f32_16x16x32_bf16 v[10:13], v[154:157], v[130:133], v[10:13]
	v_mfma_f32_16x16x32_bf16 v[14:17], v[158:161], v[130:133], v[14:17]
	v_mfma_f32_16x16x32_bf16 v[18:21], v[146:149], v[134:137], v[18:21]
	v_mfma_f32_16x16x32_bf16 v[22:25], v[150:153], v[134:137], v[22:25]
	v_mfma_f32_16x16x32_bf16 v[26:29], v[154:157], v[134:137], v[26:29]
	v_mfma_f32_16x16x32_bf16 v[30:33], v[158:161], v[134:137], v[30:33]
	v_mfma_f32_16x16x32_bf16 v[34:37], v[146:149], v[138:141], v[34:37]
	v_mfma_f32_16x16x32_bf16 v[38:41], v[150:153], v[138:141], v[38:41]
	v_mfma_f32_16x16x32_bf16 v[42:45], v[154:157], v[138:141], v[42:45]
	v_mfma_f32_16x16x32_bf16 v[46:49], v[158:161], v[138:141], v[46:49]
	v_mfma_f32_16x16x32_bf16 v[50:53], v[146:149], v[142:145], v[50:53]
	v_mfma_f32_16x16x32_bf16 v[54:57], v[150:153], v[142:145], v[54:57]
	v_mfma_f32_16x16x32_bf16 v[58:61], v[154:157], v[142:145], v[58:61]
	v_mfma_f32_16x16x32_bf16 v[62:65], v[158:161], v[142:145], v[62:65]
	v_mfma_f32_16x16x32_bf16 v[2:5], v[228:231], v[212:215], v[2:5]
	v_mfma_f32_16x16x32_bf16 v[6:9], v[232:235], v[212:215], v[6:9]
	v_mfma_f32_16x16x32_bf16 v[10:13], v[236:239], v[212:215], v[10:13]
	v_mfma_f32_16x16x32_bf16 v[14:17], v[240:243], v[212:215], v[14:17]
	v_mfma_f32_16x16x32_bf16 v[18:21], v[228:231], v[216:219], v[18:21]
	v_mfma_f32_16x16x32_bf16 v[22:25], v[232:235], v[216:219], v[22:25]
	v_mfma_f32_16x16x32_bf16 v[26:29], v[236:239], v[216:219], v[26:29]
	v_mfma_f32_16x16x32_bf16 v[30:33], v[240:243], v[216:219], v[30:33]
	v_mfma_f32_16x16x32_bf16 v[34:37], v[228:231], v[220:223], v[34:37]
	v_mfma_f32_16x16x32_bf16 v[38:41], v[232:235], v[220:223], v[38:41]
	v_mfma_f32_16x16x32_bf16 v[42:45], v[236:239], v[220:223], v[42:45]
	v_mfma_f32_16x16x32_bf16 v[46:49], v[240:243], v[220:223], v[46:49]
	v_mfma_f32_16x16x32_bf16 v[50:53], v[228:231], v[224:227], v[50:53]
	v_mfma_f32_16x16x32_bf16 v[54:57], v[232:235], v[224:227], v[54:57]
	v_mfma_f32_16x16x32_bf16 v[58:61], v[236:239], v[224:227], v[58:61]
	v_mfma_f32_16x16x32_bf16 v[62:65], v[240:243], v[224:227], v[62:65]
	s_waitcnt vmcnt(18)
	s_barrier
	v_add_u32_e32 v204, 0x18000, v200
	v_add_u32_e32 v205, 0x18000, v202
	ds_read_b128 v[130:133], v204 offset:0
	ds_read_b128 v[134:137], v204 offset:2048
	ds_read_b128 v[138:141], v204 offset:4096
	ds_read_b128 v[142:145], v204 offset:6144
	ds_read_b128 v[146:149], v205 offset:0
	ds_read_b128 v[150:153], v205 offset:2048
	ds_read_b128 v[154:157], v205 offset:4096
	ds_read_b128 v[158:161], v205 offset:6144
	v_add_u32_e32 v204, 0x18000, v201
	v_add_u32_e32 v205, 0x18000, v203
	ds_read_b128 v[212:215], v204 offset:0
	ds_read_b128 v[216:219], v204 offset:2048
	ds_read_b128 v[220:223], v204 offset:4096
	ds_read_b128 v[224:227], v204 offset:6144
	ds_read_b128 v[228:231], v205 offset:0
	ds_read_b128 v[232:235], v205 offset:2048
	ds_read_b128 v[236:239], v205 offset:4096
	ds_read_b128 v[240:243], v205 offset:6144
	s_add_u32 m0, s76, 0xc000
	s_nop 0
	global_load_lds_dwordx4 v196, s[68:69]
	s_add_u32 m0, s76, 0xe000
	s_nop 0
	global_load_lds_dwordx4 v197, s[68:69]
	s_add_u32 m0, s76, 0x10000
	s_nop 0
	global_load_lds_dwordx4 v198, s[68:69]
	s_add_u32 m0, s76, 0x12000
	s_nop 0
	global_load_lds_dwordx4 v199, s[68:69]
	s_add_u32 m0, s76, 0x14000
	s_nop 0
	global_load_lds_dwordx4 v196, s[70:71]
	s_add_u32 m0, s76, 0x16000
	s_nop 0
	global_load_lds_dwordx4 v197, s[70:71]
	s_add_u32 s68, s68, 0x80
	s_addc_u32 s69, s69, 0
	s_add_u32 s70, s70, 0x80
	s_addc_u32 s71, s71, 0
	global_load_dwordx2 v[248:249], v209, s[72:73] offset:0
	global_load_dwordx2 v[250:251], v209, s[72:73] offset:32
	global_load_dwordx2 v[166:167], v209, s[72:73] offset:64
	global_load_dwordx2 v[194:195], v209, s[72:73] offset:96
	s_add_u32 s72, s72, 0x800
	s_addc_u32 s73, s73, 0
	s_waitcnt lgkmcnt(0)
	s_barrier
	v_mfma_f32_16x16x32_bf16 v[2:5], v[146:149], v[130:133], v[2:5]
	v_mfma_f32_16x16x32_bf16 v[6:9], v[150:153], v[130:133], v[6:9]
	v_mfma_f32_16x16x32_bf16 v[10:13], v[154:157], v[130:133], v[10:13]
	v_mfma_f32_16x16x32_bf16 v[14:17], v[158:161], v[130:133], v[14:17]
	v_mfma_f32_16x16x32_bf16 v[18:21], v[146:149], v[134:137], v[18:21]
	v_mfma_f32_16x16x32_bf16 v[22:25], v[150:153], v[134:137], v[22:25]
	v_mfma_f32_16x16x32_bf16 v[26:29], v[154:157], v[134:137], v[26:29]
	v_mfma_f32_16x16x32_bf16 v[30:33], v[158:161], v[134:137], v[30:33]
	v_mfma_f32_16x16x32_bf16 v[34:37], v[146:149], v[138:141], v[34:37]
	v_mfma_f32_16x16x32_bf16 v[38:41], v[150:153], v[138:141], v[38:41]
	v_mfma_f32_16x16x32_bf16 v[42:45], v[154:157], v[138:141], v[42:45]
	v_mfma_f32_16x16x32_bf16 v[46:49], v[158:161], v[138:141], v[46:49]
	v_mfma_f32_16x16x32_bf16 v[50:53], v[146:149], v[142:145], v[50:53]
	v_mfma_f32_16x16x32_bf16 v[54:57], v[150:153], v[142:145], v[54:57]
	v_mfma_f32_16x16x32_bf16 v[58:61], v[154:157], v[142:145], v[58:61]
	v_mfma_f32_16x16x32_bf16 v[62:65], v[158:161], v[142:145], v[62:65]
	v_mfma_f32_16x16x32_bf16 v[2:5], v[228:231], v[212:215], v[2:5]
	v_mfma_f32_16x16x32_bf16 v[6:9], v[232:235], v[212:215], v[6:9]
	v_mfma_f32_16x16x32_bf16 v[10:13], v[236:239], v[212:215], v[10:13]
	v_mfma_f32_16x16x32_bf16 v[14:17], v[240:243], v[212:215], v[14:17]
	v_mfma_f32_16x16x32_bf16 v[18:21], v[228:231], v[216:219], v[18:21]
	v_mfma_f32_16x16x32_bf16 v[22:25], v[232:235], v[216:219], v[22:25]
	v_mfma_f32_16x16x32_bf16 v[26:29], v[236:239], v[216:219], v[26:29]
	v_mfma_f32_16x16x32_bf16 v[30:33], v[240:243], v[216:219], v[30:33]
	v_mfma_f32_16x16x32_bf16 v[34:37], v[228:231], v[220:223], v[34:37]
	v_mfma_f32_16x16x32_bf16 v[38:41], v[232:235], v[220:223], v[38:41]
	v_mfma_f32_16x16x32_bf16 v[42:45], v[236:239], v[220:223], v[42:45]
	v_mfma_f32_16x16x32_bf16 v[46:49], v[240:243], v[220:223], v[46:49]
	v_mfma_f32_16x16x32_bf16 v[50:53], v[228:231], v[224:227], v[50:53]
	v_mfma_f32_16x16x32_bf16 v[54:57], v[232:235], v[224:227], v[54:57]
	v_mfma_f32_16x16x32_bf16 v[58:61], v[236:239], v[224:227], v[58:61]
	v_mfma_f32_16x16x32_bf16 v[62:65], v[240:243], v[224:227], v[62:65]
	s_waitcnt vmcnt(16)
	s_barrier
	v_add_u32_e32 v204, 0x0, v200
	v_add_u32_e32 v205, 0x0, v202
	ds_read_b128 v[130:133], v204 offset:0
	ds_read_b128 v[134:137], v204 offset:2048
	ds_read_b128 v[138:141], v204 offset:4096
	ds_read_b128 v[142:145], v204 offset:6144
	ds_read_b128 v[146:149], v205 offset:0
	ds_read_b128 v[150:153], v205 offset:2048
	ds_read_b128 v[154:157], v205 offset:4096
	ds_read_b128 v[158:161], v205 offset:6144
	v_add_u32_e32 v204, 0x0, v201
	v_add_u32_e32 v205, 0x0, v203
	ds_read_b128 v[212:215], v204 offset:0
	ds_read_b128 v[216:219], v204 offset:2048
	ds_read_b128 v[220:223], v204 offset:4096
	ds_read_b128 v[224:227], v204 offset:6144
	ds_read_b128 v[228:231], v205 offset:0
	ds_read_b128 v[232:235], v205 offset:2048
	ds_read_b128 v[236:239], v205 offset:4096
	ds_read_b128 v[240:243], v205 offset:6144
	s_add_u32 m0, s76, 0x18000
	s_nop 0
	global_load_lds_dwordx4 v196, s[68:69]
	s_add_u32 m0, s76, 0x1a000
	s_nop 0
	global_load_lds_dwordx4 v197, s[68:69]
	s_add_u32 m0, s76, 0x1c000
	s_nop 0
	global_load_lds_dwordx4 v198, s[68:69]
	s_add_u32 m0, s76, 0x1e000
	s_nop 0
	global_load_lds_dwordx4 v199, s[68:69]
	s_add_u32 m0, s76, 0x20000
	s_nop 0
	global_load_lds_dwordx4 v196, s[70:71]
	s_add_u32 m0, s76, 0x22000
	s_nop 0
	global_load_lds_dwordx4 v197, s[70:71]
	s_add_u32 s68, s68, 0x80
	s_addc_u32 s69, s69, 0
	s_add_u32 s70, s70, 0x80
	s_addc_u32 s71, s71, 0
	s_waitcnt lgkmcnt(0)
	s_barrier
	v_mfma_f32_16x16x32_bf16 v[2:5], v[146:149], v[130:133], v[2:5]
	v_mfma_f32_16x16x32_bf16 v[6:9], v[150:153], v[130:133], v[6:9]
	v_mfma_f32_16x16x32_bf16 v[10:13], v[154:157], v[130:133], v[10:13]
	v_mfma_f32_16x16x32_bf16 v[14:17], v[158:161], v[130:133], v[14:17]
	v_mfma_f32_16x16x32_bf16 v[18:21], v[146:149], v[134:137], v[18:21]
	v_mfma_f32_16x16x32_bf16 v[22:25], v[150:153], v[134:137], v[22:25]
	v_mfma_f32_16x16x32_bf16 v[26:29], v[154:157], v[134:137], v[26:29]
	v_mfma_f32_16x16x32_bf16 v[30:33], v[158:161], v[134:137], v[30:33]
	v_mfma_f32_16x16x32_bf16 v[34:37], v[146:149], v[138:141], v[34:37]
	v_mfma_f32_16x16x32_bf16 v[38:41], v[150:153], v[138:141], v[38:41]
	v_mfma_f32_16x16x32_bf16 v[42:45], v[154:157], v[138:141], v[42:45]
	v_mfma_f32_16x16x32_bf16 v[46:49], v[158:161], v[138:141], v[46:49]
	v_mfma_f32_16x16x32_bf16 v[50:53], v[146:149], v[142:145], v[50:53]
	v_mfma_f32_16x16x32_bf16 v[54:57], v[150:153], v[142:145], v[54:57]
	v_mfma_f32_16x16x32_bf16 v[58:61], v[154:157], v[142:145], v[58:61]
	v_mfma_f32_16x16x32_bf16 v[62:65], v[158:161], v[142:145], v[62:65]
	v_mfma_f32_16x16x32_bf16 v[2:5], v[228:231], v[212:215], v[2:5]
	v_mfma_f32_16x16x32_bf16 v[6:9], v[232:235], v[212:215], v[6:9]
	v_mfma_f32_16x16x32_bf16 v[10:13], v[236:239], v[212:215], v[10:13]
	v_mfma_f32_16x16x32_bf16 v[14:17], v[240:243], v[212:215], v[14:17]
	v_mfma_f32_16x16x32_bf16 v[18:21], v[228:231], v[216:219], v[18:21]
	v_mfma_f32_16x16x32_bf16 v[22:25], v[232:235], v[216:219], v[22:25]
	v_mfma_f32_16x16x32_bf16 v[26:29], v[236:239], v[216:219], v[26:29]
	v_mfma_f32_16x16x32_bf16 v[30:33], v[240:243], v[216:219], v[30:33]
	v_mfma_f32_16x16x32_bf16 v[34:37], v[228:231], v[220:223], v[34:37]
	v_mfma_f32_16x16x32_bf16 v[38:41], v[232:235], v[220:223], v[38:41]
	v_mfma_f32_16x16x32_bf16 v[42:45], v[236:239], v[220:223], v[42:45]
	v_mfma_f32_16x16x32_bf16 v[46:49], v[240:243], v[220:223], v[46:49]
	v_mfma_f32_16x16x32_bf16 v[50:53], v[228:231], v[224:227], v[50:53]
	v_mfma_f32_16x16x32_bf16 v[54:57], v[232:235], v[224:227], v[54:57]
	v_mfma_f32_16x16x32_bf16 v[58:61], v[236:239], v[224:227], v[58:61]
	v_mfma_f32_16x16x32_bf16 v[62:65], v[240:243], v[224:227], v[62:65]
	s_waitcnt vmcnt(10)
	s_barrier
	v_add_u32_e32 v204, 0xc000, v200
	v_add_u32_e32 v205, 0xc000, v202
	ds_read_b128 v[130:133], v204 offset:0
	ds_read_b128 v[134:137], v204 offset:2048
	ds_read_b128 v[138:141], v204 offset:4096
	ds_read_b128 v[142:145], v204 offset:6144
	ds_read_b128 v[146:149], v205 offset:0
	ds_read_b128 v[150:153], v205 offset:2048
	ds_read_b128 v[154:157], v205 offset:4096
	ds_read_b128 v[158:161], v205 offset:6144
	v_add_u32_e32 v204, 0xc000, v201
	v_add_u32_e32 v205, 0xc000, v203
	ds_read_b128 v[212:215], v204 offset:0
	ds_read_b128 v[216:219], v204 offset:2048
	ds_read_b128 v[220:223], v204 offset:4096
	ds_read_b128 v[224:227], v204 offset:6144
	ds_read_b128 v[228:231], v205 offset:0
	ds_read_b128 v[232:235], v205 offset:2048
	ds_read_b128 v[236:239], v205 offset:4096
	ds_read_b128 v[240:243], v205 offset:6144
	s_add_u32 m0, s76, 0x0
	s_nop 0
	global_load_lds_dwordx4 v196, s[68:69]
	s_add_u32 m0, s76, 0x2000
	s_nop 0
	global_load_lds_dwordx4 v197, s[68:69]
	s_add_u32 m0, s76, 0x4000
	s_nop 0
	global_load_lds_dwordx4 v198, s[68:69]
	s_add_u32 m0, s76, 0x6000
	s_nop 0
	global_load_lds_dwordx4 v199, s[68:69]
	s_add_u32 m0, s76, 0x8000
	s_nop 0
	global_load_lds_dwordx4 v196, s[70:71]
	s_add_u32 m0, s76, 0xa000
	s_nop 0
	global_load_lds_dwordx4 v197, s[70:71]
	s_add_u32 s68, s68, 0x80
	s_addc_u32 s69, s69, 0
	s_add_u32 s70, s70, 0x80
	s_addc_u32 s71, s71, 0
	s_waitcnt lgkmcnt(0)
	s_barrier
	v_mfma_f32_16x16x32_bf16 v[2:5], v[146:149], v[130:133], v[2:5]
	v_mfma_f32_16x16x32_bf16 v[6:9], v[150:153], v[130:133], v[6:9]
	v_mfma_f32_16x16x32_bf16 v[10:13], v[154:157], v[130:133], v[10:13]
	v_mfma_f32_16x16x32_bf16 v[14:17], v[158:161], v[130:133], v[14:17]
	v_mfma_f32_16x16x32_bf16 v[18:21], v[146:149], v[134:137], v[18:21]
	v_mfma_f32_16x16x32_bf16 v[22:25], v[150:153], v[134:137], v[22:25]
	v_mfma_f32_16x16x32_bf16 v[26:29], v[154:157], v[134:137], v[26:29]
	v_mfma_f32_16x16x32_bf16 v[30:33], v[158:161], v[134:137], v[30:33]
	v_mfma_f32_16x16x32_bf16 v[34:37], v[146:149], v[138:141], v[34:37]
	v_mfma_f32_16x16x32_bf16 v[38:41], v[150:153], v[138:141], v[38:41]
	v_mfma_f32_16x16x32_bf16 v[42:45], v[154:157], v[138:141], v[42:45]
	v_mfma_f32_16x16x32_bf16 v[46:49], v[158:161], v[138:141], v[46:49]
	v_mfma_f32_16x16x32_bf16 v[50:53], v[146:149], v[142:145], v[50:53]
	v_mfma_f32_16x16x32_bf16 v[54:57], v[150:153], v[142:145], v[54:57]
	v_mfma_f32_16x16x32_bf16 v[58:61], v[154:157], v[142:145], v[58:61]
	v_mfma_f32_16x16x32_bf16 v[62:65], v[158:161], v[142:145], v[62:65]
	v_mfma_f32_16x16x32_bf16 v[2:5], v[228:231], v[212:215], v[2:5]
	v_mfma_f32_16x16x32_bf16 v[6:9], v[232:235], v[212:215], v[6:9]
	v_mfma_f32_16x16x32_bf16 v[10:13], v[236:239], v[212:215], v[10:13]
	v_mfma_f32_16x16x32_bf16 v[14:17], v[240:243], v[212:215], v[14:17]
	v_mfma_f32_16x16x32_bf16 v[18:21], v[228:231], v[216:219], v[18:21]
	v_mfma_f32_16x16x32_bf16 v[22:25], v[232:235], v[216:219], v[22:25]
	v_mfma_f32_16x16x32_bf16 v[26:29], v[236:239], v[216:219], v[26:29]
	v_mfma_f32_16x16x32_bf16 v[30:33], v[240:243], v[216:219], v[30:33]
	v_mfma_f32_16x16x32_bf16 v[34:37], v[228:231], v[220:223], v[34:37]
	v_mfma_f32_16x16x32_bf16 v[38:41], v[232:235], v[220:223], v[38:41]
	v_mfma_f32_16x16x32_bf16 v[42:45], v[236:239], v[220:223], v[42:45]
	v_mfma_f32_16x16x32_bf16 v[46:49], v[240:243], v[220:223], v[46:49]
	v_mfma_f32_16x16x32_bf16 v[50:53], v[228:231], v[224:227], v[50:53]
	v_mfma_f32_16x16x32_bf16 v[54:57], v[232:235], v[224:227], v[54:57]
	v_mfma_f32_16x16x32_bf16 v[58:61], v[236:239], v[224:227], v[58:61]
	v_mfma_f32_16x16x32_bf16 v[62:65], v[240:243], v[224:227], v[62:65]
	s_waitcnt vmcnt(6)
	s_barrier
	v_add_u32_e32 v204, 0x18000, v200
	v_add_u32_e32 v205, 0x18000, v202
	ds_read_b128 v[130:133], v204 offset:0
	ds_read_b128 v[134:137], v204 offset:2048
	ds_read_b128 v[138:141], v204 offset:4096
	ds_read_b128 v[142:145], v204 offset:6144
	ds_read_b128 v[146:149], v205 offset:0
	ds_read_b128 v[150:153], v205 offset:2048
	ds_read_b128 v[154:157], v205 offset:4096
	ds_read_b128 v[158:161], v205 offset:6144
	v_add_u32_e32 v204, 0x18000, v201
	v_add_u32_e32 v205, 0x18000, v203
	ds_read_b128 v[212:215], v204 offset:0
	ds_read_b128 v[216:219], v204 offset:2048
	ds_read_b128 v[220:223], v204 offset:4096
	ds_read_b128 v[224:227], v204 offset:6144
	ds_read_b128 v[228:231], v205 offset:0
	ds_read_b128 v[232:235], v205 offset:2048
	ds_read_b128 v[236:239], v205 offset:4096
	ds_read_b128 v[240:243], v205 offset:6144
	s_add_u32 m0, s76, 0xc000
	s_nop 0
	global_load_lds_dwordx4 v196, s[68:69]
	s_add_u32 m0, s76, 0xe000
	s_nop 0
	global_load_lds_dwordx4 v197, s[68:69]
	s_add_u32 m0, s76, 0x10000
	s_nop 0
	global_load_lds_dwordx4 v198, s[68:69]
	s_add_u32 m0, s76, 0x12000
	s_nop 0
	global_load_lds_dwordx4 v199, s[68:69]
	s_add_u32 m0, s76, 0x14000
	s_nop 0
	global_load_lds_dwordx4 v196, s[70:71]
	s_add_u32 m0, s76, 0x16000
	s_nop 0
	global_load_lds_dwordx4 v197, s[70:71]
	s_add_u32 s68, s68, 0x80
	s_addc_u32 s69, s69, 0
	s_add_u32 s70, s70, 0x80
	s_addc_u32 s71, s71, 0
	s_waitcnt lgkmcnt(0)
	s_barrier
	v_mfma_f32_16x16x32_bf16 v[2:5], v[146:149], v[130:133], v[2:5]
	v_mfma_f32_16x16x32_bf16 v[6:9], v[150:153], v[130:133], v[6:9]
	v_mfma_f32_16x16x32_bf16 v[10:13], v[154:157], v[130:133], v[10:13]
	v_mfma_f32_16x16x32_bf16 v[14:17], v[158:161], v[130:133], v[14:17]
	v_mfma_f32_16x16x32_bf16 v[18:21], v[146:149], v[134:137], v[18:21]
	v_mfma_f32_16x16x32_bf16 v[22:25], v[150:153], v[134:137], v[22:25]
	v_mfma_f32_16x16x32_bf16 v[26:29], v[154:157], v[134:137], v[26:29]
	v_mfma_f32_16x16x32_bf16 v[30:33], v[158:161], v[134:137], v[30:33]
	v_mfma_f32_16x16x32_bf16 v[34:37], v[146:149], v[138:141], v[34:37]
	v_mfma_f32_16x16x32_bf16 v[38:41], v[150:153], v[138:141], v[38:41]
	v_mfma_f32_16x16x32_bf16 v[42:45], v[154:157], v[138:141], v[42:45]
	v_mfma_f32_16x16x32_bf16 v[46:49], v[158:161], v[138:141], v[46:49]
	v_mfma_f32_16x16x32_bf16 v[50:53], v[146:149], v[142:145], v[50:53]
	v_mfma_f32_16x16x32_bf16 v[54:57], v[150:153], v[142:145], v[54:57]
	v_mfma_f32_16x16x32_bf16 v[58:61], v[154:157], v[142:145], v[58:61]
	v_mfma_f32_16x16x32_bf16 v[62:65], v[158:161], v[142:145], v[62:65]
	v_mfma_f32_16x16x32_bf16 v[2:5], v[228:231], v[212:215], v[2:5]
	v_mfma_f32_16x16x32_bf16 v[6:9], v[232:235], v[212:215], v[6:9]
	v_mfma_f32_16x16x32_bf16 v[10:13], v[236:239], v[212:215], v[10:13]
	v_mfma_f32_16x16x32_bf16 v[14:17], v[240:243], v[212:215], v[14:17]
	v_mfma_f32_16x16x32_bf16 v[18:21], v[228:231], v[216:219], v[18:21]
	v_mfma_f32_16x16x32_bf16 v[22:25], v[232:235], v[216:219], v[22:25]
	v_mfma_f32_16x16x32_bf16 v[26:29], v[236:239], v[216:219], v[26:29]
	v_mfma_f32_16x16x32_bf16 v[30:33], v[240:243], v[216:219], v[30:33]
	v_mfma_f32_16x16x32_bf16 v[34:37], v[228:231], v[220:223], v[34:37]
	v_mfma_f32_16x16x32_bf16 v[38:41], v[232:235], v[220:223], v[38:41]
	v_mfma_f32_16x16x32_bf16 v[42:45], v[236:239], v[220:223], v[42:45]
	v_mfma_f32_16x16x32_bf16 v[46:49], v[240:243], v[220:223], v[46:49]
	v_mfma_f32_16x16x32_bf16 v[50:53], v[228:231], v[224:227], v[50:53]
	v_mfma_f32_16x16x32_bf16 v[54:57], v[232:235], v[224:227], v[54:57]
	v_mfma_f32_16x16x32_bf16 v[58:61], v[236:239], v[224:227], v[58:61]
	v_mfma_f32_16x16x32_bf16 v[62:65], v[240:243], v[224:227], v[62:65]
	s_waitcnt vmcnt(6)
	s_barrier
	v_add_u32_e32 v204, 0x0, v200
	v_add_u32_e32 v205, 0x0, v202
	ds_read_b128 v[130:133], v204 offset:0
	ds_read_b128 v[134:137], v204 offset:2048
	ds_read_b128 v[138:141], v204 offset:4096
	ds_read_b128 v[142:145], v204 offset:6144
	ds_read_b128 v[146:149], v205 offset:0
	ds_read_b128 v[150:153], v205 offset:2048
	ds_read_b128 v[154:157], v205 offset:4096
	ds_read_b128 v[158:161], v205 offset:6144
	v_add_u32_e32 v204, 0x0, v201
	v_add_u32_e32 v205, 0x0, v203
	ds_read_b128 v[212:215], v204 offset:0
	ds_read_b128 v[216:219], v204 offset:2048
	ds_read_b128 v[220:223], v204 offset:4096
	ds_read_b128 v[224:227], v204 offset:6144
	ds_read_b128 v[228:231], v205 offset:0
	ds_read_b128 v[232:235], v205 offset:2048
	ds_read_b128 v[236:239], v205 offset:4096
	ds_read_b128 v[240:243], v205 offset:6144
	s_add_u32 m0, s76, 0x18000
	s_nop 0
	global_load_lds_dwordx4 v196, s[68:69]
	s_add_u32 m0, s76, 0x1a000
	s_nop 0
	global_load_lds_dwordx4 v197, s[68:69]
	s_add_u32 m0, s76, 0x1c000
	s_nop 0
	global_load_lds_dwordx4 v198, s[68:69]
	s_add_u32 m0, s76, 0x1e000
	s_nop 0
	global_load_lds_dwordx4 v199, s[68:69]
	s_add_u32 m0, s76, 0x20000
	s_nop 0
	global_load_lds_dwordx4 v196, s[70:71]
	s_add_u32 m0, s76, 0x22000
	s_nop 0
	global_load_lds_dwordx4 v197, s[70:71]
	s_add_u32 s68, s68, 0x80
	s_addc_u32 s69, s69, 0
	s_add_u32 s70, s70, 0x80
	s_addc_u32 s71, s71, 0
	s_waitcnt lgkmcnt(0)
	s_barrier
	v_mfma_f32_16x16x32_bf16 v[2:5], v[146:149], v[130:133], v[2:5]
	v_mfma_f32_16x16x32_bf16 v[6:9], v[150:153], v[130:133], v[6:9]
	v_mfma_f32_16x16x32_bf16 v[10:13], v[154:157], v[130:133], v[10:13]
	v_mfma_f32_16x16x32_bf16 v[14:17], v[158:161], v[130:133], v[14:17]
	v_mfma_f32_16x16x32_bf16 v[18:21], v[146:149], v[134:137], v[18:21]
	v_mfma_f32_16x16x32_bf16 v[22:25], v[150:153], v[134:137], v[22:25]
	v_mfma_f32_16x16x32_bf16 v[26:29], v[154:157], v[134:137], v[26:29]
	v_mfma_f32_16x16x32_bf16 v[30:33], v[158:161], v[134:137], v[30:33]
	v_mfma_f32_16x16x32_bf16 v[34:37], v[146:149], v[138:141], v[34:37]
	v_mfma_f32_16x16x32_bf16 v[38:41], v[150:153], v[138:141], v[38:41]
	v_mfma_f32_16x16x32_bf16 v[42:45], v[154:157], v[138:141], v[42:45]
	v_mfma_f32_16x16x32_bf16 v[46:49], v[158:161], v[138:141], v[46:49]
	v_mfma_f32_16x16x32_bf16 v[50:53], v[146:149], v[142:145], v[50:53]
	v_mfma_f32_16x16x32_bf16 v[54:57], v[150:153], v[142:145], v[54:57]
	v_mfma_f32_16x16x32_bf16 v[58:61], v[154:157], v[142:145], v[58:61]
	v_mfma_f32_16x16x32_bf16 v[62:65], v[158:161], v[142:145], v[62:65]
	v_mfma_f32_16x16x32_bf16 v[2:5], v[228:231], v[212:215], v[2:5]
	v_mfma_f32_16x16x32_bf16 v[6:9], v[232:235], v[212:215], v[6:9]
	v_mfma_f32_16x16x32_bf16 v[10:13], v[236:239], v[212:215], v[10:13]
	v_mfma_f32_16x16x32_bf16 v[14:17], v[240:243], v[212:215], v[14:17]
	v_mfma_f32_16x16x32_bf16 v[18:21], v[228:231], v[216:219], v[18:21]
	v_mfma_f32_16x16x32_bf16 v[22:25], v[232:235], v[216:219], v[22:25]
	v_mfma_f32_16x16x32_bf16 v[26:29], v[236:239], v[216:219], v[26:29]
	v_mfma_f32_16x16x32_bf16 v[30:33], v[240:243], v[216:219], v[30:33]
	v_mfma_f32_16x16x32_bf16 v[34:37], v[228:231], v[220:223], v[34:37]
	v_mfma_f32_16x16x32_bf16 v[38:41], v[232:235], v[220:223], v[38:41]
	v_mfma_f32_16x16x32_bf16 v[42:45], v[236:239], v[220:223], v[42:45]
	v_mfma_f32_16x16x32_bf16 v[46:49], v[240:243], v[220:223], v[46:49]
	v_mfma_f32_16x16x32_bf16 v[50:53], v[228:231], v[224:227], v[50:53]
	v_mfma_f32_16x16x32_bf16 v[54:57], v[232:235], v[224:227], v[54:57]
	v_mfma_f32_16x16x32_bf16 v[58:61], v[236:239], v[224:227], v[58:61]
	v_mfma_f32_16x16x32_bf16 v[62:65], v[240:243], v[224:227], v[62:65]
	s_waitcnt vmcnt(6)
	s_barrier
	v_add_u32_e32 v204, 0xc000, v200
	v_add_u32_e32 v205, 0xc000, v202
	ds_read_b128 v[130:133], v204 offset:0
	ds_read_b128 v[134:137], v204 offset:2048
	ds_read_b128 v[138:141], v204 offset:4096
	ds_read_b128 v[142:145], v204 offset:6144
	ds_read_b128 v[146:149], v205 offset:0
	ds_read_b128 v[150:153], v205 offset:2048
	ds_read_b128 v[154:157], v205 offset:4096
	ds_read_b128 v[158:161], v205 offset:6144
	v_add_u32_e32 v204, 0xc000, v201
	v_add_u32_e32 v205, 0xc000, v203
	ds_read_b128 v[212:215], v204 offset:0
	ds_read_b128 v[216:219], v204 offset:2048
	ds_read_b128 v[220:223], v204 offset:4096
	ds_read_b128 v[224:227], v204 offset:6144
	ds_read_b128 v[228:231], v205 offset:0
	ds_read_b128 v[232:235], v205 offset:2048
	ds_read_b128 v[236:239], v205 offset:4096
	ds_read_b128 v[240:243], v205 offset:6144
	s_add_u32 m0, s76, 0x0
	s_nop 0
	global_load_lds_dwordx4 v196, s[68:69]
	s_add_u32 m0, s76, 0x2000
	s_nop 0
	global_load_lds_dwordx4 v197, s[68:69]
	s_add_u32 m0, s76, 0x4000
	s_nop 0
	global_load_lds_dwordx4 v198, s[68:69]
	s_add_u32 m0, s76, 0x6000
	s_nop 0
	global_load_lds_dwordx4 v199, s[68:69]
	s_add_u32 m0, s76, 0x8000
	s_nop 0
	global_load_lds_dwordx4 v196, s[70:71]
	s_add_u32 m0, s76, 0xa000
	s_nop 0
	global_load_lds_dwordx4 v197, s[70:71]
	s_add_u32 s68, s68, 0x80
	s_addc_u32 s69, s69, 0
	s_add_u32 s70, s70, 0x80
	s_addc_u32 s71, s71, 0
	s_waitcnt lgkmcnt(0)
	s_barrier
	v_mfma_f32_16x16x32_bf16 v[2:5], v[146:149], v[130:133], v[2:5]
	v_mfma_f32_16x16x32_bf16 v[6:9], v[150:153], v[130:133], v[6:9]
	v_mfma_f32_16x16x32_bf16 v[10:13], v[154:157], v[130:133], v[10:13]
	v_mfma_f32_16x16x32_bf16 v[14:17], v[158:161], v[130:133], v[14:17]
	v_mfma_f32_16x16x32_bf16 v[18:21], v[146:149], v[134:137], v[18:21]
	v_mfma_f32_16x16x32_bf16 v[22:25], v[150:153], v[134:137], v[22:25]
	v_mfma_f32_16x16x32_bf16 v[26:29], v[154:157], v[134:137], v[26:29]
	v_mfma_f32_16x16x32_bf16 v[30:33], v[158:161], v[134:137], v[30:33]
	v_mfma_f32_16x16x32_bf16 v[34:37], v[146:149], v[138:141], v[34:37]
	v_mfma_f32_16x16x32_bf16 v[38:41], v[150:153], v[138:141], v[38:41]
	v_mfma_f32_16x16x32_bf16 v[42:45], v[154:157], v[138:141], v[42:45]
	v_mfma_f32_16x16x32_bf16 v[46:49], v[158:161], v[138:141], v[46:49]
	v_mfma_f32_16x16x32_bf16 v[50:53], v[146:149], v[142:145], v[50:53]
	v_mfma_f32_16x16x32_bf16 v[54:57], v[150:153], v[142:145], v[54:57]
	v_mfma_f32_16x16x32_bf16 v[58:61], v[154:157], v[142:145], v[58:61]
	v_mfma_f32_16x16x32_bf16 v[62:65], v[158:161], v[142:145], v[62:65]
	v_mfma_f32_16x16x32_bf16 v[2:5], v[228:231], v[212:215], v[2:5]
	v_mfma_f32_16x16x32_bf16 v[6:9], v[232:235], v[212:215], v[6:9]
	v_mfma_f32_16x16x32_bf16 v[10:13], v[236:239], v[212:215], v[10:13]
	v_mfma_f32_16x16x32_bf16 v[14:17], v[240:243], v[212:215], v[14:17]
	v_mfma_f32_16x16x32_bf16 v[18:21], v[228:231], v[216:219], v[18:21]
	v_mfma_f32_16x16x32_bf16 v[22:25], v[232:235], v[216:219], v[22:25]
	v_mfma_f32_16x16x32_bf16 v[26:29], v[236:239], v[216:219], v[26:29]
	v_mfma_f32_16x16x32_bf16 v[30:33], v[240:243], v[216:219], v[30:33]
	v_mfma_f32_16x16x32_bf16 v[34:37], v[228:231], v[220:223], v[34:37]
	v_mfma_f32_16x16x32_bf16 v[38:41], v[232:235], v[220:223], v[38:41]
	v_mfma_f32_16x16x32_bf16 v[42:45], v[236:239], v[220:223], v[42:45]
	v_mfma_f32_16x16x32_bf16 v[46:49], v[240:243], v[220:223], v[46:49]
	v_mfma_f32_16x16x32_bf16 v[50:53], v[228:231], v[224:227], v[50:53]
	v_mfma_f32_16x16x32_bf16 v[54:57], v[232:235], v[224:227], v[54:57]
	v_mfma_f32_16x16x32_bf16 v[58:61], v[236:239], v[224:227], v[58:61]
	v_mfma_f32_16x16x32_bf16 v[62:65], v[240:243], v[224:227], v[62:65]
	s_nop 7
	v_lshlrev_b32_e32 v212, 16, v174
	v_and_b32_e32 v213, 0xffff0000, v174
	v_lshlrev_b32_e32 v214, 16, v175
	v_and_b32_e32 v215, 0xffff0000, v175
	v_pk_fma_f32 v[66:67], v[2:3], v[212:213], v[66:67]
	v_pk_fma_f32 v[68:69], v[4:5], v[214:215], v[68:69]
	v_lshlrev_b32_e32 v216, 16, v176
	v_and_b32_e32 v217, 0xffff0000, v176
	v_lshlrev_b32_e32 v218, 16, v177
	v_and_b32_e32 v219, 0xffff0000, v177
	v_pk_fma_f32 v[70:71], v[6:7], v[216:217], v[70:71]
	v_pk_fma_f32 v[72:73], v[8:9], v[218:219], v[72:73]
	v_lshlrev_b32_e32 v220, 16, v178
	v_and_b32_e32 v221, 0xffff0000, v178
	v_lshlrev_b32_e32 v222, 16, v179
	v_and_b32_e32 v223, 0xffff0000, v179
	v_pk_fma_f32 v[74:75], v[10:11], v[220:221], v[74:75]
	v_pk_fma_f32 v[76:77], v[12:13], v[222:223], v[76:77]
	v_lshlrev_b32_e32 v224, 16, v180
	v_and_b32_e32 v225, 0xffff0000, v180
	v_lshlrev_b32_e32 v226, 16, v181
	v_and_b32_e32 v227, 0xffff0000, v181
	v_pk_fma_f32 v[78:79], v[14:15], v[224:225], v[78:79]
	v_pk_fma_f32 v[80:81], v[16:17], v[226:227], v[80:81]
	v_lshlrev_b32_e32 v228, 16, v182
	v_and_b32_e32 v229, 0xffff0000, v182
	v_lshlrev_b32_e32 v230, 16, v183
	v_and_b32_e32 v231, 0xffff0000, v183
	v_pk_fma_f32 v[82:83], v[18:19], v[228:229], v[82:83]
	v_pk_fma_f32 v[84:85], v[20:21], v[230:231], v[84:85]
	v_lshlrev_b32_e32 v232, 16, v184
	v_and_b32_e32 v233, 0xffff0000, v184
	v_lshlrev_b32_e32 v234, 16, v185
	v_and_b32_e32 v235, 0xffff0000, v185
	v_pk_fma_f32 v[86:87], v[22:23], v[232:233], v[86:87]
	v_pk_fma_f32 v[88:89], v[24:25], v[234:235], v[88:89]
	v_lshlrev_b32_e32 v236, 16, v186
	v_and_b32_e32 v237, 0xffff0000, v186
	v_lshlrev_b32_e32 v238, 16, v187
	v_and_b32_e32 v239, 0xffff0000, v187
	v_pk_fma_f32 v[90:91], v[26:27], v[236:237], v[90:91]
	v_pk_fma_f32 v[92:93], v[28:29], v[238:239], v[92:93]
	v_lshlrev_b32_e32 v240, 16, v188
	v_and_b32_e32 v241, 0xffff0000, v188
	v_lshlrev_b32_e32 v242, 16, v189
	v_and_b32_e32 v243, 0xffff0000, v189
	v_pk_fma_f32 v[94:95], v[30:31], v[240:241], v[94:95]
	v_pk_fma_f32 v[96:97], v[32:33], v[242:243], v[96:97]
	v_lshlrev_b32_e32 v212, 16, v190
	v_and_b32_e32 v213, 0xffff0000, v190
	v_lshlrev_b32_e32 v214, 16, v191
	v_and_b32_e32 v215, 0xffff0000, v191
	v_pk_fma_f32 v[98:99], v[34:35], v[212:213], v[98:99]
	v_pk_fma_f32 v[100:101], v[36:37], v[214:215], v[100:101]
	v_lshlrev_b32_e32 v216, 16, v192
	v_and_b32_e32 v217, 0xffff0000, v192
	v_lshlrev_b32_e32 v218, 16, v193
	v_and_b32_e32 v219, 0xffff0000, v193
	v_pk_fma_f32 v[102:103], v[38:39], v[216:217], v[102:103]
	v_pk_fma_f32 v[104:105], v[40:41], v[218:219], v[104:105]
	v_lshlrev_b32_e32 v220, 16, v244
	v_and_b32_e32 v221, 0xffff0000, v244
	v_lshlrev_b32_e32 v222, 16, v245
	v_and_b32_e32 v223, 0xffff0000, v245
	v_pk_fma_f32 v[106:107], v[42:43], v[220:221], v[106:107]
	v_pk_fma_f32 v[108:109], v[44:45], v[222:223], v[108:109]
	v_lshlrev_b32_e32 v224, 16, v246
	v_and_b32_e32 v225, 0xffff0000, v246
	v_lshlrev_b32_e32 v226, 16, v247
	v_and_b32_e32 v227, 0xffff0000, v247
	v_pk_fma_f32 v[110:111], v[46:47], v[224:225], v[110:111]
	v_pk_fma_f32 v[112:113], v[48:49], v[226:227], v[112:113]
	v_lshlrev_b32_e32 v228, 16, v248
	v_and_b32_e32 v229, 0xffff0000, v248
	v_lshlrev_b32_e32 v230, 16, v249
	v_and_b32_e32 v231, 0xffff0000, v249
	v_pk_fma_f32 v[114:115], v[50:51], v[228:229], v[114:115]
	v_pk_fma_f32 v[116:117], v[52:53], v[230:231], v[116:117]
	v_lshlrev_b32_e32 v232, 16, v250
	v_and_b32_e32 v233, 0xffff0000, v250
	v_lshlrev_b32_e32 v234, 16, v251
	v_and_b32_e32 v235, 0xffff0000, v251
	v_pk_fma_f32 v[118:119], v[54:55], v[232:233], v[118:119]
	v_pk_fma_f32 v[120:121], v[56:57], v[234:235], v[120:121]
	v_lshlrev_b32_e32 v236, 16, v166
	v_and_b32_e32 v237, 0xffff0000, v166
	v_lshlrev_b32_e32 v238, 16, v167
	v_and_b32_e32 v239, 0xffff0000, v167
	v_pk_fma_f32 v[122:123], v[58:59], v[236:237], v[122:123]
	v_pk_fma_f32 v[124:125], v[60:61], v[238:239], v[124:125]
	v_lshlrev_b32_e32 v240, 16, v194
	v_and_b32_e32 v241, 0xffff0000, v194
	v_lshlrev_b32_e32 v242, 16, v195
	v_and_b32_e32 v243, 0xffff0000, v195
	v_pk_fma_f32 v[126:127], v[62:63], v[240:241], v[126:127]
	v_pk_fma_f32 v[128:129], v[64:65], v[242:243], v[128:129]
	s_waitcnt vmcnt(6)
	s_barrier
	v_add_u32_e32 v204, 0x18000, v200
	v_add_u32_e32 v205, 0x18000, v202
	ds_read_b128 v[130:133], v204 offset:0
	ds_read_b128 v[134:137], v204 offset:2048
	ds_read_b128 v[138:141], v204 offset:4096
	ds_read_b128 v[142:145], v204 offset:6144
	ds_read_b128 v[146:149], v205 offset:0
	ds_read_b128 v[150:153], v205 offset:2048
	ds_read_b128 v[154:157], v205 offset:4096
	ds_read_b128 v[158:161], v205 offset:6144
	v_add_u32_e32 v204, 0x18000, v201
	v_add_u32_e32 v205, 0x18000, v203
	ds_read_b128 v[212:215], v204 offset:0
	ds_read_b128 v[216:219], v204 offset:2048
	ds_read_b128 v[220:223], v204 offset:4096
	ds_read_b128 v[224:227], v204 offset:6144
	ds_read_b128 v[228:231], v205 offset:0
	ds_read_b128 v[232:235], v205 offset:2048
	ds_read_b128 v[236:239], v205 offset:4096
	ds_read_b128 v[240:243], v205 offset:6144
	s_add_u32 m0, s76, 0xc000
	s_nop 0
	global_load_lds_dwordx4 v196, s[68:69]
	s_add_u32 m0, s76, 0xe000
	s_nop 0
	global_load_lds_dwordx4 v197, s[68:69]
	s_add_u32 m0, s76, 0x10000
	s_nop 0
	global_load_lds_dwordx4 v198, s[68:69]
	s_add_u32 m0, s76, 0x12000
	s_nop 0
	global_load_lds_dwordx4 v199, s[68:69]
	s_add_u32 m0, s76, 0x14000
	s_nop 0
	global_load_lds_dwordx4 v196, s[70:71]
	s_add_u32 m0, s76, 0x16000
	s_nop 0
	global_load_lds_dwordx4 v197, s[70:71]
	s_add_u32 s68, s68, 0x80
	s_addc_u32 s69, s69, 0
	s_add_u32 s70, s70, 0x80
	s_addc_u32 s71, s71, 0
	global_load_dwordx2 v[174:175], v206, s[72:73] offset:0
	global_load_dwordx2 v[176:177], v206, s[72:73] offset:32
	global_load_dwordx2 v[178:179], v206, s[72:73] offset:64
	global_load_dwordx2 v[180:181], v206, s[72:73] offset:96
	global_load_dwordx2 v[182:183], v207, s[72:73] offset:0
	global_load_dwordx2 v[184:185], v207, s[72:73] offset:32
	s_waitcnt lgkmcnt(0)
	s_barrier
	v_mfma_f32_16x16x32_bf16 v[2:5], v[146:149], v[130:133], 0
	v_mfma_f32_16x16x32_bf16 v[6:9], v[150:153], v[130:133], 0
	v_mfma_f32_16x16x32_bf16 v[10:13], v[154:157], v[130:133], 0
	v_mfma_f32_16x16x32_bf16 v[14:17], v[158:161], v[130:133], 0
	v_mfma_f32_16x16x32_bf16 v[18:21], v[146:149], v[134:137], 0
	v_mfma_f32_16x16x32_bf16 v[22:25], v[150:153], v[134:137], 0
	v_mfma_f32_16x16x32_bf16 v[26:29], v[154:157], v[134:137], 0
	v_mfma_f32_16x16x32_bf16 v[30:33], v[158:161], v[134:137], 0
	v_mfma_f32_16x16x32_bf16 v[34:37], v[146:149], v[138:141], 0
	v_mfma_f32_16x16x32_bf16 v[38:41], v[150:153], v[138:141], 0
	v_mfma_f32_16x16x32_bf16 v[42:45], v[154:157], v[138:141], 0
	v_mfma_f32_16x16x32_bf16 v[46:49], v[158:161], v[138:141], 0
	v_mfma_f32_16x16x32_bf16 v[50:53], v[146:149], v[142:145], 0
	v_mfma_f32_16x16x32_bf16 v[54:57], v[150:153], v[142:145], 0
	v_mfma_f32_16x16x32_bf16 v[58:61], v[154:157], v[142:145], 0
	v_mfma_f32_16x16x32_bf16 v[62:65], v[158:161], v[142:145], 0
	v_mfma_f32_16x16x32_bf16 v[2:5], v[228:231], v[212:215], v[2:5]
	v_mfma_f32_16x16x32_bf16 v[6:9], v[232:235], v[212:215], v[6:9]
	v_mfma_f32_16x16x32_bf16 v[10:13], v[236:239], v[212:215], v[10:13]
	v_mfma_f32_16x16x32_bf16 v[14:17], v[240:243], v[212:215], v[14:17]
	v_mfma_f32_16x16x32_bf16 v[18:21], v[228:231], v[216:219], v[18:21]
	v_mfma_f32_16x16x32_bf16 v[22:25], v[232:235], v[216:219], v[22:25]
	v_mfma_f32_16x16x32_bf16 v[26:29], v[236:239], v[216:219], v[26:29]
	v_mfma_f32_16x16x32_bf16 v[30:33], v[240:243], v[216:219], v[30:33]
	v_mfma_f32_16x16x32_bf16 v[34:37], v[228:231], v[220:223], v[34:37]
	v_mfma_f32_16x16x32_bf16 v[38:41], v[232:235], v[220:223], v[38:41]
	v_mfma_f32_16x16x32_bf16 v[42:45], v[236:239], v[220:223], v[42:45]
	v_mfma_f32_16x16x32_bf16 v[46:49], v[240:243], v[220:223], v[46:49]
	v_mfma_f32_16x16x32_bf16 v[50:53], v[228:231], v[224:227], v[50:53]
	v_mfma_f32_16x16x32_bf16 v[54:57], v[232:235], v[224:227], v[54:57]
	v_mfma_f32_16x16x32_bf16 v[58:61], v[236:239], v[224:227], v[58:61]
	v_mfma_f32_16x16x32_bf16 v[62:65], v[240:243], v[224:227], v[62:65]
	s_waitcnt vmcnt(12)
	s_barrier
	v_add_u32_e32 v204, 0x0, v200
	v_add_u32_e32 v205, 0x0, v202
	ds_read_b128 v[130:133], v204 offset:0
	ds_read_b128 v[134:137], v204 offset:2048
	ds_read_b128 v[138:141], v204 offset:4096
	ds_read_b128 v[142:145], v204 offset:6144
	ds_read_b128 v[146:149], v205 offset:0
	ds_read_b128 v[150:153], v205 offset:2048
	ds_read_b128 v[154:157], v205 offset:4096
	ds_read_b128 v[158:161], v205 offset:6144
	v_add_u32_e32 v204, 0x0, v201
	v_add_u32_e32 v205, 0x0, v203
	ds_read_b128 v[212:215], v204 offset:0
	ds_read_b128 v[216:219], v204 offset:2048
	ds_read_b128 v[220:223], v204 offset:4096
	ds_read_b128 v[224:227], v204 offset:6144
	ds_read_b128 v[228:231], v205 offset:0
	ds_read_b128 v[232:235], v205 offset:2048
	ds_read_b128 v[236:239], v205 offset:4096
	ds_read_b128 v[240:243], v205 offset:6144
	s_add_u32 m0, s76, 0x18000
	s_nop 0
	global_load_lds_dwordx4 v196, s[68:69]
	s_add_u32 m0, s76, 0x1a000
	s_nop 0
	global_load_lds_dwordx4 v197, s[68:69]
	s_add_u32 m0, s76, 0x1c000
	s_nop 0
	global_load_lds_dwordx4 v198, s[68:69]
	s_add_u32 m0, s76, 0x1e000
	s_nop 0
	global_load_lds_dwordx4 v199, s[68:69]
	s_add_u32 m0, s76, 0x20000
	s_nop 0
	global_load_lds_dwordx4 v196, s[70:71]
	s_add_u32 m0, s76, 0x22000
	s_nop 0
	global_load_lds_dwordx4 v197, s[70:71]
	s_add_u32 s68, s68, 0x80
	s_addc_u32 s69, s69, 0
	s_add_u32 s70, s70, 0x80
	s_addc_u32 s71, s71, 0
	global_load_dwordx2 v[186:187], v207, s[72:73] offset:64
	global_load_dwordx2 v[188:189], v207, s[72:73] offset:96
	global_load_dwordx2 v[190:191], v208, s[72:73] offset:0
	global_load_dwordx2 v[192:193], v208, s[72:73] offset:32
	global_load_dwordx2 v[244:245], v208, s[72:73] offset:64
	global_load_dwordx2 v[246:247], v208, s[72:73] offset:96
	s_waitcnt lgkmcnt(0)
	s_barrier
	v_mfma_f32_16x16x32_bf16 v[2:5], v[146:149], v[130:133], v[2:5]
	v_mfma_f32_16x16x32_bf16 v[6:9], v[150:153], v[130:133], v[6:9]
	v_mfma_f32_16x16x32_bf16 v[10:13], v[154:157], v[130:133], v[10:13]
	v_mfma_f32_16x16x32_bf16 v[14:17], v[158:161], v[130:133], v[14:17]
	v_mfma_f32_16x16x32_bf16 v[18:21], v[146:149], v[134:137], v[18:21]
	v_mfma_f32_16x16x32_bf16 v[22:25], v[150:153], v[134:137], v[22:25]
	v_mfma_f32_16x16x32_bf16 v[26:29], v[154:157], v[134:137], v[26:29]
	v_mfma_f32_16x16x32_bf16 v[30:33], v[158:161], v[134:137], v[30:33]
	v_mfma_f32_16x16x32_bf16 v[34:37], v[146:149], v[138:141], v[34:37]
	v_mfma_f32_16x16x32_bf16 v[38:41], v[150:153], v[138:141], v[38:41]
	v_mfma_f32_16x16x32_bf16 v[42:45], v[154:157], v[138:141], v[42:45]
	v_mfma_f32_16x16x32_bf16 v[46:49], v[158:161], v[138:141], v[46:49]
	v_mfma_f32_16x16x32_bf16 v[50:53], v[146:149], v[142:145], v[50:53]
	v_mfma_f32_16x16x32_bf16 v[54:57], v[150:153], v[142:145], v[54:57]
	v_mfma_f32_16x16x32_bf16 v[58:61], v[154:157], v[142:145], v[58:61]
	v_mfma_f32_16x16x32_bf16 v[62:65], v[158:161], v[142:145], v[62:65]
	v_mfma_f32_16x16x32_bf16 v[2:5], v[228:231], v[212:215], v[2:5]
	v_mfma_f32_16x16x32_bf16 v[6:9], v[232:235], v[212:215], v[6:9]
	v_mfma_f32_16x16x32_bf16 v[10:13], v[236:239], v[212:215], v[10:13]
	v_mfma_f32_16x16x32_bf16 v[14:17], v[240:243], v[212:215], v[14:17]
	v_mfma_f32_16x16x32_bf16 v[18:21], v[228:231], v[216:219], v[18:21]
	v_mfma_f32_16x16x32_bf16 v[22:25], v[232:235], v[216:219], v[22:25]
	v_mfma_f32_16x16x32_bf16 v[26:29], v[236:239], v[216:219], v[26:29]
	v_mfma_f32_16x16x32_bf16 v[30:33], v[240:243], v[216:219], v[30:33]
	v_mfma_f32_16x16x32_bf16 v[34:37], v[228:231], v[220:223], v[34:37]
	v_mfma_f32_16x16x32_bf16 v[38:41], v[232:235], v[220:223], v[38:41]
	v_mfma_f32_16x16x32_bf16 v[42:45], v[236:239], v[220:223], v[42:45]
	v_mfma_f32_16x16x32_bf16 v[46:49], v[240:243], v[220:223], v[46:49]
	v_mfma_f32_16x16x32_bf16 v[50:53], v[228:231], v[224:227], v[50:53]
	v_mfma_f32_16x16x32_bf16 v[54:57], v[232:235], v[224:227], v[54:57]
	v_mfma_f32_16x16x32_bf16 v[58:61], v[236:239], v[224:227], v[58:61]
	v_mfma_f32_16x16x32_bf16 v[62:65], v[240:243], v[224:227], v[62:65]
	s_waitcnt vmcnt(18)
	s_barrier
	v_add_u32_e32 v204, 0xc000, v200
	v_add_u32_e32 v205, 0xc000, v202
	ds_read_b128 v[130:133], v204 offset:0
	ds_read_b128 v[134:137], v204 offset:2048
	ds_read_b128 v[138:141], v204 offset:4096
	ds_read_b128 v[142:145], v204 offset:6144
	ds_read_b128 v[146:149], v205 offset:0
	ds_read_b128 v[150:153], v205 offset:2048
	ds_read_b128 v[154:157], v205 offset:4096
	ds_read_b128 v[158:161], v205 offset:6144
	v_add_u32_e32 v204, 0xc000, v201
	v_add_u32_e32 v205, 0xc000, v203
	ds_read_b128 v[212:215], v204 offset:0
	ds_read_b128 v[216:219], v204 offset:2048
	ds_read_b128 v[220:223], v204 offset:4096
	ds_read_b128 v[224:227], v204 offset:6144
	ds_read_b128 v[228:231], v205 offset:0
	ds_read_b128 v[232:235], v205 offset:2048
	ds_read_b128 v[236:239], v205 offset:4096
	ds_read_b128 v[240:243], v205 offset:6144
	s_add_u32 m0, s76, 0x0
	s_nop 0
	global_load_lds_dwordx4 v196, s[68:69]
	s_add_u32 m0, s76, 0x2000
	s_nop 0
	global_load_lds_dwordx4 v197, s[68:69]
	s_add_u32 m0, s76, 0x4000
	s_nop 0
	global_load_lds_dwordx4 v198, s[68:69]
	s_add_u32 m0, s76, 0x6000
	s_nop 0
	global_load_lds_dwordx4 v199, s[68:69]
	s_add_u32 m0, s76, 0x8000
	s_nop 0
	global_load_lds_dwordx4 v196, s[70:71]
	s_add_u32 m0, s76, 0xa000
	s_nop 0
	global_load_lds_dwordx4 v197, s[70:71]
	s_add_u32 s68, s68, 0x80
	s_addc_u32 s69, s69, 0
	s_add_u32 s70, s70, 0x80
	s_addc_u32 s71, s71, 0
	global_load_dwordx2 v[248:249], v209, s[72:73] offset:0
	global_load_dwordx2 v[250:251], v209, s[72:73] offset:32
	global_load_dwordx2 v[166:167], v209, s[72:73] offset:64
	global_load_dwordx2 v[194:195], v209, s[72:73] offset:96
	s_add_u32 s72, s72, 0x800
	s_addc_u32 s73, s73, 0
	s_waitcnt lgkmcnt(0)
	s_barrier
	v_mfma_f32_16x16x32_bf16 v[2:5], v[146:149], v[130:133], v[2:5]
	v_mfma_f32_16x16x32_bf16 v[6:9], v[150:153], v[130:133], v[6:9]
	v_mfma_f32_16x16x32_bf16 v[10:13], v[154:157], v[130:133], v[10:13]
	v_mfma_f32_16x16x32_bf16 v[14:17], v[158:161], v[130:133], v[14:17]
	v_mfma_f32_16x16x32_bf16 v[18:21], v[146:149], v[134:137], v[18:21]
	v_mfma_f32_16x16x32_bf16 v[22:25], v[150:153], v[134:137], v[22:25]
	v_mfma_f32_16x16x32_bf16 v[26:29], v[154:157], v[134:137], v[26:29]
	v_mfma_f32_16x16x32_bf16 v[30:33], v[158:161], v[134:137], v[30:33]
	v_mfma_f32_16x16x32_bf16 v[34:37], v[146:149], v[138:141], v[34:37]
	v_mfma_f32_16x16x32_bf16 v[38:41], v[150:153], v[138:141], v[38:41]
	v_mfma_f32_16x16x32_bf16 v[42:45], v[154:157], v[138:141], v[42:45]
	v_mfma_f32_16x16x32_bf16 v[46:49], v[158:161], v[138:141], v[46:49]
	v_mfma_f32_16x16x32_bf16 v[50:53], v[146:149], v[142:145], v[50:53]
	v_mfma_f32_16x16x32_bf16 v[54:57], v[150:153], v[142:145], v[54:57]
	v_mfma_f32_16x16x32_bf16 v[58:61], v[154:157], v[142:145], v[58:61]
	v_mfma_f32_16x16x32_bf16 v[62:65], v[158:161], v[142:145], v[62:65]
	v_mfma_f32_16x16x32_bf16 v[2:5], v[228:231], v[212:215], v[2:5]
	v_mfma_f32_16x16x32_bf16 v[6:9], v[232:235], v[212:215], v[6:9]
	v_mfma_f32_16x16x32_bf16 v[10:13], v[236:239], v[212:215], v[10:13]
	v_mfma_f32_16x16x32_bf16 v[14:17], v[240:243], v[212:215], v[14:17]
	v_mfma_f32_16x16x32_bf16 v[18:21], v[228:231], v[216:219], v[18:21]
	v_mfma_f32_16x16x32_bf16 v[22:25], v[232:235], v[216:219], v[22:25]
	v_mfma_f32_16x16x32_bf16 v[26:29], v[236:239], v[216:219], v[26:29]
	v_mfma_f32_16x16x32_bf16 v[30:33], v[240:243], v[216:219], v[30:33]
	v_mfma_f32_16x16x32_bf16 v[34:37], v[228:231], v[220:223], v[34:37]
	v_mfma_f32_16x16x32_bf16 v[38:41], v[232:235], v[220:223], v[38:41]
	v_mfma_f32_16x16x32_bf16 v[42:45], v[236:239], v[220:223], v[42:45]
	v_mfma_f32_16x16x32_bf16 v[46:49], v[240:243], v[220:223], v[46:49]
	v_mfma_f32_16x16x32_bf16 v[50:53], v[228:231], v[224:227], v[50:53]
	v_mfma_f32_16x16x32_bf16 v[54:57], v[232:235], v[224:227], v[54:57]
	v_mfma_f32_16x16x32_bf16 v[58:61], v[236:239], v[224:227], v[58:61]
	v_mfma_f32_16x16x32_bf16 v[62:65], v[240:243], v[224:227], v[62:65]
	s_waitcnt vmcnt(16)
	s_barrier
	v_add_u32_e32 v204, 0x18000, v200
	v_add_u32_e32 v205, 0x18000, v202
	ds_read_b128 v[130:133], v204 offset:0
	ds_read_b128 v[134:137], v204 offset:2048
	ds_read_b128 v[138:141], v204 offset:4096
	ds_read_b128 v[142:145], v204 offset:6144
	ds_read_b128 v[146:149], v205 offset:0
	ds_read_b128 v[150:153], v205 offset:2048
	ds_read_b128 v[154:157], v205 offset:4096
	ds_read_b128 v[158:161], v205 offset:6144
	v_add_u32_e32 v204, 0x18000, v201
	v_add_u32_e32 v205, 0x18000, v203
	ds_read_b128 v[212:215], v204 offset:0
	ds_read_b128 v[216:219], v204 offset:2048
	ds_read_b128 v[220:223], v204 offset:4096
	ds_read_b128 v[224:227], v204 offset:6144
	ds_read_b128 v[228:231], v205 offset:0
	ds_read_b128 v[232:235], v205 offset:2048
	ds_read_b128 v[236:239], v205 offset:4096
	ds_read_b128 v[240:243], v205 offset:6144
	s_add_u32 m0, s76, 0xc000
	s_nop 0
	global_load_lds_dwordx4 v196, s[68:69]
	s_add_u32 m0, s76, 0xe000
	s_nop 0
	global_load_lds_dwordx4 v197, s[68:69]
	s_add_u32 m0, s76, 0x10000
	s_nop 0
	global_load_lds_dwordx4 v198, s[68:69]
	s_add_u32 m0, s76, 0x12000
	s_nop 0
	global_load_lds_dwordx4 v199, s[68:69]
	s_add_u32 m0, s76, 0x14000
	s_nop 0
	global_load_lds_dwordx4 v196, s[70:71]
	s_add_u32 m0, s76, 0x16000
	s_nop 0
	global_load_lds_dwordx4 v197, s[70:71]
	s_add_u32 s68, s68, 0x80
	s_addc_u32 s69, s69, 0
	s_add_u32 s70, s70, 0x80
	s_addc_u32 s71, s71, 0
	s_waitcnt lgkmcnt(0)
	s_barrier
	v_mfma_f32_16x16x32_bf16 v[2:5], v[146:149], v[130:133], v[2:5]
	v_mfma_f32_16x16x32_bf16 v[6:9], v[150:153], v[130:133], v[6:9]
	v_mfma_f32_16x16x32_bf16 v[10:13], v[154:157], v[130:133], v[10:13]
	v_mfma_f32_16x16x32_bf16 v[14:17], v[158:161], v[130:133], v[14:17]
	v_mfma_f32_16x16x32_bf16 v[18:21], v[146:149], v[134:137], v[18:21]
	v_mfma_f32_16x16x32_bf16 v[22:25], v[150:153], v[134:137], v[22:25]
	v_mfma_f32_16x16x32_bf16 v[26:29], v[154:157], v[134:137], v[26:29]
	v_mfma_f32_16x16x32_bf16 v[30:33], v[158:161], v[134:137], v[30:33]
	v_mfma_f32_16x16x32_bf16 v[34:37], v[146:149], v[138:141], v[34:37]
	v_mfma_f32_16x16x32_bf16 v[38:41], v[150:153], v[138:141], v[38:41]
	v_mfma_f32_16x16x32_bf16 v[42:45], v[154:157], v[138:141], v[42:45]
	v_mfma_f32_16x16x32_bf16 v[46:49], v[158:161], v[138:141], v[46:49]
	v_mfma_f32_16x16x32_bf16 v[50:53], v[146:149], v[142:145], v[50:53]
	v_mfma_f32_16x16x32_bf16 v[54:57], v[150:153], v[142:145], v[54:57]
	v_mfma_f32_16x16x32_bf16 v[58:61], v[154:157], v[142:145], v[58:61]
	v_mfma_f32_16x16x32_bf16 v[62:65], v[158:161], v[142:145], v[62:65]
	v_mfma_f32_16x16x32_bf16 v[2:5], v[228:231], v[212:215], v[2:5]
	v_mfma_f32_16x16x32_bf16 v[6:9], v[232:235], v[212:215], v[6:9]
	v_mfma_f32_16x16x32_bf16 v[10:13], v[236:239], v[212:215], v[10:13]
	v_mfma_f32_16x16x32_bf16 v[14:17], v[240:243], v[212:215], v[14:17]
	v_mfma_f32_16x16x32_bf16 v[18:21], v[228:231], v[216:219], v[18:21]
	v_mfma_f32_16x16x32_bf16 v[22:25], v[232:235], v[216:219], v[22:25]
	v_mfma_f32_16x16x32_bf16 v[26:29], v[236:239], v[216:219], v[26:29]
	v_mfma_f32_16x16x32_bf16 v[30:33], v[240:243], v[216:219], v[30:33]
	v_mfma_f32_16x16x32_bf16 v[34:37], v[228:231], v[220:223], v[34:37]
	v_mfma_f32_16x16x32_bf16 v[38:41], v[232:235], v[220:223], v[38:41]
	v_mfma_f32_16x16x32_bf16 v[42:45], v[236:239], v[220:223], v[42:45]
	v_mfma_f32_16x16x32_bf16 v[46:49], v[240:243], v[220:223], v[46:49]
	v_mfma_f32_16x16x32_bf16 v[50:53], v[228:231], v[224:227], v[50:53]
	v_mfma_f32_16x16x32_bf16 v[54:57], v[232:235], v[224:227], v[54:57]
	v_mfma_f32_16x16x32_bf16 v[58:61], v[236:239], v[224:227], v[58:61]
	v_mfma_f32_16x16x32_bf16 v[62:65], v[240:243], v[224:227], v[62:65]
	s_waitcnt vmcnt(10)
	s_barrier
	v_add_u32_e32 v204, 0x0, v200
	v_add_u32_e32 v205, 0x0, v202
	ds_read_b128 v[130:133], v204 offset:0
	ds_read_b128 v[134:137], v204 offset:2048
	ds_read_b128 v[138:141], v204 offset:4096
	ds_read_b128 v[142:145], v204 offset:6144
	ds_read_b128 v[146:149], v205 offset:0
	ds_read_b128 v[150:153], v205 offset:2048
	ds_read_b128 v[154:157], v205 offset:4096
	ds_read_b128 v[158:161], v205 offset:6144
	v_add_u32_e32 v204, 0x0, v201
	v_add_u32_e32 v205, 0x0, v203
	ds_read_b128 v[212:215], v204 offset:0
	ds_read_b128 v[216:219], v204 offset:2048
	ds_read_b128 v[220:223], v204 offset:4096
	ds_read_b128 v[224:227], v204 offset:6144
	ds_read_b128 v[228:231], v205 offset:0
	ds_read_b128 v[232:235], v205 offset:2048
	ds_read_b128 v[236:239], v205 offset:4096
	ds_read_b128 v[240:243], v205 offset:6144
	s_add_u32 m0, s76, 0x18000
	s_nop 0
	global_load_lds_dwordx4 v196, s[68:69]
	s_add_u32 m0, s76, 0x1a000
	s_nop 0
	global_load_lds_dwordx4 v197, s[68:69]
	s_add_u32 m0, s76, 0x1c000
	s_nop 0
	global_load_lds_dwordx4 v198, s[68:69]
	s_add_u32 m0, s76, 0x1e000
	s_nop 0
	global_load_lds_dwordx4 v199, s[68:69]
	s_add_u32 m0, s76, 0x20000
	s_nop 0
	global_load_lds_dwordx4 v196, s[70:71]
	s_add_u32 m0, s76, 0x22000
	s_nop 0
	global_load_lds_dwordx4 v197, s[70:71]
	s_add_u32 s68, s68, 0x80
	s_addc_u32 s69, s69, 0
	s_add_u32 s70, s70, 0x80
	s_addc_u32 s71, s71, 0
	s_waitcnt lgkmcnt(0)
	s_barrier
	v_mfma_f32_16x16x32_bf16 v[2:5], v[146:149], v[130:133], v[2:5]
	v_mfma_f32_16x16x32_bf16 v[6:9], v[150:153], v[130:133], v[6:9]
	v_mfma_f32_16x16x32_bf16 v[10:13], v[154:157], v[130:133], v[10:13]
	v_mfma_f32_16x16x32_bf16 v[14:17], v[158:161], v[130:133], v[14:17]
	v_mfma_f32_16x16x32_bf16 v[18:21], v[146:149], v[134:137], v[18:21]
	v_mfma_f32_16x16x32_bf16 v[22:25], v[150:153], v[134:137], v[22:25]
	v_mfma_f32_16x16x32_bf16 v[26:29], v[154:157], v[134:137], v[26:29]
	v_mfma_f32_16x16x32_bf16 v[30:33], v[158:161], v[134:137], v[30:33]
	v_mfma_f32_16x16x32_bf16 v[34:37], v[146:149], v[138:141], v[34:37]
	v_mfma_f32_16x16x32_bf16 v[38:41], v[150:153], v[138:141], v[38:41]
	v_mfma_f32_16x16x32_bf16 v[42:45], v[154:157], v[138:141], v[42:45]
	v_mfma_f32_16x16x32_bf16 v[46:49], v[158:161], v[138:141], v[46:49]
	v_mfma_f32_16x16x32_bf16 v[50:53], v[146:149], v[142:145], v[50:53]
	v_mfma_f32_16x16x32_bf16 v[54:57], v[150:153], v[142:145], v[54:57]
	v_mfma_f32_16x16x32_bf16 v[58:61], v[154:157], v[142:145], v[58:61]
	v_mfma_f32_16x16x32_bf16 v[62:65], v[158:161], v[142:145], v[62:65]
	v_mfma_f32_16x16x32_bf16 v[2:5], v[228:231], v[212:215], v[2:5]
	v_mfma_f32_16x16x32_bf16 v[6:9], v[232:235], v[212:215], v[6:9]
	v_mfma_f32_16x16x32_bf16 v[10:13], v[236:239], v[212:215], v[10:13]
	v_mfma_f32_16x16x32_bf16 v[14:17], v[240:243], v[212:215], v[14:17]
	v_mfma_f32_16x16x32_bf16 v[18:21], v[228:231], v[216:219], v[18:21]
	v_mfma_f32_16x16x32_bf16 v[22:25], v[232:235], v[216:219], v[22:25]
	v_mfma_f32_16x16x32_bf16 v[26:29], v[236:239], v[216:219], v[26:29]
	v_mfma_f32_16x16x32_bf16 v[30:33], v[240:243], v[216:219], v[30:33]
	v_mfma_f32_16x16x32_bf16 v[34:37], v[228:231], v[220:223], v[34:37]
	v_mfma_f32_16x16x32_bf16 v[38:41], v[232:235], v[220:223], v[38:41]
	v_mfma_f32_16x16x32_bf16 v[42:45], v[236:239], v[220:223], v[42:45]
	v_mfma_f32_16x16x32_bf16 v[46:49], v[240:243], v[220:223], v[46:49]
	v_mfma_f32_16x16x32_bf16 v[50:53], v[228:231], v[224:227], v[50:53]
	v_mfma_f32_16x16x32_bf16 v[54:57], v[232:235], v[224:227], v[54:57]
	v_mfma_f32_16x16x32_bf16 v[58:61], v[236:239], v[224:227], v[58:61]
	v_mfma_f32_16x16x32_bf16 v[62:65], v[240:243], v[224:227], v[62:65]
	s_waitcnt vmcnt(6)
	s_barrier
	v_add_u32_e32 v204, 0xc000, v200
	v_add_u32_e32 v205, 0xc000, v202
	ds_read_b128 v[130:133], v204 offset:0
	ds_read_b128 v[134:137], v204 offset:2048
	ds_read_b128 v[138:141], v204 offset:4096
	ds_read_b128 v[142:145], v204 offset:6144
	ds_read_b128 v[146:149], v205 offset:0
	ds_read_b128 v[150:153], v205 offset:2048
	ds_read_b128 v[154:157], v205 offset:4096
	ds_read_b128 v[158:161], v205 offset:6144
	v_add_u32_e32 v204, 0xc000, v201
	v_add_u32_e32 v205, 0xc000, v203
	ds_read_b128 v[212:215], v204 offset:0
	ds_read_b128 v[216:219], v204 offset:2048
	ds_read_b128 v[220:223], v204 offset:4096
	ds_read_b128 v[224:227], v204 offset:6144
	ds_read_b128 v[228:231], v205 offset:0
	ds_read_b128 v[232:235], v205 offset:2048
	ds_read_b128 v[236:239], v205 offset:4096
	ds_read_b128 v[240:243], v205 offset:6144
	s_add_u32 m0, s76, 0x0
	s_nop 0
	global_load_lds_dwordx4 v196, s[68:69]
	s_add_u32 m0, s76, 0x2000
	s_nop 0
	global_load_lds_dwordx4 v197, s[68:69]
	s_add_u32 m0, s76, 0x4000
	s_nop 0
	global_load_lds_dwordx4 v198, s[68:69]
	s_add_u32 m0, s76, 0x6000
	s_nop 0
	global_load_lds_dwordx4 v199, s[68:69]
	s_add_u32 m0, s76, 0x8000
	s_nop 0
	global_load_lds_dwordx4 v196, s[70:71]
	s_add_u32 m0, s76, 0xa000
	s_nop 0
	global_load_lds_dwordx4 v197, s[70:71]
	s_add_u32 s68, s68, 0x80
	s_addc_u32 s69, s69, 0
	s_add_u32 s70, s70, 0x80
	s_addc_u32 s71, s71, 0
	s_waitcnt lgkmcnt(0)
	s_barrier
	v_mfma_f32_16x16x32_bf16 v[2:5], v[146:149], v[130:133], v[2:5]
	v_mfma_f32_16x16x32_bf16 v[6:9], v[150:153], v[130:133], v[6:9]
	v_mfma_f32_16x16x32_bf16 v[10:13], v[154:157], v[130:133], v[10:13]
	v_mfma_f32_16x16x32_bf16 v[14:17], v[158:161], v[130:133], v[14:17]
	v_mfma_f32_16x16x32_bf16 v[18:21], v[146:149], v[134:137], v[18:21]
	v_mfma_f32_16x16x32_bf16 v[22:25], v[150:153], v[134:137], v[22:25]
	v_mfma_f32_16x16x32_bf16 v[26:29], v[154:157], v[134:137], v[26:29]
	v_mfma_f32_16x16x32_bf16 v[30:33], v[158:161], v[134:137], v[30:33]
	v_mfma_f32_16x16x32_bf16 v[34:37], v[146:149], v[138:141], v[34:37]
	v_mfma_f32_16x16x32_bf16 v[38:41], v[150:153], v[138:141], v[38:41]
	v_mfma_f32_16x16x32_bf16 v[42:45], v[154:157], v[138:141], v[42:45]
	v_mfma_f32_16x16x32_bf16 v[46:49], v[158:161], v[138:141], v[46:49]
	v_mfma_f32_16x16x32_bf16 v[50:53], v[146:149], v[142:145], v[50:53]
	v_mfma_f32_16x16x32_bf16 v[54:57], v[150:153], v[142:145], v[54:57]
	v_mfma_f32_16x16x32_bf16 v[58:61], v[154:157], v[142:145], v[58:61]
	v_mfma_f32_16x16x32_bf16 v[62:65], v[158:161], v[142:145], v[62:65]
	v_mfma_f32_16x16x32_bf16 v[2:5], v[228:231], v[212:215], v[2:5]
	v_mfma_f32_16x16x32_bf16 v[6:9], v[232:235], v[212:215], v[6:9]
	v_mfma_f32_16x16x32_bf16 v[10:13], v[236:239], v[212:215], v[10:13]
	v_mfma_f32_16x16x32_bf16 v[14:17], v[240:243], v[212:215], v[14:17]
	v_mfma_f32_16x16x32_bf16 v[18:21], v[228:231], v[216:219], v[18:21]
	v_mfma_f32_16x16x32_bf16 v[22:25], v[232:235], v[216:219], v[22:25]
	v_mfma_f32_16x16x32_bf16 v[26:29], v[236:239], v[216:219], v[26:29]
	v_mfma_f32_16x16x32_bf16 v[30:33], v[240:243], v[216:219], v[30:33]
	v_mfma_f32_16x16x32_bf16 v[34:37], v[228:231], v[220:223], v[34:37]
	v_mfma_f32_16x16x32_bf16 v[38:41], v[232:235], v[220:223], v[38:41]
	v_mfma_f32_16x16x32_bf16 v[42:45], v[236:239], v[220:223], v[42:45]
	v_mfma_f32_16x16x32_bf16 v[46:49], v[240:243], v[220:223], v[46:49]
	v_mfma_f32_16x16x32_bf16 v[50:53], v[228:231], v[224:227], v[50:53]
	v_mfma_f32_16x16x32_bf16 v[54:57], v[232:235], v[224:227], v[54:57]
	v_mfma_f32_16x16x32_bf16 v[58:61], v[236:239], v[224:227], v[58:61]
	v_mfma_f32_16x16x32_bf16 v[62:65], v[240:243], v[224:227], v[62:65]
	s_waitcnt vmcnt(6)
	s_barrier
	v_add_u32_e32 v204, 0x18000, v200
	v_add_u32_e32 v205, 0x18000, v202
	ds_read_b128 v[130:133], v204 offset:0
	ds_read_b128 v[134:137], v204 offset:2048
	ds_read_b128 v[138:141], v204 offset:4096
	ds_read_b128 v[142:145], v204 offset:6144
	ds_read_b128 v[146:149], v205 offset:0
	ds_read_b128 v[150:153], v205 offset:2048
	ds_read_b128 v[154:157], v205 offset:4096
	ds_read_b128 v[158:161], v205 offset:6144
	v_add_u32_e32 v204, 0x18000, v201
	v_add_u32_e32 v205, 0x18000, v203
	ds_read_b128 v[212:215], v204 offset:0
	ds_read_b128 v[216:219], v204 offset:2048
	ds_read_b128 v[220:223], v204 offset:4096
	ds_read_b128 v[224:227], v204 offset:6144
	ds_read_b128 v[228:231], v205 offset:0
	ds_read_b128 v[232:235], v205 offset:2048
	ds_read_b128 v[236:239], v205 offset:4096
	ds_read_b128 v[240:243], v205 offset:6144
	s_add_u32 m0, s76, 0xc000
	s_nop 0
	global_load_lds_dwordx4 v196, s[68:69]
	s_add_u32 m0, s76, 0xe000
	s_nop 0
	global_load_lds_dwordx4 v197, s[68:69]
	s_add_u32 m0, s76, 0x10000
	s_nop 0
	global_load_lds_dwordx4 v198, s[68:69]
	s_add_u32 m0, s76, 0x12000
	s_nop 0
	global_load_lds_dwordx4 v199, s[68:69]
	s_add_u32 m0, s76, 0x14000
	s_nop 0
	global_load_lds_dwordx4 v196, s[70:71]
	s_add_u32 m0, s76, 0x16000
	s_nop 0
	global_load_lds_dwordx4 v197, s[70:71]
	s_add_u32 s68, s68, 0x80
	s_addc_u32 s69, s69, 0
	s_add_u32 s70, s70, 0x80
	s_addc_u32 s71, s71, 0
	s_waitcnt lgkmcnt(0)
	s_barrier
	v_mfma_f32_16x16x32_bf16 v[2:5], v[146:149], v[130:133], v[2:5]
	v_mfma_f32_16x16x32_bf16 v[6:9], v[150:153], v[130:133], v[6:9]
	v_mfma_f32_16x16x32_bf16 v[10:13], v[154:157], v[130:133], v[10:13]
	v_mfma_f32_16x16x32_bf16 v[14:17], v[158:161], v[130:133], v[14:17]
	v_mfma_f32_16x16x32_bf16 v[18:21], v[146:149], v[134:137], v[18:21]
	v_mfma_f32_16x16x32_bf16 v[22:25], v[150:153], v[134:137], v[22:25]
	v_mfma_f32_16x16x32_bf16 v[26:29], v[154:157], v[134:137], v[26:29]
	v_mfma_f32_16x16x32_bf16 v[30:33], v[158:161], v[134:137], v[30:33]
	v_mfma_f32_16x16x32_bf16 v[34:37], v[146:149], v[138:141], v[34:37]
	v_mfma_f32_16x16x32_bf16 v[38:41], v[150:153], v[138:141], v[38:41]
	v_mfma_f32_16x16x32_bf16 v[42:45], v[154:157], v[138:141], v[42:45]
	v_mfma_f32_16x16x32_bf16 v[46:49], v[158:161], v[138:141], v[46:49]
	v_mfma_f32_16x16x32_bf16 v[50:53], v[146:149], v[142:145], v[50:53]
	v_mfma_f32_16x16x32_bf16 v[54:57], v[150:153], v[142:145], v[54:57]
	v_mfma_f32_16x16x32_bf16 v[58:61], v[154:157], v[142:145], v[58:61]
	v_mfma_f32_16x16x32_bf16 v[62:65], v[158:161], v[142:145], v[62:65]
	v_mfma_f32_16x16x32_bf16 v[2:5], v[228:231], v[212:215], v[2:5]
	v_mfma_f32_16x16x32_bf16 v[6:9], v[232:235], v[212:215], v[6:9]
	v_mfma_f32_16x16x32_bf16 v[10:13], v[236:239], v[212:215], v[10:13]
	v_mfma_f32_16x16x32_bf16 v[14:17], v[240:243], v[212:215], v[14:17]
	v_mfma_f32_16x16x32_bf16 v[18:21], v[228:231], v[216:219], v[18:21]
	v_mfma_f32_16x16x32_bf16 v[22:25], v[232:235], v[216:219], v[22:25]
	v_mfma_f32_16x16x32_bf16 v[26:29], v[236:239], v[216:219], v[26:29]
	v_mfma_f32_16x16x32_bf16 v[30:33], v[240:243], v[216:219], v[30:33]
	v_mfma_f32_16x16x32_bf16 v[34:37], v[228:231], v[220:223], v[34:37]
	v_mfma_f32_16x16x32_bf16 v[38:41], v[232:235], v[220:223], v[38:41]
	v_mfma_f32_16x16x32_bf16 v[42:45], v[236:239], v[220:223], v[42:45]
	v_mfma_f32_16x16x32_bf16 v[46:49], v[240:243], v[220:223], v[46:49]
	v_mfma_f32_16x16x32_bf16 v[50:53], v[228:231], v[224:227], v[50:53]
	v_mfma_f32_16x16x32_bf16 v[54:57], v[232:235], v[224:227], v[54:57]
	v_mfma_f32_16x16x32_bf16 v[58:61], v[236:239], v[224:227], v[58:61]
	v_mfma_f32_16x16x32_bf16 v[62:65], v[240:243], v[224:227], v[62:65]
	s_waitcnt vmcnt(6)
	s_barrier
	v_add_u32_e32 v204, 0x0, v200
	v_add_u32_e32 v205, 0x0, v202
	ds_read_b128 v[130:133], v204 offset:0
	ds_read_b128 v[134:137], v204 offset:2048
	ds_read_b128 v[138:141], v204 offset:4096
	ds_read_b128 v[142:145], v204 offset:6144
	ds_read_b128 v[146:149], v205 offset:0
	ds_read_b128 v[150:153], v205 offset:2048
	ds_read_b128 v[154:157], v205 offset:4096
	ds_read_b128 v[158:161], v205 offset:6144
	v_add_u32_e32 v204, 0x0, v201
	v_add_u32_e32 v205, 0x0, v203
	ds_read_b128 v[212:215], v204 offset:0
	ds_read_b128 v[216:219], v204 offset:2048
	ds_read_b128 v[220:223], v204 offset:4096
	ds_read_b128 v[224:227], v204 offset:6144
	ds_read_b128 v[228:231], v205 offset:0
	ds_read_b128 v[232:235], v205 offset:2048
	ds_read_b128 v[236:239], v205 offset:4096
	ds_read_b128 v[240:243], v205 offset:6144
	s_add_u32 m0, s76, 0x18000
	s_nop 0
	global_load_lds_dwordx4 v196, s[68:69]
	s_add_u32 m0, s76, 0x1a000
	s_nop 0
	global_load_lds_dwordx4 v197, s[68:69]
	s_add_u32 m0, s76, 0x1c000
	s_nop 0
	global_load_lds_dwordx4 v198, s[68:69]
	s_add_u32 m0, s76, 0x1e000
	s_nop 0
	global_load_lds_dwordx4 v199, s[68:69]
	s_add_u32 m0, s76, 0x20000
	s_nop 0
	global_load_lds_dwordx4 v196, s[70:71]
	s_add_u32 m0, s76, 0x22000
	s_nop 0
	global_load_lds_dwordx4 v197, s[70:71]
	s_add_u32 s68, s68, 0x80
	s_addc_u32 s69, s69, 0
	s_add_u32 s70, s70, 0x80
	s_addc_u32 s71, s71, 0
	s_waitcnt lgkmcnt(0)
	s_barrier
	v_mfma_f32_16x16x32_bf16 v[2:5], v[146:149], v[130:133], v[2:5]
	v_mfma_f32_16x16x32_bf16 v[6:9], v[150:153], v[130:133], v[6:9]
	v_mfma_f32_16x16x32_bf16 v[10:13], v[154:157], v[130:133], v[10:13]
	v_mfma_f32_16x16x32_bf16 v[14:17], v[158:161], v[130:133], v[14:17]
	v_mfma_f32_16x16x32_bf16 v[18:21], v[146:149], v[134:137], v[18:21]
	v_mfma_f32_16x16x32_bf16 v[22:25], v[150:153], v[134:137], v[22:25]
	v_mfma_f32_16x16x32_bf16 v[26:29], v[154:157], v[134:137], v[26:29]
	v_mfma_f32_16x16x32_bf16 v[30:33], v[158:161], v[134:137], v[30:33]
	v_mfma_f32_16x16x32_bf16 v[34:37], v[146:149], v[138:141], v[34:37]
	v_mfma_f32_16x16x32_bf16 v[38:41], v[150:153], v[138:141], v[38:41]
	v_mfma_f32_16x16x32_bf16 v[42:45], v[154:157], v[138:141], v[42:45]
	v_mfma_f32_16x16x32_bf16 v[46:49], v[158:161], v[138:141], v[46:49]
	v_mfma_f32_16x16x32_bf16 v[50:53], v[146:149], v[142:145], v[50:53]
	v_mfma_f32_16x16x32_bf16 v[54:57], v[150:153], v[142:145], v[54:57]
	v_mfma_f32_16x16x32_bf16 v[58:61], v[154:157], v[142:145], v[58:61]
	v_mfma_f32_16x16x32_bf16 v[62:65], v[158:161], v[142:145], v[62:65]
	v_mfma_f32_16x16x32_bf16 v[2:5], v[228:231], v[212:215], v[2:5]
	v_mfma_f32_16x16x32_bf16 v[6:9], v[232:235], v[212:215], v[6:9]
	v_mfma_f32_16x16x32_bf16 v[10:13], v[236:239], v[212:215], v[10:13]
	v_mfma_f32_16x16x32_bf16 v[14:17], v[240:243], v[212:215], v[14:17]
	v_mfma_f32_16x16x32_bf16 v[18:21], v[228:231], v[216:219], v[18:21]
	v_mfma_f32_16x16x32_bf16 v[22:25], v[232:235], v[216:219], v[22:25]
	v_mfma_f32_16x16x32_bf16 v[26:29], v[236:239], v[216:219], v[26:29]
	v_mfma_f32_16x16x32_bf16 v[30:33], v[240:243], v[216:219], v[30:33]
	v_mfma_f32_16x16x32_bf16 v[34:37], v[228:231], v[220:223], v[34:37]
	v_mfma_f32_16x16x32_bf16 v[38:41], v[232:235], v[220:223], v[38:41]
	v_mfma_f32_16x16x32_bf16 v[42:45], v[236:239], v[220:223], v[42:45]
	v_mfma_f32_16x16x32_bf16 v[46:49], v[240:243], v[220:223], v[46:49]
	v_mfma_f32_16x16x32_bf16 v[50:53], v[228:231], v[224:227], v[50:53]
	v_mfma_f32_16x16x32_bf16 v[54:57], v[232:235], v[224:227], v[54:57]
	v_mfma_f32_16x16x32_bf16 v[58:61], v[236:239], v[224:227], v[58:61]
	v_mfma_f32_16x16x32_bf16 v[62:65], v[240:243], v[224:227], v[62:65]
	s_nop 7
	v_lshlrev_b32_e32 v212, 16, v174
	v_and_b32_e32 v213, 0xffff0000, v174
	v_lshlrev_b32_e32 v214, 16, v175
	v_and_b32_e32 v215, 0xffff0000, v175
	v_pk_fma_f32 v[66:67], v[2:3], v[212:213], v[66:67]
	v_pk_fma_f32 v[68:69], v[4:5], v[214:215], v[68:69]
	v_lshlrev_b32_e32 v216, 16, v176
	v_and_b32_e32 v217, 0xffff0000, v176
	v_lshlrev_b32_e32 v218, 16, v177
	v_and_b32_e32 v219, 0xffff0000, v177
	v_pk_fma_f32 v[70:71], v[6:7], v[216:217], v[70:71]
	v_pk_fma_f32 v[72:73], v[8:9], v[218:219], v[72:73]
	v_lshlrev_b32_e32 v220, 16, v178
	v_and_b32_e32 v221, 0xffff0000, v178
	v_lshlrev_b32_e32 v222, 16, v179
	v_and_b32_e32 v223, 0xffff0000, v179
	v_pk_fma_f32 v[74:75], v[10:11], v[220:221], v[74:75]
	v_pk_fma_f32 v[76:77], v[12:13], v[222:223], v[76:77]
	v_lshlrev_b32_e32 v224, 16, v180
	v_and_b32_e32 v225, 0xffff0000, v180
	v_lshlrev_b32_e32 v226, 16, v181
	v_and_b32_e32 v227, 0xffff0000, v181
	v_pk_fma_f32 v[78:79], v[14:15], v[224:225], v[78:79]
	v_pk_fma_f32 v[80:81], v[16:17], v[226:227], v[80:81]
	v_lshlrev_b32_e32 v228, 16, v182
	v_and_b32_e32 v229, 0xffff0000, v182
	v_lshlrev_b32_e32 v230, 16, v183
	v_and_b32_e32 v231, 0xffff0000, v183
	v_pk_fma_f32 v[82:83], v[18:19], v[228:229], v[82:83]
	v_pk_fma_f32 v[84:85], v[20:21], v[230:231], v[84:85]
	v_lshlrev_b32_e32 v232, 16, v184
	v_and_b32_e32 v233, 0xffff0000, v184
	v_lshlrev_b32_e32 v234, 16, v185
	v_and_b32_e32 v235, 0xffff0000, v185
	v_pk_fma_f32 v[86:87], v[22:23], v[232:233], v[86:87]
	v_pk_fma_f32 v[88:89], v[24:25], v[234:235], v[88:89]
	v_lshlrev_b32_e32 v236, 16, v186
	v_and_b32_e32 v237, 0xffff0000, v186
	v_lshlrev_b32_e32 v238, 16, v187
	v_and_b32_e32 v239, 0xffff0000, v187
	v_pk_fma_f32 v[90:91], v[26:27], v[236:237], v[90:91]
	v_pk_fma_f32 v[92:93], v[28:29], v[238:239], v[92:93]
	v_lshlrev_b32_e32 v240, 16, v188
	v_and_b32_e32 v241, 0xffff0000, v188
	v_lshlrev_b32_e32 v242, 16, v189
	v_and_b32_e32 v243, 0xffff0000, v189
	v_pk_fma_f32 v[94:95], v[30:31], v[240:241], v[94:95]
	v_pk_fma_f32 v[96:97], v[32:33], v[242:243], v[96:97]
	v_lshlrev_b32_e32 v212, 16, v190
	v_and_b32_e32 v213, 0xffff0000, v190
	v_lshlrev_b32_e32 v214, 16, v191
	v_and_b32_e32 v215, 0xffff0000, v191
	v_pk_fma_f32 v[98:99], v[34:35], v[212:213], v[98:99]
	v_pk_fma_f32 v[100:101], v[36:37], v[214:215], v[100:101]
	v_lshlrev_b32_e32 v216, 16, v192
	v_and_b32_e32 v217, 0xffff0000, v192
	v_lshlrev_b32_e32 v218, 16, v193
	v_and_b32_e32 v219, 0xffff0000, v193
	v_pk_fma_f32 v[102:103], v[38:39], v[216:217], v[102:103]
	v_pk_fma_f32 v[104:105], v[40:41], v[218:219], v[104:105]
	v_lshlrev_b32_e32 v220, 16, v244
	v_and_b32_e32 v221, 0xffff0000, v244
	v_lshlrev_b32_e32 v222, 16, v245
	v_and_b32_e32 v223, 0xffff0000, v245
	v_pk_fma_f32 v[106:107], v[42:43], v[220:221], v[106:107]
	v_pk_fma_f32 v[108:109], v[44:45], v[222:223], v[108:109]
	v_lshlrev_b32_e32 v224, 16, v246
	v_and_b32_e32 v225, 0xffff0000, v246
	v_lshlrev_b32_e32 v226, 16, v247
	v_and_b32_e32 v227, 0xffff0000, v247
	v_pk_fma_f32 v[110:111], v[46:47], v[224:225], v[110:111]
	v_pk_fma_f32 v[112:113], v[48:49], v[226:227], v[112:113]
	v_lshlrev_b32_e32 v228, 16, v248
	v_and_b32_e32 v229, 0xffff0000, v248
	v_lshlrev_b32_e32 v230, 16, v249
	v_and_b32_e32 v231, 0xffff0000, v249
	v_pk_fma_f32 v[114:115], v[50:51], v[228:229], v[114:115]
	v_pk_fma_f32 v[116:117], v[52:53], v[230:231], v[116:117]
	v_lshlrev_b32_e32 v232, 16, v250
	v_and_b32_e32 v233, 0xffff0000, v250
	v_lshlrev_b32_e32 v234, 16, v251
	v_and_b32_e32 v235, 0xffff0000, v251
	v_pk_fma_f32 v[118:119], v[54:55], v[232:233], v[118:119]
	v_pk_fma_f32 v[120:121], v[56:57], v[234:235], v[120:121]
	v_lshlrev_b32_e32 v236, 16, v166
	v_and_b32_e32 v237, 0xffff0000, v166
	v_lshlrev_b32_e32 v238, 16, v167
	v_and_b32_e32 v239, 0xffff0000, v167
	v_pk_fma_f32 v[122:123], v[58:59], v[236:237], v[122:123]
	v_pk_fma_f32 v[124:125], v[60:61], v[238:239], v[124:125]
	v_lshlrev_b32_e32 v240, 16, v194
	v_and_b32_e32 v241, 0xffff0000, v194
	v_lshlrev_b32_e32 v242, 16, v195
	v_and_b32_e32 v243, 0xffff0000, v195
	v_pk_fma_f32 v[126:127], v[62:63], v[240:241], v[126:127]
	v_pk_fma_f32 v[128:129], v[64:65], v[242:243], v[128:129]
	s_waitcnt vmcnt(6)
	s_barrier
	v_add_u32_e32 v204, 0xc000, v200
	v_add_u32_e32 v205, 0xc000, v202
	ds_read_b128 v[130:133], v204 offset:0
	ds_read_b128 v[134:137], v204 offset:2048
	ds_read_b128 v[138:141], v204 offset:4096
	ds_read_b128 v[142:145], v204 offset:6144
	ds_read_b128 v[146:149], v205 offset:0
	ds_read_b128 v[150:153], v205 offset:2048
	ds_read_b128 v[154:157], v205 offset:4096
	ds_read_b128 v[158:161], v205 offset:6144
	v_add_u32_e32 v204, 0xc000, v201
	v_add_u32_e32 v205, 0xc000, v203
	ds_read_b128 v[212:215], v204 offset:0
	ds_read_b128 v[216:219], v204 offset:2048
	ds_read_b128 v[220:223], v204 offset:4096
	ds_read_b128 v[224:227], v204 offset:6144
	ds_read_b128 v[228:231], v205 offset:0
	ds_read_b128 v[232:235], v205 offset:2048
	ds_read_b128 v[236:239], v205 offset:4096
	ds_read_b128 v[240:243], v205 offset:6144
	s_add_u32 m0, s76, 0x0
	s_nop 0
	global_load_lds_dwordx4 v196, s[68:69]
	s_add_u32 m0, s76, 0x2000
	s_nop 0
	global_load_lds_dwordx4 v197, s[68:69]
	s_add_u32 m0, s76, 0x4000
	s_nop 0
	global_load_lds_dwordx4 v198, s[68:69]
	s_add_u32 m0, s76, 0x6000
	s_nop 0
	global_load_lds_dwordx4 v199, s[68:69]
	s_add_u32 m0, s76, 0x8000
	s_nop 0
	global_load_lds_dwordx4 v196, s[70:71]
	s_add_u32 m0, s76, 0xa000
	s_nop 0
	global_load_lds_dwordx4 v197, s[70:71]
	s_add_u32 s68, s68, 0x80
	s_addc_u32 s69, s69, 0
	s_add_u32 s70, s70, 0x80
	s_addc_u32 s71, s71, 0
	global_load_dwordx2 v[174:175], v206, s[72:73] offset:0
	global_load_dwordx2 v[176:177], v206, s[72:73] offset:32
	global_load_dwordx2 v[178:179], v206, s[72:73] offset:64
	global_load_dwordx2 v[180:181], v206, s[72:73] offset:96
	global_load_dwordx2 v[182:183], v207, s[72:73] offset:0
	global_load_dwordx2 v[184:185], v207, s[72:73] offset:32
	s_waitcnt lgkmcnt(0)
	s_barrier
	v_mfma_f32_16x16x32_bf16 v[2:5], v[146:149], v[130:133], 0
	v_mfma_f32_16x16x32_bf16 v[6:9], v[150:153], v[130:133], 0
	v_mfma_f32_16x16x32_bf16 v[10:13], v[154:157], v[130:133], 0
	v_mfma_f32_16x16x32_bf16 v[14:17], v[158:161], v[130:133], 0
	v_mfma_f32_16x16x32_bf16 v[18:21], v[146:149], v[134:137], 0
	v_mfma_f32_16x16x32_bf16 v[22:25], v[150:153], v[134:137], 0
	v_mfma_f32_16x16x32_bf16 v[26:29], v[154:157], v[134:137], 0
	v_mfma_f32_16x16x32_bf16 v[30:33], v[158:161], v[134:137], 0
	v_mfma_f32_16x16x32_bf16 v[34:37], v[146:149], v[138:141], 0
	v_mfma_f32_16x16x32_bf16 v[38:41], v[150:153], v[138:141], 0
	v_mfma_f32_16x16x32_bf16 v[42:45], v[154:157], v[138:141], 0
	v_mfma_f32_16x16x32_bf16 v[46:49], v[158:161], v[138:141], 0
	v_mfma_f32_16x16x32_bf16 v[50:53], v[146:149], v[142:145], 0
	v_mfma_f32_16x16x32_bf16 v[54:57], v[150:153], v[142:145], 0
	v_mfma_f32_16x16x32_bf16 v[58:61], v[154:157], v[142:145], 0
	v_mfma_f32_16x16x32_bf16 v[62:65], v[158:161], v[142:145], 0
	v_mfma_f32_16x16x32_bf16 v[2:5], v[228:231], v[212:215], v[2:5]
	v_mfma_f32_16x16x32_bf16 v[6:9], v[232:235], v[212:215], v[6:9]
	v_mfma_f32_16x16x32_bf16 v[10:13], v[236:239], v[212:215], v[10:13]
	v_mfma_f32_16x16x32_bf16 v[14:17], v[240:243], v[212:215], v[14:17]
	v_mfma_f32_16x16x32_bf16 v[18:21], v[228:231], v[216:219], v[18:21]
	v_mfma_f32_16x16x32_bf16 v[22:25], v[232:235], v[216:219], v[22:25]
	v_mfma_f32_16x16x32_bf16 v[26:29], v[236:239], v[216:219], v[26:29]
	v_mfma_f32_16x16x32_bf16 v[30:33], v[240:243], v[216:219], v[30:33]
	v_mfma_f32_16x16x32_bf16 v[34:37], v[228:231], v[220:223], v[34:37]
	v_mfma_f32_16x16x32_bf16 v[38:41], v[232:235], v[220:223], v[38:41]
	v_mfma_f32_16x16x32_bf16 v[42:45], v[236:239], v[220:223], v[42:45]
	v_mfma_f32_16x16x32_bf16 v[46:49], v[240:243], v[220:223], v[46:49]
	v_mfma_f32_16x16x32_bf16 v[50:53], v[228:231], v[224:227], v[50:53]
	v_mfma_f32_16x16x32_bf16 v[54:57], v[232:235], v[224:227], v[54:57]
	v_mfma_f32_16x16x32_bf16 v[58:61], v[236:239], v[224:227], v[58:61]
	v_mfma_f32_16x16x32_bf16 v[62:65], v[240:243], v[224:227], v[62:65]
	s_waitcnt vmcnt(12)
	s_barrier
	v_add_u32_e32 v204, 0x18000, v200
	v_add_u32_e32 v205, 0x18000, v202
	ds_read_b128 v[130:133], v204 offset:0
	ds_read_b128 v[134:137], v204 offset:2048
	ds_read_b128 v[138:141], v204 offset:4096
	ds_read_b128 v[142:145], v204 offset:6144
	ds_read_b128 v[146:149], v205 offset:0
	ds_read_b128 v[150:153], v205 offset:2048
	ds_read_b128 v[154:157], v205 offset:4096
	ds_read_b128 v[158:161], v205 offset:6144
	v_add_u32_e32 v204, 0x18000, v201
	v_add_u32_e32 v205, 0x18000, v203
	ds_read_b128 v[212:215], v204 offset:0
	ds_read_b128 v[216:219], v204 offset:2048
	ds_read_b128 v[220:223], v204 offset:4096
	ds_read_b128 v[224:227], v204 offset:6144
	ds_read_b128 v[228:231], v205 offset:0
	ds_read_b128 v[232:235], v205 offset:2048
	ds_read_b128 v[236:239], v205 offset:4096
	ds_read_b128 v[240:243], v205 offset:6144
	s_add_u32 m0, s76, 0xc000
	s_nop 0
	global_load_lds_dwordx4 v196, s[68:69]
	s_add_u32 m0, s76, 0xe000
	s_nop 0
	global_load_lds_dwordx4 v197, s[68:69]
	s_add_u32 m0, s76, 0x10000
	s_nop 0
	global_load_lds_dwordx4 v198, s[68:69]
	s_add_u32 m0, s76, 0x12000
	s_nop 0
	global_load_lds_dwordx4 v199, s[68:69]
	s_add_u32 m0, s76, 0x14000
	s_nop 0
	global_load_lds_dwordx4 v196, s[70:71]
	s_add_u32 m0, s76, 0x16000
	s_nop 0
	global_load_lds_dwordx4 v197, s[70:71]
	s_add_u32 s68, s68, 0x80
	s_addc_u32 s69, s69, 0
	s_add_u32 s70, s70, 0x80
	s_addc_u32 s71, s71, 0
	global_load_dwordx2 v[186:187], v207, s[72:73] offset:64
	global_load_dwordx2 v[188:189], v207, s[72:73] offset:96
	global_load_dwordx2 v[190:191], v208, s[72:73] offset:0
	global_load_dwordx2 v[192:193], v208, s[72:73] offset:32
	global_load_dwordx2 v[244:245], v208, s[72:73] offset:64
	global_load_dwordx2 v[246:247], v208, s[72:73] offset:96
	s_waitcnt lgkmcnt(0)
	s_barrier
	v_mfma_f32_16x16x32_bf16 v[2:5], v[146:149], v[130:133], v[2:5]
	v_mfma_f32_16x16x32_bf16 v[6:9], v[150:153], v[130:133], v[6:9]
	v_mfma_f32_16x16x32_bf16 v[10:13], v[154:157], v[130:133], v[10:13]
	v_mfma_f32_16x16x32_bf16 v[14:17], v[158:161], v[130:133], v[14:17]
	v_mfma_f32_16x16x32_bf16 v[18:21], v[146:149], v[134:137], v[18:21]
	v_mfma_f32_16x16x32_bf16 v[22:25], v[150:153], v[134:137], v[22:25]
	v_mfma_f32_16x16x32_bf16 v[26:29], v[154:157], v[134:137], v[26:29]
	v_mfma_f32_16x16x32_bf16 v[30:33], v[158:161], v[134:137], v[30:33]
	v_mfma_f32_16x16x32_bf16 v[34:37], v[146:149], v[138:141], v[34:37]
	v_mfma_f32_16x16x32_bf16 v[38:41], v[150:153], v[138:141], v[38:41]
	v_mfma_f32_16x16x32_bf16 v[42:45], v[154:157], v[138:141], v[42:45]
	v_mfma_f32_16x16x32_bf16 v[46:49], v[158:161], v[138:141], v[46:49]
	v_mfma_f32_16x16x32_bf16 v[50:53], v[146:149], v[142:145], v[50:53]
	v_mfma_f32_16x16x32_bf16 v[54:57], v[150:153], v[142:145], v[54:57]
	v_mfma_f32_16x16x32_bf16 v[58:61], v[154:157], v[142:145], v[58:61]
	v_mfma_f32_16x16x32_bf16 v[62:65], v[158:161], v[142:145], v[62:65]
	v_mfma_f32_16x16x32_bf16 v[2:5], v[228:231], v[212:215], v[2:5]
	v_mfma_f32_16x16x32_bf16 v[6:9], v[232:235], v[212:215], v[6:9]
	v_mfma_f32_16x16x32_bf16 v[10:13], v[236:239], v[212:215], v[10:13]
	v_mfma_f32_16x16x32_bf16 v[14:17], v[240:243], v[212:215], v[14:17]
	v_mfma_f32_16x16x32_bf16 v[18:21], v[228:231], v[216:219], v[18:21]
	v_mfma_f32_16x16x32_bf16 v[22:25], v[232:235], v[216:219], v[22:25]
	v_mfma_f32_16x16x32_bf16 v[26:29], v[236:239], v[216:219], v[26:29]
	v_mfma_f32_16x16x32_bf16 v[30:33], v[240:243], v[216:219], v[30:33]
	v_mfma_f32_16x16x32_bf16 v[34:37], v[228:231], v[220:223], v[34:37]
	v_mfma_f32_16x16x32_bf16 v[38:41], v[232:235], v[220:223], v[38:41]
	v_mfma_f32_16x16x32_bf16 v[42:45], v[236:239], v[220:223], v[42:45]
	v_mfma_f32_16x16x32_bf16 v[46:49], v[240:243], v[220:223], v[46:49]
	v_mfma_f32_16x16x32_bf16 v[50:53], v[228:231], v[224:227], v[50:53]
	v_mfma_f32_16x16x32_bf16 v[54:57], v[232:235], v[224:227], v[54:57]
	v_mfma_f32_16x16x32_bf16 v[58:61], v[236:239], v[224:227], v[58:61]
	v_mfma_f32_16x16x32_bf16 v[62:65], v[240:243], v[224:227], v[62:65]
	s_waitcnt vmcnt(18)
	s_barrier
	v_add_u32_e32 v204, 0x0, v200
	v_add_u32_e32 v205, 0x0, v202
	ds_read_b128 v[130:133], v204 offset:0
	ds_read_b128 v[134:137], v204 offset:2048
	ds_read_b128 v[138:141], v204 offset:4096
	ds_read_b128 v[142:145], v204 offset:6144
	ds_read_b128 v[146:149], v205 offset:0
	ds_read_b128 v[150:153], v205 offset:2048
	ds_read_b128 v[154:157], v205 offset:4096
	ds_read_b128 v[158:161], v205 offset:6144
	v_add_u32_e32 v204, 0x0, v201
	v_add_u32_e32 v205, 0x0, v203
	ds_read_b128 v[212:215], v204 offset:0
	ds_read_b128 v[216:219], v204 offset:2048
	ds_read_b128 v[220:223], v204 offset:4096
	ds_read_b128 v[224:227], v204 offset:6144
	ds_read_b128 v[228:231], v205 offset:0
	ds_read_b128 v[232:235], v205 offset:2048
	ds_read_b128 v[236:239], v205 offset:4096
	ds_read_b128 v[240:243], v205 offset:6144
	s_add_u32 m0, s76, 0x18000
	s_nop 0
	global_load_lds_dwordx4 v196, s[68:69]
	s_add_u32 m0, s76, 0x1a000
	s_nop 0
	global_load_lds_dwordx4 v197, s[68:69]
	s_add_u32 m0, s76, 0x1c000
	s_nop 0
	global_load_lds_dwordx4 v198, s[68:69]
	s_add_u32 m0, s76, 0x1e000
	s_nop 0
	global_load_lds_dwordx4 v199, s[68:69]
	s_add_u32 m0, s76, 0x20000
	s_nop 0
	global_load_lds_dwordx4 v196, s[70:71]
	s_add_u32 m0, s76, 0x22000
	s_nop 0
	global_load_lds_dwordx4 v197, s[70:71]
	s_add_u32 s68, s68, 0x80
	s_addc_u32 s69, s69, 0
	s_add_u32 s70, s70, 0x80
	s_addc_u32 s71, s71, 0
	global_load_dwordx2 v[248:249], v209, s[72:73] offset:0
	global_load_dwordx2 v[250:251], v209, s[72:73] offset:32
	global_load_dwordx2 v[166:167], v209, s[72:73] offset:64
	global_load_dwordx2 v[194:195], v209, s[72:73] offset:96
	s_add_u32 s72, s72, 0x800
	s_addc_u32 s73, s73, 0
	s_waitcnt lgkmcnt(0)
	s_barrier
	v_mfma_f32_16x16x32_bf16 v[2:5], v[146:149], v[130:133], v[2:5]
	v_mfma_f32_16x16x32_bf16 v[6:9], v[150:153], v[130:133], v[6:9]
	v_mfma_f32_16x16x32_bf16 v[10:13], v[154:157], v[130:133], v[10:13]
	v_mfma_f32_16x16x32_bf16 v[14:17], v[158:161], v[130:133], v[14:17]
	v_mfma_f32_16x16x32_bf16 v[18:21], v[146:149], v[134:137], v[18:21]
	v_mfma_f32_16x16x32_bf16 v[22:25], v[150:153], v[134:137], v[22:25]
	v_mfma_f32_16x16x32_bf16 v[26:29], v[154:157], v[134:137], v[26:29]
	v_mfma_f32_16x16x32_bf16 v[30:33], v[158:161], v[134:137], v[30:33]
	v_mfma_f32_16x16x32_bf16 v[34:37], v[146:149], v[138:141], v[34:37]
	v_mfma_f32_16x16x32_bf16 v[38:41], v[150:153], v[138:141], v[38:41]
	v_mfma_f32_16x16x32_bf16 v[42:45], v[154:157], v[138:141], v[42:45]
	v_mfma_f32_16x16x32_bf16 v[46:49], v[158:161], v[138:141], v[46:49]
	v_mfma_f32_16x16x32_bf16 v[50:53], v[146:149], v[142:145], v[50:53]
	v_mfma_f32_16x16x32_bf16 v[54:57], v[150:153], v[142:145], v[54:57]
	v_mfma_f32_16x16x32_bf16 v[58:61], v[154:157], v[142:145], v[58:61]
	v_mfma_f32_16x16x32_bf16 v[62:65], v[158:161], v[142:145], v[62:65]
	v_mfma_f32_16x16x32_bf16 v[2:5], v[228:231], v[212:215], v[2:5]
	v_mfma_f32_16x16x32_bf16 v[6:9], v[232:235], v[212:215], v[6:9]
	v_mfma_f32_16x16x32_bf16 v[10:13], v[236:239], v[212:215], v[10:13]
	v_mfma_f32_16x16x32_bf16 v[14:17], v[240:243], v[212:215], v[14:17]
	v_mfma_f32_16x16x32_bf16 v[18:21], v[228:231], v[216:219], v[18:21]
	v_mfma_f32_16x16x32_bf16 v[22:25], v[232:235], v[216:219], v[22:25]
	v_mfma_f32_16x16x32_bf16 v[26:29], v[236:239], v[216:219], v[26:29]
	v_mfma_f32_16x16x32_bf16 v[30:33], v[240:243], v[216:219], v[30:33]
	v_mfma_f32_16x16x32_bf16 v[34:37], v[228:231], v[220:223], v[34:37]
	v_mfma_f32_16x16x32_bf16 v[38:41], v[232:235], v[220:223], v[38:41]
	v_mfma_f32_16x16x32_bf16 v[42:45], v[236:239], v[220:223], v[42:45]
	v_mfma_f32_16x16x32_bf16 v[46:49], v[240:243], v[220:223], v[46:49]
	v_mfma_f32_16x16x32_bf16 v[50:53], v[228:231], v[224:227], v[50:53]
	v_mfma_f32_16x16x32_bf16 v[54:57], v[232:235], v[224:227], v[54:57]
	v_mfma_f32_16x16x32_bf16 v[58:61], v[236:239], v[224:227], v[58:61]
	v_mfma_f32_16x16x32_bf16 v[62:65], v[240:243], v[224:227], v[62:65]
	s_waitcnt vmcnt(16)
	s_barrier
	v_add_u32_e32 v204, 0xc000, v200
	v_add_u32_e32 v205, 0xc000, v202
	ds_read_b128 v[130:133], v204 offset:0
	ds_read_b128 v[134:137], v204 offset:2048
	ds_read_b128 v[138:141], v204 offset:4096
	ds_read_b128 v[142:145], v204 offset:6144
	ds_read_b128 v[146:149], v205 offset:0
	ds_read_b128 v[150:153], v205 offset:2048
	ds_read_b128 v[154:157], v205 offset:4096
	ds_read_b128 v[158:161], v205 offset:6144
	v_add_u32_e32 v204, 0xc000, v201
	v_add_u32_e32 v205, 0xc000, v203
	ds_read_b128 v[212:215], v204 offset:0
	ds_read_b128 v[216:219], v204 offset:2048
	ds_read_b128 v[220:223], v204 offset:4096
	ds_read_b128 v[224:227], v204 offset:6144
	ds_read_b128 v[228:231], v205 offset:0
	ds_read_b128 v[232:235], v205 offset:2048
	ds_read_b128 v[236:239], v205 offset:4096
	ds_read_b128 v[240:243], v205 offset:6144
	s_add_u32 m0, s76, 0x0
	s_nop 0
	global_load_lds_dwordx4 v196, s[68:69]
	s_add_u32 m0, s76, 0x2000
	s_nop 0
	global_load_lds_dwordx4 v197, s[68:69]
	s_add_u32 m0, s76, 0x4000
	s_nop 0
	global_load_lds_dwordx4 v198, s[68:69]
	s_add_u32 m0, s76, 0x6000
	s_nop 0
	global_load_lds_dwordx4 v199, s[68:69]
	s_add_u32 m0, s76, 0x8000
	s_nop 0
	global_load_lds_dwordx4 v196, s[70:71]
	s_add_u32 m0, s76, 0xa000
	s_nop 0
	global_load_lds_dwordx4 v197, s[70:71]
	s_add_u32 s68, s68, 0x80
	s_addc_u32 s69, s69, 0
	s_add_u32 s70, s70, 0x80
	s_addc_u32 s71, s71, 0
	s_waitcnt lgkmcnt(0)
	s_barrier
	v_mfma_f32_16x16x32_bf16 v[2:5], v[146:149], v[130:133], v[2:5]
	v_mfma_f32_16x16x32_bf16 v[6:9], v[150:153], v[130:133], v[6:9]
	v_mfma_f32_16x16x32_bf16 v[10:13], v[154:157], v[130:133], v[10:13]
	v_mfma_f32_16x16x32_bf16 v[14:17], v[158:161], v[130:133], v[14:17]
	v_mfma_f32_16x16x32_bf16 v[18:21], v[146:149], v[134:137], v[18:21]
	v_mfma_f32_16x16x32_bf16 v[22:25], v[150:153], v[134:137], v[22:25]
	v_mfma_f32_16x16x32_bf16 v[26:29], v[154:157], v[134:137], v[26:29]
	v_mfma_f32_16x16x32_bf16 v[30:33], v[158:161], v[134:137], v[30:33]
	v_mfma_f32_16x16x32_bf16 v[34:37], v[146:149], v[138:141], v[34:37]
	v_mfma_f32_16x16x32_bf16 v[38:41], v[150:153], v[138:141], v[38:41]
	v_mfma_f32_16x16x32_bf16 v[42:45], v[154:157], v[138:141], v[42:45]
	v_mfma_f32_16x16x32_bf16 v[46:49], v[158:161], v[138:141], v[46:49]
	v_mfma_f32_16x16x32_bf16 v[50:53], v[146:149], v[142:145], v[50:53]
	v_mfma_f32_16x16x32_bf16 v[54:57], v[150:153], v[142:145], v[54:57]
	v_mfma_f32_16x16x32_bf16 v[58:61], v[154:157], v[142:145], v[58:61]
	v_mfma_f32_16x16x32_bf16 v[62:65], v[158:161], v[142:145], v[62:65]
	v_mfma_f32_16x16x32_bf16 v[2:5], v[228:231], v[212:215], v[2:5]
	v_mfma_f32_16x16x32_bf16 v[6:9], v[232:235], v[212:215], v[6:9]
	v_mfma_f32_16x16x32_bf16 v[10:13], v[236:239], v[212:215], v[10:13]
	v_mfma_f32_16x16x32_bf16 v[14:17], v[240:243], v[212:215], v[14:17]
	v_mfma_f32_16x16x32_bf16 v[18:21], v[228:231], v[216:219], v[18:21]
	v_mfma_f32_16x16x32_bf16 v[22:25], v[232:235], v[216:219], v[22:25]
	v_mfma_f32_16x16x32_bf16 v[26:29], v[236:239], v[216:219], v[26:29]
	v_mfma_f32_16x16x32_bf16 v[30:33], v[240:243], v[216:219], v[30:33]
	v_mfma_f32_16x16x32_bf16 v[34:37], v[228:231], v[220:223], v[34:37]
	v_mfma_f32_16x16x32_bf16 v[38:41], v[232:235], v[220:223], v[38:41]
	v_mfma_f32_16x16x32_bf16 v[42:45], v[236:239], v[220:223], v[42:45]
	v_mfma_f32_16x16x32_bf16 v[46:49], v[240:243], v[220:223], v[46:49]
	v_mfma_f32_16x16x32_bf16 v[50:53], v[228:231], v[224:227], v[50:53]
	v_mfma_f32_16x16x32_bf16 v[54:57], v[232:235], v[224:227], v[54:57]
	v_mfma_f32_16x16x32_bf16 v[58:61], v[236:239], v[224:227], v[58:61]
	v_mfma_f32_16x16x32_bf16 v[62:65], v[240:243], v[224:227], v[62:65]
	s_waitcnt vmcnt(10)
	s_barrier
	v_add_u32_e32 v204, 0x18000, v200
	v_add_u32_e32 v205, 0x18000, v202
	ds_read_b128 v[130:133], v204 offset:0
	ds_read_b128 v[134:137], v204 offset:2048
	ds_read_b128 v[138:141], v204 offset:4096
	ds_read_b128 v[142:145], v204 offset:6144
	ds_read_b128 v[146:149], v205 offset:0
	ds_read_b128 v[150:153], v205 offset:2048
	ds_read_b128 v[154:157], v205 offset:4096
	ds_read_b128 v[158:161], v205 offset:6144
	v_add_u32_e32 v204, 0x18000, v201
	v_add_u32_e32 v205, 0x18000, v203
	ds_read_b128 v[212:215], v204 offset:0
	ds_read_b128 v[216:219], v204 offset:2048
	ds_read_b128 v[220:223], v204 offset:4096
	ds_read_b128 v[224:227], v204 offset:6144
	ds_read_b128 v[228:231], v205 offset:0
	ds_read_b128 v[232:235], v205 offset:2048
	ds_read_b128 v[236:239], v205 offset:4096
	ds_read_b128 v[240:243], v205 offset:6144
	s_add_u32 m0, s76, 0xc000
	s_nop 0
	global_load_lds_dwordx4 v196, s[68:69]
	s_add_u32 m0, s76, 0xe000
	s_nop 0
	global_load_lds_dwordx4 v197, s[68:69]
	s_add_u32 m0, s76, 0x10000
	s_nop 0
	global_load_lds_dwordx4 v198, s[68:69]
	s_add_u32 m0, s76, 0x12000
	s_nop 0
	global_load_lds_dwordx4 v199, s[68:69]
	s_add_u32 m0, s76, 0x14000
	s_nop 0
	global_load_lds_dwordx4 v196, s[70:71]
	s_add_u32 m0, s76, 0x16000
	s_nop 0
	global_load_lds_dwordx4 v197, s[70:71]
	s_add_u32 s68, s68, 0x80
	s_addc_u32 s69, s69, 0
	s_add_u32 s70, s70, 0x80
	s_addc_u32 s71, s71, 0
	s_waitcnt lgkmcnt(0)
	s_barrier
	v_mfma_f32_16x16x32_bf16 v[2:5], v[146:149], v[130:133], v[2:5]
	v_mfma_f32_16x16x32_bf16 v[6:9], v[150:153], v[130:133], v[6:9]
	v_mfma_f32_16x16x32_bf16 v[10:13], v[154:157], v[130:133], v[10:13]
	v_mfma_f32_16x16x32_bf16 v[14:17], v[158:161], v[130:133], v[14:17]
	v_mfma_f32_16x16x32_bf16 v[18:21], v[146:149], v[134:137], v[18:21]
	v_mfma_f32_16x16x32_bf16 v[22:25], v[150:153], v[134:137], v[22:25]
	v_mfma_f32_16x16x32_bf16 v[26:29], v[154:157], v[134:137], v[26:29]
	v_mfma_f32_16x16x32_bf16 v[30:33], v[158:161], v[134:137], v[30:33]
	v_mfma_f32_16x16x32_bf16 v[34:37], v[146:149], v[138:141], v[34:37]
	v_mfma_f32_16x16x32_bf16 v[38:41], v[150:153], v[138:141], v[38:41]
	v_mfma_f32_16x16x32_bf16 v[42:45], v[154:157], v[138:141], v[42:45]
	v_mfma_f32_16x16x32_bf16 v[46:49], v[158:161], v[138:141], v[46:49]
	v_mfma_f32_16x16x32_bf16 v[50:53], v[146:149], v[142:145], v[50:53]
	v_mfma_f32_16x16x32_bf16 v[54:57], v[150:153], v[142:145], v[54:57]
	v_mfma_f32_16x16x32_bf16 v[58:61], v[154:157], v[142:145], v[58:61]
	v_mfma_f32_16x16x32_bf16 v[62:65], v[158:161], v[142:145], v[62:65]
	v_mfma_f32_16x16x32_bf16 v[2:5], v[228:231], v[212:215], v[2:5]
	v_mfma_f32_16x16x32_bf16 v[6:9], v[232:235], v[212:215], v[6:9]
	v_mfma_f32_16x16x32_bf16 v[10:13], v[236:239], v[212:215], v[10:13]
	v_mfma_f32_16x16x32_bf16 v[14:17], v[240:243], v[212:215], v[14:17]
	v_mfma_f32_16x16x32_bf16 v[18:21], v[228:231], v[216:219], v[18:21]
	v_mfma_f32_16x16x32_bf16 v[22:25], v[232:235], v[216:219], v[22:25]
	v_mfma_f32_16x16x32_bf16 v[26:29], v[236:239], v[216:219], v[26:29]
	v_mfma_f32_16x16x32_bf16 v[30:33], v[240:243], v[216:219], v[30:33]
	v_mfma_f32_16x16x32_bf16 v[34:37], v[228:231], v[220:223], v[34:37]
	v_mfma_f32_16x16x32_bf16 v[38:41], v[232:235], v[220:223], v[38:41]
	v_mfma_f32_16x16x32_bf16 v[42:45], v[236:239], v[220:223], v[42:45]
	v_mfma_f32_16x16x32_bf16 v[46:49], v[240:243], v[220:223], v[46:49]
	v_mfma_f32_16x16x32_bf16 v[50:53], v[228:231], v[224:227], v[50:53]
	v_mfma_f32_16x16x32_bf16 v[54:57], v[232:235], v[224:227], v[54:57]
	v_mfma_f32_16x16x32_bf16 v[58:61], v[236:239], v[224:227], v[58:61]
	v_mfma_f32_16x16x32_bf16 v[62:65], v[240:243], v[224:227], v[62:65]
	s_waitcnt vmcnt(6)
	s_barrier
	v_add_u32_e32 v204, 0x0, v200
	v_add_u32_e32 v205, 0x0, v202
	ds_read_b128 v[130:133], v204 offset:0
	ds_read_b128 v[134:137], v204 offset:2048
	ds_read_b128 v[138:141], v204 offset:4096
	ds_read_b128 v[142:145], v204 offset:6144
	ds_read_b128 v[146:149], v205 offset:0
	ds_read_b128 v[150:153], v205 offset:2048
	ds_read_b128 v[154:157], v205 offset:4096
	ds_read_b128 v[158:161], v205 offset:6144
	v_add_u32_e32 v204, 0x0, v201
	v_add_u32_e32 v205, 0x0, v203
	ds_read_b128 v[212:215], v204 offset:0
	ds_read_b128 v[216:219], v204 offset:2048
	ds_read_b128 v[220:223], v204 offset:4096
	ds_read_b128 v[224:227], v204 offset:6144
	ds_read_b128 v[228:231], v205 offset:0
	ds_read_b128 v[232:235], v205 offset:2048
	ds_read_b128 v[236:239], v205 offset:4096
	ds_read_b128 v[240:243], v205 offset:6144
	s_add_u32 m0, s76, 0x18000
	s_nop 0
	global_load_lds_dwordx4 v196, s[68:69]
	s_add_u32 m0, s76, 0x1a000
	s_nop 0
	global_load_lds_dwordx4 v197, s[68:69]
	s_add_u32 m0, s76, 0x1c000
	s_nop 0
	global_load_lds_dwordx4 v198, s[68:69]
	s_add_u32 m0, s76, 0x1e000
	s_nop 0
	global_load_lds_dwordx4 v199, s[68:69]
	s_add_u32 m0, s76, 0x20000
	s_nop 0
	global_load_lds_dwordx4 v196, s[70:71]
	s_add_u32 m0, s76, 0x22000
	s_nop 0
	global_load_lds_dwordx4 v197, s[70:71]
	s_add_u32 s68, s68, 0x80
	s_addc_u32 s69, s69, 0
	s_add_u32 s70, s70, 0x80
	s_addc_u32 s71, s71, 0
	s_waitcnt lgkmcnt(0)
	s_barrier
	v_mfma_f32_16x16x32_bf16 v[2:5], v[146:149], v[130:133], v[2:5]
	v_mfma_f32_16x16x32_bf16 v[6:9], v[150:153], v[130:133], v[6:9]
	v_mfma_f32_16x16x32_bf16 v[10:13], v[154:157], v[130:133], v[10:13]
	v_mfma_f32_16x16x32_bf16 v[14:17], v[158:161], v[130:133], v[14:17]
	v_mfma_f32_16x16x32_bf16 v[18:21], v[146:149], v[134:137], v[18:21]
	v_mfma_f32_16x16x32_bf16 v[22:25], v[150:153], v[134:137], v[22:25]
	v_mfma_f32_16x16x32_bf16 v[26:29], v[154:157], v[134:137], v[26:29]
	v_mfma_f32_16x16x32_bf16 v[30:33], v[158:161], v[134:137], v[30:33]
	v_mfma_f32_16x16x32_bf16 v[34:37], v[146:149], v[138:141], v[34:37]
	v_mfma_f32_16x16x32_bf16 v[38:41], v[150:153], v[138:141], v[38:41]
	v_mfma_f32_16x16x32_bf16 v[42:45], v[154:157], v[138:141], v[42:45]
	v_mfma_f32_16x16x32_bf16 v[46:49], v[158:161], v[138:141], v[46:49]
	v_mfma_f32_16x16x32_bf16 v[50:53], v[146:149], v[142:145], v[50:53]
	v_mfma_f32_16x16x32_bf16 v[54:57], v[150:153], v[142:145], v[54:57]
	v_mfma_f32_16x16x32_bf16 v[58:61], v[154:157], v[142:145], v[58:61]
	v_mfma_f32_16x16x32_bf16 v[62:65], v[158:161], v[142:145], v[62:65]
	v_mfma_f32_16x16x32_bf16 v[2:5], v[228:231], v[212:215], v[2:5]
	v_mfma_f32_16x16x32_bf16 v[6:9], v[232:235], v[212:215], v[6:9]
	v_mfma_f32_16x16x32_bf16 v[10:13], v[236:239], v[212:215], v[10:13]
	v_mfma_f32_16x16x32_bf16 v[14:17], v[240:243], v[212:215], v[14:17]
	v_mfma_f32_16x16x32_bf16 v[18:21], v[228:231], v[216:219], v[18:21]
	v_mfma_f32_16x16x32_bf16 v[22:25], v[232:235], v[216:219], v[22:25]
	v_mfma_f32_16x16x32_bf16 v[26:29], v[236:239], v[216:219], v[26:29]
	v_mfma_f32_16x16x32_bf16 v[30:33], v[240:243], v[216:219], v[30:33]
	v_mfma_f32_16x16x32_bf16 v[34:37], v[228:231], v[220:223], v[34:37]
	v_mfma_f32_16x16x32_bf16 v[38:41], v[232:235], v[220:223], v[38:41]
	v_mfma_f32_16x16x32_bf16 v[42:45], v[236:239], v[220:223], v[42:45]
	v_mfma_f32_16x16x32_bf16 v[46:49], v[240:243], v[220:223], v[46:49]
	v_mfma_f32_16x16x32_bf16 v[50:53], v[228:231], v[224:227], v[50:53]
	v_mfma_f32_16x16x32_bf16 v[54:57], v[232:235], v[224:227], v[54:57]
	v_mfma_f32_16x16x32_bf16 v[58:61], v[236:239], v[224:227], v[58:61]
	v_mfma_f32_16x16x32_bf16 v[62:65], v[240:243], v[224:227], v[62:65]
	s_waitcnt vmcnt(6)
	s_barrier
	v_add_u32_e32 v204, 0xc000, v200
	v_add_u32_e32 v205, 0xc000, v202
	ds_read_b128 v[130:133], v204 offset:0
	ds_read_b128 v[134:137], v204 offset:2048
	ds_read_b128 v[138:141], v204 offset:4096
	ds_read_b128 v[142:145], v204 offset:6144
	ds_read_b128 v[146:149], v205 offset:0
	ds_read_b128 v[150:153], v205 offset:2048
	ds_read_b128 v[154:157], v205 offset:4096
	ds_read_b128 v[158:161], v205 offset:6144
	v_add_u32_e32 v204, 0xc000, v201
	v_add_u32_e32 v205, 0xc000, v203
	ds_read_b128 v[212:215], v204 offset:0
	ds_read_b128 v[216:219], v204 offset:2048
	ds_read_b128 v[220:223], v204 offset:4096
	ds_read_b128 v[224:227], v204 offset:6144
	ds_read_b128 v[228:231], v205 offset:0
	ds_read_b128 v[232:235], v205 offset:2048
	ds_read_b128 v[236:239], v205 offset:4096
	ds_read_b128 v[240:243], v205 offset:6144
	s_waitcnt lgkmcnt(0)
	s_barrier
	v_mfma_f32_16x16x32_bf16 v[2:5], v[146:149], v[130:133], v[2:5]
	v_mfma_f32_16x16x32_bf16 v[6:9], v[150:153], v[130:133], v[6:9]
	v_mfma_f32_16x16x32_bf16 v[10:13], v[154:157], v[130:133], v[10:13]
	v_mfma_f32_16x16x32_bf16 v[14:17], v[158:161], v[130:133], v[14:17]
	v_mfma_f32_16x16x32_bf16 v[18:21], v[146:149], v[134:137], v[18:21]
	v_mfma_f32_16x16x32_bf16 v[22:25], v[150:153], v[134:137], v[22:25]
	v_mfma_f32_16x16x32_bf16 v[26:29], v[154:157], v[134:137], v[26:29]
	v_mfma_f32_16x16x32_bf16 v[30:33], v[158:161], v[134:137], v[30:33]
	v_mfma_f32_16x16x32_bf16 v[34:37], v[146:149], v[138:141], v[34:37]
	v_mfma_f32_16x16x32_bf16 v[38:41], v[150:153], v[138:141], v[38:41]
	v_mfma_f32_16x16x32_bf16 v[42:45], v[154:157], v[138:141], v[42:45]
	v_mfma_f32_16x16x32_bf16 v[46:49], v[158:161], v[138:141], v[46:49]
	v_mfma_f32_16x16x32_bf16 v[50:53], v[146:149], v[142:145], v[50:53]
	v_mfma_f32_16x16x32_bf16 v[54:57], v[150:153], v[142:145], v[54:57]
	v_mfma_f32_16x16x32_bf16 v[58:61], v[154:157], v[142:145], v[58:61]
	v_mfma_f32_16x16x32_bf16 v[62:65], v[158:161], v[142:145], v[62:65]
	v_mfma_f32_16x16x32_bf16 v[2:5], v[228:231], v[212:215], v[2:5]
	v_mfma_f32_16x16x32_bf16 v[6:9], v[232:235], v[212:215], v[6:9]
	v_mfma_f32_16x16x32_bf16 v[10:13], v[236:239], v[212:215], v[10:13]
	v_mfma_f32_16x16x32_bf16 v[14:17], v[240:243], v[212:215], v[14:17]
	v_mfma_f32_16x16x32_bf16 v[18:21], v[228:231], v[216:219], v[18:21]
	v_mfma_f32_16x16x32_bf16 v[22:25], v[232:235], v[216:219], v[22:25]
	v_mfma_f32_16x16x32_bf16 v[26:29], v[236:239], v[216:219], v[26:29]
	v_mfma_f32_16x16x32_bf16 v[30:33], v[240:243], v[216:219], v[30:33]
	v_mfma_f32_16x16x32_bf16 v[34:37], v[228:231], v[220:223], v[34:37]
	v_mfma_f32_16x16x32_bf16 v[38:41], v[232:235], v[220:223], v[38:41]
	v_mfma_f32_16x16x32_bf16 v[42:45], v[236:239], v[220:223], v[42:45]
	v_mfma_f32_16x16x32_bf16 v[46:49], v[240:243], v[220:223], v[46:49]
	v_mfma_f32_16x16x32_bf16 v[50:53], v[228:231], v[224:227], v[50:53]
	v_mfma_f32_16x16x32_bf16 v[54:57], v[232:235], v[224:227], v[54:57]
	v_mfma_f32_16x16x32_bf16 v[58:61], v[236:239], v[224:227], v[58:61]
	v_mfma_f32_16x16x32_bf16 v[62:65], v[240:243], v[224:227], v[62:65]
	s_waitcnt vmcnt(0)
	s_barrier
	v_add_u32_e32 v204, 0x18000, v200
	v_add_u32_e32 v205, 0x18000, v202
	ds_read_b128 v[130:133], v204 offset:0
	ds_read_b128 v[134:137], v204 offset:2048
	ds_read_b128 v[138:141], v204 offset:4096
	ds_read_b128 v[142:145], v204 offset:6144
	ds_read_b128 v[146:149], v205 offset:0
	ds_read_b128 v[150:153], v205 offset:2048
	ds_read_b128 v[154:157], v205 offset:4096
	ds_read_b128 v[158:161], v205 offset:6144
	v_add_u32_e32 v204, 0x18000, v201
	v_add_u32_e32 v205, 0x18000, v203
	ds_read_b128 v[212:215], v204 offset:0
	ds_read_b128 v[216:219], v204 offset:2048
	ds_read_b128 v[220:223], v204 offset:4096
	ds_read_b128 v[224:227], v204 offset:6144
	ds_read_b128 v[228:231], v205 offset:0
	ds_read_b128 v[232:235], v205 offset:2048
	ds_read_b128 v[236:239], v205 offset:4096
	ds_read_b128 v[240:243], v205 offset:6144
	s_waitcnt lgkmcnt(0)
	s_barrier
	v_mfma_f32_16x16x32_bf16 v[2:5], v[146:149], v[130:133], v[2:5]
	v_mfma_f32_16x16x32_bf16 v[6:9], v[150:153], v[130:133], v[6:9]
	v_mfma_f32_16x16x32_bf16 v[10:13], v[154:157], v[130:133], v[10:13]
	v_mfma_f32_16x16x32_bf16 v[14:17], v[158:161], v[130:133], v[14:17]
	v_mfma_f32_16x16x32_bf16 v[18:21], v[146:149], v[134:137], v[18:21]
	v_mfma_f32_16x16x32_bf16 v[22:25], v[150:153], v[134:137], v[22:25]
	v_mfma_f32_16x16x32_bf16 v[26:29], v[154:157], v[134:137], v[26:29]
	v_mfma_f32_16x16x32_bf16 v[30:33], v[158:161], v[134:137], v[30:33]
	v_mfma_f32_16x16x32_bf16 v[34:37], v[146:149], v[138:141], v[34:37]
	v_mfma_f32_16x16x32_bf16 v[38:41], v[150:153], v[138:141], v[38:41]
	v_mfma_f32_16x16x32_bf16 v[42:45], v[154:157], v[138:141], v[42:45]
	v_mfma_f32_16x16x32_bf16 v[46:49], v[158:161], v[138:141], v[46:49]
	v_mfma_f32_16x16x32_bf16 v[50:53], v[146:149], v[142:145], v[50:53]
	v_mfma_f32_16x16x32_bf16 v[54:57], v[150:153], v[142:145], v[54:57]
	v_mfma_f32_16x16x32_bf16 v[58:61], v[154:157], v[142:145], v[58:61]
	v_mfma_f32_16x16x32_bf16 v[62:65], v[158:161], v[142:145], v[62:65]
	v_mfma_f32_16x16x32_bf16 v[2:5], v[228:231], v[212:215], v[2:5]
	v_mfma_f32_16x16x32_bf16 v[6:9], v[232:235], v[212:215], v[6:9]
	v_mfma_f32_16x16x32_bf16 v[10:13], v[236:239], v[212:215], v[10:13]
	v_mfma_f32_16x16x32_bf16 v[14:17], v[240:243], v[212:215], v[14:17]
	v_mfma_f32_16x16x32_bf16 v[18:21], v[228:231], v[216:219], v[18:21]
	v_mfma_f32_16x16x32_bf16 v[22:25], v[232:235], v[216:219], v[22:25]
	v_mfma_f32_16x16x32_bf16 v[26:29], v[236:239], v[216:219], v[26:29]
	v_mfma_f32_16x16x32_bf16 v[30:33], v[240:243], v[216:219], v[30:33]
	v_mfma_f32_16x16x32_bf16 v[34:37], v[228:231], v[220:223], v[34:37]
	v_mfma_f32_16x16x32_bf16 v[38:41], v[232:235], v[220:223], v[38:41]
	v_mfma_f32_16x16x32_bf16 v[42:45], v[236:239], v[220:223], v[42:45]
	v_mfma_f32_16x16x32_bf16 v[46:49], v[240:243], v[220:223], v[46:49]
	v_mfma_f32_16x16x32_bf16 v[50:53], v[228:231], v[224:227], v[50:53]
	v_mfma_f32_16x16x32_bf16 v[54:57], v[232:235], v[224:227], v[54:57]
	v_mfma_f32_16x16x32_bf16 v[58:61], v[236:239], v[224:227], v[58:61]
	v_mfma_f32_16x16x32_bf16 v[62:65], v[240:243], v[224:227], v[62:65]
	s_nop 7
	v_lshlrev_b32_e32 v212, 16, v174
	v_and_b32_e32 v213, 0xffff0000, v174
	v_lshlrev_b32_e32 v214, 16, v175
	v_and_b32_e32 v215, 0xffff0000, v175
	v_pk_fma_f32 v[66:67], v[2:3], v[212:213], v[66:67]
	v_pk_fma_f32 v[68:69], v[4:5], v[214:215], v[68:69]
	s_nop 0
	v_cvt_pk_bf16_f32 v66, v66, v67
	v_cvt_pk_bf16_f32 v67, v68, v69
	v_lshlrev_b32_e32 v216, 16, v176
	v_and_b32_e32 v217, 0xffff0000, v176
	v_lshlrev_b32_e32 v218, 16, v177
	v_and_b32_e32 v219, 0xffff0000, v177
	v_pk_fma_f32 v[70:71], v[6:7], v[216:217], v[70:71]
	v_pk_fma_f32 v[72:73], v[8:9], v[218:219], v[72:73]
	s_nop 0
	v_cvt_pk_bf16_f32 v70, v70, v71
	v_cvt_pk_bf16_f32 v71, v72, v73
	v_lshlrev_b32_e32 v220, 16, v178
	v_and_b32_e32 v221, 0xffff0000, v178
	v_lshlrev_b32_e32 v222, 16, v179
	v_and_b32_e32 v223, 0xffff0000, v179
	v_pk_fma_f32 v[74:75], v[10:11], v[220:221], v[74:75]
	v_pk_fma_f32 v[76:77], v[12:13], v[222:223], v[76:77]
	s_nop 0
	v_cvt_pk_bf16_f32 v74, v74, v75
	v_cvt_pk_bf16_f32 v75, v76, v77
	v_lshlrev_b32_e32 v224, 16, v180
	v_and_b32_e32 v225, 0xffff0000, v180
	v_lshlrev_b32_e32 v226, 16, v181
	v_and_b32_e32 v227, 0xffff0000, v181
	v_pk_fma_f32 v[78:79], v[14:15], v[224:225], v[78:79]
	v_pk_fma_f32 v[80:81], v[16:17], v[226:227], v[80:81]
	s_nop 0
	v_cvt_pk_bf16_f32 v78, v78, v79
	v_cvt_pk_bf16_f32 v79, v80, v81
	v_lshlrev_b32_e32 v228, 16, v182
	v_and_b32_e32 v229, 0xffff0000, v182
	v_lshlrev_b32_e32 v230, 16, v183
	v_and_b32_e32 v231, 0xffff0000, v183
	v_pk_fma_f32 v[82:83], v[18:19], v[228:229], v[82:83]
	v_pk_fma_f32 v[84:85], v[20:21], v[230:231], v[84:85]
	s_nop 0
	v_cvt_pk_bf16_f32 v82, v82, v83
	v_cvt_pk_bf16_f32 v83, v84, v85
	v_lshlrev_b32_e32 v232, 16, v184
	v_and_b32_e32 v233, 0xffff0000, v184
	v_lshlrev_b32_e32 v234, 16, v185
	v_and_b32_e32 v235, 0xffff0000, v185
	v_pk_fma_f32 v[86:87], v[22:23], v[232:233], v[86:87]
	v_pk_fma_f32 v[88:89], v[24:25], v[234:235], v[88:89]
	s_nop 0
	v_cvt_pk_bf16_f32 v86, v86, v87
	v_cvt_pk_bf16_f32 v87, v88, v89
	v_lshlrev_b32_e32 v236, 16, v186
	v_and_b32_e32 v237, 0xffff0000, v186
	v_lshlrev_b32_e32 v238, 16, v187
	v_and_b32_e32 v239, 0xffff0000, v187
	v_pk_fma_f32 v[90:91], v[26:27], v[236:237], v[90:91]
	v_pk_fma_f32 v[92:93], v[28:29], v[238:239], v[92:93]
	s_nop 0
	v_cvt_pk_bf16_f32 v90, v90, v91
	v_cvt_pk_bf16_f32 v91, v92, v93
	v_lshlrev_b32_e32 v240, 16, v188
	v_and_b32_e32 v241, 0xffff0000, v188
	v_lshlrev_b32_e32 v242, 16, v189
	v_and_b32_e32 v243, 0xffff0000, v189
	v_pk_fma_f32 v[94:95], v[30:31], v[240:241], v[94:95]
	v_pk_fma_f32 v[96:97], v[32:33], v[242:243], v[96:97]
	s_nop 0
	v_cvt_pk_bf16_f32 v94, v94, v95
	v_cvt_pk_bf16_f32 v95, v96, v97
	v_lshlrev_b32_e32 v212, 16, v190
	v_and_b32_e32 v213, 0xffff0000, v190
	v_lshlrev_b32_e32 v214, 16, v191
	v_and_b32_e32 v215, 0xffff0000, v191
	v_pk_fma_f32 v[98:99], v[34:35], v[212:213], v[98:99]
	v_pk_fma_f32 v[100:101], v[36:37], v[214:215], v[100:101]
	s_nop 0
	v_cvt_pk_bf16_f32 v98, v98, v99
	v_cvt_pk_bf16_f32 v99, v100, v101
	v_lshlrev_b32_e32 v216, 16, v192
	v_and_b32_e32 v217, 0xffff0000, v192
	v_lshlrev_b32_e32 v218, 16, v193
	v_and_b32_e32 v219, 0xffff0000, v193
	v_pk_fma_f32 v[102:103], v[38:39], v[216:217], v[102:103]
	v_pk_fma_f32 v[104:105], v[40:41], v[218:219], v[104:105]
	s_nop 0
	v_cvt_pk_bf16_f32 v102, v102, v103
	v_cvt_pk_bf16_f32 v103, v104, v105
	v_lshlrev_b32_e32 v220, 16, v244
	v_and_b32_e32 v221, 0xffff0000, v244
	v_lshlrev_b32_e32 v222, 16, v245
	v_and_b32_e32 v223, 0xffff0000, v245
	v_pk_fma_f32 v[106:107], v[42:43], v[220:221], v[106:107]
	v_pk_fma_f32 v[108:109], v[44:45], v[222:223], v[108:109]
	s_nop 0
	v_cvt_pk_bf16_f32 v106, v106, v107
	v_cvt_pk_bf16_f32 v107, v108, v109
	v_lshlrev_b32_e32 v224, 16, v246
	v_and_b32_e32 v225, 0xffff0000, v246
	v_lshlrev_b32_e32 v226, 16, v247
	v_and_b32_e32 v227, 0xffff0000, v247
	v_pk_fma_f32 v[110:111], v[46:47], v[224:225], v[110:111]
	v_pk_fma_f32 v[112:113], v[48:49], v[226:227], v[112:113]
	s_nop 0
	v_cvt_pk_bf16_f32 v110, v110, v111
	v_cvt_pk_bf16_f32 v111, v112, v113
	v_lshlrev_b32_e32 v228, 16, v248
	v_and_b32_e32 v229, 0xffff0000, v248
	v_lshlrev_b32_e32 v230, 16, v249
	v_and_b32_e32 v231, 0xffff0000, v249
	v_pk_fma_f32 v[114:115], v[50:51], v[228:229], v[114:115]
	v_pk_fma_f32 v[116:117], v[52:53], v[230:231], v[116:117]
	s_nop 0
	v_cvt_pk_bf16_f32 v114, v114, v115
	v_cvt_pk_bf16_f32 v115, v116, v117
	v_lshlrev_b32_e32 v232, 16, v250
	v_and_b32_e32 v233, 0xffff0000, v250
	v_lshlrev_b32_e32 v234, 16, v251
	v_and_b32_e32 v235, 0xffff0000, v251
	v_pk_fma_f32 v[118:119], v[54:55], v[232:233], v[118:119]
	v_pk_fma_f32 v[120:121], v[56:57], v[234:235], v[120:121]
	s_nop 0
	v_cvt_pk_bf16_f32 v118, v118, v119
	v_cvt_pk_bf16_f32 v119, v120, v121
	v_lshlrev_b32_e32 v236, 16, v166
	v_and_b32_e32 v237, 0xffff0000, v166
	v_lshlrev_b32_e32 v238, 16, v167
	v_and_b32_e32 v239, 0xffff0000, v167
	v_pk_fma_f32 v[122:123], v[58:59], v[236:237], v[122:123]
	v_pk_fma_f32 v[124:125], v[60:61], v[238:239], v[124:125]
	s_nop 0
	v_cvt_pk_bf16_f32 v122, v122, v123
	v_cvt_pk_bf16_f32 v123, v124, v125
	v_lshlrev_b32_e32 v240, 16, v194
	v_and_b32_e32 v241, 0xffff0000, v194
	v_lshlrev_b32_e32 v242, 16, v195
	v_and_b32_e32 v243, 0xffff0000, v195
	v_pk_fma_f32 v[126:127], v[62:63], v[240:241], v[126:127]
	v_pk_fma_f32 v[128:129], v[64:65], v[242:243], v[128:129]
	s_nop 0
	v_cvt_pk_bf16_f32 v126, v126, v127
	v_cvt_pk_bf16_f32 v127, v128, v129
	s_barrier
	s_branch .Lbr_join
.Lbr_streamB:
	s_barrier
	v_add_u32_e32 v204, 0x0, v200
	v_add_u32_e32 v205, 0x0, v202
	ds_read_b128 v[130:133], v204 offset:0
	ds_read_b128 v[134:137], v204 offset:2048
	ds_read_b128 v[138:141], v204 offset:4096
	ds_read_b128 v[142:145], v204 offset:6144
	ds_read_b128 v[146:149], v205 offset:0
	ds_read_b128 v[150:153], v205 offset:2048
	ds_read_b128 v[154:157], v205 offset:4096
	ds_read_b128 v[158:161], v205 offset:6144
	v_add_u32_e32 v204, 0x0, v201
	v_add_u32_e32 v205, 0x0, v203
	ds_read_b128 v[212:215], v204 offset:0
	ds_read_b128 v[216:219], v204 offset:2048
	ds_read_b128 v[220:223], v204 offset:4096
	ds_read_b128 v[224:227], v204 offset:6144
	ds_read_b128 v[228:231], v205 offset:0
	ds_read_b128 v[232:235], v205 offset:2048
	ds_read_b128 v[236:239], v205 offset:4096
	ds_read_b128 v[240:243], v205 offset:6144
	s_add_u32 m0, s76, 0x18000
	s_nop 0
	global_load_lds_dwordx4 v196, s[68:69]
	s_add_u32 m0, s76, 0x1a000
	s_nop 0
	global_load_lds_dwordx4 v197, s[68:69]
	s_add_u32 m0, s76, 0x1c000
	s_nop 0
	global_load_lds_dwordx4 v198, s[68:69]
	s_add_u32 m0, s76, 0x1e000
	s_nop 0
	global_load_lds_dwordx4 v199, s[68:69]
	s_add_u32 m0, s76, 0x20000
	s_nop 0
	global_load_lds_dwordx4 v196, s[70:71]
	s_add_u32 m0, s76, 0x22000
	s_nop 0
	global_load_lds_dwordx4 v197, s[70:71]
	s_add_u32 s68, s68, 0x80
	s_addc_u32 s69, s69, 0
	s_add_u32 s70, s70, 0x80
	s_addc_u32 s71, s71, 0
	global_load_dwordx2 v[174:175], v206, s[72:73] offset:0
	global_load_dwordx2 v[176:177], v206, s[72:73] offset:32
	global_load_dwordx2 v[178:179], v206, s[72:73] offset:64
	global_load_dwordx2 v[180:181], v206, s[72:73] offset:96
	global_load_dwordx2 v[182:183], v207, s[72:73] offset:0
	global_load_dwordx2 v[184:185], v207, s[72:73] offset:32
	s_waitcnt vmcnt(12)
	s_waitcnt lgkmcnt(0)
	s_barrier
	v_mfma_f32_16x16x32_bf16 v[2:5], v[146:149], v[130:133], 0
	v_mfma_f32_16x16x32_bf16 v[6:9], v[150:153], v[130:133], 0
	v_mfma_f32_16x16x32_bf16 v[10:13], v[154:157], v[130:133], 0
	v_mfma_f32_16x16x32_bf16 v[14:17], v[158:161], v[130:133], 0
	v_mfma_f32_16x16x32_bf16 v[18:21], v[146:149], v[134:137], 0
	v_mfma_f32_16x16x32_bf16 v[22:25], v[150:153], v[134:137], 0
	v_mfma_f32_16x16x32_bf16 v[26:29], v[154:157], v[134:137], 0
	v_mfma_f32_16x16x32_bf16 v[30:33], v[158:161], v[134:137], 0
	v_mfma_f32_16x16x32_bf16 v[34:37], v[146:149], v[138:141], 0
	v_mfma_f32_16x16x32_bf16 v[38:41], v[150:153], v[138:141], 0
	v_mfma_f32_16x16x32_bf16 v[42:45], v[154:157], v[138:141], 0
	v_mfma_f32_16x16x32_bf16 v[46:49], v[158:161], v[138:141], 0
	v_mfma_f32_16x16x32_bf16 v[50:53], v[146:149], v[142:145], 0
	v_mfma_f32_16x16x32_bf16 v[54:57], v[150:153], v[142:145], 0
	v_mfma_f32_16x16x32_bf16 v[58:61], v[154:157], v[142:145], 0
	v_mfma_f32_16x16x32_bf16 v[62:65], v[158:161], v[142:145], 0
	v_mfma_f32_16x16x32_bf16 v[2:5], v[228:231], v[212:215], v[2:5]
	v_mfma_f32_16x16x32_bf16 v[6:9], v[232:235], v[212:215], v[6:9]
	v_mfma_f32_16x16x32_bf16 v[10:13], v[236:239], v[212:215], v[10:13]
	v_mfma_f32_16x16x32_bf16 v[14:17], v[240:243], v[212:215], v[14:17]
	v_mfma_f32_16x16x32_bf16 v[18:21], v[228:231], v[216:219], v[18:21]
	v_mfma_f32_16x16x32_bf16 v[22:25], v[232:235], v[216:219], v[22:25]
	v_mfma_f32_16x16x32_bf16 v[26:29], v[236:239], v[216:219], v[26:29]
	v_mfma_f32_16x16x32_bf16 v[30:33], v[240:243], v[216:219], v[30:33]
	v_mfma_f32_16x16x32_bf16 v[34:37], v[228:231], v[220:223], v[34:37]
	v_mfma_f32_16x16x32_bf16 v[38:41], v[232:235], v[220:223], v[38:41]
	v_mfma_f32_16x16x32_bf16 v[42:45], v[236:239], v[220:223], v[42:45]
	v_mfma_f32_16x16x32_bf16 v[46:49], v[240:243], v[220:223], v[46:49]
	v_mfma_f32_16x16x32_bf16 v[50:53], v[228:231], v[224:227], v[50:53]
	v_mfma_f32_16x16x32_bf16 v[54:57], v[232:235], v[224:227], v[54:57]
	v_mfma_f32_16x16x32_bf16 v[58:61], v[236:239], v[224:227], v[58:61]
	v_mfma_f32_16x16x32_bf16 v[62:65], v[240:243], v[224:227], v[62:65]
	s_barrier
	v_add_u32_e32 v204, 0xc000, v200
	v_add_u32_e32 v205, 0xc000, v202
	ds_read_b128 v[130:133], v204 offset:0
	ds_read_b128 v[134:137], v204 offset:2048
	ds_read_b128 v[138:141], v204 offset:4096
	ds_read_b128 v[142:145], v204 offset:6144
	ds_read_b128 v[146:149], v205 offset:0
	ds_read_b128 v[150:153], v205 offset:2048
	ds_read_b128 v[154:157], v205 offset:4096
	ds_read_b128 v[158:161], v205 offset:6144
	v_add_u32_e32 v204, 0xc000, v201
	v_add_u32_e32 v205, 0xc000, v203
	ds_read_b128 v[212:215], v204 offset:0
	ds_read_b128 v[216:219], v204 offset:2048
	ds_read_b128 v[220:223], v204 offset:4096
	ds_read_b128 v[224:227], v204 offset:6144
	ds_read_b128 v[228:231], v205 offset:0
	ds_read_b128 v[232:235], v205 offset:2048
	ds_read_b128 v[236:239], v205 offset:4096
	ds_read_b128 v[240:243], v205 offset:6144
	s_add_u32 m0, s76, 0x0
	s_nop 0
	global_load_lds_dwordx4 v196, s[68:69]
	s_add_u32 m0, s76, 0x2000
	s_nop 0
	global_load_lds_dwordx4 v197, s[68:69]
	s_add_u32 m0, s76, 0x4000
	s_nop 0
	global_load_lds_dwordx4 v198, s[68:69]
	s_add_u32 m0, s76, 0x6000
	s_nop 0
	global_load_lds_dwordx4 v199, s[68:69]
	s_add_u32 m0, s76, 0x8000
	s_nop 0
	global_load_lds_dwordx4 v196, s[70:71]
	s_add_u32 m0, s76, 0xa000
	s_nop 0
	global_load_lds_dwordx4 v197, s[70:71]
	s_add_u32 s68, s68, 0x80
	s_addc_u32 s69, s69, 0
	s_add_u32 s70, s70, 0x80
	s_addc_u32 s71, s71, 0
	global_load_dwordx2 v[186:187], v207, s[72:73] offset:64
	global_load_dwordx2 v[188:189], v207, s[72:73] offset:96
	global_load_dwordx2 v[190:191], v208, s[72:73] offset:0
	global_load_dwordx2 v[192:193], v208, s[72:73] offset:32
	global_load_dwordx2 v[244:245], v208, s[72:73] offset:64
	global_load_dwordx2 v[246:247], v208, s[72:73] offset:96
	s_waitcnt vmcnt(18)
	s_waitcnt lgkmcnt(0)
	s_barrier
	v_mfma_f32_16x16x32_bf16 v[2:5], v[146:149], v[130:133], v[2:5]
	v_mfma_f32_16x16x32_bf16 v[6:9], v[150:153], v[130:133], v[6:9]
	v_mfma_f32_16x16x32_bf16 v[10:13], v[154:157], v[130:133], v[10:13]
	v_mfma_f32_16x16x32_bf16 v[14:17], v[158:161], v[130:133], v[14:17]
	v_mfma_f32_16x16x32_bf16 v[18:21], v[146:149], v[134:137], v[18:21]
	v_mfma_f32_16x16x32_bf16 v[22:25], v[150:153], v[134:137], v[22:25]
	v_mfma_f32_16x16x32_bf16 v[26:29], v[154:157], v[134:137], v[26:29]
	v_mfma_f32_16x16x32_bf16 v[30:33], v[158:161], v[134:137], v[30:33]
	v_mfma_f32_16x16x32_bf16 v[34:37], v[146:149], v[138:141], v[34:37]
	v_mfma_f32_16x16x32_bf16 v[38:41], v[150:153], v[138:141], v[38:41]
	v_mfma_f32_16x16x32_bf16 v[42:45], v[154:157], v[138:141], v[42:45]
	v_mfma_f32_16x16x32_bf16 v[46:49], v[158:161], v[138:141], v[46:49]
	v_mfma_f32_16x16x32_bf16 v[50:53], v[146:149], v[142:145], v[50:53]
	v_mfma_f32_16x16x32_bf16 v[54:57], v[150:153], v[142:145], v[54:57]
	v_mfma_f32_16x16x32_bf16 v[58:61], v[154:157], v[142:145], v[58:61]
	v_mfma_f32_16x16x32_bf16 v[62:65], v[158:161], v[142:145], v[62:65]
	v_mfma_f32_16x16x32_bf16 v[2:5], v[228:231], v[212:215], v[2:5]
	v_mfma_f32_16x16x32_bf16 v[6:9], v[232:235], v[212:215], v[6:9]
	v_mfma_f32_16x16x32_bf16 v[10:13], v[236:239], v[212:215], v[10:13]
	v_mfma_f32_16x16x32_bf16 v[14:17], v[240:243], v[212:215], v[14:17]
	v_mfma_f32_16x16x32_bf16 v[18:21], v[228:231], v[216:219], v[18:21]
	v_mfma_f32_16x16x32_bf16 v[22:25], v[232:235], v[216:219], v[22:25]
	v_mfma_f32_16x16x32_bf16 v[26:29], v[236:239], v[216:219], v[26:29]
	v_mfma_f32_16x16x32_bf16 v[30:33], v[240:243], v[216:219], v[30:33]
	v_mfma_f32_16x16x32_bf16 v[34:37], v[228:231], v[220:223], v[34:37]
	v_mfma_f32_16x16x32_bf16 v[38:41], v[232:235], v[220:223], v[38:41]
	v_mfma_f32_16x16x32_bf16 v[42:45], v[236:239], v[220:223], v[42:45]
	v_mfma_f32_16x16x32_bf16 v[46:49], v[240:243], v[220:223], v[46:49]
	v_mfma_f32_16x16x32_bf16 v[50:53], v[228:231], v[224:227], v[50:53]
	v_mfma_f32_16x16x32_bf16 v[54:57], v[232:235], v[224:227], v[54:57]
	v_mfma_f32_16x16x32_bf16 v[58:61], v[236:239], v[224:227], v[58:61]
	v_mfma_f32_16x16x32_bf16 v[62:65], v[240:243], v[224:227], v[62:65]
	s_barrier
	v_add_u32_e32 v204, 0x18000, v200
	v_add_u32_e32 v205, 0x18000, v202
	ds_read_b128 v[130:133], v204 offset:0
	ds_read_b128 v[134:137], v204 offset:2048
	ds_read_b128 v[138:141], v204 offset:4096
	ds_read_b128 v[142:145], v204 offset:6144
	ds_read_b128 v[146:149], v205 offset:0
	ds_read_b128 v[150:153], v205 offset:2048
	ds_read_b128 v[154:157], v205 offset:4096
	ds_read_b128 v[158:161], v205 offset:6144
	v_add_u32_e32 v204, 0x18000, v201
	v_add_u32_e32 v205, 0x18000, v203
	ds_read_b128 v[212:215], v204 offset:0
	ds_read_b128 v[216:219], v204 offset:2048
	ds_read_b128 v[220:223], v204 offset:4096
	ds_read_b128 v[224:227], v204 offset:6144
	ds_read_b128 v[228:231], v205 offset:0
	ds_read_b128 v[232:235], v205 offset:2048
	ds_read_b128 v[236:239], v205 offset:4096
	ds_read_b128 v[240:243], v205 offset:6144
	s_add_u32 m0, s76, 0xc000
	s_nop 0
	global_load_lds_dwordx4 v196, s[68:69]
	s_add_u32 m0, s76, 0xe000
	s_nop 0
	global_load_lds_dwordx4 v197, s[68:69]
	s_add_u32 m0, s76, 0x10000
	s_nop 0
	global_load_lds_dwordx4 v198, s[68:69]
	s_add_u32 m0, s76, 0x12000
	s_nop 0
	global_load_lds_dwordx4 v199, s[68:69]
	s_add_u32 m0, s76, 0x14000
	s_nop 0
	global_load_lds_dwordx4 v196, s[70:71]
	s_add_u32 m0, s76, 0x16000
	s_nop 0
	global_load_lds_dwordx4 v197, s[70:71]
	s_add_u32 s68, s68, 0x80
	s_addc_u32 s69, s69, 0
	s_add_u32 s70, s70, 0x80
	s_addc_u32 s71, s71, 0
	global_load_dwordx2 v[248:249], v209, s[72:73] offset:0
	global_load_dwordx2 v[250:251], v209, s[72:73] offset:32
	global_load_dwordx2 v[166:167], v209, s[72:73] offset:64
	global_load_dwordx2 v[194:195], v209, s[72:73] offset:96
	s_add_u32 s72, s72, 0x800
	s_addc_u32 s73, s73, 0
	s_waitcnt vmcnt(16)
	s_waitcnt lgkmcnt(0)
	s_barrier
	v_mfma_f32_16x16x32_bf16 v[2:5], v[146:149], v[130:133], v[2:5]
	v_mfma_f32_16x16x32_bf16 v[6:9], v[150:153], v[130:133], v[6:9]
	v_mfma_f32_16x16x32_bf16 v[10:13], v[154:157], v[130:133], v[10:13]
	v_mfma_f32_16x16x32_bf16 v[14:17], v[158:161], v[130:133], v[14:17]
	v_mfma_f32_16x16x32_bf16 v[18:21], v[146:149], v[134:137], v[18:21]
	v_mfma_f32_16x16x32_bf16 v[22:25], v[150:153], v[134:137], v[22:25]
	v_mfma_f32_16x16x32_bf16 v[26:29], v[154:157], v[134:137], v[26:29]
	v_mfma_f32_16x16x32_bf16 v[30:33], v[158:161], v[134:137], v[30:33]
	v_mfma_f32_16x16x32_bf16 v[34:37], v[146:149], v[138:141], v[34:37]
	v_mfma_f32_16x16x32_bf16 v[38:41], v[150:153], v[138:141], v[38:41]
	v_mfma_f32_16x16x32_bf16 v[42:45], v[154:157], v[138:141], v[42:45]
	v_mfma_f32_16x16x32_bf16 v[46:49], v[158:161], v[138:141], v[46:49]
	v_mfma_f32_16x16x32_bf16 v[50:53], v[146:149], v[142:145], v[50:53]
	v_mfma_f32_16x16x32_bf16 v[54:57], v[150:153], v[142:145], v[54:57]
	v_mfma_f32_16x16x32_bf16 v[58:61], v[154:157], v[142:145], v[58:61]
	v_mfma_f32_16x16x32_bf16 v[62:65], v[158:161], v[142:145], v[62:65]
	v_mfma_f32_16x16x32_bf16 v[2:5], v[228:231], v[212:215], v[2:5]
	v_mfma_f32_16x16x32_bf16 v[6:9], v[232:235], v[212:215], v[6:9]
	v_mfma_f32_16x16x32_bf16 v[10:13], v[236:239], v[212:215], v[10:13]
	v_mfma_f32_16x16x32_bf16 v[14:17], v[240:243], v[212:215], v[14:17]
	v_mfma_f32_16x16x32_bf16 v[18:21], v[228:231], v[216:219], v[18:21]
	v_mfma_f32_16x16x32_bf16 v[22:25], v[232:235], v[216:219], v[22:25]
	v_mfma_f32_16x16x32_bf16 v[26:29], v[236:239], v[216:219], v[26:29]
	v_mfma_f32_16x16x32_bf16 v[30:33], v[240:243], v[216:219], v[30:33]
	v_mfma_f32_16x16x32_bf16 v[34:37], v[228:231], v[220:223], v[34:37]
	v_mfma_f32_16x16x32_bf16 v[38:41], v[232:235], v[220:223], v[38:41]
	v_mfma_f32_16x16x32_bf16 v[42:45], v[236:239], v[220:223], v[42:45]
	v_mfma_f32_16x16x32_bf16 v[46:49], v[240:243], v[220:223], v[46:49]
	v_mfma_f32_16x16x32_bf16 v[50:53], v[228:231], v[224:227], v[50:53]
	v_mfma_f32_16x16x32_bf16 v[54:57], v[232:235], v[224:227], v[54:57]
	v_mfma_f32_16x16x32_bf16 v[58:61], v[236:239], v[224:227], v[58:61]
	v_mfma_f32_16x16x32_bf16 v[62:65], v[240:243], v[224:227], v[62:65]
	s_barrier
	v_add_u32_e32 v204, 0x0, v200
	v_add_u32_e32 v205, 0x0, v202
	ds_read_b128 v[130:133], v204 offset:0
	ds_read_b128 v[134:137], v204 offset:2048
	ds_read_b128 v[138:141], v204 offset:4096
	ds_read_b128 v[142:145], v204 offset:6144
	ds_read_b128 v[146:149], v205 offset:0
	ds_read_b128 v[150:153], v205 offset:2048
	ds_read_b128 v[154:157], v205 offset:4096
	ds_read_b128 v[158:161], v205 offset:6144
	v_add_u32_e32 v204, 0x0, v201
	v_add_u32_e32 v205, 0x0, v203
	ds_read_b128 v[212:215], v204 offset:0
	ds_read_b128 v[216:219], v204 offset:2048
	ds_read_b128 v[220:223], v204 offset:4096
	ds_read_b128 v[224:227], v204 offset:6144
	ds_read_b128 v[228:231], v205 offset:0
	ds_read_b128 v[232:235], v205 offset:2048
	ds_read_b128 v[236:239], v205 offset:4096
	ds_read_b128 v[240:243], v205 offset:6144
	s_add_u32 m0, s76, 0x18000
	s_nop 0
	global_load_lds_dwordx4 v196, s[68:69]
	s_add_u32 m0, s76, 0x1a000
	s_nop 0
	global_load_lds_dwordx4 v197, s[68:69]
	s_add_u32 m0, s76, 0x1c000
	s_nop 0
	global_load_lds_dwordx4 v198, s[68:69]
	s_add_u32 m0, s76, 0x1e000
	s_nop 0
	global_load_lds_dwordx4 v199, s[68:69]
	s_add_u32 m0, s76, 0x20000
	s_nop 0
	global_load_lds_dwordx4 v196, s[70:71]
	s_add_u32 m0, s76, 0x22000
	s_nop 0
	global_load_lds_dwordx4 v197, s[70:71]
	s_add_u32 s68, s68, 0x80
	s_addc_u32 s69, s69, 0
	s_add_u32 s70, s70, 0x80
	s_addc_u32 s71, s71, 0
	s_waitcnt vmcnt(10)
	s_waitcnt lgkmcnt(0)
	s_barrier
	v_mfma_f32_16x16x32_bf16 v[2:5], v[146:149], v[130:133], v[2:5]
	v_mfma_f32_16x16x32_bf16 v[6:9], v[150:153], v[130:133], v[6:9]
	v_mfma_f32_16x16x32_bf16 v[10:13], v[154:157], v[130:133], v[10:13]
	v_mfma_f32_16x16x32_bf16 v[14:17], v[158:161], v[130:133], v[14:17]
	v_mfma_f32_16x16x32_bf16 v[18:21], v[146:149], v[134:137], v[18:21]
	v_mfma_f32_16x16x32_bf16 v[22:25], v[150:153], v[134:137], v[22:25]
	v_mfma_f32_16x16x32_bf16 v[26:29], v[154:157], v[134:137], v[26:29]
	v_mfma_f32_16x16x32_bf16 v[30:33], v[158:161], v[134:137], v[30:33]
	v_mfma_f32_16x16x32_bf16 v[34:37], v[146:149], v[138:141], v[34:37]
	v_mfma_f32_16x16x32_bf16 v[38:41], v[150:153], v[138:141], v[38:41]
	v_mfma_f32_16x16x32_bf16 v[42:45], v[154:157], v[138:141], v[42:45]
	v_mfma_f32_16x16x32_bf16 v[46:49], v[158:161], v[138:141], v[46:49]
	v_mfma_f32_16x16x32_bf16 v[50:53], v[146:149], v[142:145], v[50:53]
	v_mfma_f32_16x16x32_bf16 v[54:57], v[150:153], v[142:145], v[54:57]
	v_mfma_f32_16x16x32_bf16 v[58:61], v[154:157], v[142:145], v[58:61]
	v_mfma_f32_16x16x32_bf16 v[62:65], v[158:161], v[142:145], v[62:65]
	v_mfma_f32_16x16x32_bf16 v[2:5], v[228:231], v[212:215], v[2:5]
	v_mfma_f32_16x16x32_bf16 v[6:9], v[232:235], v[212:215], v[6:9]
	v_mfma_f32_16x16x32_bf16 v[10:13], v[236:239], v[212:215], v[10:13]
	v_mfma_f32_16x16x32_bf16 v[14:17], v[240:243], v[212:215], v[14:17]
	v_mfma_f32_16x16x32_bf16 v[18:21], v[228:231], v[216:219], v[18:21]
	v_mfma_f32_16x16x32_bf16 v[22:25], v[232:235], v[216:219], v[22:25]
	v_mfma_f32_16x16x32_bf16 v[26:29], v[236:239], v[216:219], v[26:29]
	v_mfma_f32_16x16x32_bf16 v[30:33], v[240:243], v[216:219], v[30:33]
	v_mfma_f32_16x16x32_bf16 v[34:37], v[228:231], v[220:223], v[34:37]
	v_mfma_f32_16x16x32_bf16 v[38:41], v[232:235], v[220:223], v[38:41]
	v_mfma_f32_16x16x32_bf16 v[42:45], v[236:239], v[220:223], v[42:45]
	v_mfma_f32_16x16x32_bf16 v[46:49], v[240:243], v[220:223], v[46:49]
	v_mfma_f32_16x16x32_bf16 v[50:53], v[228:231], v[224:227], v[50:53]
	v_mfma_f32_16x16x32_bf16 v[54:57], v[232:235], v[224:227], v[54:57]
	v_mfma_f32_16x16x32_bf16 v[58:61], v[236:239], v[224:227], v[58:61]
	v_mfma_f32_16x16x32_bf16 v[62:65], v[240:243], v[224:227], v[62:65]
	s_barrier
	v_add_u32_e32 v204, 0xc000, v200
	v_add_u32_e32 v205, 0xc000, v202
	ds_read_b128 v[130:133], v204 offset:0
	ds_read_b128 v[134:137], v204 offset:2048
	ds_read_b128 v[138:141], v204 offset:4096
	ds_read_b128 v[142:145], v204 offset:6144
	ds_read_b128 v[146:149], v205 offset:0
	ds_read_b128 v[150:153], v205 offset:2048
	ds_read_b128 v[154:157], v205 offset:4096
	ds_read_b128 v[158:161], v205 offset:6144
	v_add_u32_e32 v204, 0xc000, v201
	v_add_u32_e32 v205, 0xc000, v203
	ds_read_b128 v[212:215], v204 offset:0
	ds_read_b128 v[216:219], v204 offset:2048
	ds_read_b128 v[220:223], v204 offset:4096
	ds_read_b128 v[224:227], v204 offset:6144
	ds_read_b128 v[228:231], v205 offset:0
	ds_read_b128 v[232:235], v205 offset:2048
	ds_read_b128 v[236:239], v205 offset:4096
	ds_read_b128 v[240:243], v205 offset:6144
	s_add_u32 m0, s76, 0x0
	s_nop 0
	global_load_lds_dwordx4 v196, s[68:69]
	s_add_u32 m0, s76, 0x2000
	s_nop 0
	global_load_lds_dwordx4 v197, s[68:69]
	s_add_u32 m0, s76, 0x4000
	s_nop 0
	global_load_lds_dwordx4 v198, s[68:69]
	s_add_u32 m0, s76, 0x6000
	s_nop 0
	global_load_lds_dwordx4 v199, s[68:69]
	s_add_u32 m0, s76, 0x8000
	s_nop 0
	global_load_lds_dwordx4 v196, s[70:71]
	s_add_u32 m0, s76, 0xa000
	s_nop 0
	global_load_lds_dwordx4 v197, s[70:71]
	s_add_u32 s68, s68, 0x80
	s_addc_u32 s69, s69, 0
	s_add_u32 s70, s70, 0x80
	s_addc_u32 s71, s71, 0
	s_waitcnt vmcnt(6)
	s_waitcnt lgkmcnt(0)
	s_barrier
	v_mfma_f32_16x16x32_bf16 v[2:5], v[146:149], v[130:133], v[2:5]
	v_mfma_f32_16x16x32_bf16 v[6:9], v[150:153], v[130:133], v[6:9]
	v_mfma_f32_16x16x32_bf16 v[10:13], v[154:157], v[130:133], v[10:13]
	v_mfma_f32_16x16x32_bf16 v[14:17], v[158:161], v[130:133], v[14:17]
	v_mfma_f32_16x16x32_bf16 v[18:21], v[146:149], v[134:137], v[18:21]
	v_mfma_f32_16x16x32_bf16 v[22:25], v[150:153], v[134:137], v[22:25]
	v_mfma_f32_16x16x32_bf16 v[26:29], v[154:157], v[134:137], v[26:29]
	v_mfma_f32_16x16x32_bf16 v[30:33], v[158:161], v[134:137], v[30:33]
	v_mfma_f32_16x16x32_bf16 v[34:37], v[146:149], v[138:141], v[34:37]
	v_mfma_f32_16x16x32_bf16 v[38:41], v[150:153], v[138:141], v[38:41]
	v_mfma_f32_16x16x32_bf16 v[42:45], v[154:157], v[138:141], v[42:45]
	v_mfma_f32_16x16x32_bf16 v[46:49], v[158:161], v[138:141], v[46:49]
	v_mfma_f32_16x16x32_bf16 v[50:53], v[146:149], v[142:145], v[50:53]
	v_mfma_f32_16x16x32_bf16 v[54:57], v[150:153], v[142:145], v[54:57]
	v_mfma_f32_16x16x32_bf16 v[58:61], v[154:157], v[142:145], v[58:61]
	v_mfma_f32_16x16x32_bf16 v[62:65], v[158:161], v[142:145], v[62:65]
	v_mfma_f32_16x16x32_bf16 v[2:5], v[228:231], v[212:215], v[2:5]
	v_mfma_f32_16x16x32_bf16 v[6:9], v[232:235], v[212:215], v[6:9]
	v_mfma_f32_16x16x32_bf16 v[10:13], v[236:239], v[212:215], v[10:13]
	v_mfma_f32_16x16x32_bf16 v[14:17], v[240:243], v[212:215], v[14:17]
	v_mfma_f32_16x16x32_bf16 v[18:21], v[228:231], v[216:219], v[18:21]
	v_mfma_f32_16x16x32_bf16 v[22:25], v[232:235], v[216:219], v[22:25]
	v_mfma_f32_16x16x32_bf16 v[26:29], v[236:239], v[216:219], v[26:29]
	v_mfma_f32_16x16x32_bf16 v[30:33], v[240:243], v[216:219], v[30:33]
	v_mfma_f32_16x16x32_bf16 v[34:37], v[228:231], v[220:223], v[34:37]
	v_mfma_f32_16x16x32_bf16 v[38:41], v[232:235], v[220:223], v[38:41]
	v_mfma_f32_16x16x32_bf16 v[42:45], v[236:239], v[220:223], v[42:45]
	v_mfma_f32_16x16x32_bf16 v[46:49], v[240:243], v[220:223], v[46:49]
	v_mfma_f32_16x16x32_bf16 v[50:53], v[228:231], v[224:227], v[50:53]
	v_mfma_f32_16x16x32_bf16 v[54:57], v[232:235], v[224:227], v[54:57]
	v_mfma_f32_16x16x32_bf16 v[58:61], v[236:239], v[224:227], v[58:61]
	v_mfma_f32_16x16x32_bf16 v[62:65], v[240:243], v[224:227], v[62:65]
	s_barrier
	v_add_u32_e32 v204, 0x18000, v200
	v_add_u32_e32 v205, 0x18000, v202
	ds_read_b128 v[130:133], v204 offset:0
	ds_read_b128 v[134:137], v204 offset:2048
	ds_read_b128 v[138:141], v204 offset:4096
	ds_read_b128 v[142:145], v204 offset:6144
	ds_read_b128 v[146:149], v205 offset:0
	ds_read_b128 v[150:153], v205 offset:2048
	ds_read_b128 v[154:157], v205 offset:4096
	ds_read_b128 v[158:161], v205 offset:6144
	v_add_u32_e32 v204, 0x18000, v201
	v_add_u32_e32 v205, 0x18000, v203
	ds_read_b128 v[212:215], v204 offset:0
	ds_read_b128 v[216:219], v204 offset:2048
	ds_read_b128 v[220:223], v204 offset:4096
	ds_read_b128 v[224:227], v204 offset:6144
	ds_read_b128 v[228:231], v205 offset:0
	ds_read_b128 v[232:235], v205 offset:2048
	ds_read_b128 v[236:239], v205 offset:4096
	ds_read_b128 v[240:243], v205 offset:6144
	s_add_u32 m0, s76, 0xc000
	s_nop 0
	global_load_lds_dwordx4 v196, s[68:69]
	s_add_u32 m0, s76, 0xe000
	s_nop 0
	global_load_lds_dwordx4 v197, s[68:69]
	s_add_u32 m0, s76, 0x10000
	s_nop 0
	global_load_lds_dwordx4 v198, s[68:69]
	s_add_u32 m0, s76, 0x12000
	s_nop 0
	global_load_lds_dwordx4 v199, s[68:69]
	s_add_u32 m0, s76, 0x14000
	s_nop 0
	global_load_lds_dwordx4 v196, s[70:71]
	s_add_u32 m0, s76, 0x16000
	s_nop 0
	global_load_lds_dwordx4 v197, s[70:71]
	s_add_u32 s68, s68, 0x80
	s_addc_u32 s69, s69, 0
	s_add_u32 s70, s70, 0x80
	s_addc_u32 s71, s71, 0
	s_waitcnt vmcnt(6)
	s_waitcnt lgkmcnt(0)
	s_barrier
	v_mfma_f32_16x16x32_bf16 v[2:5], v[146:149], v[130:133], v[2:5]
	v_mfma_f32_16x16x32_bf16 v[6:9], v[150:153], v[130:133], v[6:9]
	v_mfma_f32_16x16x32_bf16 v[10:13], v[154:157], v[130:133], v[10:13]
	v_mfma_f32_16x16x32_bf16 v[14:17], v[158:161], v[130:133], v[14:17]
	v_mfma_f32_16x16x32_bf16 v[18:21], v[146:149], v[134:137], v[18:21]
	v_mfma_f32_16x16x32_bf16 v[22:25], v[150:153], v[134:137], v[22:25]
	v_mfma_f32_16x16x32_bf16 v[26:29], v[154:157], v[134:137], v[26:29]
	v_mfma_f32_16x16x32_bf16 v[30:33], v[158:161], v[134:137], v[30:33]
	v_mfma_f32_16x16x32_bf16 v[34:37], v[146:149], v[138:141], v[34:37]
	v_mfma_f32_16x16x32_bf16 v[38:41], v[150:153], v[138:141], v[38:41]
	v_mfma_f32_16x16x32_bf16 v[42:45], v[154:157], v[138:141], v[42:45]
	v_mfma_f32_16x16x32_bf16 v[46:49], v[158:161], v[138:141], v[46:49]
	v_mfma_f32_16x16x32_bf16 v[50:53], v[146:149], v[142:145], v[50:53]
	v_mfma_f32_16x16x32_bf16 v[54:57], v[150:153], v[142:145], v[54:57]
	v_mfma_f32_16x16x32_bf16 v[58:61], v[154:157], v[142:145], v[58:61]
	v_mfma_f32_16x16x32_bf16 v[62:65], v[158:161], v[142:145], v[62:65]
	v_mfma_f32_16x16x32_bf16 v[2:5], v[228:231], v[212:215], v[2:5]
	v_mfma_f32_16x16x32_bf16 v[6:9], v[232:235], v[212:215], v[6:9]
	v_mfma_f32_16x16x32_bf16 v[10:13], v[236:239], v[212:215], v[10:13]
	v_mfma_f32_16x16x32_bf16 v[14:17], v[240:243], v[212:215], v[14:17]
	v_mfma_f32_16x16x32_bf16 v[18:21], v[228:231], v[216:219], v[18:21]
	v_mfma_f32_16x16x32_bf16 v[22:25], v[232:235], v[216:219], v[22:25]
	v_mfma_f32_16x16x32_bf16 v[26:29], v[236:239], v[216:219], v[26:29]
	v_mfma_f32_16x16x32_bf16 v[30:33], v[240:243], v[216:219], v[30:33]
	v_mfma_f32_16x16x32_bf16 v[34:37], v[228:231], v[220:223], v[34:37]
	v_mfma_f32_16x16x32_bf16 v[38:41], v[232:235], v[220:223], v[38:41]
	v_mfma_f32_16x16x32_bf16 v[42:45], v[236:239], v[220:223], v[42:45]
	v_mfma_f32_16x16x32_bf16 v[46:49], v[240:243], v[220:223], v[46:49]
	v_mfma_f32_16x16x32_bf16 v[50:53], v[228:231], v[224:227], v[50:53]
	v_mfma_f32_16x16x32_bf16 v[54:57], v[232:235], v[224:227], v[54:57]
	v_mfma_f32_16x16x32_bf16 v[58:61], v[236:239], v[224:227], v[58:61]
	v_mfma_f32_16x16x32_bf16 v[62:65], v[240:243], v[224:227], v[62:65]
	s_barrier
	v_add_u32_e32 v204, 0x0, v200
	v_add_u32_e32 v205, 0x0, v202
	ds_read_b128 v[130:133], v204 offset:0
	ds_read_b128 v[134:137], v204 offset:2048
	ds_read_b128 v[138:141], v204 offset:4096
	ds_read_b128 v[142:145], v204 offset:6144
	ds_read_b128 v[146:149], v205 offset:0
	ds_read_b128 v[150:153], v205 offset:2048
	ds_read_b128 v[154:157], v205 offset:4096
	ds_read_b128 v[158:161], v205 offset:6144
	v_add_u32_e32 v204, 0x0, v201
	v_add_u32_e32 v205, 0x0, v203
	ds_read_b128 v[212:215], v204 offset:0
	ds_read_b128 v[216:219], v204 offset:2048
	ds_read_b128 v[220:223], v204 offset:4096
	ds_read_b128 v[224:227], v204 offset:6144
	ds_read_b128 v[228:231], v205 offset:0
	ds_read_b128 v[232:235], v205 offset:2048
	ds_read_b128 v[236:239], v205 offset:4096
	ds_read_b128 v[240:243], v205 offset:6144
	s_add_u32 m0, s76, 0x18000
	s_nop 0
	global_load_lds_dwordx4 v196, s[68:69]
	s_add_u32 m0, s76, 0x1a000
	s_nop 0
	global_load_lds_dwordx4 v197, s[68:69]
	s_add_u32 m0, s76, 0x1c000
	s_nop 0
	global_load_lds_dwordx4 v198, s[68:69]
	s_add_u32 m0, s76, 0x1e000
	s_nop 0
	global_load_lds_dwordx4 v199, s[68:69]
	s_add_u32 m0, s76, 0x20000
	s_nop 0
	global_load_lds_dwordx4 v196, s[70:71]
	s_add_u32 m0, s76, 0x22000
	s_nop 0
	global_load_lds_dwordx4 v197, s[70:71]
	s_add_u32 s68, s68, 0x80
	s_addc_u32 s69, s69, 0
	s_add_u32 s70, s70, 0x80
	s_addc_u32 s71, s71, 0
	s_waitcnt vmcnt(6)
	s_waitcnt lgkmcnt(0)
	s_barrier
	v_mfma_f32_16x16x32_bf16 v[2:5], v[146:149], v[130:133], v[2:5]
	v_mfma_f32_16x16x32_bf16 v[6:9], v[150:153], v[130:133], v[6:9]
	v_mfma_f32_16x16x32_bf16 v[10:13], v[154:157], v[130:133], v[10:13]
	v_mfma_f32_16x16x32_bf16 v[14:17], v[158:161], v[130:133], v[14:17]
	v_mfma_f32_16x16x32_bf16 v[18:21], v[146:149], v[134:137], v[18:21]
	v_mfma_f32_16x16x32_bf16 v[22:25], v[150:153], v[134:137], v[22:25]
	v_mfma_f32_16x16x32_bf16 v[26:29], v[154:157], v[134:137], v[26:29]
	v_mfma_f32_16x16x32_bf16 v[30:33], v[158:161], v[134:137], v[30:33]
	v_mfma_f32_16x16x32_bf16 v[34:37], v[146:149], v[138:141], v[34:37]
	v_mfma_f32_16x16x32_bf16 v[38:41], v[150:153], v[138:141], v[38:41]
	v_mfma_f32_16x16x32_bf16 v[42:45], v[154:157], v[138:141], v[42:45]
	v_mfma_f32_16x16x32_bf16 v[46:49], v[158:161], v[138:141], v[46:49]
	v_mfma_f32_16x16x32_bf16 v[50:53], v[146:149], v[142:145], v[50:53]
	v_mfma_f32_16x16x32_bf16 v[54:57], v[150:153], v[142:145], v[54:57]
	v_mfma_f32_16x16x32_bf16 v[58:61], v[154:157], v[142:145], v[58:61]
	v_mfma_f32_16x16x32_bf16 v[62:65], v[158:161], v[142:145], v[62:65]
	v_mfma_f32_16x16x32_bf16 v[2:5], v[228:231], v[212:215], v[2:5]
	v_mfma_f32_16x16x32_bf16 v[6:9], v[232:235], v[212:215], v[6:9]
	v_mfma_f32_16x16x32_bf16 v[10:13], v[236:239], v[212:215], v[10:13]
	v_mfma_f32_16x16x32_bf16 v[14:17], v[240:243], v[212:215], v[14:17]
	v_mfma_f32_16x16x32_bf16 v[18:21], v[228:231], v[216:219], v[18:21]
	v_mfma_f32_16x16x32_bf16 v[22:25], v[232:235], v[216:219], v[22:25]
	v_mfma_f32_16x16x32_bf16 v[26:29], v[236:239], v[216:219], v[26:29]
	v_mfma_f32_16x16x32_bf16 v[30:33], v[240:243], v[216:219], v[30:33]
	v_mfma_f32_16x16x32_bf16 v[34:37], v[228:231], v[220:223], v[34:37]
	v_mfma_f32_16x16x32_bf16 v[38:41], v[232:235], v[220:223], v[38:41]
	v_mfma_f32_16x16x32_bf16 v[42:45], v[236:239], v[220:223], v[42:45]
	v_mfma_f32_16x16x32_bf16 v[46:49], v[240:243], v[220:223], v[46:49]
	v_mfma_f32_16x16x32_bf16 v[50:53], v[228:231], v[224:227], v[50:53]
	v_mfma_f32_16x16x32_bf16 v[54:57], v[232:235], v[224:227], v[54:57]
	v_mfma_f32_16x16x32_bf16 v[58:61], v[236:239], v[224:227], v[58:61]
	v_mfma_f32_16x16x32_bf16 v[62:65], v[240:243], v[224:227], v[62:65]
	s_barrier
	v_add_u32_e32 v204, 0xc000, v200
	v_add_u32_e32 v205, 0xc000, v202
	ds_read_b128 v[130:133], v204 offset:0
	ds_read_b128 v[134:137], v204 offset:2048
	ds_read_b128 v[138:141], v204 offset:4096
	ds_read_b128 v[142:145], v204 offset:6144
	ds_read_b128 v[146:149], v205 offset:0
	ds_read_b128 v[150:153], v205 offset:2048
	ds_read_b128 v[154:157], v205 offset:4096
	ds_read_b128 v[158:161], v205 offset:6144
	v_add_u32_e32 v204, 0xc000, v201
	v_add_u32_e32 v205, 0xc000, v203
	ds_read_b128 v[212:215], v204 offset:0
	ds_read_b128 v[216:219], v204 offset:2048
	ds_read_b128 v[220:223], v204 offset:4096
	ds_read_b128 v[224:227], v204 offset:6144
	ds_read_b128 v[228:231], v205 offset:0
	ds_read_b128 v[232:235], v205 offset:2048
	ds_read_b128 v[236:239], v205 offset:4096
	ds_read_b128 v[240:243], v205 offset:6144
	s_add_u32 m0, s76, 0x0
	s_nop 0
	global_load_lds_dwordx4 v196, s[68:69]
	s_add_u32 m0, s76, 0x2000
	s_nop 0
	global_load_lds_dwordx4 v197, s[68:69]
	s_add_u32 m0, s76, 0x4000
	s_nop 0
	global_load_lds_dwordx4 v198, s[68:69]
	s_add_u32 m0, s76, 0x6000
	s_nop 0
	global_load_lds_dwordx4 v199, s[68:69]
	s_add_u32 m0, s76, 0x8000
	s_nop 0
	global_load_lds_dwordx4 v196, s[70:71]
	s_add_u32 m0, s76, 0xa000
	s_nop 0
	global_load_lds_dwordx4 v197, s[70:71]
	s_add_u32 s68, s68, 0x80
	s_addc_u32 s69, s69, 0
	s_add_u32 s70, s70, 0x80
	s_addc_u32 s71, s71, 0
	s_waitcnt vmcnt(6)
	s_waitcnt lgkmcnt(0)
	s_barrier
	v_mfma_f32_16x16x32_bf16 v[2:5], v[146:149], v[130:133], v[2:5]
	v_mfma_f32_16x16x32_bf16 v[6:9], v[150:153], v[130:133], v[6:9]
	v_mfma_f32_16x16x32_bf16 v[10:13], v[154:157], v[130:133], v[10:13]
	v_mfma_f32_16x16x32_bf16 v[14:17], v[158:161], v[130:133], v[14:17]
	v_mfma_f32_16x16x32_bf16 v[18:21], v[146:149], v[134:137], v[18:21]
	v_mfma_f32_16x16x32_bf16 v[22:25], v[150:153], v[134:137], v[22:25]
	v_mfma_f32_16x16x32_bf16 v[26:29], v[154:157], v[134:137], v[26:29]
	v_mfma_f32_16x16x32_bf16 v[30:33], v[158:161], v[134:137], v[30:33]
	v_mfma_f32_16x16x32_bf16 v[34:37], v[146:149], v[138:141], v[34:37]
	v_mfma_f32_16x16x32_bf16 v[38:41], v[150:153], v[138:141], v[38:41]
	v_mfma_f32_16x16x32_bf16 v[42:45], v[154:157], v[138:141], v[42:45]
	v_mfma_f32_16x16x32_bf16 v[46:49], v[158:161], v[138:141], v[46:49]
	v_mfma_f32_16x16x32_bf16 v[50:53], v[146:149], v[142:145], v[50:53]
	v_mfma_f32_16x16x32_bf16 v[54:57], v[150:153], v[142:145], v[54:57]
	v_mfma_f32_16x16x32_bf16 v[58:61], v[154:157], v[142:145], v[58:61]
	v_mfma_f32_16x16x32_bf16 v[62:65], v[158:161], v[142:145], v[62:65]
	v_mfma_f32_16x16x32_bf16 v[2:5], v[228:231], v[212:215], v[2:5]
	v_mfma_f32_16x16x32_bf16 v[6:9], v[232:235], v[212:215], v[6:9]
	v_mfma_f32_16x16x32_bf16 v[10:13], v[236:239], v[212:215], v[10:13]
	v_mfma_f32_16x16x32_bf16 v[14:17], v[240:243], v[212:215], v[14:17]
	v_mfma_f32_16x16x32_bf16 v[18:21], v[228:231], v[216:219], v[18:21]
	v_mfma_f32_16x16x32_bf16 v[22:25], v[232:235], v[216:219], v[22:25]
	v_mfma_f32_16x16x32_bf16 v[26:29], v[236:239], v[216:219], v[26:29]
	v_mfma_f32_16x16x32_bf16 v[30:33], v[240:243], v[216:219], v[30:33]
	v_mfma_f32_16x16x32_bf16 v[34:37], v[228:231], v[220:223], v[34:37]
	v_mfma_f32_16x16x32_bf16 v[38:41], v[232:235], v[220:223], v[38:41]
	v_mfma_f32_16x16x32_bf16 v[42:45], v[236:239], v[220:223], v[42:45]
	v_mfma_f32_16x16x32_bf16 v[46:49], v[240:243], v[220:223], v[46:49]
	v_mfma_f32_16x16x32_bf16 v[50:53], v[228:231], v[224:227], v[50:53]
	v_mfma_f32_16x16x32_bf16 v[54:57], v[232:235], v[224:227], v[54:57]
	v_mfma_f32_16x16x32_bf16 v[58:61], v[236:239], v[224:227], v[58:61]
	v_mfma_f32_16x16x32_bf16 v[62:65], v[240:243], v[224:227], v[62:65]
	s_nop 7
	v_lshlrev_b32_e32 v212, 16, v174
	v_and_b32_e32 v213, 0xffff0000, v174
	v_lshlrev_b32_e32 v214, 16, v175
	v_and_b32_e32 v215, 0xffff0000, v175
	v_pk_fma_f32 v[66:67], v[2:3], v[212:213], v[66:67]
	v_pk_fma_f32 v[68:69], v[4:5], v[214:215], v[68:69]
	v_lshlrev_b32_e32 v216, 16, v176
	v_and_b32_e32 v217, 0xffff0000, v176
	v_lshlrev_b32_e32 v218, 16, v177
	v_and_b32_e32 v219, 0xffff0000, v177
	v_pk_fma_f32 v[70:71], v[6:7], v[216:217], v[70:71]
	v_pk_fma_f32 v[72:73], v[8:9], v[218:219], v[72:73]
	v_lshlrev_b32_e32 v220, 16, v178
	v_and_b32_e32 v221, 0xffff0000, v178
	v_lshlrev_b32_e32 v222, 16, v179
	v_and_b32_e32 v223, 0xffff0000, v179
	v_pk_fma_f32 v[74:75], v[10:11], v[220:221], v[74:75]
	v_pk_fma_f32 v[76:77], v[12:13], v[222:223], v[76:77]
	v_lshlrev_b32_e32 v224, 16, v180
	v_and_b32_e32 v225, 0xffff0000, v180
	v_lshlrev_b32_e32 v226, 16, v181
	v_and_b32_e32 v227, 0xffff0000, v181
	v_pk_fma_f32 v[78:79], v[14:15], v[224:225], v[78:79]
	v_pk_fma_f32 v[80:81], v[16:17], v[226:227], v[80:81]
	v_lshlrev_b32_e32 v228, 16, v182
	v_and_b32_e32 v229, 0xffff0000, v182
	v_lshlrev_b32_e32 v230, 16, v183
	v_and_b32_e32 v231, 0xffff0000, v183
	v_pk_fma_f32 v[82:83], v[18:19], v[228:229], v[82:83]
	v_pk_fma_f32 v[84:85], v[20:21], v[230:231], v[84:85]
	v_lshlrev_b32_e32 v232, 16, v184
	v_and_b32_e32 v233, 0xffff0000, v184
	v_lshlrev_b32_e32 v234, 16, v185
	v_and_b32_e32 v235, 0xffff0000, v185
	v_pk_fma_f32 v[86:87], v[22:23], v[232:233], v[86:87]
	v_pk_fma_f32 v[88:89], v[24:25], v[234:235], v[88:89]
	v_lshlrev_b32_e32 v236, 16, v186
	v_and_b32_e32 v237, 0xffff0000, v186
	v_lshlrev_b32_e32 v238, 16, v187
	v_and_b32_e32 v239, 0xffff0000, v187
	v_pk_fma_f32 v[90:91], v[26:27], v[236:237], v[90:91]
	v_pk_fma_f32 v[92:93], v[28:29], v[238:239], v[92:93]
	v_lshlrev_b32_e32 v240, 16, v188
	v_and_b32_e32 v241, 0xffff0000, v188
	v_lshlrev_b32_e32 v242, 16, v189
	v_and_b32_e32 v243, 0xffff0000, v189
	v_pk_fma_f32 v[94:95], v[30:31], v[240:241], v[94:95]
	v_pk_fma_f32 v[96:97], v[32:33], v[242:243], v[96:97]
	v_lshlrev_b32_e32 v212, 16, v190
	v_and_b32_e32 v213, 0xffff0000, v190
	v_lshlrev_b32_e32 v214, 16, v191
	v_and_b32_e32 v215, 0xffff0000, v191
	v_pk_fma_f32 v[98:99], v[34:35], v[212:213], v[98:99]
	v_pk_fma_f32 v[100:101], v[36:37], v[214:215], v[100:101]
	v_lshlrev_b32_e32 v216, 16, v192
	v_and_b32_e32 v217, 0xffff0000, v192
	v_lshlrev_b32_e32 v218, 16, v193
	v_and_b32_e32 v219, 0xffff0000, v193
	v_pk_fma_f32 v[102:103], v[38:39], v[216:217], v[102:103]
	v_pk_fma_f32 v[104:105], v[40:41], v[218:219], v[104:105]
	v_lshlrev_b32_e32 v220, 16, v244
	v_and_b32_e32 v221, 0xffff0000, v244
	v_lshlrev_b32_e32 v222, 16, v245
	v_and_b32_e32 v223, 0xffff0000, v245
	v_pk_fma_f32 v[106:107], v[42:43], v[220:221], v[106:107]
	v_pk_fma_f32 v[108:109], v[44:45], v[222:223], v[108:109]
	v_lshlrev_b32_e32 v224, 16, v246
	v_and_b32_e32 v225, 0xffff0000, v246
	v_lshlrev_b32_e32 v226, 16, v247
	v_and_b32_e32 v227, 0xffff0000, v247
	v_pk_fma_f32 v[110:111], v[46:47], v[224:225], v[110:111]
	v_pk_fma_f32 v[112:113], v[48:49], v[226:227], v[112:113]
	v_lshlrev_b32_e32 v228, 16, v248
	v_and_b32_e32 v229, 0xffff0000, v248
	v_lshlrev_b32_e32 v230, 16, v249
	v_and_b32_e32 v231, 0xffff0000, v249
	v_pk_fma_f32 v[114:115], v[50:51], v[228:229], v[114:115]
	v_pk_fma_f32 v[116:117], v[52:53], v[230:231], v[116:117]
	v_lshlrev_b32_e32 v232, 16, v250
	v_and_b32_e32 v233, 0xffff0000, v250
	v_lshlrev_b32_e32 v234, 16, v251
	v_and_b32_e32 v235, 0xffff0000, v251
	v_pk_fma_f32 v[118:119], v[54:55], v[232:233], v[118:119]
	v_pk_fma_f32 v[120:121], v[56:57], v[234:235], v[120:121]
	v_lshlrev_b32_e32 v236, 16, v166
	v_and_b32_e32 v237, 0xffff0000, v166
	v_lshlrev_b32_e32 v238, 16, v167
	v_and_b32_e32 v239, 0xffff0000, v167
	v_pk_fma_f32 v[122:123], v[58:59], v[236:237], v[122:123]
	v_pk_fma_f32 v[124:125], v[60:61], v[238:239], v[124:125]
	v_lshlrev_b32_e32 v240, 16, v194
	v_and_b32_e32 v241, 0xffff0000, v194
	v_lshlrev_b32_e32 v242, 16, v195
	v_and_b32_e32 v243, 0xffff0000, v195
	v_pk_fma_f32 v[126:127], v[62:63], v[240:241], v[126:127]
	v_pk_fma_f32 v[128:129], v[64:65], v[242:243], v[128:129]
	s_barrier
	v_add_u32_e32 v204, 0x18000, v200
	v_add_u32_e32 v205, 0x18000, v202
	ds_read_b128 v[130:133], v204 offset:0
	ds_read_b128 v[134:137], v204 offset:2048
	ds_read_b128 v[138:141], v204 offset:4096
	ds_read_b128 v[142:145], v204 offset:6144
	ds_read_b128 v[146:149], v205 offset:0
	ds_read_b128 v[150:153], v205 offset:2048
	ds_read_b128 v[154:157], v205 offset:4096
	ds_read_b128 v[158:161], v205 offset:6144
	v_add_u32_e32 v204, 0x18000, v201
	v_add_u32_e32 v205, 0x18000, v203
	ds_read_b128 v[212:215], v204 offset:0
	ds_read_b128 v[216:219], v204 offset:2048
	ds_read_b128 v[220:223], v204 offset:4096
	ds_read_b128 v[224:227], v204 offset:6144
	ds_read_b128 v[228:231], v205 offset:0
	ds_read_b128 v[232:235], v205 offset:2048
	ds_read_b128 v[236:239], v205 offset:4096
	ds_read_b128 v[240:243], v205 offset:6144
	s_add_u32 m0, s76, 0xc000
	s_nop 0
	global_load_lds_dwordx4 v196, s[68:69]
	s_add_u32 m0, s76, 0xe000
	s_nop 0
	global_load_lds_dwordx4 v197, s[68:69]
	s_add_u32 m0, s76, 0x10000
	s_nop 0
	global_load_lds_dwordx4 v198, s[68:69]
	s_add_u32 m0, s76, 0x12000
	s_nop 0
	global_load_lds_dwordx4 v199, s[68:69]
	s_add_u32 m0, s76, 0x14000
	s_nop 0
	global_load_lds_dwordx4 v196, s[70:71]
	s_add_u32 m0, s76, 0x16000
	s_nop 0
	global_load_lds_dwordx4 v197, s[70:71]
	s_add_u32 s68, s68, 0x80
	s_addc_u32 s69, s69, 0
	s_add_u32 s70, s70, 0x80
	s_addc_u32 s71, s71, 0
	global_load_dwordx2 v[174:175], v206, s[72:73] offset:0
	global_load_dwordx2 v[176:177], v206, s[72:73] offset:32
	global_load_dwordx2 v[178:179], v206, s[72:73] offset:64
	global_load_dwordx2 v[180:181], v206, s[72:73] offset:96
	global_load_dwordx2 v[182:183], v207, s[72:73] offset:0
	global_load_dwordx2 v[184:185], v207, s[72:73] offset:32
	s_waitcnt vmcnt(12)
	s_waitcnt lgkmcnt(0)
	s_barrier
	v_mfma_f32_16x16x32_bf16 v[2:5], v[146:149], v[130:133], 0
	v_mfma_f32_16x16x32_bf16 v[6:9], v[150:153], v[130:133], 0
	v_mfma_f32_16x16x32_bf16 v[10:13], v[154:157], v[130:133], 0
	v_mfma_f32_16x16x32_bf16 v[14:17], v[158:161], v[130:133], 0
	v_mfma_f32_16x16x32_bf16 v[18:21], v[146:149], v[134:137], 0
	v_mfma_f32_16x16x32_bf16 v[22:25], v[150:153], v[134:137], 0
	v_mfma_f32_16x16x32_bf16 v[26:29], v[154:157], v[134:137], 0
	v_mfma_f32_16x16x32_bf16 v[30:33], v[158:161], v[134:137], 0
	v_mfma_f32_16x16x32_bf16 v[34:37], v[146:149], v[138:141], 0
	v_mfma_f32_16x16x32_bf16 v[38:41], v[150:153], v[138:141], 0
	v_mfma_f32_16x16x32_bf16 v[42:45], v[154:157], v[138:141], 0
	v_mfma_f32_16x16x32_bf16 v[46:49], v[158:161], v[138:141], 0
	v_mfma_f32_16x16x32_bf16 v[50:53], v[146:149], v[142:145], 0
	v_mfma_f32_16x16x32_bf16 v[54:57], v[150:153], v[142:145], 0
	v_mfma_f32_16x16x32_bf16 v[58:61], v[154:157], v[142:145], 0
	v_mfma_f32_16x16x32_bf16 v[62:65], v[158:161], v[142:145], 0
	v_mfma_f32_16x16x32_bf16 v[2:5], v[228:231], v[212:215], v[2:5]
	v_mfma_f32_16x16x32_bf16 v[6:9], v[232:235], v[212:215], v[6:9]
	v_mfma_f32_16x16x32_bf16 v[10:13], v[236:239], v[212:215], v[10:13]
	v_mfma_f32_16x16x32_bf16 v[14:17], v[240:243], v[212:215], v[14:17]
	v_mfma_f32_16x16x32_bf16 v[18:21], v[228:231], v[216:219], v[18:21]
	v_mfma_f32_16x16x32_bf16 v[22:25], v[232:235], v[216:219], v[22:25]
	v_mfma_f32_16x16x32_bf16 v[26:29], v[236:239], v[216:219], v[26:29]
	v_mfma_f32_16x16x32_bf16 v[30:33], v[240:243], v[216:219], v[30:33]
	v_mfma_f32_16x16x32_bf16 v[34:37], v[228:231], v[220:223], v[34:37]
	v_mfma_f32_16x16x32_bf16 v[38:41], v[232:235], v[220:223], v[38:41]
	v_mfma_f32_16x16x32_bf16 v[42:45], v[236:239], v[220:223], v[42:45]
	v_mfma_f32_16x16x32_bf16 v[46:49], v[240:243], v[220:223], v[46:49]
	v_mfma_f32_16x16x32_bf16 v[50:53], v[228:231], v[224:227], v[50:53]
	v_mfma_f32_16x16x32_bf16 v[54:57], v[232:235], v[224:227], v[54:57]
	v_mfma_f32_16x16x32_bf16 v[58:61], v[236:239], v[224:227], v[58:61]
	v_mfma_f32_16x16x32_bf16 v[62:65], v[240:243], v[224:227], v[62:65]
	s_barrier
	v_add_u32_e32 v204, 0x0, v200
	v_add_u32_e32 v205, 0x0, v202
	ds_read_b128 v[130:133], v204 offset:0
	ds_read_b128 v[134:137], v204 offset:2048
	ds_read_b128 v[138:141], v204 offset:4096
	ds_read_b128 v[142:145], v204 offset:6144
	ds_read_b128 v[146:149], v205 offset:0
	ds_read_b128 v[150:153], v205 offset:2048
	ds_read_b128 v[154:157], v205 offset:4096
	ds_read_b128 v[158:161], v205 offset:6144
	v_add_u32_e32 v204, 0x0, v201
	v_add_u32_e32 v205, 0x0, v203
	ds_read_b128 v[212:215], v204 offset:0
	ds_read_b128 v[216:219], v204 offset:2048
	ds_read_b128 v[220:223], v204 offset:4096
	ds_read_b128 v[224:227], v204 offset:6144
	ds_read_b128 v[228:231], v205 offset:0
	ds_read_b128 v[232:235], v205 offset:2048
	ds_read_b128 v[236:239], v205 offset:4096
	ds_read_b128 v[240:243], v205 offset:6144
	s_add_u32 m0, s76, 0x18000
	s_nop 0
	global_load_lds_dwordx4 v196, s[68:69]
	s_add_u32 m0, s76, 0x1a000
	s_nop 0
	global_load_lds_dwordx4 v197, s[68:69]
	s_add_u32 m0, s76, 0x1c000
	s_nop 0
	global_load_lds_dwordx4 v198, s[68:69]
	s_add_u32 m0, s76, 0x1e000
	s_nop 0
	global_load_lds_dwordx4 v199, s[68:69]
	s_add_u32 m0, s76, 0x20000
	s_nop 0
	global_load_lds_dwordx4 v196, s[70:71]
	s_add_u32 m0, s76, 0x22000
	s_nop 0
	global_load_lds_dwordx4 v197, s[70:71]
	s_add_u32 s68, s68, 0x80
	s_addc_u32 s69, s69, 0
	s_add_u32 s70, s70, 0x80
	s_addc_u32 s71, s71, 0
	global_load_dwordx2 v[186:187], v207, s[72:73] offset:64
	global_load_dwordx2 v[188:189], v207, s[72:73] offset:96
	global_load_dwordx2 v[190:191], v208, s[72:73] offset:0
	global_load_dwordx2 v[192:193], v208, s[72:73] offset:32
	global_load_dwordx2 v[244:245], v208, s[72:73] offset:64
	global_load_dwordx2 v[246:247], v208, s[72:73] offset:96
	s_waitcnt vmcnt(18)
	s_waitcnt lgkmcnt(0)
	s_barrier
	v_mfma_f32_16x16x32_bf16 v[2:5], v[146:149], v[130:133], v[2:5]
	v_mfma_f32_16x16x32_bf16 v[6:9], v[150:153], v[130:133], v[6:9]
	v_mfma_f32_16x16x32_bf16 v[10:13], v[154:157], v[130:133], v[10:13]
	v_mfma_f32_16x16x32_bf16 v[14:17], v[158:161], v[130:133], v[14:17]
	v_mfma_f32_16x16x32_bf16 v[18:21], v[146:149], v[134:137], v[18:21]
	v_mfma_f32_16x16x32_bf16 v[22:25], v[150:153], v[134:137], v[22:25]
	v_mfma_f32_16x16x32_bf16 v[26:29], v[154:157], v[134:137], v[26:29]
	v_mfma_f32_16x16x32_bf16 v[30:33], v[158:161], v[134:137], v[30:33]
	v_mfma_f32_16x16x32_bf16 v[34:37], v[146:149], v[138:141], v[34:37]
	v_mfma_f32_16x16x32_bf16 v[38:41], v[150:153], v[138:141], v[38:41]
	v_mfma_f32_16x16x32_bf16 v[42:45], v[154:157], v[138:141], v[42:45]
	v_mfma_f32_16x16x32_bf16 v[46:49], v[158:161], v[138:141], v[46:49]
	v_mfma_f32_16x16x32_bf16 v[50:53], v[146:149], v[142:145], v[50:53]
	v_mfma_f32_16x16x32_bf16 v[54:57], v[150:153], v[142:145], v[54:57]
	v_mfma_f32_16x16x32_bf16 v[58:61], v[154:157], v[142:145], v[58:61]
	v_mfma_f32_16x16x32_bf16 v[62:65], v[158:161], v[142:145], v[62:65]
	v_mfma_f32_16x16x32_bf16 v[2:5], v[228:231], v[212:215], v[2:5]
	v_mfma_f32_16x16x32_bf16 v[6:9], v[232:235], v[212:215], v[6:9]
	v_mfma_f32_16x16x32_bf16 v[10:13], v[236:239], v[212:215], v[10:13]
	v_mfma_f32_16x16x32_bf16 v[14:17], v[240:243], v[212:215], v[14:17]
	v_mfma_f32_16x16x32_bf16 v[18:21], v[228:231], v[216:219], v[18:21]
	v_mfma_f32_16x16x32_bf16 v[22:25], v[232:235], v[216:219], v[22:25]
	v_mfma_f32_16x16x32_bf16 v[26:29], v[236:239], v[216:219], v[26:29]
	v_mfma_f32_16x16x32_bf16 v[30:33], v[240:243], v[216:219], v[30:33]
	v_mfma_f32_16x16x32_bf16 v[34:37], v[228:231], v[220:223], v[34:37]
	v_mfma_f32_16x16x32_bf16 v[38:41], v[232:235], v[220:223], v[38:41]
	v_mfma_f32_16x16x32_bf16 v[42:45], v[236:239], v[220:223], v[42:45]
	v_mfma_f32_16x16x32_bf16 v[46:49], v[240:243], v[220:223], v[46:49]
	v_mfma_f32_16x16x32_bf16 v[50:53], v[228:231], v[224:227], v[50:53]
	v_mfma_f32_16x16x32_bf16 v[54:57], v[232:235], v[224:227], v[54:57]
	v_mfma_f32_16x16x32_bf16 v[58:61], v[236:239], v[224:227], v[58:61]
	v_mfma_f32_16x16x32_bf16 v[62:65], v[240:243], v[224:227], v[62:65]
	s_barrier
	v_add_u32_e32 v204, 0xc000, v200
	v_add_u32_e32 v205, 0xc000, v202
	ds_read_b128 v[130:133], v204 offset:0
	ds_read_b128 v[134:137], v204 offset:2048
	ds_read_b128 v[138:141], v204 offset:4096
	ds_read_b128 v[142:145], v204 offset:6144
	ds_read_b128 v[146:149], v205 offset:0
	ds_read_b128 v[150:153], v205 offset:2048
	ds_read_b128 v[154:157], v205 offset:4096
	ds_read_b128 v[158:161], v205 offset:6144
	v_add_u32_e32 v204, 0xc000, v201
	v_add_u32_e32 v205, 0xc000, v203
	ds_read_b128 v[212:215], v204 offset:0
	ds_read_b128 v[216:219], v204 offset:2048
	ds_read_b128 v[220:223], v204 offset:4096
	ds_read_b128 v[224:227], v204 offset:6144
	ds_read_b128 v[228:231], v205 offset:0
	ds_read_b128 v[232:235], v205 offset:2048
	ds_read_b128 v[236:239], v205 offset:4096
	ds_read_b128 v[240:243], v205 offset:6144
	s_add_u32 m0, s76, 0x0
	s_nop 0
	global_load_lds_dwordx4 v196, s[68:69]
	s_add_u32 m0, s76, 0x2000
	s_nop 0
	global_load_lds_dwordx4 v197, s[68:69]
	s_add_u32 m0, s76, 0x4000
	s_nop 0
	global_load_lds_dwordx4 v198, s[68:69]
	s_add_u32 m0, s76, 0x6000
	s_nop 0
	global_load_lds_dwordx4 v199, s[68:69]
	s_add_u32 m0, s76, 0x8000
	s_nop 0
	global_load_lds_dwordx4 v196, s[70:71]
	s_add_u32 m0, s76, 0xa000
	s_nop 0
	global_load_lds_dwordx4 v197, s[70:71]
	s_add_u32 s68, s68, 0x80
	s_addc_u32 s69, s69, 0
	s_add_u32 s70, s70, 0x80
	s_addc_u32 s71, s71, 0
	global_load_dwordx2 v[248:249], v209, s[72:73] offset:0
	global_load_dwordx2 v[250:251], v209, s[72:73] offset:32
	global_load_dwordx2 v[166:167], v209, s[72:73] offset:64
	global_load_dwordx2 v[194:195], v209, s[72:73] offset:96
	s_add_u32 s72, s72, 0x800
	s_addc_u32 s73, s73, 0
	s_waitcnt vmcnt(16)
	s_waitcnt lgkmcnt(0)
	s_barrier
	v_mfma_f32_16x16x32_bf16 v[2:5], v[146:149], v[130:133], v[2:5]
	v_mfma_f32_16x16x32_bf16 v[6:9], v[150:153], v[130:133], v[6:9]
	v_mfma_f32_16x16x32_bf16 v[10:13], v[154:157], v[130:133], v[10:13]
	v_mfma_f32_16x16x32_bf16 v[14:17], v[158:161], v[130:133], v[14:17]
	v_mfma_f32_16x16x32_bf16 v[18:21], v[146:149], v[134:137], v[18:21]
	v_mfma_f32_16x16x32_bf16 v[22:25], v[150:153], v[134:137], v[22:25]
	v_mfma_f32_16x16x32_bf16 v[26:29], v[154:157], v[134:137], v[26:29]
	v_mfma_f32_16x16x32_bf16 v[30:33], v[158:161], v[134:137], v[30:33]
	v_mfma_f32_16x16x32_bf16 v[34:37], v[146:149], v[138:141], v[34:37]
	v_mfma_f32_16x16x32_bf16 v[38:41], v[150:153], v[138:141], v[38:41]
	v_mfma_f32_16x16x32_bf16 v[42:45], v[154:157], v[138:141], v[42:45]
	v_mfma_f32_16x16x32_bf16 v[46:49], v[158:161], v[138:141], v[46:49]
	v_mfma_f32_16x16x32_bf16 v[50:53], v[146:149], v[142:145], v[50:53]
	v_mfma_f32_16x16x32_bf16 v[54:57], v[150:153], v[142:145], v[54:57]
	v_mfma_f32_16x16x32_bf16 v[58:61], v[154:157], v[142:145], v[58:61]
	v_mfma_f32_16x16x32_bf16 v[62:65], v[158:161], v[142:145], v[62:65]
	v_mfma_f32_16x16x32_bf16 v[2:5], v[228:231], v[212:215], v[2:5]
	v_mfma_f32_16x16x32_bf16 v[6:9], v[232:235], v[212:215], v[6:9]
	v_mfma_f32_16x16x32_bf16 v[10:13], v[236:239], v[212:215], v[10:13]
	v_mfma_f32_16x16x32_bf16 v[14:17], v[240:243], v[212:215], v[14:17]
	v_mfma_f32_16x16x32_bf16 v[18:21], v[228:231], v[216:219], v[18:21]
	v_mfma_f32_16x16x32_bf16 v[22:25], v[232:235], v[216:219], v[22:25]
	v_mfma_f32_16x16x32_bf16 v[26:29], v[236:239], v[216:219], v[26:29]
	v_mfma_f32_16x16x32_bf16 v[30:33], v[240:243], v[216:219], v[30:33]
	v_mfma_f32_16x16x32_bf16 v[34:37], v[228:231], v[220:223], v[34:37]
	v_mfma_f32_16x16x32_bf16 v[38:41], v[232:235], v[220:223], v[38:41]
	v_mfma_f32_16x16x32_bf16 v[42:45], v[236:239], v[220:223], v[42:45]
	v_mfma_f32_16x16x32_bf16 v[46:49], v[240:243], v[220:223], v[46:49]
	v_mfma_f32_16x16x32_bf16 v[50:53], v[228:231], v[224:227], v[50:53]
	v_mfma_f32_16x16x32_bf16 v[54:57], v[232:235], v[224:227], v[54:57]
	v_mfma_f32_16x16x32_bf16 v[58:61], v[236:239], v[224:227], v[58:61]
	v_mfma_f32_16x16x32_bf16 v[62:65], v[240:243], v[224:227], v[62:65]
	s_barrier
	v_add_u32_e32 v204, 0x18000, v200
	v_add_u32_e32 v205, 0x18000, v202
	ds_read_b128 v[130:133], v204 offset:0
	ds_read_b128 v[134:137], v204 offset:2048
	ds_read_b128 v[138:141], v204 offset:4096
	ds_read_b128 v[142:145], v204 offset:6144
	ds_read_b128 v[146:149], v205 offset:0
	ds_read_b128 v[150:153], v205 offset:2048
	ds_read_b128 v[154:157], v205 offset:4096
	ds_read_b128 v[158:161], v205 offset:6144
	v_add_u32_e32 v204, 0x18000, v201
	v_add_u32_e32 v205, 0x18000, v203
	ds_read_b128 v[212:215], v204 offset:0
	ds_read_b128 v[216:219], v204 offset:2048
	ds_read_b128 v[220:223], v204 offset:4096
	ds_read_b128 v[224:227], v204 offset:6144
	ds_read_b128 v[228:231], v205 offset:0
	ds_read_b128 v[232:235], v205 offset:2048
	ds_read_b128 v[236:239], v205 offset:4096
	ds_read_b128 v[240:243], v205 offset:6144
	s_add_u32 m0, s76, 0xc000
	s_nop 0
	global_load_lds_dwordx4 v196, s[68:69]
	s_add_u32 m0, s76, 0xe000
	s_nop 0
	global_load_lds_dwordx4 v197, s[68:69]
	s_add_u32 m0, s76, 0x10000
	s_nop 0
	global_load_lds_dwordx4 v198, s[68:69]
	s_add_u32 m0, s76, 0x12000
	s_nop 0
	global_load_lds_dwordx4 v199, s[68:69]
	s_add_u32 m0, s76, 0x14000
	s_nop 0
	global_load_lds_dwordx4 v196, s[70:71]
	s_add_u32 m0, s76, 0x16000
	s_nop 0
	global_load_lds_dwordx4 v197, s[70:71]
	s_add_u32 s68, s68, 0x80
	s_addc_u32 s69, s69, 0
	s_add_u32 s70, s70, 0x80
	s_addc_u32 s71, s71, 0
	s_waitcnt vmcnt(10)
	s_waitcnt lgkmcnt(0)
	s_barrier
	v_mfma_f32_16x16x32_bf16 v[2:5], v[146:149], v[130:133], v[2:5]
	v_mfma_f32_16x16x32_bf16 v[6:9], v[150:153], v[130:133], v[6:9]
	v_mfma_f32_16x16x32_bf16 v[10:13], v[154:157], v[130:133], v[10:13]
	v_mfma_f32_16x16x32_bf16 v[14:17], v[158:161], v[130:133], v[14:17]
	v_mfma_f32_16x16x32_bf16 v[18:21], v[146:149], v[134:137], v[18:21]
	v_mfma_f32_16x16x32_bf16 v[22:25], v[150:153], v[134:137], v[22:25]
	v_mfma_f32_16x16x32_bf16 v[26:29], v[154:157], v[134:137], v[26:29]
	v_mfma_f32_16x16x32_bf16 v[30:33], v[158:161], v[134:137], v[30:33]
	v_mfma_f32_16x16x32_bf16 v[34:37], v[146:149], v[138:141], v[34:37]
	v_mfma_f32_16x16x32_bf16 v[38:41], v[150:153], v[138:141], v[38:41]
	v_mfma_f32_16x16x32_bf16 v[42:45], v[154:157], v[138:141], v[42:45]
	v_mfma_f32_16x16x32_bf16 v[46:49], v[158:161], v[138:141], v[46:49]
	v_mfma_f32_16x16x32_bf16 v[50:53], v[146:149], v[142:145], v[50:53]
	v_mfma_f32_16x16x32_bf16 v[54:57], v[150:153], v[142:145], v[54:57]
	v_mfma_f32_16x16x32_bf16 v[58:61], v[154:157], v[142:145], v[58:61]
	v_mfma_f32_16x16x32_bf16 v[62:65], v[158:161], v[142:145], v[62:65]
	v_mfma_f32_16x16x32_bf16 v[2:5], v[228:231], v[212:215], v[2:5]
	v_mfma_f32_16x16x32_bf16 v[6:9], v[232:235], v[212:215], v[6:9]
	v_mfma_f32_16x16x32_bf16 v[10:13], v[236:239], v[212:215], v[10:13]
	v_mfma_f32_16x16x32_bf16 v[14:17], v[240:243], v[212:215], v[14:17]
	v_mfma_f32_16x16x32_bf16 v[18:21], v[228:231], v[216:219], v[18:21]
	v_mfma_f32_16x16x32_bf16 v[22:25], v[232:235], v[216:219], v[22:25]
	v_mfma_f32_16x16x32_bf16 v[26:29], v[236:239], v[216:219], v[26:29]
	v_mfma_f32_16x16x32_bf16 v[30:33], v[240:243], v[216:219], v[30:33]
	v_mfma_f32_16x16x32_bf16 v[34:37], v[228:231], v[220:223], v[34:37]
	v_mfma_f32_16x16x32_bf16 v[38:41], v[232:235], v[220:223], v[38:41]
	v_mfma_f32_16x16x32_bf16 v[42:45], v[236:239], v[220:223], v[42:45]
	v_mfma_f32_16x16x32_bf16 v[46:49], v[240:243], v[220:223], v[46:49]
	v_mfma_f32_16x16x32_bf16 v[50:53], v[228:231], v[224:227], v[50:53]
	v_mfma_f32_16x16x32_bf16 v[54:57], v[232:235], v[224:227], v[54:57]
	v_mfma_f32_16x16x32_bf16 v[58:61], v[236:239], v[224:227], v[58:61]
	v_mfma_f32_16x16x32_bf16 v[62:65], v[240:243], v[224:227], v[62:65]
	s_barrier
	v_add_u32_e32 v204, 0x0, v200
	v_add_u32_e32 v205, 0x0, v202
	ds_read_b128 v[130:133], v204 offset:0
	ds_read_b128 v[134:137], v204 offset:2048
	ds_read_b128 v[138:141], v204 offset:4096
	ds_read_b128 v[142:145], v204 offset:6144
	ds_read_b128 v[146:149], v205 offset:0
	ds_read_b128 v[150:153], v205 offset:2048
	ds_read_b128 v[154:157], v205 offset:4096
	ds_read_b128 v[158:161], v205 offset:6144
	v_add_u32_e32 v204, 0x0, v201
	v_add_u32_e32 v205, 0x0, v203
	ds_read_b128 v[212:215], v204 offset:0
	ds_read_b128 v[216:219], v204 offset:2048
	ds_read_b128 v[220:223], v204 offset:4096
	ds_read_b128 v[224:227], v204 offset:6144
	ds_read_b128 v[228:231], v205 offset:0
	ds_read_b128 v[232:235], v205 offset:2048
	ds_read_b128 v[236:239], v205 offset:4096
	ds_read_b128 v[240:243], v205 offset:6144
	s_add_u32 m0, s76, 0x18000
	s_nop 0
	global_load_lds_dwordx4 v196, s[68:69]
	s_add_u32 m0, s76, 0x1a000
	s_nop 0
	global_load_lds_dwordx4 v197, s[68:69]
	s_add_u32 m0, s76, 0x1c000
	s_nop 0
	global_load_lds_dwordx4 v198, s[68:69]
	s_add_u32 m0, s76, 0x1e000
	s_nop 0
	global_load_lds_dwordx4 v199, s[68:69]
	s_add_u32 m0, s76, 0x20000
	s_nop 0
	global_load_lds_dwordx4 v196, s[70:71]
	s_add_u32 m0, s76, 0x22000
	s_nop 0
	global_load_lds_dwordx4 v197, s[70:71]
	s_add_u32 s68, s68, 0x80
	s_addc_u32 s69, s69, 0
	s_add_u32 s70, s70, 0x80
	s_addc_u32 s71, s71, 0
	s_waitcnt vmcnt(6)
	s_waitcnt lgkmcnt(0)
	s_barrier
	v_mfma_f32_16x16x32_bf16 v[2:5], v[146:149], v[130:133], v[2:5]
	v_mfma_f32_16x16x32_bf16 v[6:9], v[150:153], v[130:133], v[6:9]
	v_mfma_f32_16x16x32_bf16 v[10:13], v[154:157], v[130:133], v[10:13]
	v_mfma_f32_16x16x32_bf16 v[14:17], v[158:161], v[130:133], v[14:17]
	v_mfma_f32_16x16x32_bf16 v[18:21], v[146:149], v[134:137], v[18:21]
	v_mfma_f32_16x16x32_bf16 v[22:25], v[150:153], v[134:137], v[22:25]
	v_mfma_f32_16x16x32_bf16 v[26:29], v[154:157], v[134:137], v[26:29]
	v_mfma_f32_16x16x32_bf16 v[30:33], v[158:161], v[134:137], v[30:33]
	v_mfma_f32_16x16x32_bf16 v[34:37], v[146:149], v[138:141], v[34:37]
	v_mfma_f32_16x16x32_bf16 v[38:41], v[150:153], v[138:141], v[38:41]
	v_mfma_f32_16x16x32_bf16 v[42:45], v[154:157], v[138:141], v[42:45]
	v_mfma_f32_16x16x32_bf16 v[46:49], v[158:161], v[138:141], v[46:49]
	v_mfma_f32_16x16x32_bf16 v[50:53], v[146:149], v[142:145], v[50:53]
	v_mfma_f32_16x16x32_bf16 v[54:57], v[150:153], v[142:145], v[54:57]
	v_mfma_f32_16x16x32_bf16 v[58:61], v[154:157], v[142:145], v[58:61]
	v_mfma_f32_16x16x32_bf16 v[62:65], v[158:161], v[142:145], v[62:65]
	v_mfma_f32_16x16x32_bf16 v[2:5], v[228:231], v[212:215], v[2:5]
	v_mfma_f32_16x16x32_bf16 v[6:9], v[232:235], v[212:215], v[6:9]
	v_mfma_f32_16x16x32_bf16 v[10:13], v[236:239], v[212:215], v[10:13]
	v_mfma_f32_16x16x32_bf16 v[14:17], v[240:243], v[212:215], v[14:17]
	v_mfma_f32_16x16x32_bf16 v[18:21], v[228:231], v[216:219], v[18:21]
	v_mfma_f32_16x16x32_bf16 v[22:25], v[232:235], v[216:219], v[22:25]
	v_mfma_f32_16x16x32_bf16 v[26:29], v[236:239], v[216:219], v[26:29]
	v_mfma_f32_16x16x32_bf16 v[30:33], v[240:243], v[216:219], v[30:33]
	v_mfma_f32_16x16x32_bf16 v[34:37], v[228:231], v[220:223], v[34:37]
	v_mfma_f32_16x16x32_bf16 v[38:41], v[232:235], v[220:223], v[38:41]
	v_mfma_f32_16x16x32_bf16 v[42:45], v[236:239], v[220:223], v[42:45]
	v_mfma_f32_16x16x32_bf16 v[46:49], v[240:243], v[220:223], v[46:49]
	v_mfma_f32_16x16x32_bf16 v[50:53], v[228:231], v[224:227], v[50:53]
	v_mfma_f32_16x16x32_bf16 v[54:57], v[232:235], v[224:227], v[54:57]
	v_mfma_f32_16x16x32_bf16 v[58:61], v[236:239], v[224:227], v[58:61]
	v_mfma_f32_16x16x32_bf16 v[62:65], v[240:243], v[224:227], v[62:65]
	s_barrier
	v_add_u32_e32 v204, 0xc000, v200
	v_add_u32_e32 v205, 0xc000, v202
	ds_read_b128 v[130:133], v204 offset:0
	ds_read_b128 v[134:137], v204 offset:2048
	ds_read_b128 v[138:141], v204 offset:4096
	ds_read_b128 v[142:145], v204 offset:6144
	ds_read_b128 v[146:149], v205 offset:0
	ds_read_b128 v[150:153], v205 offset:2048
	ds_read_b128 v[154:157], v205 offset:4096
	ds_read_b128 v[158:161], v205 offset:6144
	v_add_u32_e32 v204, 0xc000, v201
	v_add_u32_e32 v205, 0xc000, v203
	ds_read_b128 v[212:215], v204 offset:0
	ds_read_b128 v[216:219], v204 offset:2048
	ds_read_b128 v[220:223], v204 offset:4096
	ds_read_b128 v[224:227], v204 offset:6144
	ds_read_b128 v[228:231], v205 offset:0
	ds_read_b128 v[232:235], v205 offset:2048
	ds_read_b128 v[236:239], v205 offset:4096
	ds_read_b128 v[240:243], v205 offset:6144
	s_add_u32 m0, s76, 0x0
	s_nop 0
	global_load_lds_dwordx4 v196, s[68:69]
	s_add_u32 m0, s76, 0x2000
	s_nop 0
	global_load_lds_dwordx4 v197, s[68:69]
	s_add_u32 m0, s76, 0x4000
	s_nop 0
	global_load_lds_dwordx4 v198, s[68:69]
	s_add_u32 m0, s76, 0x6000
	s_nop 0
	global_load_lds_dwordx4 v199, s[68:69]
	s_add_u32 m0, s76, 0x8000
	s_nop 0
	global_load_lds_dwordx4 v196, s[70:71]
	s_add_u32 m0, s76, 0xa000
	s_nop 0
	global_load_lds_dwordx4 v197, s[70:71]
	s_add_u32 s68, s68, 0x80
	s_addc_u32 s69, s69, 0
	s_add_u32 s70, s70, 0x80
	s_addc_u32 s71, s71, 0
	s_waitcnt vmcnt(6)
	s_waitcnt lgkmcnt(0)
	s_barrier
	v_mfma_f32_16x16x32_bf16 v[2:5], v[146:149], v[130:133], v[2:5]
	v_mfma_f32_16x16x32_bf16 v[6:9], v[150:153], v[130:133], v[6:9]
	v_mfma_f32_16x16x32_bf16 v[10:13], v[154:157], v[130:133], v[10:13]
	v_mfma_f32_16x16x32_bf16 v[14:17], v[158:161], v[130:133], v[14:17]
	v_mfma_f32_16x16x32_bf16 v[18:21], v[146:149], v[134:137], v[18:21]
	v_mfma_f32_16x16x32_bf16 v[22:25], v[150:153], v[134:137], v[22:25]
	v_mfma_f32_16x16x32_bf16 v[26:29], v[154:157], v[134:137], v[26:29]
	v_mfma_f32_16x16x32_bf16 v[30:33], v[158:161], v[134:137], v[30:33]
	v_mfma_f32_16x16x32_bf16 v[34:37], v[146:149], v[138:141], v[34:37]
	v_mfma_f32_16x16x32_bf16 v[38:41], v[150:153], v[138:141], v[38:41]
	v_mfma_f32_16x16x32_bf16 v[42:45], v[154:157], v[138:141], v[42:45]
	v_mfma_f32_16x16x32_bf16 v[46:49], v[158:161], v[138:141], v[46:49]
	v_mfma_f32_16x16x32_bf16 v[50:53], v[146:149], v[142:145], v[50:53]
	v_mfma_f32_16x16x32_bf16 v[54:57], v[150:153], v[142:145], v[54:57]
	v_mfma_f32_16x16x32_bf16 v[58:61], v[154:157], v[142:145], v[58:61]
	v_mfma_f32_16x16x32_bf16 v[62:65], v[158:161], v[142:145], v[62:65]
	v_mfma_f32_16x16x32_bf16 v[2:5], v[228:231], v[212:215], v[2:5]
	v_mfma_f32_16x16x32_bf16 v[6:9], v[232:235], v[212:215], v[6:9]
	v_mfma_f32_16x16x32_bf16 v[10:13], v[236:239], v[212:215], v[10:13]
	v_mfma_f32_16x16x32_bf16 v[14:17], v[240:243], v[212:215], v[14:17]
	v_mfma_f32_16x16x32_bf16 v[18:21], v[228:231], v[216:219], v[18:21]
	v_mfma_f32_16x16x32_bf16 v[22:25], v[232:235], v[216:219], v[22:25]
	v_mfma_f32_16x16x32_bf16 v[26:29], v[236:239], v[216:219], v[26:29]
	v_mfma_f32_16x16x32_bf16 v[30:33], v[240:243], v[216:219], v[30:33]
	v_mfma_f32_16x16x32_bf16 v[34:37], v[228:231], v[220:223], v[34:37]
	v_mfma_f32_16x16x32_bf16 v[38:41], v[232:235], v[220:223], v[38:41]
	v_mfma_f32_16x16x32_bf16 v[42:45], v[236:239], v[220:223], v[42:45]
	v_mfma_f32_16x16x32_bf16 v[46:49], v[240:243], v[220:223], v[46:49]
	v_mfma_f32_16x16x32_bf16 v[50:53], v[228:231], v[224:227], v[50:53]
	v_mfma_f32_16x16x32_bf16 v[54:57], v[232:235], v[224:227], v[54:57]
	v_mfma_f32_16x16x32_bf16 v[58:61], v[236:239], v[224:227], v[58:61]
	v_mfma_f32_16x16x32_bf16 v[62:65], v[240:243], v[224:227], v[62:65]
	s_barrier
	v_add_u32_e32 v204, 0x18000, v200
	v_add_u32_e32 v205, 0x18000, v202
	ds_read_b128 v[130:133], v204 offset:0
	ds_read_b128 v[134:137], v204 offset:2048
	ds_read_b128 v[138:141], v204 offset:4096
	ds_read_b128 v[142:145], v204 offset:6144
	ds_read_b128 v[146:149], v205 offset:0
	ds_read_b128 v[150:153], v205 offset:2048
	ds_read_b128 v[154:157], v205 offset:4096
	ds_read_b128 v[158:161], v205 offset:6144
	v_add_u32_e32 v204, 0x18000, v201
	v_add_u32_e32 v205, 0x18000, v203
	ds_read_b128 v[212:215], v204 offset:0
	ds_read_b128 v[216:219], v204 offset:2048
	ds_read_b128 v[220:223], v204 offset:4096
	ds_read_b128 v[224:227], v204 offset:6144
	ds_read_b128 v[228:231], v205 offset:0
	ds_read_b128 v[232:235], v205 offset:2048
	ds_read_b128 v[236:239], v205 offset:4096
	ds_read_b128 v[240:243], v205 offset:6144
	s_add_u32 m0, s76, 0xc000
	s_nop 0
	global_load_lds_dwordx4 v196, s[68:69]
	s_add_u32 m0, s76, 0xe000
	s_nop 0
	global_load_lds_dwordx4 v197, s[68:69]
	s_add_u32 m0, s76, 0x10000
	s_nop 0
	global_load_lds_dwordx4 v198, s[68:69]
	s_add_u32 m0, s76, 0x12000
	s_nop 0
	global_load_lds_dwordx4 v199, s[68:69]
	s_add_u32 m0, s76, 0x14000
	s_nop 0
	global_load_lds_dwordx4 v196, s[70:71]
	s_add_u32 m0, s76, 0x16000
	s_nop 0
	global_load_lds_dwordx4 v197, s[70:71]
	s_add_u32 s68, s68, 0x80
	s_addc_u32 s69, s69, 0
	s_add_u32 s70, s70, 0x80
	s_addc_u32 s71, s71, 0
	s_waitcnt vmcnt(6)
	s_waitcnt lgkmcnt(0)
	s_barrier
	v_mfma_f32_16x16x32_bf16 v[2:5], v[146:149], v[130:133], v[2:5]
	v_mfma_f32_16x16x32_bf16 v[6:9], v[150:153], v[130:133], v[6:9]
	v_mfma_f32_16x16x32_bf16 v[10:13], v[154:157], v[130:133], v[10:13]
	v_mfma_f32_16x16x32_bf16 v[14:17], v[158:161], v[130:133], v[14:17]
	v_mfma_f32_16x16x32_bf16 v[18:21], v[146:149], v[134:137], v[18:21]
	v_mfma_f32_16x16x32_bf16 v[22:25], v[150:153], v[134:137], v[22:25]
	v_mfma_f32_16x16x32_bf16 v[26:29], v[154:157], v[134:137], v[26:29]
	v_mfma_f32_16x16x32_bf16 v[30:33], v[158:161], v[134:137], v[30:33]
	v_mfma_f32_16x16x32_bf16 v[34:37], v[146:149], v[138:141], v[34:37]
	v_mfma_f32_16x16x32_bf16 v[38:41], v[150:153], v[138:141], v[38:41]
	v_mfma_f32_16x16x32_bf16 v[42:45], v[154:157], v[138:141], v[42:45]
	v_mfma_f32_16x16x32_bf16 v[46:49], v[158:161], v[138:141], v[46:49]
	v_mfma_f32_16x16x32_bf16 v[50:53], v[146:149], v[142:145], v[50:53]
	v_mfma_f32_16x16x32_bf16 v[54:57], v[150:153], v[142:145], v[54:57]
	v_mfma_f32_16x16x32_bf16 v[58:61], v[154:157], v[142:145], v[58:61]
	v_mfma_f32_16x16x32_bf16 v[62:65], v[158:161], v[142:145], v[62:65]
	v_mfma_f32_16x16x32_bf16 v[2:5], v[228:231], v[212:215], v[2:5]
	v_mfma_f32_16x16x32_bf16 v[6:9], v[232:235], v[212:215], v[6:9]
	v_mfma_f32_16x16x32_bf16 v[10:13], v[236:239], v[212:215], v[10:13]
	v_mfma_f32_16x16x32_bf16 v[14:17], v[240:243], v[212:215], v[14:17]
	v_mfma_f32_16x16x32_bf16 v[18:21], v[228:231], v[216:219], v[18:21]
	v_mfma_f32_16x16x32_bf16 v[22:25], v[232:235], v[216:219], v[22:25]
	v_mfma_f32_16x16x32_bf16 v[26:29], v[236:239], v[216:219], v[26:29]
	v_mfma_f32_16x16x32_bf16 v[30:33], v[240:243], v[216:219], v[30:33]
	v_mfma_f32_16x16x32_bf16 v[34:37], v[228:231], v[220:223], v[34:37]
	v_mfma_f32_16x16x32_bf16 v[38:41], v[232:235], v[220:223], v[38:41]
	v_mfma_f32_16x16x32_bf16 v[42:45], v[236:239], v[220:223], v[42:45]
	v_mfma_f32_16x16x32_bf16 v[46:49], v[240:243], v[220:223], v[46:49]
	v_mfma_f32_16x16x32_bf16 v[50:53], v[228:231], v[224:227], v[50:53]
	v_mfma_f32_16x16x32_bf16 v[54:57], v[232:235], v[224:227], v[54:57]
	v_mfma_f32_16x16x32_bf16 v[58:61], v[236:239], v[224:227], v[58:61]
	v_mfma_f32_16x16x32_bf16 v[62:65], v[240:243], v[224:227], v[62:65]
	s_barrier
	v_add_u32_e32 v204, 0x0, v200
	v_add_u32_e32 v205, 0x0, v202
	ds_read_b128 v[130:133], v204 offset:0
	ds_read_b128 v[134:137], v204 offset:2048
	ds_read_b128 v[138:141], v204 offset:4096
	ds_read_b128 v[142:145], v204 offset:6144
	ds_read_b128 v[146:149], v205 offset:0
	ds_read_b128 v[150:153], v205 offset:2048
	ds_read_b128 v[154:157], v205 offset:4096
	ds_read_b128 v[158:161], v205 offset:6144
	v_add_u32_e32 v204, 0x0, v201
	v_add_u32_e32 v205, 0x0, v203
	ds_read_b128 v[212:215], v204 offset:0
	ds_read_b128 v[216:219], v204 offset:2048
	ds_read_b128 v[220:223], v204 offset:4096
	ds_read_b128 v[224:227], v204 offset:6144
	ds_read_b128 v[228:231], v205 offset:0
	ds_read_b128 v[232:235], v205 offset:2048
	ds_read_b128 v[236:239], v205 offset:4096
	ds_read_b128 v[240:243], v205 offset:6144
	s_add_u32 m0, s76, 0x18000
	s_nop 0
	global_load_lds_dwordx4 v196, s[68:69]
	s_add_u32 m0, s76, 0x1a000
	s_nop 0
	global_load_lds_dwordx4 v197, s[68:69]
	s_add_u32 m0, s76, 0x1c000
	s_nop 0
	global_load_lds_dwordx4 v198, s[68:69]
	s_add_u32 m0, s76, 0x1e000
	s_nop 0
	global_load_lds_dwordx4 v199, s[68:69]
	s_add_u32 m0, s76, 0x20000
	s_nop 0
	global_load_lds_dwordx4 v196, s[70:71]
	s_add_u32 m0, s76, 0x22000
	s_nop 0
	global_load_lds_dwordx4 v197, s[70:71]
	s_add_u32 s68, s68, 0x80
	s_addc_u32 s69, s69, 0
	s_add_u32 s70, s70, 0x80
	s_addc_u32 s71, s71, 0
	s_waitcnt vmcnt(6)
	s_waitcnt lgkmcnt(0)
	s_barrier
	v_mfma_f32_16x16x32_bf16 v[2:5], v[146:149], v[130:133], v[2:5]
	v_mfma_f32_16x16x32_bf16 v[6:9], v[150:153], v[130:133], v[6:9]
	v_mfma_f32_16x16x32_bf16 v[10:13], v[154:157], v[130:133], v[10:13]
	v_mfma_f32_16x16x32_bf16 v[14:17], v[158:161], v[130:133], v[14:17]
	v_mfma_f32_16x16x32_bf16 v[18:21], v[146:149], v[134:137], v[18:21]
	v_mfma_f32_16x16x32_bf16 v[22:25], v[150:153], v[134:137], v[22:25]
	v_mfma_f32_16x16x32_bf16 v[26:29], v[154:157], v[134:137], v[26:29]
	v_mfma_f32_16x16x32_bf16 v[30:33], v[158:161], v[134:137], v[30:33]
	v_mfma_f32_16x16x32_bf16 v[34:37], v[146:149], v[138:141], v[34:37]
	v_mfma_f32_16x16x32_bf16 v[38:41], v[150:153], v[138:141], v[38:41]
	v_mfma_f32_16x16x32_bf16 v[42:45], v[154:157], v[138:141], v[42:45]
	v_mfma_f32_16x16x32_bf16 v[46:49], v[158:161], v[138:141], v[46:49]
	v_mfma_f32_16x16x32_bf16 v[50:53], v[146:149], v[142:145], v[50:53]
	v_mfma_f32_16x16x32_bf16 v[54:57], v[150:153], v[142:145], v[54:57]
	v_mfma_f32_16x16x32_bf16 v[58:61], v[154:157], v[142:145], v[58:61]
	v_mfma_f32_16x16x32_bf16 v[62:65], v[158:161], v[142:145], v[62:65]
	v_mfma_f32_16x16x32_bf16 v[2:5], v[228:231], v[212:215], v[2:5]
	v_mfma_f32_16x16x32_bf16 v[6:9], v[232:235], v[212:215], v[6:9]
	v_mfma_f32_16x16x32_bf16 v[10:13], v[236:239], v[212:215], v[10:13]
	v_mfma_f32_16x16x32_bf16 v[14:17], v[240:243], v[212:215], v[14:17]
	v_mfma_f32_16x16x32_bf16 v[18:21], v[228:231], v[216:219], v[18:21]
	v_mfma_f32_16x16x32_bf16 v[22:25], v[232:235], v[216:219], v[22:25]
	v_mfma_f32_16x16x32_bf16 v[26:29], v[236:239], v[216:219], v[26:29]
	v_mfma_f32_16x16x32_bf16 v[30:33], v[240:243], v[216:219], v[30:33]
	v_mfma_f32_16x16x32_bf16 v[34:37], v[228:231], v[220:223], v[34:37]
	v_mfma_f32_16x16x32_bf16 v[38:41], v[232:235], v[220:223], v[38:41]
	v_mfma_f32_16x16x32_bf16 v[42:45], v[236:239], v[220:223], v[42:45]
	v_mfma_f32_16x16x32_bf16 v[46:49], v[240:243], v[220:223], v[46:49]
	v_mfma_f32_16x16x32_bf16 v[50:53], v[228:231], v[224:227], v[50:53]
	v_mfma_f32_16x16x32_bf16 v[54:57], v[232:235], v[224:227], v[54:57]
	v_mfma_f32_16x16x32_bf16 v[58:61], v[236:239], v[224:227], v[58:61]
	v_mfma_f32_16x16x32_bf16 v[62:65], v[240:243], v[224:227], v[62:65]
	s_nop 7
	v_lshlrev_b32_e32 v212, 16, v174
	v_and_b32_e32 v213, 0xffff0000, v174
	v_lshlrev_b32_e32 v214, 16, v175
	v_and_b32_e32 v215, 0xffff0000, v175
	v_pk_fma_f32 v[66:67], v[2:3], v[212:213], v[66:67]
	v_pk_fma_f32 v[68:69], v[4:5], v[214:215], v[68:69]
	v_lshlrev_b32_e32 v216, 16, v176
	v_and_b32_e32 v217, 0xffff0000, v176
	v_lshlrev_b32_e32 v218, 16, v177
	v_and_b32_e32 v219, 0xffff0000, v177
	v_pk_fma_f32 v[70:71], v[6:7], v[216:217], v[70:71]
	v_pk_fma_f32 v[72:73], v[8:9], v[218:219], v[72:73]
	v_lshlrev_b32_e32 v220, 16, v178
	v_and_b32_e32 v221, 0xffff0000, v178
	v_lshlrev_b32_e32 v222, 16, v179
	v_and_b32_e32 v223, 0xffff0000, v179
	v_pk_fma_f32 v[74:75], v[10:11], v[220:221], v[74:75]
	v_pk_fma_f32 v[76:77], v[12:13], v[222:223], v[76:77]
	v_lshlrev_b32_e32 v224, 16, v180
	v_and_b32_e32 v225, 0xffff0000, v180
	v_lshlrev_b32_e32 v226, 16, v181
	v_and_b32_e32 v227, 0xffff0000, v181
	v_pk_fma_f32 v[78:79], v[14:15], v[224:225], v[78:79]
	v_pk_fma_f32 v[80:81], v[16:17], v[226:227], v[80:81]
	v_lshlrev_b32_e32 v228, 16, v182
	v_and_b32_e32 v229, 0xffff0000, v182
	v_lshlrev_b32_e32 v230, 16, v183
	v_and_b32_e32 v231, 0xffff0000, v183
	v_pk_fma_f32 v[82:83], v[18:19], v[228:229], v[82:83]
	v_pk_fma_f32 v[84:85], v[20:21], v[230:231], v[84:85]
	v_lshlrev_b32_e32 v232, 16, v184
	v_and_b32_e32 v233, 0xffff0000, v184
	v_lshlrev_b32_e32 v234, 16, v185
	v_and_b32_e32 v235, 0xffff0000, v185
	v_pk_fma_f32 v[86:87], v[22:23], v[232:233], v[86:87]
	v_pk_fma_f32 v[88:89], v[24:25], v[234:235], v[88:89]
	v_lshlrev_b32_e32 v236, 16, v186
	v_and_b32_e32 v237, 0xffff0000, v186
	v_lshlrev_b32_e32 v238, 16, v187
	v_and_b32_e32 v239, 0xffff0000, v187
	v_pk_fma_f32 v[90:91], v[26:27], v[236:237], v[90:91]
	v_pk_fma_f32 v[92:93], v[28:29], v[238:239], v[92:93]
	v_lshlrev_b32_e32 v240, 16, v188
	v_and_b32_e32 v241, 0xffff0000, v188
	v_lshlrev_b32_e32 v242, 16, v189
	v_and_b32_e32 v243, 0xffff0000, v189
	v_pk_fma_f32 v[94:95], v[30:31], v[240:241], v[94:95]
	v_pk_fma_f32 v[96:97], v[32:33], v[242:243], v[96:97]
	v_lshlrev_b32_e32 v212, 16, v190
	v_and_b32_e32 v213, 0xffff0000, v190
	v_lshlrev_b32_e32 v214, 16, v191
	v_and_b32_e32 v215, 0xffff0000, v191
	v_pk_fma_f32 v[98:99], v[34:35], v[212:213], v[98:99]
	v_pk_fma_f32 v[100:101], v[36:37], v[214:215], v[100:101]
	v_lshlrev_b32_e32 v216, 16, v192
	v_and_b32_e32 v217, 0xffff0000, v192
	v_lshlrev_b32_e32 v218, 16, v193
	v_and_b32_e32 v219, 0xffff0000, v193
	v_pk_fma_f32 v[102:103], v[38:39], v[216:217], v[102:103]
	v_pk_fma_f32 v[104:105], v[40:41], v[218:219], v[104:105]
	v_lshlrev_b32_e32 v220, 16, v244
	v_and_b32_e32 v221, 0xffff0000, v244
	v_lshlrev_b32_e32 v222, 16, v245
	v_and_b32_e32 v223, 0xffff0000, v245
	v_pk_fma_f32 v[106:107], v[42:43], v[220:221], v[106:107]
	v_pk_fma_f32 v[108:109], v[44:45], v[222:223], v[108:109]
	v_lshlrev_b32_e32 v224, 16, v246
	v_and_b32_e32 v225, 0xffff0000, v246
	v_lshlrev_b32_e32 v226, 16, v247
	v_and_b32_e32 v227, 0xffff0000, v247
	v_pk_fma_f32 v[110:111], v[46:47], v[224:225], v[110:111]
	v_pk_fma_f32 v[112:113], v[48:49], v[226:227], v[112:113]
	v_lshlrev_b32_e32 v228, 16, v248
	v_and_b32_e32 v229, 0xffff0000, v248
	v_lshlrev_b32_e32 v230, 16, v249
	v_and_b32_e32 v231, 0xffff0000, v249
	v_pk_fma_f32 v[114:115], v[50:51], v[228:229], v[114:115]
	v_pk_fma_f32 v[116:117], v[52:53], v[230:231], v[116:117]
	v_lshlrev_b32_e32 v232, 16, v250
	v_and_b32_e32 v233, 0xffff0000, v250
	v_lshlrev_b32_e32 v234, 16, v251
	v_and_b32_e32 v235, 0xffff0000, v251
	v_pk_fma_f32 v[118:119], v[54:55], v[232:233], v[118:119]
	v_pk_fma_f32 v[120:121], v[56:57], v[234:235], v[120:121]
	v_lshlrev_b32_e32 v236, 16, v166
	v_and_b32_e32 v237, 0xffff0000, v166
	v_lshlrev_b32_e32 v238, 16, v167
	v_and_b32_e32 v239, 0xffff0000, v167
	v_pk_fma_f32 v[122:123], v[58:59], v[236:237], v[122:123]
	v_pk_fma_f32 v[124:125], v[60:61], v[238:239], v[124:125]
	v_lshlrev_b32_e32 v240, 16, v194
	v_and_b32_e32 v241, 0xffff0000, v194
	v_lshlrev_b32_e32 v242, 16, v195
	v_and_b32_e32 v243, 0xffff0000, v195
	v_pk_fma_f32 v[126:127], v[62:63], v[240:241], v[126:127]
	v_pk_fma_f32 v[128:129], v[64:65], v[242:243], v[128:129]
	s_barrier
	v_add_u32_e32 v204, 0xc000, v200
	v_add_u32_e32 v205, 0xc000, v202
	ds_read_b128 v[130:133], v204 offset:0
	ds_read_b128 v[134:137], v204 offset:2048
	ds_read_b128 v[138:141], v204 offset:4096
	ds_read_b128 v[142:145], v204 offset:6144
	ds_read_b128 v[146:149], v205 offset:0
	ds_read_b128 v[150:153], v205 offset:2048
	ds_read_b128 v[154:157], v205 offset:4096
	ds_read_b128 v[158:161], v205 offset:6144
	v_add_u32_e32 v204, 0xc000, v201
	v_add_u32_e32 v205, 0xc000, v203
	ds_read_b128 v[212:215], v204 offset:0
	ds_read_b128 v[216:219], v204 offset:2048
	ds_read_b128 v[220:223], v204 offset:4096
	ds_read_b128 v[224:227], v204 offset:6144
	ds_read_b128 v[228:231], v205 offset:0
	ds_read_b128 v[232:235], v205 offset:2048
	ds_read_b128 v[236:239], v205 offset:4096
	ds_read_b128 v[240:243], v205 offset:6144
	s_add_u32 m0, s76, 0x0
	s_nop 0
	global_load_lds_dwordx4 v196, s[68:69]
	s_add_u32 m0, s76, 0x2000
	s_nop 0
	global_load_lds_dwordx4 v197, s[68:69]
	s_add_u32 m0, s76, 0x4000
	s_nop 0
	global_load_lds_dwordx4 v198, s[68:69]
	s_add_u32 m0, s76, 0x6000
	s_nop 0
	global_load_lds_dwordx4 v199, s[68:69]
	s_add_u32 m0, s76, 0x8000
	s_nop 0
	global_load_lds_dwordx4 v196, s[70:71]
	s_add_u32 m0, s76, 0xa000
	s_nop 0
	global_load_lds_dwordx4 v197, s[70:71]
	s_add_u32 s68, s68, 0x80
	s_addc_u32 s69, s69, 0
	s_add_u32 s70, s70, 0x80
	s_addc_u32 s71, s71, 0
	global_load_dwordx2 v[174:175], v206, s[72:73] offset:0
	global_load_dwordx2 v[176:177], v206, s[72:73] offset:32
	global_load_dwordx2 v[178:179], v206, s[72:73] offset:64
	global_load_dwordx2 v[180:181], v206, s[72:73] offset:96
	global_load_dwordx2 v[182:183], v207, s[72:73] offset:0
	global_load_dwordx2 v[184:185], v207, s[72:73] offset:32
	s_waitcnt vmcnt(12)
	s_waitcnt lgkmcnt(0)
	s_barrier
	v_mfma_f32_16x16x32_bf16 v[2:5], v[146:149], v[130:133], 0
	v_mfma_f32_16x16x32_bf16 v[6:9], v[150:153], v[130:133], 0
	v_mfma_f32_16x16x32_bf16 v[10:13], v[154:157], v[130:133], 0
	v_mfma_f32_16x16x32_bf16 v[14:17], v[158:161], v[130:133], 0
	v_mfma_f32_16x16x32_bf16 v[18:21], v[146:149], v[134:137], 0
	v_mfma_f32_16x16x32_bf16 v[22:25], v[150:153], v[134:137], 0
	v_mfma_f32_16x16x32_bf16 v[26:29], v[154:157], v[134:137], 0
	v_mfma_f32_16x16x32_bf16 v[30:33], v[158:161], v[134:137], 0
	v_mfma_f32_16x16x32_bf16 v[34:37], v[146:149], v[138:141], 0
	v_mfma_f32_16x16x32_bf16 v[38:41], v[150:153], v[138:141], 0
	v_mfma_f32_16x16x32_bf16 v[42:45], v[154:157], v[138:141], 0
	v_mfma_f32_16x16x32_bf16 v[46:49], v[158:161], v[138:141], 0
	v_mfma_f32_16x16x32_bf16 v[50:53], v[146:149], v[142:145], 0
	v_mfma_f32_16x16x32_bf16 v[54:57], v[150:153], v[142:145], 0
	v_mfma_f32_16x16x32_bf16 v[58:61], v[154:157], v[142:145], 0
	v_mfma_f32_16x16x32_bf16 v[62:65], v[158:161], v[142:145], 0
	v_mfma_f32_16x16x32_bf16 v[2:5], v[228:231], v[212:215], v[2:5]
	v_mfma_f32_16x16x32_bf16 v[6:9], v[232:235], v[212:215], v[6:9]
	v_mfma_f32_16x16x32_bf16 v[10:13], v[236:239], v[212:215], v[10:13]
	v_mfma_f32_16x16x32_bf16 v[14:17], v[240:243], v[212:215], v[14:17]
	v_mfma_f32_16x16x32_bf16 v[18:21], v[228:231], v[216:219], v[18:21]
	v_mfma_f32_16x16x32_bf16 v[22:25], v[232:235], v[216:219], v[22:25]
	v_mfma_f32_16x16x32_bf16 v[26:29], v[236:239], v[216:219], v[26:29]
	v_mfma_f32_16x16x32_bf16 v[30:33], v[240:243], v[216:219], v[30:33]
	v_mfma_f32_16x16x32_bf16 v[34:37], v[228:231], v[220:223], v[34:37]
	v_mfma_f32_16x16x32_bf16 v[38:41], v[232:235], v[220:223], v[38:41]
	v_mfma_f32_16x16x32_bf16 v[42:45], v[236:239], v[220:223], v[42:45]
	v_mfma_f32_16x16x32_bf16 v[46:49], v[240:243], v[220:223], v[46:49]
	v_mfma_f32_16x16x32_bf16 v[50:53], v[228:231], v[224:227], v[50:53]
	v_mfma_f32_16x16x32_bf16 v[54:57], v[232:235], v[224:227], v[54:57]
	v_mfma_f32_16x16x32_bf16 v[58:61], v[236:239], v[224:227], v[58:61]
	v_mfma_f32_16x16x32_bf16 v[62:65], v[240:243], v[224:227], v[62:65]
	s_barrier
	v_add_u32_e32 v204, 0x18000, v200
	v_add_u32_e32 v205, 0x18000, v202
	ds_read_b128 v[130:133], v204 offset:0
	ds_read_b128 v[134:137], v204 offset:2048
	ds_read_b128 v[138:141], v204 offset:4096
	ds_read_b128 v[142:145], v204 offset:6144
	ds_read_b128 v[146:149], v205 offset:0
	ds_read_b128 v[150:153], v205 offset:2048
	ds_read_b128 v[154:157], v205 offset:4096
	ds_read_b128 v[158:161], v205 offset:6144
	v_add_u32_e32 v204, 0x18000, v201
	v_add_u32_e32 v205, 0x18000, v203
	ds_read_b128 v[212:215], v204 offset:0
	ds_read_b128 v[216:219], v204 offset:2048
	ds_read_b128 v[220:223], v204 offset:4096
	ds_read_b128 v[224:227], v204 offset:6144
	ds_read_b128 v[228:231], v205 offset:0
	ds_read_b128 v[232:235], v205 offset:2048
	ds_read_b128 v[236:239], v205 offset:4096
	ds_read_b128 v[240:243], v205 offset:6144
	s_add_u32 m0, s76, 0xc000
	s_nop 0
	global_load_lds_dwordx4 v196, s[68:69]
	s_add_u32 m0, s76, 0xe000
	s_nop 0
	global_load_lds_dwordx4 v197, s[68:69]
	s_add_u32 m0, s76, 0x10000
	s_nop 0
	global_load_lds_dwordx4 v198, s[68:69]
	s_add_u32 m0, s76, 0x12000
	s_nop 0
	global_load_lds_dwordx4 v199, s[68:69]
	s_add_u32 m0, s76, 0x14000
	s_nop 0
	global_load_lds_dwordx4 v196, s[70:71]
	s_add_u32 m0, s76, 0x16000
	s_nop 0
	global_load_lds_dwordx4 v197, s[70:71]
	s_add_u32 s68, s68, 0x80
	s_addc_u32 s69, s69, 0
	s_add_u32 s70, s70, 0x80
	s_addc_u32 s71, s71, 0
	global_load_dwordx2 v[186:187], v207, s[72:73] offset:64
	global_load_dwordx2 v[188:189], v207, s[72:73] offset:96
	global_load_dwordx2 v[190:191], v208, s[72:73] offset:0
	global_load_dwordx2 v[192:193], v208, s[72:73] offset:32
	global_load_dwordx2 v[244:245], v208, s[72:73] offset:64
	global_load_dwordx2 v[246:247], v208, s[72:73] offset:96
	s_waitcnt vmcnt(18)
	s_waitcnt lgkmcnt(0)
	s_barrier
	v_mfma_f32_16x16x32_bf16 v[2:5], v[146:149], v[130:133], v[2:5]
	v_mfma_f32_16x16x32_bf16 v[6:9], v[150:153], v[130:133], v[6:9]
	v_mfma_f32_16x16x32_bf16 v[10:13], v[154:157], v[130:133], v[10:13]
	v_mfma_f32_16x16x32_bf16 v[14:17], v[158:161], v[130:133], v[14:17]
	v_mfma_f32_16x16x32_bf16 v[18:21], v[146:149], v[134:137], v[18:21]
	v_mfma_f32_16x16x32_bf16 v[22:25], v[150:153], v[134:137], v[22:25]
	v_mfma_f32_16x16x32_bf16 v[26:29], v[154:157], v[134:137], v[26:29]
	v_mfma_f32_16x16x32_bf16 v[30:33], v[158:161], v[134:137], v[30:33]
	v_mfma_f32_16x16x32_bf16 v[34:37], v[146:149], v[138:141], v[34:37]
	v_mfma_f32_16x16x32_bf16 v[38:41], v[150:153], v[138:141], v[38:41]
	v_mfma_f32_16x16x32_bf16 v[42:45], v[154:157], v[138:141], v[42:45]
	v_mfma_f32_16x16x32_bf16 v[46:49], v[158:161], v[138:141], v[46:49]
	v_mfma_f32_16x16x32_bf16 v[50:53], v[146:149], v[142:145], v[50:53]
	v_mfma_f32_16x16x32_bf16 v[54:57], v[150:153], v[142:145], v[54:57]
	v_mfma_f32_16x16x32_bf16 v[58:61], v[154:157], v[142:145], v[58:61]
	v_mfma_f32_16x16x32_bf16 v[62:65], v[158:161], v[142:145], v[62:65]
	v_mfma_f32_16x16x32_bf16 v[2:5], v[228:231], v[212:215], v[2:5]
	v_mfma_f32_16x16x32_bf16 v[6:9], v[232:235], v[212:215], v[6:9]
	v_mfma_f32_16x16x32_bf16 v[10:13], v[236:239], v[212:215], v[10:13]
	v_mfma_f32_16x16x32_bf16 v[14:17], v[240:243], v[212:215], v[14:17]
	v_mfma_f32_16x16x32_bf16 v[18:21], v[228:231], v[216:219], v[18:21]
	v_mfma_f32_16x16x32_bf16 v[22:25], v[232:235], v[216:219], v[22:25]
	v_mfma_f32_16x16x32_bf16 v[26:29], v[236:239], v[216:219], v[26:29]
	v_mfma_f32_16x16x32_bf16 v[30:33], v[240:243], v[216:219], v[30:33]
	v_mfma_f32_16x16x32_bf16 v[34:37], v[228:231], v[220:223], v[34:37]
	v_mfma_f32_16x16x32_bf16 v[38:41], v[232:235], v[220:223], v[38:41]
	v_mfma_f32_16x16x32_bf16 v[42:45], v[236:239], v[220:223], v[42:45]
	v_mfma_f32_16x16x32_bf16 v[46:49], v[240:243], v[220:223], v[46:49]
	v_mfma_f32_16x16x32_bf16 v[50:53], v[228:231], v[224:227], v[50:53]
	v_mfma_f32_16x16x32_bf16 v[54:57], v[232:235], v[224:227], v[54:57]
	v_mfma_f32_16x16x32_bf16 v[58:61], v[236:239], v[224:227], v[58:61]
	v_mfma_f32_16x16x32_bf16 v[62:65], v[240:243], v[224:227], v[62:65]
	s_barrier
	v_add_u32_e32 v204, 0x0, v200
	v_add_u32_e32 v205, 0x0, v202
	ds_read_b128 v[130:133], v204 offset:0
	ds_read_b128 v[134:137], v204 offset:2048
	ds_read_b128 v[138:141], v204 offset:4096
	ds_read_b128 v[142:145], v204 offset:6144
	ds_read_b128 v[146:149], v205 offset:0
	ds_read_b128 v[150:153], v205 offset:2048
	ds_read_b128 v[154:157], v205 offset:4096
	ds_read_b128 v[158:161], v205 offset:6144
	v_add_u32_e32 v204, 0x0, v201
	v_add_u32_e32 v205, 0x0, v203
	ds_read_b128 v[212:215], v204 offset:0
	ds_read_b128 v[216:219], v204 offset:2048
	ds_read_b128 v[220:223], v204 offset:4096
	ds_read_b128 v[224:227], v204 offset:6144
	ds_read_b128 v[228:231], v205 offset:0
	ds_read_b128 v[232:235], v205 offset:2048
	ds_read_b128 v[236:239], v205 offset:4096
	ds_read_b128 v[240:243], v205 offset:6144
	s_add_u32 m0, s76, 0x18000
	s_nop 0
	global_load_lds_dwordx4 v196, s[68:69]
	s_add_u32 m0, s76, 0x1a000
	s_nop 0
	global_load_lds_dwordx4 v197, s[68:69]
	s_add_u32 m0, s76, 0x1c000
	s_nop 0
	global_load_lds_dwordx4 v198, s[68:69]
	s_add_u32 m0, s76, 0x1e000
	s_nop 0
	global_load_lds_dwordx4 v199, s[68:69]
	s_add_u32 m0, s76, 0x20000
	s_nop 0
	global_load_lds_dwordx4 v196, s[70:71]
	s_add_u32 m0, s76, 0x22000
	s_nop 0
	global_load_lds_dwordx4 v197, s[70:71]
	s_add_u32 s68, s68, 0x80
	s_addc_u32 s69, s69, 0
	s_add_u32 s70, s70, 0x80
	s_addc_u32 s71, s71, 0
	global_load_dwordx2 v[248:249], v209, s[72:73] offset:0
	global_load_dwordx2 v[250:251], v209, s[72:73] offset:32
	global_load_dwordx2 v[166:167], v209, s[72:73] offset:64
	global_load_dwordx2 v[194:195], v209, s[72:73] offset:96
	s_add_u32 s72, s72, 0x800
	s_addc_u32 s73, s73, 0
	s_waitcnt vmcnt(16)
	s_waitcnt lgkmcnt(0)
	s_barrier
	v_mfma_f32_16x16x32_bf16 v[2:5], v[146:149], v[130:133], v[2:5]
	v_mfma_f32_16x16x32_bf16 v[6:9], v[150:153], v[130:133], v[6:9]
	v_mfma_f32_16x16x32_bf16 v[10:13], v[154:157], v[130:133], v[10:13]
	v_mfma_f32_16x16x32_bf16 v[14:17], v[158:161], v[130:133], v[14:17]
	v_mfma_f32_16x16x32_bf16 v[18:21], v[146:149], v[134:137], v[18:21]
	v_mfma_f32_16x16x32_bf16 v[22:25], v[150:153], v[134:137], v[22:25]
	v_mfma_f32_16x16x32_bf16 v[26:29], v[154:157], v[134:137], v[26:29]
	v_mfma_f32_16x16x32_bf16 v[30:33], v[158:161], v[134:137], v[30:33]
	v_mfma_f32_16x16x32_bf16 v[34:37], v[146:149], v[138:141], v[34:37]
	v_mfma_f32_16x16x32_bf16 v[38:41], v[150:153], v[138:141], v[38:41]
	v_mfma_f32_16x16x32_bf16 v[42:45], v[154:157], v[138:141], v[42:45]
	v_mfma_f32_16x16x32_bf16 v[46:49], v[158:161], v[138:141], v[46:49]
	v_mfma_f32_16x16x32_bf16 v[50:53], v[146:149], v[142:145], v[50:53]
	v_mfma_f32_16x16x32_bf16 v[54:57], v[150:153], v[142:145], v[54:57]
	v_mfma_f32_16x16x32_bf16 v[58:61], v[154:157], v[142:145], v[58:61]
	v_mfma_f32_16x16x32_bf16 v[62:65], v[158:161], v[142:145], v[62:65]
	v_mfma_f32_16x16x32_bf16 v[2:5], v[228:231], v[212:215], v[2:5]
	v_mfma_f32_16x16x32_bf16 v[6:9], v[232:235], v[212:215], v[6:9]
	v_mfma_f32_16x16x32_bf16 v[10:13], v[236:239], v[212:215], v[10:13]
	v_mfma_f32_16x16x32_bf16 v[14:17], v[240:243], v[212:215], v[14:17]
	v_mfma_f32_16x16x32_bf16 v[18:21], v[228:231], v[216:219], v[18:21]
	v_mfma_f32_16x16x32_bf16 v[22:25], v[232:235], v[216:219], v[22:25]
	v_mfma_f32_16x16x32_bf16 v[26:29], v[236:239], v[216:219], v[26:29]
	v_mfma_f32_16x16x32_bf16 v[30:33], v[240:243], v[216:219], v[30:33]
	v_mfma_f32_16x16x32_bf16 v[34:37], v[228:231], v[220:223], v[34:37]
	v_mfma_f32_16x16x32_bf16 v[38:41], v[232:235], v[220:223], v[38:41]
	v_mfma_f32_16x16x32_bf16 v[42:45], v[236:239], v[220:223], v[42:45]
	v_mfma_f32_16x16x32_bf16 v[46:49], v[240:243], v[220:223], v[46:49]
	v_mfma_f32_16x16x32_bf16 v[50:53], v[228:231], v[224:227], v[50:53]
	v_mfma_f32_16x16x32_bf16 v[54:57], v[232:235], v[224:227], v[54:57]
	v_mfma_f32_16x16x32_bf16 v[58:61], v[236:239], v[224:227], v[58:61]
	v_mfma_f32_16x16x32_bf16 v[62:65], v[240:243], v[224:227], v[62:65]
	s_barrier
	v_add_u32_e32 v204, 0xc000, v200
	v_add_u32_e32 v205, 0xc000, v202
	ds_read_b128 v[130:133], v204 offset:0
	ds_read_b128 v[134:137], v204 offset:2048
	ds_read_b128 v[138:141], v204 offset:4096
	ds_read_b128 v[142:145], v204 offset:6144
	ds_read_b128 v[146:149], v205 offset:0
	ds_read_b128 v[150:153], v205 offset:2048
	ds_read_b128 v[154:157], v205 offset:4096
	ds_read_b128 v[158:161], v205 offset:6144
	v_add_u32_e32 v204, 0xc000, v201
	v_add_u32_e32 v205, 0xc000, v203
	ds_read_b128 v[212:215], v204 offset:0
	ds_read_b128 v[216:219], v204 offset:2048
	ds_read_b128 v[220:223], v204 offset:4096
	ds_read_b128 v[224:227], v204 offset:6144
	ds_read_b128 v[228:231], v205 offset:0
	ds_read_b128 v[232:235], v205 offset:2048
	ds_read_b128 v[236:239], v205 offset:4096
	ds_read_b128 v[240:243], v205 offset:6144
	s_add_u32 m0, s76, 0x0
	s_nop 0
	global_load_lds_dwordx4 v196, s[68:69]
	s_add_u32 m0, s76, 0x2000
	s_nop 0
	global_load_lds_dwordx4 v197, s[68:69]
	s_add_u32 m0, s76, 0x4000
	s_nop 0
	global_load_lds_dwordx4 v198, s[68:69]
	s_add_u32 m0, s76, 0x6000
	s_nop 0
	global_load_lds_dwordx4 v199, s[68:69]
	s_add_u32 m0, s76, 0x8000
	s_nop 0
	global_load_lds_dwordx4 v196, s[70:71]
	s_add_u32 m0, s76, 0xa000
	s_nop 0
	global_load_lds_dwordx4 v197, s[70:71]
	s_add_u32 s68, s68, 0x80
	s_addc_u32 s69, s69, 0
	s_add_u32 s70, s70, 0x80
	s_addc_u32 s71, s71, 0
	s_waitcnt vmcnt(10)
	s_waitcnt lgkmcnt(0)
	s_barrier
	v_mfma_f32_16x16x32_bf16 v[2:5], v[146:149], v[130:133], v[2:5]
	v_mfma_f32_16x16x32_bf16 v[6:9], v[150:153], v[130:133], v[6:9]
	v_mfma_f32_16x16x32_bf16 v[10:13], v[154:157], v[130:133], v[10:13]
	v_mfma_f32_16x16x32_bf16 v[14:17], v[158:161], v[130:133], v[14:17]
	v_mfma_f32_16x16x32_bf16 v[18:21], v[146:149], v[134:137], v[18:21]
	v_mfma_f32_16x16x32_bf16 v[22:25], v[150:153], v[134:137], v[22:25]
	v_mfma_f32_16x16x32_bf16 v[26:29], v[154:157], v[134:137], v[26:29]
	v_mfma_f32_16x16x32_bf16 v[30:33], v[158:161], v[134:137], v[30:33]
	v_mfma_f32_16x16x32_bf16 v[34:37], v[146:149], v[138:141], v[34:37]
	v_mfma_f32_16x16x32_bf16 v[38:41], v[150:153], v[138:141], v[38:41]
	v_mfma_f32_16x16x32_bf16 v[42:45], v[154:157], v[138:141], v[42:45]
	v_mfma_f32_16x16x32_bf16 v[46:49], v[158:161], v[138:141], v[46:49]
	v_mfma_f32_16x16x32_bf16 v[50:53], v[146:149], v[142:145], v[50:53]
	v_mfma_f32_16x16x32_bf16 v[54:57], v[150:153], v[142:145], v[54:57]
	v_mfma_f32_16x16x32_bf16 v[58:61], v[154:157], v[142:145], v[58:61]
	v_mfma_f32_16x16x32_bf16 v[62:65], v[158:161], v[142:145], v[62:65]
	v_mfma_f32_16x16x32_bf16 v[2:5], v[228:231], v[212:215], v[2:5]
	v_mfma_f32_16x16x32_bf16 v[6:9], v[232:235], v[212:215], v[6:9]
	v_mfma_f32_16x16x32_bf16 v[10:13], v[236:239], v[212:215], v[10:13]
	v_mfma_f32_16x16x32_bf16 v[14:17], v[240:243], v[212:215], v[14:17]
	v_mfma_f32_16x16x32_bf16 v[18:21], v[228:231], v[216:219], v[18:21]
	v_mfma_f32_16x16x32_bf16 v[22:25], v[232:235], v[216:219], v[22:25]
	v_mfma_f32_16x16x32_bf16 v[26:29], v[236:239], v[216:219], v[26:29]
	v_mfma_f32_16x16x32_bf16 v[30:33], v[240:243], v[216:219], v[30:33]
	v_mfma_f32_16x16x32_bf16 v[34:37], v[228:231], v[220:223], v[34:37]
	v_mfma_f32_16x16x32_bf16 v[38:41], v[232:235], v[220:223], v[38:41]
	v_mfma_f32_16x16x32_bf16 v[42:45], v[236:239], v[220:223], v[42:45]
	v_mfma_f32_16x16x32_bf16 v[46:49], v[240:243], v[220:223], v[46:49]
	v_mfma_f32_16x16x32_bf16 v[50:53], v[228:231], v[224:227], v[50:53]
	v_mfma_f32_16x16x32_bf16 v[54:57], v[232:235], v[224:227], v[54:57]
	v_mfma_f32_16x16x32_bf16 v[58:61], v[236:239], v[224:227], v[58:61]
	v_mfma_f32_16x16x32_bf16 v[62:65], v[240:243], v[224:227], v[62:65]
	s_barrier
	v_add_u32_e32 v204, 0x18000, v200
	v_add_u32_e32 v205, 0x18000, v202
	ds_read_b128 v[130:133], v204 offset:0
	ds_read_b128 v[134:137], v204 offset:2048
	ds_read_b128 v[138:141], v204 offset:4096
	ds_read_b128 v[142:145], v204 offset:6144
	ds_read_b128 v[146:149], v205 offset:0
	ds_read_b128 v[150:153], v205 offset:2048
	ds_read_b128 v[154:157], v205 offset:4096
	ds_read_b128 v[158:161], v205 offset:6144
	v_add_u32_e32 v204, 0x18000, v201
	v_add_u32_e32 v205, 0x18000, v203
	ds_read_b128 v[212:215], v204 offset:0
	ds_read_b128 v[216:219], v204 offset:2048
	ds_read_b128 v[220:223], v204 offset:4096
	ds_read_b128 v[224:227], v204 offset:6144
	ds_read_b128 v[228:231], v205 offset:0
	ds_read_b128 v[232:235], v205 offset:2048
	ds_read_b128 v[236:239], v205 offset:4096
	ds_read_b128 v[240:243], v205 offset:6144
	s_add_u32 m0, s76, 0xc000
	s_nop 0
	global_load_lds_dwordx4 v196, s[68:69]
	s_add_u32 m0, s76, 0xe000
	s_nop 0
	global_load_lds_dwordx4 v197, s[68:69]
	s_add_u32 m0, s76, 0x10000
	s_nop 0
	global_load_lds_dwordx4 v198, s[68:69]
	s_add_u32 m0, s76, 0x12000
	s_nop 0
	global_load_lds_dwordx4 v199, s[68:69]
	s_add_u32 m0, s76, 0x14000
	s_nop 0
	global_load_lds_dwordx4 v196, s[70:71]
	s_add_u32 m0, s76, 0x16000
	s_nop 0
	global_load_lds_dwordx4 v197, s[70:71]
	s_add_u32 s68, s68, 0x80
	s_addc_u32 s69, s69, 0
	s_add_u32 s70, s70, 0x80
	s_addc_u32 s71, s71, 0
	s_waitcnt vmcnt(6)
	s_waitcnt lgkmcnt(0)
	s_barrier
	v_mfma_f32_16x16x32_bf16 v[2:5], v[146:149], v[130:133], v[2:5]
	v_mfma_f32_16x16x32_bf16 v[6:9], v[150:153], v[130:133], v[6:9]
	v_mfma_f32_16x16x32_bf16 v[10:13], v[154:157], v[130:133], v[10:13]
	v_mfma_f32_16x16x32_bf16 v[14:17], v[158:161], v[130:133], v[14:17]
	v_mfma_f32_16x16x32_bf16 v[18:21], v[146:149], v[134:137], v[18:21]
	v_mfma_f32_16x16x32_bf16 v[22:25], v[150:153], v[134:137], v[22:25]
	v_mfma_f32_16x16x32_bf16 v[26:29], v[154:157], v[134:137], v[26:29]
	v_mfma_f32_16x16x32_bf16 v[30:33], v[158:161], v[134:137], v[30:33]
	v_mfma_f32_16x16x32_bf16 v[34:37], v[146:149], v[138:141], v[34:37]
	v_mfma_f32_16x16x32_bf16 v[38:41], v[150:153], v[138:141], v[38:41]
	v_mfma_f32_16x16x32_bf16 v[42:45], v[154:157], v[138:141], v[42:45]
	v_mfma_f32_16x16x32_bf16 v[46:49], v[158:161], v[138:141], v[46:49]
	v_mfma_f32_16x16x32_bf16 v[50:53], v[146:149], v[142:145], v[50:53]
	v_mfma_f32_16x16x32_bf16 v[54:57], v[150:153], v[142:145], v[54:57]
	v_mfma_f32_16x16x32_bf16 v[58:61], v[154:157], v[142:145], v[58:61]
	v_mfma_f32_16x16x32_bf16 v[62:65], v[158:161], v[142:145], v[62:65]
	v_mfma_f32_16x16x32_bf16 v[2:5], v[228:231], v[212:215], v[2:5]
	v_mfma_f32_16x16x32_bf16 v[6:9], v[232:235], v[212:215], v[6:9]
	v_mfma_f32_16x16x32_bf16 v[10:13], v[236:239], v[212:215], v[10:13]
	v_mfma_f32_16x16x32_bf16 v[14:17], v[240:243], v[212:215], v[14:17]
	v_mfma_f32_16x16x32_bf16 v[18:21], v[228:231], v[216:219], v[18:21]
	v_mfma_f32_16x16x32_bf16 v[22:25], v[232:235], v[216:219], v[22:25]
	v_mfma_f32_16x16x32_bf16 v[26:29], v[236:239], v[216:219], v[26:29]
	v_mfma_f32_16x16x32_bf16 v[30:33], v[240:243], v[216:219], v[30:33]
	v_mfma_f32_16x16x32_bf16 v[34:37], v[228:231], v[220:223], v[34:37]
	v_mfma_f32_16x16x32_bf16 v[38:41], v[232:235], v[220:223], v[38:41]
	v_mfma_f32_16x16x32_bf16 v[42:45], v[236:239], v[220:223], v[42:45]
	v_mfma_f32_16x16x32_bf16 v[46:49], v[240:243], v[220:223], v[46:49]
	v_mfma_f32_16x16x32_bf16 v[50:53], v[228:231], v[224:227], v[50:53]
	v_mfma_f32_16x16x32_bf16 v[54:57], v[232:235], v[224:227], v[54:57]
	v_mfma_f32_16x16x32_bf16 v[58:61], v[236:239], v[224:227], v[58:61]
	v_mfma_f32_16x16x32_bf16 v[62:65], v[240:243], v[224:227], v[62:65]
	s_barrier
	v_add_u32_e32 v204, 0x0, v200
	v_add_u32_e32 v205, 0x0, v202
	ds_read_b128 v[130:133], v204 offset:0
	ds_read_b128 v[134:137], v204 offset:2048
	ds_read_b128 v[138:141], v204 offset:4096
	ds_read_b128 v[142:145], v204 offset:6144
	ds_read_b128 v[146:149], v205 offset:0
	ds_read_b128 v[150:153], v205 offset:2048
	ds_read_b128 v[154:157], v205 offset:4096
	ds_read_b128 v[158:161], v205 offset:6144
	v_add_u32_e32 v204, 0x0, v201
	v_add_u32_e32 v205, 0x0, v203
	ds_read_b128 v[212:215], v204 offset:0
	ds_read_b128 v[216:219], v204 offset:2048
	ds_read_b128 v[220:223], v204 offset:4096
	ds_read_b128 v[224:227], v204 offset:6144
	ds_read_b128 v[228:231], v205 offset:0
	ds_read_b128 v[232:235], v205 offset:2048
	ds_read_b128 v[236:239], v205 offset:4096
	ds_read_b128 v[240:243], v205 offset:6144
	s_add_u32 m0, s76, 0x18000
	s_nop 0
	global_load_lds_dwordx4 v196, s[68:69]
	s_add_u32 m0, s76, 0x1a000
	s_nop 0
	global_load_lds_dwordx4 v197, s[68:69]
	s_add_u32 m0, s76, 0x1c000
	s_nop 0
	global_load_lds_dwordx4 v198, s[68:69]
	s_add_u32 m0, s76, 0x1e000
	s_nop 0
	global_load_lds_dwordx4 v199, s[68:69]
	s_add_u32 m0, s76, 0x20000
	s_nop 0
	global_load_lds_dwordx4 v196, s[70:71]
	s_add_u32 m0, s76, 0x22000
	s_nop 0
	global_load_lds_dwordx4 v197, s[70:71]
	s_add_u32 s68, s68, 0x80
	s_addc_u32 s69, s69, 0
	s_add_u32 s70, s70, 0x80
	s_addc_u32 s71, s71, 0
	s_waitcnt vmcnt(6)
	s_waitcnt lgkmcnt(0)
	s_barrier
	v_mfma_f32_16x16x32_bf16 v[2:5], v[146:149], v[130:133], v[2:5]
	v_mfma_f32_16x16x32_bf16 v[6:9], v[150:153], v[130:133], v[6:9]
	v_mfma_f32_16x16x32_bf16 v[10:13], v[154:157], v[130:133], v[10:13]
	v_mfma_f32_16x16x32_bf16 v[14:17], v[158:161], v[130:133], v[14:17]
	v_mfma_f32_16x16x32_bf16 v[18:21], v[146:149], v[134:137], v[18:21]
	v_mfma_f32_16x16x32_bf16 v[22:25], v[150:153], v[134:137], v[22:25]
	v_mfma_f32_16x16x32_bf16 v[26:29], v[154:157], v[134:137], v[26:29]
	v_mfma_f32_16x16x32_bf16 v[30:33], v[158:161], v[134:137], v[30:33]
	v_mfma_f32_16x16x32_bf16 v[34:37], v[146:149], v[138:141], v[34:37]
	v_mfma_f32_16x16x32_bf16 v[38:41], v[150:153], v[138:141], v[38:41]
	v_mfma_f32_16x16x32_bf16 v[42:45], v[154:157], v[138:141], v[42:45]
	v_mfma_f32_16x16x32_bf16 v[46:49], v[158:161], v[138:141], v[46:49]
	v_mfma_f32_16x16x32_bf16 v[50:53], v[146:149], v[142:145], v[50:53]
	v_mfma_f32_16x16x32_bf16 v[54:57], v[150:153], v[142:145], v[54:57]
	v_mfma_f32_16x16x32_bf16 v[58:61], v[154:157], v[142:145], v[58:61]
	v_mfma_f32_16x16x32_bf16 v[62:65], v[158:161], v[142:145], v[62:65]
	v_mfma_f32_16x16x32_bf16 v[2:5], v[228:231], v[212:215], v[2:5]
	v_mfma_f32_16x16x32_bf16 v[6:9], v[232:235], v[212:215], v[6:9]
	v_mfma_f32_16x16x32_bf16 v[10:13], v[236:239], v[212:215], v[10:13]
	v_mfma_f32_16x16x32_bf16 v[14:17], v[240:243], v[212:215], v[14:17]
	v_mfma_f32_16x16x32_bf16 v[18:21], v[228:231], v[216:219], v[18:21]
	v_mfma_f32_16x16x32_bf16 v[22:25], v[232:235], v[216:219], v[22:25]
	v_mfma_f32_16x16x32_bf16 v[26:29], v[236:239], v[216:219], v[26:29]
	v_mfma_f32_16x16x32_bf16 v[30:33], v[240:243], v[216:219], v[30:33]
	v_mfma_f32_16x16x32_bf16 v[34:37], v[228:231], v[220:223], v[34:37]
	v_mfma_f32_16x16x32_bf16 v[38:41], v[232:235], v[220:223], v[38:41]
	v_mfma_f32_16x16x32_bf16 v[42:45], v[236:239], v[220:223], v[42:45]
	v_mfma_f32_16x16x32_bf16 v[46:49], v[240:243], v[220:223], v[46:49]
	v_mfma_f32_16x16x32_bf16 v[50:53], v[228:231], v[224:227], v[50:53]
	v_mfma_f32_16x16x32_bf16 v[54:57], v[232:235], v[224:227], v[54:57]
	v_mfma_f32_16x16x32_bf16 v[58:61], v[236:239], v[224:227], v[58:61]
	v_mfma_f32_16x16x32_bf16 v[62:65], v[240:243], v[224:227], v[62:65]
	s_barrier
	v_add_u32_e32 v204, 0xc000, v200
	v_add_u32_e32 v205, 0xc000, v202
	ds_read_b128 v[130:133], v204 offset:0
	ds_read_b128 v[134:137], v204 offset:2048
	ds_read_b128 v[138:141], v204 offset:4096
	ds_read_b128 v[142:145], v204 offset:6144
	ds_read_b128 v[146:149], v205 offset:0
	ds_read_b128 v[150:153], v205 offset:2048
	ds_read_b128 v[154:157], v205 offset:4096
	ds_read_b128 v[158:161], v205 offset:6144
	v_add_u32_e32 v204, 0xc000, v201
	v_add_u32_e32 v205, 0xc000, v203
	ds_read_b128 v[212:215], v204 offset:0
	ds_read_b128 v[216:219], v204 offset:2048
	ds_read_b128 v[220:223], v204 offset:4096
	ds_read_b128 v[224:227], v204 offset:6144
	ds_read_b128 v[228:231], v205 offset:0
	ds_read_b128 v[232:235], v205 offset:2048
	ds_read_b128 v[236:239], v205 offset:4096
	ds_read_b128 v[240:243], v205 offset:6144
	s_waitcnt vmcnt(0)
	s_waitcnt lgkmcnt(0)
	s_barrier
	v_mfma_f32_16x16x32_bf16 v[2:5], v[146:149], v[130:133], v[2:5]
	v_mfma_f32_16x16x32_bf16 v[6:9], v[150:153], v[130:133], v[6:9]
	v_mfma_f32_16x16x32_bf16 v[10:13], v[154:157], v[130:133], v[10:13]
	v_mfma_f32_16x16x32_bf16 v[14:17], v[158:161], v[130:133], v[14:17]
	v_mfma_f32_16x16x32_bf16 v[18:21], v[146:149], v[134:137], v[18:21]
	v_mfma_f32_16x16x32_bf16 v[22:25], v[150:153], v[134:137], v[22:25]
	v_mfma_f32_16x16x32_bf16 v[26:29], v[154:157], v[134:137], v[26:29]
	v_mfma_f32_16x16x32_bf16 v[30:33], v[158:161], v[134:137], v[30:33]
	v_mfma_f32_16x16x32_bf16 v[34:37], v[146:149], v[138:141], v[34:37]
	v_mfma_f32_16x16x32_bf16 v[38:41], v[150:153], v[138:141], v[38:41]
	v_mfma_f32_16x16x32_bf16 v[42:45], v[154:157], v[138:141], v[42:45]
	v_mfma_f32_16x16x32_bf16 v[46:49], v[158:161], v[138:141], v[46:49]
	v_mfma_f32_16x16x32_bf16 v[50:53], v[146:149], v[142:145], v[50:53]
	v_mfma_f32_16x16x32_bf16 v[54:57], v[150:153], v[142:145], v[54:57]
	v_mfma_f32_16x16x32_bf16 v[58:61], v[154:157], v[142:145], v[58:61]
	v_mfma_f32_16x16x32_bf16 v[62:65], v[158:161], v[142:145], v[62:65]
	v_mfma_f32_16x16x32_bf16 v[2:5], v[228:231], v[212:215], v[2:5]
	v_mfma_f32_16x16x32_bf16 v[6:9], v[232:235], v[212:215], v[6:9]
	v_mfma_f32_16x16x32_bf16 v[10:13], v[236:239], v[212:215], v[10:13]
	v_mfma_f32_16x16x32_bf16 v[14:17], v[240:243], v[212:215], v[14:17]
	v_mfma_f32_16x16x32_bf16 v[18:21], v[228:231], v[216:219], v[18:21]
	v_mfma_f32_16x16x32_bf16 v[22:25], v[232:235], v[216:219], v[22:25]
	v_mfma_f32_16x16x32_bf16 v[26:29], v[236:239], v[216:219], v[26:29]
	v_mfma_f32_16x16x32_bf16 v[30:33], v[240:243], v[216:219], v[30:33]
	v_mfma_f32_16x16x32_bf16 v[34:37], v[228:231], v[220:223], v[34:37]
	v_mfma_f32_16x16x32_bf16 v[38:41], v[232:235], v[220:223], v[38:41]
	v_mfma_f32_16x16x32_bf16 v[42:45], v[236:239], v[220:223], v[42:45]
	v_mfma_f32_16x16x32_bf16 v[46:49], v[240:243], v[220:223], v[46:49]
	v_mfma_f32_16x16x32_bf16 v[50:53], v[228:231], v[224:227], v[50:53]
	v_mfma_f32_16x16x32_bf16 v[54:57], v[232:235], v[224:227], v[54:57]
	v_mfma_f32_16x16x32_bf16 v[58:61], v[236:239], v[224:227], v[58:61]
	v_mfma_f32_16x16x32_bf16 v[62:65], v[240:243], v[224:227], v[62:65]
	s_barrier
	v_add_u32_e32 v204, 0x18000, v200
	v_add_u32_e32 v205, 0x18000, v202
	ds_read_b128 v[130:133], v204 offset:0
	ds_read_b128 v[134:137], v204 offset:2048
	ds_read_b128 v[138:141], v204 offset:4096
	ds_read_b128 v[142:145], v204 offset:6144
	ds_read_b128 v[146:149], v205 offset:0
	ds_read_b128 v[150:153], v205 offset:2048
	ds_read_b128 v[154:157], v205 offset:4096
	ds_read_b128 v[158:161], v205 offset:6144
	v_add_u32_e32 v204, 0x18000, v201
	v_add_u32_e32 v205, 0x18000, v203
	ds_read_b128 v[212:215], v204 offset:0
	ds_read_b128 v[216:219], v204 offset:2048
	ds_read_b128 v[220:223], v204 offset:4096
	ds_read_b128 v[224:227], v204 offset:6144
	ds_read_b128 v[228:231], v205 offset:0
	ds_read_b128 v[232:235], v205 offset:2048
	ds_read_b128 v[236:239], v205 offset:4096
	ds_read_b128 v[240:243], v205 offset:6144
	s_waitcnt lgkmcnt(0)
	s_barrier
	v_mfma_f32_16x16x32_bf16 v[2:5], v[146:149], v[130:133], v[2:5]
	v_mfma_f32_16x16x32_bf16 v[6:9], v[150:153], v[130:133], v[6:9]
	v_mfma_f32_16x16x32_bf16 v[10:13], v[154:157], v[130:133], v[10:13]
	v_mfma_f32_16x16x32_bf16 v[14:17], v[158:161], v[130:133], v[14:17]
	v_mfma_f32_16x16x32_bf16 v[18:21], v[146:149], v[134:137], v[18:21]
	v_mfma_f32_16x16x32_bf16 v[22:25], v[150:153], v[134:137], v[22:25]
	v_mfma_f32_16x16x32_bf16 v[26:29], v[154:157], v[134:137], v[26:29]
	v_mfma_f32_16x16x32_bf16 v[30:33], v[158:161], v[134:137], v[30:33]
	v_mfma_f32_16x16x32_bf16 v[34:37], v[146:149], v[138:141], v[34:37]
	v_mfma_f32_16x16x32_bf16 v[38:41], v[150:153], v[138:141], v[38:41]
	v_mfma_f32_16x16x32_bf16 v[42:45], v[154:157], v[138:141], v[42:45]
	v_mfma_f32_16x16x32_bf16 v[46:49], v[158:161], v[138:141], v[46:49]
	v_mfma_f32_16x16x32_bf16 v[50:53], v[146:149], v[142:145], v[50:53]
	v_mfma_f32_16x16x32_bf16 v[54:57], v[150:153], v[142:145], v[54:57]
	v_mfma_f32_16x16x32_bf16 v[58:61], v[154:157], v[142:145], v[58:61]
	v_mfma_f32_16x16x32_bf16 v[62:65], v[158:161], v[142:145], v[62:65]
	v_mfma_f32_16x16x32_bf16 v[2:5], v[228:231], v[212:215], v[2:5]
	v_mfma_f32_16x16x32_bf16 v[6:9], v[232:235], v[212:215], v[6:9]
	v_mfma_f32_16x16x32_bf16 v[10:13], v[236:239], v[212:215], v[10:13]
	v_mfma_f32_16x16x32_bf16 v[14:17], v[240:243], v[212:215], v[14:17]
	v_mfma_f32_16x16x32_bf16 v[18:21], v[228:231], v[216:219], v[18:21]
	v_mfma_f32_16x16x32_bf16 v[22:25], v[232:235], v[216:219], v[22:25]
	v_mfma_f32_16x16x32_bf16 v[26:29], v[236:239], v[216:219], v[26:29]
	v_mfma_f32_16x16x32_bf16 v[30:33], v[240:243], v[216:219], v[30:33]
	v_mfma_f32_16x16x32_bf16 v[34:37], v[228:231], v[220:223], v[34:37]
	v_mfma_f32_16x16x32_bf16 v[38:41], v[232:235], v[220:223], v[38:41]
	v_mfma_f32_16x16x32_bf16 v[42:45], v[236:239], v[220:223], v[42:45]
	v_mfma_f32_16x16x32_bf16 v[46:49], v[240:243], v[220:223], v[46:49]
	v_mfma_f32_16x16x32_bf16 v[50:53], v[228:231], v[224:227], v[50:53]
	v_mfma_f32_16x16x32_bf16 v[54:57], v[232:235], v[224:227], v[54:57]
	v_mfma_f32_16x16x32_bf16 v[58:61], v[236:239], v[224:227], v[58:61]
	v_mfma_f32_16x16x32_bf16 v[62:65], v[240:243], v[224:227], v[62:65]
	s_nop 7
	v_lshlrev_b32_e32 v212, 16, v174
	v_and_b32_e32 v213, 0xffff0000, v174
	v_lshlrev_b32_e32 v214, 16, v175
	v_and_b32_e32 v215, 0xffff0000, v175
	v_pk_fma_f32 v[66:67], v[2:3], v[212:213], v[66:67]
	v_pk_fma_f32 v[68:69], v[4:5], v[214:215], v[68:69]
	s_nop 0
	v_cvt_pk_bf16_f32 v66, v66, v67
	v_cvt_pk_bf16_f32 v67, v68, v69
	v_lshlrev_b32_e32 v216, 16, v176
	v_and_b32_e32 v217, 0xffff0000, v176
	v_lshlrev_b32_e32 v218, 16, v177
	v_and_b32_e32 v219, 0xffff0000, v177
	v_pk_fma_f32 v[70:71], v[6:7], v[216:217], v[70:71]
	v_pk_fma_f32 v[72:73], v[8:9], v[218:219], v[72:73]
	s_nop 0
	v_cvt_pk_bf16_f32 v70, v70, v71
	v_cvt_pk_bf16_f32 v71, v72, v73
	v_lshlrev_b32_e32 v220, 16, v178
	v_and_b32_e32 v221, 0xffff0000, v178
	v_lshlrev_b32_e32 v222, 16, v179
	v_and_b32_e32 v223, 0xffff0000, v179
	v_pk_fma_f32 v[74:75], v[10:11], v[220:221], v[74:75]
	v_pk_fma_f32 v[76:77], v[12:13], v[222:223], v[76:77]
	s_nop 0
	v_cvt_pk_bf16_f32 v74, v74, v75
	v_cvt_pk_bf16_f32 v75, v76, v77
	v_lshlrev_b32_e32 v224, 16, v180
	v_and_b32_e32 v225, 0xffff0000, v180
	v_lshlrev_b32_e32 v226, 16, v181
	v_and_b32_e32 v227, 0xffff0000, v181
	v_pk_fma_f32 v[78:79], v[14:15], v[224:225], v[78:79]
	v_pk_fma_f32 v[80:81], v[16:17], v[226:227], v[80:81]
	s_nop 0
	v_cvt_pk_bf16_f32 v78, v78, v79
	v_cvt_pk_bf16_f32 v79, v80, v81
	v_lshlrev_b32_e32 v228, 16, v182
	v_and_b32_e32 v229, 0xffff0000, v182
	v_lshlrev_b32_e32 v230, 16, v183
	v_and_b32_e32 v231, 0xffff0000, v183
	v_pk_fma_f32 v[82:83], v[18:19], v[228:229], v[82:83]
	v_pk_fma_f32 v[84:85], v[20:21], v[230:231], v[84:85]
	s_nop 0
	v_cvt_pk_bf16_f32 v82, v82, v83
	v_cvt_pk_bf16_f32 v83, v84, v85
	v_lshlrev_b32_e32 v232, 16, v184
	v_and_b32_e32 v233, 0xffff0000, v184
	v_lshlrev_b32_e32 v234, 16, v185
	v_and_b32_e32 v235, 0xffff0000, v185
	v_pk_fma_f32 v[86:87], v[22:23], v[232:233], v[86:87]
	v_pk_fma_f32 v[88:89], v[24:25], v[234:235], v[88:89]
	s_nop 0
	v_cvt_pk_bf16_f32 v86, v86, v87
	v_cvt_pk_bf16_f32 v87, v88, v89
	v_lshlrev_b32_e32 v236, 16, v186
	v_and_b32_e32 v237, 0xffff0000, v186
	v_lshlrev_b32_e32 v238, 16, v187
	v_and_b32_e32 v239, 0xffff0000, v187
	v_pk_fma_f32 v[90:91], v[26:27], v[236:237], v[90:91]
	v_pk_fma_f32 v[92:93], v[28:29], v[238:239], v[92:93]
	s_nop 0
	v_cvt_pk_bf16_f32 v90, v90, v91
	v_cvt_pk_bf16_f32 v91, v92, v93
	v_lshlrev_b32_e32 v240, 16, v188
	v_and_b32_e32 v241, 0xffff0000, v188
	v_lshlrev_b32_e32 v242, 16, v189
	v_and_b32_e32 v243, 0xffff0000, v189
	v_pk_fma_f32 v[94:95], v[30:31], v[240:241], v[94:95]
	v_pk_fma_f32 v[96:97], v[32:33], v[242:243], v[96:97]
	s_nop 0
	v_cvt_pk_bf16_f32 v94, v94, v95
	v_cvt_pk_bf16_f32 v95, v96, v97
	v_lshlrev_b32_e32 v212, 16, v190
	v_and_b32_e32 v213, 0xffff0000, v190
	v_lshlrev_b32_e32 v214, 16, v191
	v_and_b32_e32 v215, 0xffff0000, v191
	v_pk_fma_f32 v[98:99], v[34:35], v[212:213], v[98:99]
	v_pk_fma_f32 v[100:101], v[36:37], v[214:215], v[100:101]
	s_nop 0
	v_cvt_pk_bf16_f32 v98, v98, v99
	v_cvt_pk_bf16_f32 v99, v100, v101
	v_lshlrev_b32_e32 v216, 16, v192
	v_and_b32_e32 v217, 0xffff0000, v192
	v_lshlrev_b32_e32 v218, 16, v193
	v_and_b32_e32 v219, 0xffff0000, v193
	v_pk_fma_f32 v[102:103], v[38:39], v[216:217], v[102:103]
	v_pk_fma_f32 v[104:105], v[40:41], v[218:219], v[104:105]
	s_nop 0
	v_cvt_pk_bf16_f32 v102, v102, v103
	v_cvt_pk_bf16_f32 v103, v104, v105
	v_lshlrev_b32_e32 v220, 16, v244
	v_and_b32_e32 v221, 0xffff0000, v244
	v_lshlrev_b32_e32 v222, 16, v245
	v_and_b32_e32 v223, 0xffff0000, v245
	v_pk_fma_f32 v[106:107], v[42:43], v[220:221], v[106:107]
	v_pk_fma_f32 v[108:109], v[44:45], v[222:223], v[108:109]
	s_nop 0
	v_cvt_pk_bf16_f32 v106, v106, v107
	v_cvt_pk_bf16_f32 v107, v108, v109
	v_lshlrev_b32_e32 v224, 16, v246
	v_and_b32_e32 v225, 0xffff0000, v246
	v_lshlrev_b32_e32 v226, 16, v247
	v_and_b32_e32 v227, 0xffff0000, v247
	v_pk_fma_f32 v[110:111], v[46:47], v[224:225], v[110:111]
	v_pk_fma_f32 v[112:113], v[48:49], v[226:227], v[112:113]
	s_nop 0
	v_cvt_pk_bf16_f32 v110, v110, v111
	v_cvt_pk_bf16_f32 v111, v112, v113
	v_lshlrev_b32_e32 v228, 16, v248
	v_and_b32_e32 v229, 0xffff0000, v248
	v_lshlrev_b32_e32 v230, 16, v249
	v_and_b32_e32 v231, 0xffff0000, v249
	v_pk_fma_f32 v[114:115], v[50:51], v[228:229], v[114:115]
	v_pk_fma_f32 v[116:117], v[52:53], v[230:231], v[116:117]
	s_nop 0
	v_cvt_pk_bf16_f32 v114, v114, v115
	v_cvt_pk_bf16_f32 v115, v116, v117
	v_lshlrev_b32_e32 v232, 16, v250
	v_and_b32_e32 v233, 0xffff0000, v250
	v_lshlrev_b32_e32 v234, 16, v251
	v_and_b32_e32 v235, 0xffff0000, v251
	v_pk_fma_f32 v[118:119], v[54:55], v[232:233], v[118:119]
	v_pk_fma_f32 v[120:121], v[56:57], v[234:235], v[120:121]
	s_nop 0
	v_cvt_pk_bf16_f32 v118, v118, v119
	v_cvt_pk_bf16_f32 v119, v120, v121
	v_lshlrev_b32_e32 v236, 16, v166
	v_and_b32_e32 v237, 0xffff0000, v166
	v_lshlrev_b32_e32 v238, 16, v167
	v_and_b32_e32 v239, 0xffff0000, v167
	v_pk_fma_f32 v[122:123], v[58:59], v[236:237], v[122:123]
	v_pk_fma_f32 v[124:125], v[60:61], v[238:239], v[124:125]
	s_nop 0
	v_cvt_pk_bf16_f32 v122, v122, v123
	v_cvt_pk_bf16_f32 v123, v124, v125
	v_lshlrev_b32_e32 v240, 16, v194
	v_and_b32_e32 v241, 0xffff0000, v194
	v_lshlrev_b32_e32 v242, 16, v195
	v_and_b32_e32 v243, 0xffff0000, v195
	v_pk_fma_f32 v[126:127], v[62:63], v[240:241], v[126:127]
	v_pk_fma_f32 v[128:129], v[64:65], v[242:243], v[128:129]
	s_nop 0
	v_cvt_pk_bf16_f32 v126, v126, v127
	v_cvt_pk_bf16_f32 v127, v128, v129
.Lbr_join:
	s_waitcnt vmcnt(0)
	s_barrier
	s_mul_i32 s12, s76, 9
	v_and_b32_e32 v170, 15, v1
	v_bfe_u32 v171, v1, 4, 2
	v_mul_u32_u24_e32 v130, 0x90, v170
	v_lshl_add_u32 v130, v171, 3, v130
	v_add_u32_e32 v130, s12, v130
	v_bfe_u32 v170, v1, 3, 3
	v_and_b32_e32 v171, 7, v1
	v_mul_u32_u24_e32 v131, 0x90, v170
	v_lshl_add_u32 v131, v171, 4, v131
	v_add_u32_e32 v131, s12, v131
	v_lshrrev_b32_e32 v172, 7, v1
	v_lshl_add_u32 v170, v172, 6, v170
	v_lshlrev_b32_e32 v132, 11, v170
	v_lshl_add_u32 v132, v171, 4, v132
	v_bfe_u32 v172, v1, 6, 1
	v_lshl_add_u32 v132, v172, 7, v132
	ds_write_b64 v130, v[66:67] offset:0
	ds_write_b64 v130, v[70:71] offset:32
	ds_write_b64 v130, v[74:75] offset:64
	ds_write_b64 v130, v[78:79] offset:96
	ds_write_b64 v130, v[82:83] offset:2304
	ds_write_b64 v130, v[86:87] offset:2336
	ds_write_b64 v130, v[90:91] offset:2368
	ds_write_b64 v130, v[94:95] offset:2400
	ds_write_b64 v130, v[98:99] offset:4608
	ds_write_b64 v130, v[102:103] offset:4640
	ds_write_b64 v130, v[106:107] offset:4672
	ds_write_b64 v130, v[110:111] offset:4704
	ds_write_b64 v130, v[114:115] offset:6912
	ds_write_b64 v130, v[118:119] offset:6944
	ds_write_b64 v130, v[122:123] offset:6976
	ds_write_b64 v130, v[126:127] offset:7008
	s_waitcnt lgkmcnt(0)
	ds_read_b128 v[2:5], v131 offset:0
	ds_read_b128 v[6:9], v131 offset:1152
	ds_read_b128 v[10:13], v131 offset:2304
	ds_read_b128 v[14:17], v131 offset:3456
	ds_read_b128 v[18:21], v131 offset:4608
	ds_read_b128 v[22:25], v131 offset:5760
	ds_read_b128 v[26:29], v131 offset:6912
	ds_read_b128 v[30:33], v131 offset:8064
	s_waitcnt lgkmcnt(7)
	global_store_dwordx4 v132, v[2:5], s[74:75] sc1
	s_add_u32 s74, s74, 0x4000
	s_addc_u32 s75, s75, 0
	s_waitcnt lgkmcnt(6)
	global_store_dwordx4 v132, v[6:9], s[74:75] sc1
	s_add_u32 s74, s74, 0x4000
	s_addc_u32 s75, s75, 0
	s_waitcnt lgkmcnt(5)
	global_store_dwordx4 v132, v[10:13], s[74:75] sc1
	s_add_u32 s74, s74, 0x4000
	s_addc_u32 s75, s75, 0
	s_waitcnt lgkmcnt(4)
	global_store_dwordx4 v132, v[14:17], s[74:75] sc1
	s_add_u32 s74, s74, 0x4000
	s_addc_u32 s75, s75, 0
	s_waitcnt lgkmcnt(3)
	global_store_dwordx4 v132, v[18:21], s[74:75] sc1
	s_add_u32 s74, s74, 0x4000
	s_addc_u32 s75, s75, 0
	s_waitcnt lgkmcnt(2)
	global_store_dwordx4 v132, v[22:25], s[74:75] sc1
	s_add_u32 s74, s74, 0x4000
	s_addc_u32 s75, s75, 0
	s_waitcnt lgkmcnt(1)
	global_store_dwordx4 v132, v[26:29], s[74:75] sc1
	s_add_u32 s74, s74, 0x4000
	s_addc_u32 s75, s75, 0
	s_waitcnt lgkmcnt(0)
	global_store_dwordx4 v132, v[30:33], s[74:75] sc1
	s_waitcnt vmcnt(0)
	s_barrier
	s_cmp_lg_u32 s76, 0
	s_cbranch_scc1 .Lbr_noflag
	v_readlane_b32 s12, v253, 5
	v_readlane_b32 s13, v253, 6
	s_and_b32 s2, s78, 3
	s_or_b32 s2, s2, s77
	s_lshl_b32 s2, s2, 2
	s_add_u32 s2, s2, 0x100
	v_mov_b32_e32 v170, s2
	v_mov_b32_e32 v171, 1
	s_nop 3
	s_mov_b64 exec, 1
	global_atomic_add v170, v171, s[12:13]
	s_mov_b64 exec, -1

.LBB0_727:
	s_mov_b64 s[2:3], s[46:47]
	s_add_i32 s18, s2, 1
	s_cmp_ge_i32 s18, s3
	v_readlane_b32 s30, v254, 6
	v_readlane_b32 s38, v254, 8
	v_readlane_b32 s56, v254, 22
	v_readlane_b32 s31, v254, 7
	v_readlane_b32 s39, v254, 9
	v_readlane_b32 s57, v254, 23
	s_cbranch_scc1 .LBB0_781
	s_cmp_eq_u32 s2, 4
	s_cbranch_scc1 .LBB0_781
	s_cmp_eq_u32 s2, 13
	s_cbranch_scc1 .LBB0_781
	s_cmp_eq_u32 s2, 5
	s_cbranch_scc1 .LBB0_781
	s_cmp_eq_u32 s2, 14
	s_cbranch_scc1 .LBB0_781
	s_cmp_eq_u32 s2, 9
	s_cbranch_scc1 .LBB0_781
	s_cmp_eq_u32 s2, 18
	s_cbranch_scc1 .LBB0_781
	s_waitcnt vmcnt(0)
	s_waitcnt lgkmcnt(0)
	s_barrier
	s_mov_b64 s[2:3], exec
	v_readlane_b32 s4, v253, 7
	v_readlane_b32 s5, v253, 8
	s_and_b64 s[4:5], s[2:3], s[4:5]
	s_mov_b64 exec, s[4:5]
	s_cbranch_execz .LBB0_780
	s_add_i32 s13, 0, 0x24000
	s_mov_b64 s[4:5], src_shared_base
	s_cmp_lg_u32 s13, -1
	s_cselect_b32 s4, s13, 0
	s_cselect_b32 s6, s5, 0
	s_add_i32 s12, 0, 0x24004
	s_cmp_lg_u32 s12, -1
	v_mov_b32_e32 v2, s4
	v_mov_b32_e32 v3, s6
	s_cselect_b32 s4, s12, 0
	s_cselect_b32 s5, s5, 0
	s_waitcnt vmcnt(0) expcnt(0) lgkmcnt(0)
	s_and_b32 s4, s101, 0xffff
	v_mov_b32_e32 v4, s4
	v_mov_b32_e32 v2, s4
	v_mov_b32_e32 v3, s5
	s_lshr_b32 s4, s101, 16
	v_mov_b32_e32 v2, s4
	s_waitcnt vmcnt(0) lgkmcnt(0)
	v_cmp_eq_u32_e32 vcc, 0, v4
	s_and_saveexec_b64 s[4:5], vcc
	s_cbranch_execz .LBB0_744
	s_mov_b32 s14, 1
	s_branch .LBB0_732
